# FFN1+FFN2 K-loops: 128x256 tiles, LDS-DMA staging, K-blocked weights and hidden activations
# speedup vs baseline: 1.0467x; 1.0467x over previous
; DI void st8(u16* dst, const float (&v)[8]) { *(u32x4*)dst = pack8(v); }
; DI void prep_tile(const float* __restrict__ W, int K, int N, const float* __restrict__ gain, u16* __restrict__ dst, int mode, int tile, char* smem) {
;     ...
; #pragma unroll
;   for (int i = 0; i < 2; ++i) {
;     const int cid = tid + 256 * i, nl = cid >> 3, kc = cid & 7, n = n0 + nl;
;     if (n < N) {
;       float v[8];
; #pragma unroll
;       for (int j = 0; j < 8; ++j) v[j] = Ts[nl * 65 + kc * 8 + j];
;       st8(dst + (size_t)colmap(mode, n) * K + k0 + kc * 8, v);
;     }
;   }
; DI void phase_prep(const Params& p, char* smem) {
;     ...
;       case 0: W = p.w_in + (size_t)l * 1024 * DIN; K = 1024; N = DIN; gain = p.mix_norm + l * 1024; dst = (u16*)(p.ws + OFF_WIN + l * SZ_WIN); mode = 1; break;
;       case 1: W = p.w_mla_q_b + (size_t)l * 384 * 768; K = 384; N = 768; gain = p.mla_q_a_norm + l * 384; dst = (u16*)(p.ws + OFF_WQB + l * SZ_WQB); mode = 2; break;
;       case 2: W = p.w_mla_kv_b + (size_t)l * 256 * 1024; K = 256; N = 1024; gain = p.mla_kv_a_norm + l * 256; dst = (u16*)(p.ws + OFF_WKVB + l * SZ_WKVB); break;
;       case 3: W = p.w_mem_kv + (size_t)l * 1024 * 1024; K = 1024; N = 1024; gain = p.mem_norm + l * 1024; dst = (u16*)(p.ws + OFF_WMEM + l * SZ_WMEM); break;
;       case 4: case 5: case 6: W = p.w_branch + (size_t)(l * 3 + (k - 4)) * 512 * 1024; K = 512; N = 1024; dst = (u16*)(p.ws + OFF_WBR + (l * 3 + (k - 4)) * SZ_WBR); break;
;       case 7: W = p.w_out + (size_t)l * 1024 * 1024; K = 1024; N = 1024; dst = (u16*)(p.ws + OFF_WOUT + l * SZ_WOUT); break;
;       case 8: W = p.w_ff1 + (size_t)l * 1024 * 4096; K = 1024; N = 4096; gain = p.ffn_norm + l * 1024; dst = (u16*)(p.ws + OFF_WFF1 + l * SZ_WFF1); break;
;       default: W = p.w_ff2 + (size_t)l * 4096 * 1024; K = 4096; N = 1024; dst = (u16*)(p.ws + OFF_WFF2 + l * SZ_WFF2); break;
.LBB1_41:
	s_mov_b32 s40, 0
	s_cmp_eq_u32 s73, 8
	s_cselect_b32 s40, 0x40000, s40
	s_cmp_eq_u32 s73, 9
	s_cselect_b32 s40, 0x10000, s40
	s_cmp_eq_u32 s73, 18
	s_cselect_b32 s40, 0x40000, s40
	s_cmp_eq_u32 s73, 19
	s_cselect_b32 s40, 0x10000, s40
	s_cmp_eq_u32 s40, 0
	s_cbranch_scc0 .Lprep_blk2
	v_ashrrev_i32_e32 v16, 31, v14
	v_mad_u64_u32 v[14:15], s[40:41], v14, s74, 0
	v_mov_b32_e32 v2, v15
	v_mad_u64_u32 v[16:17], s[40:41], v16, s74, v[2:3]
	v_mov_b32_e32 v15, v16
	v_lshl_add_u64 v[14:15], v[14:15], 1, v[4:5]
	s_branch .Lprep_st2
.Lprep_blk2:
	v_subrev_u32_e32 v15, s34, v4
	v_lshrrev_b32_e32 v16, 6, v15
	v_and_b32_e32 v15, 63, v15
	v_mul_lo_u32 v16, v16, s40
	v_lshl_add_u32 v14, v14, 6, v15
	v_add_u32_e32 v14, v14, v16
	v_mov_b32_e32 v15, 0
	v_lshl_add_u64 v[14:15], s[34:35], 0, v[14:15]
.Lprep_st2:
	s_waitcnt lgkmcnt(3)
	v_cvt_pk_bf16_f32 v4, v6, v7
	s_waitcnt lgkmcnt(2)
	v_cvt_pk_bf16_f32 v5, v8, v9
	s_waitcnt lgkmcnt(1)
	v_cvt_pk_bf16_f32 v6, v10, v11
	s_waitcnt lgkmcnt(0)
	v_cvt_pk_bf16_f32 v7, v12, v13
	global_store_dwordx4 v[14:15], v[4:7], off

; DI void st8(u16* dst, const float (&v)[8]) { *(u32x4*)dst = pack8(v); }
; DI void prep_tile(const float* __restrict__ W, int K, int N, const float* __restrict__ gain, u16* __restrict__ dst, int mode, int tile, char* smem) {
;     ...
; #pragma unroll
;   for (int i = 0; i < 2; ++i) {
;     const int cid = tid + 256 * i, nl = cid >> 3, kc = cid & 7, n = n0 + nl;
;     if (n < N) {
;       float v[8];
; #pragma unroll
;       for (int j = 0; j < 8; ++j) v[j] = Ts[nl * 65 + kc * 8 + j];
;       st8(dst + (size_t)colmap(mode, n) * K + k0 + kc * 8, v);
;     }
;   }
; DI void phase_prep(const Params& p, char* smem) {
;     ...
;       case 0: W = p.w_in + (size_t)l * 1024 * DIN; K = 1024; N = DIN; gain = p.mix_norm + l * 1024; dst = (u16*)(p.ws + OFF_WIN + l * SZ_WIN); mode = 1; break;
;       case 1: W = p.w_mla_q_b + (size_t)l * 384 * 768; K = 384; N = 768; gain = p.mla_q_a_norm + l * 384; dst = (u16*)(p.ws + OFF_WQB + l * SZ_WQB); mode = 2; break;
;       case 2: W = p.w_mla_kv_b + (size_t)l * 256 * 1024; K = 256; N = 1024; gain = p.mla_kv_a_norm + l * 256; dst = (u16*)(p.ws + OFF_WKVB + l * SZ_WKVB); break;
;       case 3: W = p.w_mem_kv + (size_t)l * 1024 * 1024; K = 1024; N = 1024; gain = p.mem_norm + l * 1024; dst = (u16*)(p.ws + OFF_WMEM + l * SZ_WMEM); break;
;       case 4: case 5: case 6: W = p.w_branch + (size_t)(l * 3 + (k - 4)) * 512 * 1024; K = 512; N = 1024; dst = (u16*)(p.ws + OFF_WBR + (l * 3 + (k - 4)) * SZ_WBR); break;
;       case 7: W = p.w_out + (size_t)l * 1024 * 1024; K = 1024; N = 1024; dst = (u16*)(p.ws + OFF_WOUT + l * SZ_WOUT); break;
;       case 8: W = p.w_ff1 + (size_t)l * 1024 * 4096; K = 1024; N = 4096; gain = p.ffn_norm + l * 1024; dst = (u16*)(p.ws + OFF_WFF1 + l * SZ_WFF1); break;
;       default: W = p.w_ff2 + (size_t)l * 4096 * 1024; K = 4096; N = 1024; dst = (u16*)(p.ws + OFF_WFF2 + l * SZ_WFF2); break;
.LBB1_122:
	s_mov_b32 s40, 0
	s_cmp_eq_u32 s73, 8
	s_cselect_b32 s40, 0x40000, s40
	s_cmp_eq_u32 s73, 9
	s_cselect_b32 s40, 0x10000, s40
	s_cmp_eq_u32 s73, 18
	s_cselect_b32 s40, 0x40000, s40
	s_cmp_eq_u32 s73, 19
	s_cselect_b32 s40, 0x10000, s40
	s_cmp_eq_u32 s40, 0
	s_cbranch_scc0 .Lprep_blk1
	v_ashrrev_i32_e32 v18, 31, v16
	v_mad_u64_u32 v[16:17], s[40:41], v16, s74, 0
	v_mov_b32_e32 v2, v17
	v_mad_u64_u32 v[18:19], s[40:41], v18, s74, v[2:3]
	v_mov_b32_e32 v17, v18
	v_lshl_add_u64 v[16:17], v[16:17], 1, v[4:5]
	s_branch .Lprep_st1
.Lprep_blk1:
	v_subrev_u32_e32 v17, s34, v4
	v_lshrrev_b32_e32 v18, 6, v17
	v_and_b32_e32 v17, 63, v17
	v_mul_lo_u32 v18, v18, s40
	v_lshl_add_u32 v16, v16, 6, v17
	v_add_u32_e32 v16, v16, v18
	v_mov_b32_e32 v17, 0
	v_lshl_add_u64 v[16:17], s[34:35], 0, v[16:17]
.Lprep_st1:
	s_waitcnt lgkmcnt(3)
	v_cvt_pk_bf16_f32 v6, v6, v7
	s_waitcnt lgkmcnt(2)
	v_cvt_pk_bf16_f32 v7, v8, v9
	s_waitcnt lgkmcnt(1)
	v_cvt_pk_bf16_f32 v8, v10, v11
	s_waitcnt lgkmcnt(0)
	v_cvt_pk_bf16_f32 v9, v12, v13
	global_store_dwordx4 v[16:17], v[6:9], off

; DI int TID() { int t = (int)__builtin_amdgcn_workitem_id_x(); asm volatile("" : "+v"(t)); return t; }
; DI int BID() { int b = (int)__builtin_amdgcn_workgroup_id_x(); asm volatile("" : "+s"(b)); return b; }
; DI void gemm_issue(PF& pf, const u16* __restrict__ Ap, int lda, const u16* __restrict__ Wt, int K) {
;   const int tid = TID(); const int srow = tid >> 3, sc8 = (tid & 7) * 8;
;   const unsigned aoff = (unsigned)(srow * lda + sc8) * 2u, woff = (unsigned)(srow * K + sc8) * 2u;
; #pragma unroll
;   for (int i = 0; i < 4; ++i) {
;     pf.a0[i] = *(const u32x4*)((const char*)Ap + (aoff + (unsigned)(32 * i * lda) * 2u)); pf.b0[i] = *(const u32x4*)((const char*)Wt + (woff + (unsigned)(32 * i * K) * 2u));
;   }
; #pragma unroll
;   for (int i = 0; i < 4; ++i) {
;     pf.a1[i] = *(const u32x4*)((const char*)Ap + (aoff + (unsigned)(32 * i * lda + 64) * 2u)); pf.b1[i] = *(const u32x4*)((const char*)Wt + (woff + (unsigned)(32 * i * K + 64) * 2u));
;   }
; }
; DI void run_phase(const Params& p, int ph, int l, int c, char* smem) {
;     ...
;     default: {
;       PF pf; int t = BID();
;       if (t < MTN * 8) { const u16* A0; const u16* W0; ffn2_ptrs(p, l, t, A0, W0); gemm_issue(pf, A0, 4096, W0, 4096); }
;       for (; t < MTN * 8; t += gridDim.x) { const int tn = t + (int)gridDim.x; tile_ffn2(p, l, ck, t, tn < MTN * 8 ? tn : -1, pf, smem); }
.LBB1_198:
	s_andn2_b64 vcc, exec, s[26:27]
	s_cbranch_vccnz .LBB1_250
	v_readlane_b32 s0, v255, 30
	s_cmp_lg_u32 s0, 8
	s_mov_b64 s[22:23], -1
	s_cbranch_scc0 .LBB1_242
	s_mov_b32 s26, s92
	s_cmpk_lt_i32 s26, 0x400
	s_cselect_b64 s[22:23], -1, 0
	s_cmpk_gt_i32 s26, 0x3ff
	s_cbranch_scc1 .LBB1_202
	s_lshl_b32 s0, s26, 20
	s_and_b32 s0, s0, 0x7f00000
	s_add_u32 s0, s18, s0
	s_addc_u32 s17, s19, 0
	v_readlane_b32 s24, v255, 28
	s_add_u32 s16, s0, 0x6b80000
	v_readlane_b32 s25, v255, 29
	s_addc_u32 s17, s17, 0
	s_ashr_i32 s25, s24, 31
	s_mov_b32 s0, s24
	v_writelane_b32 v255, s0, 28
	s_lshl_b64 s[24:25], s[24:25], 23
	v_writelane_b32 v255, s1, 29
	s_add_u32 s0, s18, s24
	s_addc_u32 s27, s19, s25
	s_and_b32 s24, s26, 0xffffff80
	s_ashr_i32 s25, s24, 31
	s_lshl_b64 s[24:25], s[24:25], 13
	s_add_u32 s0, s0, s24
	s_addc_u32 s25, s27, s25
	s_add_u32 s24, s0, 0x4380000
	s_movk_i32 s0, 0xe000
	s_addc_u32 s25, s25, 0

; DI int TID() { int t = (int)__builtin_amdgcn_workitem_id_x(); asm volatile("" : "+v"(t)); return t; }
; DI u32x4 pack8(const float (&v)[8]) { u32x4 r = {pk2(v[0], v[1]), pk2(v[2], v[3]), pk2(v[4], v[5]), pk2(v[6], v[7])}; return r; }
; DI void tile_ffn2(const Params& p, int l, const Chunk& ck, int tile, int next, PF& pf, char* smem) {
;     ...
;   const int tid = TID(); const int mi = tile & (MTN - 1), ni = tile >> MTS; const int m0 = mi * 128, n0 = ni * 128;
;   f32x16 acc[2][2]; zero_acc(acc);
;   { const u16* Ap; const u16* Wt; ffn2_ptrs(p, l, tile, Ap, Wt); gemm_run<64>(pf, Ap, 4096, Wt, acc, smem); }
;   if (next >= 0) { const u16* An; const u16* Wn; ffn2_ptrs(p, l, next, An, Wn); gemm_issue(pf, An, 4096, Wn, 4096); }
;   acc_to_cs(acc, Cs);
;   const int row = tid >> 1, half = tid & 1; float ssq = 0.f;
;   float* xd = p.out + (size_t)(ck.tok0 + m0 + row) * 1024 + n0 + half * 64;
;   u16* xb = (u16*)(p.ws + OFF_XB) + (size_t)(m0 + row) * 1024 + n0 + half * 64;
; #pragma unroll
;   for (int c8 = 0; c8 < 8; ++c8) {
;     float v[8], x[8]; cs_ld8(Cs, row, half * 64 + c8 * 8, v); unpack8(*(const u32x4*)(xb + c8 * 8), x);
; #pragma unroll
;     for (int j = 0; j < 8; ++j) { v[j] += x[j]; ssq += v[j] * v[j]; }
;     if (l == 0) *(u32x4*)(xb + c8 * 8) = pack8(v);
;     else { *(f32x4*)(xd + c8 * 8) = f32x4{v[0], v[1], v[2], v[3]}; *(f32x4*)(xd + c8 * 8 + 4) = f32x4{v[4], v[5], v[6], v[7]}; }
;   }
;   if (l == 0) ((float*)(p.ws + OFF_PSIN))[(size_t)(m0 + row) * 16 + ni * 2 + half] = ssq;
; }
.LBB1_205:
	s_cmp_lg_u32 s16, 0
	s_cbranch_scc1 .Lffn2_p2done
	s_mov_b32 s16, 1
	v_mov_b32_e32 v0, v172
	s_add_u32 s26, s26, 0x80
	s_and_b32 s36, s26, 0xffffff80
	s_mov_b32 s37, 0
	v_mov_b32_e32 v34, v74
	v_mov_b32_e32 v35, v75
	v_mov_b32_e32 v36, v76
	v_mov_b32_e32 v37, v77
	v_mov_b32_e32 v38, v78
	v_mov_b32_e32 v39, v79
	v_mov_b32_e32 v40, v80
	v_mov_b32_e32 v41, v81
	v_mov_b32_e32 v42, v82
	v_mov_b32_e32 v43, v83
	v_mov_b32_e32 v44, v84
	v_mov_b32_e32 v45, v85
	v_mov_b32_e32 v46, v86
	v_mov_b32_e32 v47, v87
	v_mov_b32_e32 v48, v88
	v_mov_b32_e32 v49, v89
	v_mov_b32_e32 v50, v90
	v_mov_b32_e32 v51, v91
	v_mov_b32_e32 v52, v92
	v_mov_b32_e32 v53, v93
	v_mov_b32_e32 v54, v94
	v_mov_b32_e32 v55, v95
	v_mov_b32_e32 v56, v96
	v_mov_b32_e32 v57, v97
	v_mov_b32_e32 v58, v98
	v_mov_b32_e32 v59, v99
	v_mov_b32_e32 v60, v100
	v_mov_b32_e32 v61, v101
	v_mov_b32_e32 v62, v102
	v_mov_b32_e32 v63, v103
	v_mov_b32_e32 v64, v104
	v_mov_b32_e32 v65, v105
	v_mov_b32_e32 v2, v106
	v_mov_b32_e32 v3, v107
	v_mov_b32_e32 v4, v108
	v_mov_b32_e32 v5, v109
	v_mov_b32_e32 v6, v110
	v_mov_b32_e32 v7, v111
	v_mov_b32_e32 v8, v112
	v_mov_b32_e32 v9, v113
	v_mov_b32_e32 v10, v114
	v_mov_b32_e32 v11, v115
	v_mov_b32_e32 v12, v116
	v_mov_b32_e32 v13, v117
	v_mov_b32_e32 v14, v118
	v_mov_b32_e32 v15, v119
	v_mov_b32_e32 v16, v120
	v_mov_b32_e32 v17, v121
	v_mov_b32_e32 v18, v208
	v_mov_b32_e32 v19, v209
	v_mov_b32_e32 v20, v210
	v_mov_b32_e32 v21, v211
	v_mov_b32_e32 v22, v212
	v_mov_b32_e32 v23, v213
	v_mov_b32_e32 v24, v214
	v_mov_b32_e32 v25, v215
	v_mov_b32_e32 v26, v216
	v_mov_b32_e32 v27, v217
	v_mov_b32_e32 v28, v218
	v_mov_b32_e32 v29, v219
	v_mov_b32_e32 v30, v220
	v_mov_b32_e32 v31, v221
	v_mov_b32_e32 v32, v222
	v_mov_b32_e32 v33, v223
	s_waitcnt lgkmcnt(0)
	s_barrier
	s_branch .Lffn2_epi2

; DI int TID() { int t = (int)__builtin_amdgcn_workitem_id_x(); asm volatile("" : "+v"(t)); return t; }
; #define BLOAD(A_, B_, kt) do { _Pragma("unroll") for (int i = 0; i < 4; ++i) { \
;     A_[i] = *(const u32x4*)((const char*)Ap + (aoff + (unsigned)(32 * i * lda + (kt) * 64) * 2u)); B_[i] = *(const u32x4*)((const char*)Wt + (woff + (unsigned)(32 * i * K + (kt) * 64) * 2u)); } } while (0)
; #define BLOAD(A_, B_, kt) do { _Pragma("unroll") for (int i = 0; i < 4; ++i) { \
;     A_[i] = *(const u32x4*)((const char*)Ap + (aoff + (unsigned)(32 * i * lda + (kt) * 64) * 2u)); B_[i] = *(const u32x4*)((const char*)Wt + (woff + (unsigned)(32 * i * K + (kt) * 64) * 2u)); } } while (0)
; #define BSTORE(A_, B_, buf) do { _Pragma("unroll") for (int i = 0; i < 4; ++i) { \
;     *(u32x4*)&As[(buf) * GBUF + (srow + 32 * i) * LDT + sc8] = A_[i]; \
;     *(u32x4*)&Bs[(buf) * GBUF + (srow + 32 * i) * LDT + sc8] = B_[i]; } } while (0)
; template <int NK>
; DI void gemm_run(PF& pf, const u16* __restrict__ Ap, int lda, const u16* __restrict__ Wt, f32x16 (&acc)[2][2], char* smem) {
;   constexpr int K = NK * 64;
;   const int tid = TID(), lane = tid & 63, w = tid >> 6, wm = w >> 1, wn = w & 1, r32 = lane & 31, hi = lane >> 5;
;   u16* As = (u16*)smem; u16* Bs = As + 128 * LDT;
;   const int srow = tid >> 3, sc8 = (tid & 7) * 8;
;   constexpr int nk = NK;
;   const unsigned aoff = (unsigned)(srow * lda + sc8) * 2u, woff = (unsigned)(srow * K + sc8) * 2u;
;     ...
;   __builtin_amdgcn_s_setprio(0);
;   __syncthreads();
;   BSTORE(pf.a0, pf.b0, 0);
;   BLOAD(pf.a0, pf.b0, 2);
;   __syncthreads();
; #pragma unroll
;   for (int kt = 0; kt < nk; kt += 2) {
;     BCOMP(0);
;     BSTORE(pf.a1, pf.b1, 1);
;     if (kt + 3 < nk) BLOAD(pf.a1, pf.b1, kt + 3);
;     __syncthreads();
;     BCOMP(1);
;     if (kt + 2 < nk) { BSTORE(pf.a0, pf.b0, 0); if (kt + 4 < nk) BLOAD(pf.a0, pf.b0, kt + 4); }
;     __syncthreads();
;   }
.LBB1_206:
	s_add_i32 s25, s26, s78
	s_cmpk_gt_i32 s25, 0x1ff
	s_cselect_b64 s[28:29], -1, 0
	s_cmpk_lt_i32 s25, 0x200
	s_cselect_b32 s0, s25, -1
	s_and_b32 s16, s41, 0x3f80000
	s_and_b32 s36, s26, 0xffffff80
	s_add_i32 s26, s26, s36
	s_lshl_b32 s36, s36, 1
	s_lshl_b32 s16, s16, 1
	s_add_u32 vcc_lo, s17, s16
	v_mov_b32_e32 v0, v172
	s_addc_u32 vcc_hi, s27, 0
	s_ashr_i32 s37, s36, 31
	s_lshl_b64 s[30:31], s[36:37], 6
	s_add_u32 s30, s34, s30
	s_addc_u32 s31, s40, s31
	s_setprio 0
	s_waitcnt lgkmcnt(0)
	s_lshr_b32 s16, s16, 7
	s_add_u32 s42, s17, s16
	s_addc_u32 s43, s27, 0
	v_and_b32_e32 v174, 63, v172
	v_lshrrev_b32_e32 v175, 6, v172
	v_lshrrev_b32_e32 v176, 4, v174
	v_xor_b32_e32 v176, v176, v174
	v_and_b32_e32 v176, 3, v176
	v_lshlrev_b32_e32 v176, 4, v176
	v_lshrrev_b32_e32 v177, 2, v174
	v_lshl_add_u32 v137, v175, 5, v177
	v_lshl_add_u32 v137, v137, 6, v176
	v_mov_b32_e32 v150, v137
	v_lshl_add_u32 v151, v175, 6, v177
	v_lshl_add_u32 v151, v151, 6, v176
	v_mov_b32_e32 v152, v151
	v_mov_b32_e32 v153, v151
	v_mov_b32_e32 v154, v151
	v_readfirstlane_b32 s16, v175
	s_lshl_b32 s0, s16, 12
	s_lshl_b32 s16, s16, 11
	s_add_u32 s0, s0, 0x2000
	v_and_b32_e32 v176, 31, v174
	v_lshrrev_b32_e32 v177, 5, v174
	v_lshrrev_b32_e32 v174, 2, v176
	v_and_b32_e32 v174, 3, v174
	v_xor_b32_e32 v174, v174, v177
	v_lshlrev_b32_e32 v174, 4, v174
	v_lshl_add_u32 v174, v176, 6, v174
	v_lshrrev_b32_e32 v176, 1, v175
	v_and_b32_e32 v177, 1, v175
	v_lshl_add_u32 v126, v176, 12, v174
	v_lshl_add_u32 v128, v177, 12, v174
	v_add_u32_e32 v128, 0x2000, v128
	v_xor_b32_e32 v127, 32, v126
	v_xor_b32_e32 v129, 32, v128
	s_barrier
	s_add_u32 m0, s16, 0x0
	s_nop 0
	global_load_lds_dwordx4 v137, s[42:43]
	global_load_lds_dwordx4 v150, s[42:43] offset:1024
	s_add_u32 m0, s0, 0x0
	s_nop 0
	global_load_lds_dwordx4 v151, s[30:31]
	global_load_lds_dwordx4 v152, s[30:31] offset:1024
	global_load_lds_dwordx4 v153, s[30:31] offset:2048
	global_load_lds_dwordx4 v154, s[30:31] offset:3072
	s_add_u32 m0, s16, 0x6000
	s_add_u32 s42, s42, 0x100000
	s_addc_u32 s43, s43, 0
	global_load_lds_dwordx4 v137, s[42:43]
	global_load_lds_dwordx4 v150, s[42:43] offset:1024
	s_add_u32 m0, s0, 0x6000
	s_add_u32 s30, s30, 0x10000
	s_addc_u32 s31, s31, 0
	global_load_lds_dwordx4 v151, s[30:31]
	global_load_lds_dwordx4 v152, s[30:31] offset:1024
	global_load_lds_dwordx4 v153, s[30:31] offset:2048
	global_load_lds_dwordx4 v154, s[30:31] offset:3072
	s_waitcnt vmcnt(6)
	s_barrier
	s_setprio 1
	ds_read_b128 v[224:227], v126 offset:0
	ds_read_b128 v[232:235], v128 offset:0
	ds_read_b128 v[236:239], v128 offset:2048
	ds_read_b128 v[228:231], v126 offset:2048
	ds_read_b128 v[240:243], v128 offset:8192
	ds_read_b128 v[244:247], v128 offset:10240
	ds_read_b128 v[248:251], v127 offset:0
	ds_read_b128 v[160:163], v129 offset:0
	ds_read_b128 v[164:167], v129 offset:2048
	ds_read_b128 v[156:159], v127 offset:2048
	ds_read_b128 v[168:171], v129 offset:8192
	ds_read_b128 v[122:125], v129 offset:10240
	s_add_u32 m0, s16, 0xc000
	s_add_u32 s42, s42, 0x100000
	s_addc_u32 s43, s43, 0
	global_load_lds_dwordx4 v137, s[42:43]
	global_load_lds_dwordx4 v150, s[42:43] offset:1024
	s_add_u32 m0, s0, 0xc000
	s_add_u32 s30, s30, 0x10000
	s_addc_u32 s31, s31, 0
	global_load_lds_dwordx4 v151, s[30:31]
	global_load_lds_dwordx4 v152, s[30:31] offset:1024
	global_load_lds_dwordx4 v153, s[30:31] offset:2048
	global_load_lds_dwordx4 v154, s[30:31] offset:3072
	s_waitcnt lgkmcnt(10)
	v_mfma_f32_32x32x16_bf16 v[34:49], v[224:227], v[232:235], 0
	s_waitcnt lgkmcnt(9)
	v_mfma_f32_32x32x16_bf16 v[50:65], v[224:227], v[236:239], 0
	s_waitcnt lgkmcnt(8)
	v_mfma_f32_32x32x16_bf16 v[2:17], v[228:231], v[232:235], 0
	v_mfma_f32_32x32x16_bf16 v[18:33], v[228:231], v[236:239], 0
	s_waitcnt lgkmcnt(7)
	v_mfma_f32_32x32x16_bf16 v[74:89], v[224:227], v[240:243], 0
	s_waitcnt lgkmcnt(6)
	v_mfma_f32_32x32x16_bf16 v[90:105], v[224:227], v[244:247], 0
	v_mfma_f32_32x32x16_bf16 v[106:121], v[228:231], v[240:243], 0
	v_mfma_f32_32x32x16_bf16 v[208:223], v[228:231], v[244:247], 0
	s_waitcnt lgkmcnt(4)
	v_mfma_f32_32x32x16_bf16 v[34:49], v[248:251], v[160:163], v[34:49]
	s_waitcnt lgkmcnt(3)
	v_mfma_f32_32x32x16_bf16 v[50:65], v[248:251], v[164:167], v[50:65]
	s_waitcnt lgkmcnt(2)
	v_mfma_f32_32x32x16_bf16 v[2:17], v[156:159], v[160:163], v[2:17]
	v_mfma_f32_32x32x16_bf16 v[18:33], v[156:159], v[164:167], v[18:33]
	s_waitcnt lgkmcnt(1)
	v_mfma_f32_32x32x16_bf16 v[74:89], v[248:251], v[168:171], v[74:89]
	s_waitcnt lgkmcnt(0)
	v_mfma_f32_32x32x16_bf16 v[90:105], v[248:251], v[122:125], v[90:105]
	v_mfma_f32_32x32x16_bf16 v[106:121], v[156:159], v[168:171], v[106:121]
	v_mfma_f32_32x32x16_bf16 v[208:223], v[156:159], v[122:125], v[208:223]
	s_setprio 0
	s_waitcnt vmcnt(6)
	s_barrier
; #define BLOAD(A_, B_, kt) do { _Pragma("unroll") for (int i = 0; i < 4; ++i) { \
;     A_[i] = *(const u32x4*)((const char*)Ap + (aoff + (unsigned)(32 * i * lda + (kt) * 64) * 2u)); B_[i] = *(const u32x4*)((const char*)Wt + (woff + (unsigned)(32 * i * K + (kt) * 64) * 2u)); } } while (0)
; #define BLOAD(A_, B_, kt) do { _Pragma("unroll") for (int i = 0; i < 4; ++i) { \
;     A_[i] = *(const u32x4*)((const char*)Ap + (aoff + (unsigned)(32 * i * lda + (kt) * 64) * 2u)); B_[i] = *(const u32x4*)((const char*)Wt + (woff + (unsigned)(32 * i * K + (kt) * 64) * 2u)); } } while (0)
; #define BSTORE(A_, B_, buf) do { _Pragma("unroll") for (int i = 0; i < 4; ++i) { \
;     *(u32x4*)&As[(buf) * GBUF + (srow + 32 * i) * LDT + sc8] = A_[i]; \
;     *(u32x4*)&Bs[(buf) * GBUF + (srow + 32 * i) * LDT + sc8] = B_[i]; } } while (0)
; template <int NK>
; DI void gemm_run(PF& pf, const u16* __restrict__ Ap, int lda, const u16* __restrict__ Wt, f32x16 (&acc)[2][2], char* smem) {
;     ...
; #pragma unroll
;   for (int kt = 0; kt < nk; kt += 2) {
;     BCOMP(0);
;     BSTORE(pf.a1, pf.b1, 1);
;     if (kt + 3 < nk) BLOAD(pf.a1, pf.b1, kt + 3);
;     __syncthreads();
;     BCOMP(1);
;     if (kt + 2 < nk) { BSTORE(pf.a0, pf.b0, 0); if (kt + 4 < nk) BLOAD(pf.a0, pf.b0, kt + 4); }
;     __syncthreads();
;   }
	s_setprio 1
	ds_read_b128 v[224:227], v126 offset:24576
	ds_read_b128 v[232:235], v128 offset:24576
	ds_read_b128 v[236:239], v128 offset:26624
	ds_read_b128 v[228:231], v126 offset:26624
	ds_read_b128 v[240:243], v128 offset:32768
	ds_read_b128 v[244:247], v128 offset:34816
	ds_read_b128 v[248:251], v127 offset:24576
	ds_read_b128 v[160:163], v129 offset:24576
	ds_read_b128 v[164:167], v129 offset:26624
	ds_read_b128 v[156:159], v127 offset:26624
	ds_read_b128 v[168:171], v129 offset:32768
	ds_read_b128 v[122:125], v129 offset:34816
	s_add_u32 m0, s16, 0x0
	s_add_u32 s42, s42, 0x100000
	s_addc_u32 s43, s43, 0
	global_load_lds_dwordx4 v137, s[42:43]
	global_load_lds_dwordx4 v150, s[42:43] offset:1024
	s_add_u32 m0, s0, 0x0
	s_add_u32 s30, s30, 0x10000
	s_addc_u32 s31, s31, 0
	global_load_lds_dwordx4 v151, s[30:31]
	global_load_lds_dwordx4 v152, s[30:31] offset:1024
	global_load_lds_dwordx4 v153, s[30:31] offset:2048
	global_load_lds_dwordx4 v154, s[30:31] offset:3072
	s_waitcnt lgkmcnt(10)
	v_mfma_f32_32x32x16_bf16 v[34:49], v[224:227], v[232:235], v[34:49]
	s_waitcnt lgkmcnt(9)
	v_mfma_f32_32x32x16_bf16 v[50:65], v[224:227], v[236:239], v[50:65]
	s_waitcnt lgkmcnt(8)
	v_mfma_f32_32x32x16_bf16 v[2:17], v[228:231], v[232:235], v[2:17]
	v_mfma_f32_32x32x16_bf16 v[18:33], v[228:231], v[236:239], v[18:33]
	s_waitcnt lgkmcnt(7)
	v_mfma_f32_32x32x16_bf16 v[74:89], v[224:227], v[240:243], v[74:89]
	s_waitcnt lgkmcnt(6)
	v_mfma_f32_32x32x16_bf16 v[90:105], v[224:227], v[244:247], v[90:105]
	v_mfma_f32_32x32x16_bf16 v[106:121], v[228:231], v[240:243], v[106:121]
	v_mfma_f32_32x32x16_bf16 v[208:223], v[228:231], v[244:247], v[208:223]
	s_waitcnt lgkmcnt(4)
	v_mfma_f32_32x32x16_bf16 v[34:49], v[248:251], v[160:163], v[34:49]
	s_waitcnt lgkmcnt(3)
	v_mfma_f32_32x32x16_bf16 v[50:65], v[248:251], v[164:167], v[50:65]
	s_waitcnt lgkmcnt(2)
	v_mfma_f32_32x32x16_bf16 v[2:17], v[156:159], v[160:163], v[2:17]
	v_mfma_f32_32x32x16_bf16 v[18:33], v[156:159], v[164:167], v[18:33]
	s_waitcnt lgkmcnt(1)
	v_mfma_f32_32x32x16_bf16 v[74:89], v[248:251], v[168:171], v[74:89]
	s_waitcnt lgkmcnt(0)
	v_mfma_f32_32x32x16_bf16 v[90:105], v[248:251], v[122:125], v[90:105]
	v_mfma_f32_32x32x16_bf16 v[106:121], v[156:159], v[168:171], v[106:121]
	v_mfma_f32_32x32x16_bf16 v[208:223], v[156:159], v[122:125], v[208:223]
	s_setprio 0
	s_waitcnt vmcnt(6)
	s_barrier
	s_setprio 1
	ds_read_b128 v[224:227], v126 offset:49152
	ds_read_b128 v[232:235], v128 offset:49152
	ds_read_b128 v[236:239], v128 offset:51200
	ds_read_b128 v[228:231], v126 offset:51200
	ds_read_b128 v[240:243], v128 offset:57344
	ds_read_b128 v[244:247], v128 offset:59392
	ds_read_b128 v[248:251], v127 offset:49152
	ds_read_b128 v[160:163], v129 offset:49152
	ds_read_b128 v[164:167], v129 offset:51200
	ds_read_b128 v[156:159], v127 offset:51200
	ds_read_b128 v[168:171], v129 offset:57344
	ds_read_b128 v[122:125], v129 offset:59392
	s_add_u32 m0, s16, 0x6000
	s_add_u32 s42, s42, 0x100000
	s_addc_u32 s43, s43, 0
	global_load_lds_dwordx4 v137, s[42:43]
	global_load_lds_dwordx4 v150, s[42:43] offset:1024
	s_add_u32 m0, s0, 0x6000
	s_add_u32 s30, s30, 0x10000
	s_addc_u32 s31, s31, 0
	global_load_lds_dwordx4 v151, s[30:31]
	global_load_lds_dwordx4 v152, s[30:31] offset:1024
	global_load_lds_dwordx4 v153, s[30:31] offset:2048
	global_load_lds_dwordx4 v154, s[30:31] offset:3072
	s_waitcnt lgkmcnt(10)
	v_mfma_f32_32x32x16_bf16 v[34:49], v[224:227], v[232:235], v[34:49]
	s_waitcnt lgkmcnt(9)
	v_mfma_f32_32x32x16_bf16 v[50:65], v[224:227], v[236:239], v[50:65]
	s_waitcnt lgkmcnt(8)
	v_mfma_f32_32x32x16_bf16 v[2:17], v[228:231], v[232:235], v[2:17]
	v_mfma_f32_32x32x16_bf16 v[18:33], v[228:231], v[236:239], v[18:33]
	s_waitcnt lgkmcnt(7)
	v_mfma_f32_32x32x16_bf16 v[74:89], v[224:227], v[240:243], v[74:89]
	s_waitcnt lgkmcnt(6)
	v_mfma_f32_32x32x16_bf16 v[90:105], v[224:227], v[244:247], v[90:105]
	v_mfma_f32_32x32x16_bf16 v[106:121], v[228:231], v[240:243], v[106:121]
	v_mfma_f32_32x32x16_bf16 v[208:223], v[228:231], v[244:247], v[208:223]
	s_waitcnt lgkmcnt(4)
	v_mfma_f32_32x32x16_bf16 v[34:49], v[248:251], v[160:163], v[34:49]
	s_waitcnt lgkmcnt(3)
	v_mfma_f32_32x32x16_bf16 v[50:65], v[248:251], v[164:167], v[50:65]
	s_waitcnt lgkmcnt(2)
	v_mfma_f32_32x32x16_bf16 v[2:17], v[156:159], v[160:163], v[2:17]
	v_mfma_f32_32x32x16_bf16 v[18:33], v[156:159], v[164:167], v[18:33]
	s_waitcnt lgkmcnt(1)
	v_mfma_f32_32x32x16_bf16 v[74:89], v[248:251], v[168:171], v[74:89]
	s_waitcnt lgkmcnt(0)
	v_mfma_f32_32x32x16_bf16 v[90:105], v[248:251], v[122:125], v[90:105]
	v_mfma_f32_32x32x16_bf16 v[106:121], v[156:159], v[168:171], v[106:121]
	v_mfma_f32_32x32x16_bf16 v[208:223], v[156:159], v[122:125], v[208:223]
	s_setprio 0
	s_waitcnt vmcnt(6)
	s_barrier
; #define BLOAD(A_, B_, kt) do { _Pragma("unroll") for (int i = 0; i < 4; ++i) { \
;     A_[i] = *(const u32x4*)((const char*)Ap + (aoff + (unsigned)(32 * i * lda + (kt) * 64) * 2u)); B_[i] = *(const u32x4*)((const char*)Wt + (woff + (unsigned)(32 * i * K + (kt) * 64) * 2u)); } } while (0)
; #define BLOAD(A_, B_, kt) do { _Pragma("unroll") for (int i = 0; i < 4; ++i) { \
;     A_[i] = *(const u32x4*)((const char*)Ap + (aoff + (unsigned)(32 * i * lda + (kt) * 64) * 2u)); B_[i] = *(const u32x4*)((const char*)Wt + (woff + (unsigned)(32 * i * K + (kt) * 64) * 2u)); } } while (0)
; #define BSTORE(A_, B_, buf) do { _Pragma("unroll") for (int i = 0; i < 4; ++i) { \
;     *(u32x4*)&As[(buf) * GBUF + (srow + 32 * i) * LDT + sc8] = A_[i]; \
;     *(u32x4*)&Bs[(buf) * GBUF + (srow + 32 * i) * LDT + sc8] = B_[i]; } } while (0)
; template <int NK>
; DI void gemm_run(PF& pf, const u16* __restrict__ Ap, int lda, const u16* __restrict__ Wt, f32x16 (&acc)[2][2], char* smem) {
;     ...
; #pragma unroll
;   for (int kt = 0; kt < nk; kt += 2) {
;     BCOMP(0);
;     BSTORE(pf.a1, pf.b1, 1);
;     if (kt + 3 < nk) BLOAD(pf.a1, pf.b1, kt + 3);
;     __syncthreads();
;     BCOMP(1);
;     if (kt + 2 < nk) { BSTORE(pf.a0, pf.b0, 0); if (kt + 4 < nk) BLOAD(pf.a0, pf.b0, kt + 4); }
;     __syncthreads();
;   }
	s_setprio 1
	ds_read_b128 v[224:227], v126 offset:0
	ds_read_b128 v[232:235], v128 offset:0
	ds_read_b128 v[236:239], v128 offset:2048
	ds_read_b128 v[228:231], v126 offset:2048
	ds_read_b128 v[240:243], v128 offset:8192
	ds_read_b128 v[244:247], v128 offset:10240
	ds_read_b128 v[248:251], v127 offset:0
	ds_read_b128 v[160:163], v129 offset:0
	ds_read_b128 v[164:167], v129 offset:2048
	ds_read_b128 v[156:159], v127 offset:2048
	ds_read_b128 v[168:171], v129 offset:8192
	ds_read_b128 v[122:125], v129 offset:10240
	s_add_u32 m0, s16, 0xc000
	s_add_u32 s42, s42, 0x100000
	s_addc_u32 s43, s43, 0
	global_load_lds_dwordx4 v137, s[42:43]
	global_load_lds_dwordx4 v150, s[42:43] offset:1024
	s_add_u32 m0, s0, 0xc000
	s_add_u32 s30, s30, 0x10000
	s_addc_u32 s31, s31, 0
	global_load_lds_dwordx4 v151, s[30:31]
	global_load_lds_dwordx4 v152, s[30:31] offset:1024
	global_load_lds_dwordx4 v153, s[30:31] offset:2048
	global_load_lds_dwordx4 v154, s[30:31] offset:3072
	s_waitcnt lgkmcnt(10)
	v_mfma_f32_32x32x16_bf16 v[34:49], v[224:227], v[232:235], v[34:49]
	s_waitcnt lgkmcnt(9)
	v_mfma_f32_32x32x16_bf16 v[50:65], v[224:227], v[236:239], v[50:65]
	s_waitcnt lgkmcnt(8)
	v_mfma_f32_32x32x16_bf16 v[2:17], v[228:231], v[232:235], v[2:17]
	v_mfma_f32_32x32x16_bf16 v[18:33], v[228:231], v[236:239], v[18:33]
	s_waitcnt lgkmcnt(7)
	v_mfma_f32_32x32x16_bf16 v[74:89], v[224:227], v[240:243], v[74:89]
	s_waitcnt lgkmcnt(6)
	v_mfma_f32_32x32x16_bf16 v[90:105], v[224:227], v[244:247], v[90:105]
	v_mfma_f32_32x32x16_bf16 v[106:121], v[228:231], v[240:243], v[106:121]
	v_mfma_f32_32x32x16_bf16 v[208:223], v[228:231], v[244:247], v[208:223]
	s_waitcnt lgkmcnt(4)
	v_mfma_f32_32x32x16_bf16 v[34:49], v[248:251], v[160:163], v[34:49]
	s_waitcnt lgkmcnt(3)
	v_mfma_f32_32x32x16_bf16 v[50:65], v[248:251], v[164:167], v[50:65]
	s_waitcnt lgkmcnt(2)
	v_mfma_f32_32x32x16_bf16 v[2:17], v[156:159], v[160:163], v[2:17]
	v_mfma_f32_32x32x16_bf16 v[18:33], v[156:159], v[164:167], v[18:33]
	s_waitcnt lgkmcnt(1)
	v_mfma_f32_32x32x16_bf16 v[74:89], v[248:251], v[168:171], v[74:89]
	s_waitcnt lgkmcnt(0)
	v_mfma_f32_32x32x16_bf16 v[90:105], v[248:251], v[122:125], v[90:105]
	v_mfma_f32_32x32x16_bf16 v[106:121], v[156:159], v[168:171], v[106:121]
	v_mfma_f32_32x32x16_bf16 v[208:223], v[156:159], v[122:125], v[208:223]
	s_setprio 0
	s_waitcnt vmcnt(6)
	s_barrier
	s_setprio 1
	ds_read_b128 v[224:227], v126 offset:24576
	ds_read_b128 v[232:235], v128 offset:24576
	ds_read_b128 v[236:239], v128 offset:26624
	ds_read_b128 v[228:231], v126 offset:26624
	ds_read_b128 v[240:243], v128 offset:32768
	ds_read_b128 v[244:247], v128 offset:34816
	ds_read_b128 v[248:251], v127 offset:24576
	ds_read_b128 v[160:163], v129 offset:24576
	ds_read_b128 v[164:167], v129 offset:26624
	ds_read_b128 v[156:159], v127 offset:26624
	ds_read_b128 v[168:171], v129 offset:32768
	ds_read_b128 v[122:125], v129 offset:34816
	s_add_u32 m0, s16, 0x0
	s_add_u32 s42, s42, 0x100000
	s_addc_u32 s43, s43, 0
	global_load_lds_dwordx4 v137, s[42:43]
	global_load_lds_dwordx4 v150, s[42:43] offset:1024
	s_add_u32 m0, s0, 0x0
	s_add_u32 s30, s30, 0x10000
	s_addc_u32 s31, s31, 0
	global_load_lds_dwordx4 v151, s[30:31]
	global_load_lds_dwordx4 v152, s[30:31] offset:1024
	global_load_lds_dwordx4 v153, s[30:31] offset:2048
	global_load_lds_dwordx4 v154, s[30:31] offset:3072
	s_waitcnt lgkmcnt(10)
	v_mfma_f32_32x32x16_bf16 v[34:49], v[224:227], v[232:235], v[34:49]
	s_waitcnt lgkmcnt(9)
	v_mfma_f32_32x32x16_bf16 v[50:65], v[224:227], v[236:239], v[50:65]
	s_waitcnt lgkmcnt(8)
	v_mfma_f32_32x32x16_bf16 v[2:17], v[228:231], v[232:235], v[2:17]
	v_mfma_f32_32x32x16_bf16 v[18:33], v[228:231], v[236:239], v[18:33]
	s_waitcnt lgkmcnt(7)
	v_mfma_f32_32x32x16_bf16 v[74:89], v[224:227], v[240:243], v[74:89]
	s_waitcnt lgkmcnt(6)
	v_mfma_f32_32x32x16_bf16 v[90:105], v[224:227], v[244:247], v[90:105]
	v_mfma_f32_32x32x16_bf16 v[106:121], v[228:231], v[240:243], v[106:121]
	v_mfma_f32_32x32x16_bf16 v[208:223], v[228:231], v[244:247], v[208:223]
	s_waitcnt lgkmcnt(4)
	v_mfma_f32_32x32x16_bf16 v[34:49], v[248:251], v[160:163], v[34:49]
	s_waitcnt lgkmcnt(3)
	v_mfma_f32_32x32x16_bf16 v[50:65], v[248:251], v[164:167], v[50:65]
	s_waitcnt lgkmcnt(2)
	v_mfma_f32_32x32x16_bf16 v[2:17], v[156:159], v[160:163], v[2:17]
	v_mfma_f32_32x32x16_bf16 v[18:33], v[156:159], v[164:167], v[18:33]
	s_waitcnt lgkmcnt(1)
	v_mfma_f32_32x32x16_bf16 v[74:89], v[248:251], v[168:171], v[74:89]
	s_waitcnt lgkmcnt(0)
	v_mfma_f32_32x32x16_bf16 v[90:105], v[248:251], v[122:125], v[90:105]
	v_mfma_f32_32x32x16_bf16 v[106:121], v[156:159], v[168:171], v[106:121]
	v_mfma_f32_32x32x16_bf16 v[208:223], v[156:159], v[122:125], v[208:223]
	s_setprio 0
	s_waitcnt vmcnt(6)
	s_barrier
; #define BLOAD(A_, B_, kt) do { _Pragma("unroll") for (int i = 0; i < 4; ++i) { \
;     A_[i] = *(const u32x4*)((const char*)Ap + (aoff + (unsigned)(32 * i * lda + (kt) * 64) * 2u)); B_[i] = *(const u32x4*)((const char*)Wt + (woff + (unsigned)(32 * i * K + (kt) * 64) * 2u)); } } while (0)
; #define BLOAD(A_, B_, kt) do { _Pragma("unroll") for (int i = 0; i < 4; ++i) { \
;     A_[i] = *(const u32x4*)((const char*)Ap + (aoff + (unsigned)(32 * i * lda + (kt) * 64) * 2u)); B_[i] = *(const u32x4*)((const char*)Wt + (woff + (unsigned)(32 * i * K + (kt) * 64) * 2u)); } } while (0)
; #define BSTORE(A_, B_, buf) do { _Pragma("unroll") for (int i = 0; i < 4; ++i) { \
;     *(u32x4*)&As[(buf) * GBUF + (srow + 32 * i) * LDT + sc8] = A_[i]; \
;     *(u32x4*)&Bs[(buf) * GBUF + (srow + 32 * i) * LDT + sc8] = B_[i]; } } while (0)
; template <int NK>
; DI void gemm_run(PF& pf, const u16* __restrict__ Ap, int lda, const u16* __restrict__ Wt, f32x16 (&acc)[2][2], char* smem) {
;     ...
; #pragma unroll
;   for (int kt = 0; kt < nk; kt += 2) {
;     BCOMP(0);
;     BSTORE(pf.a1, pf.b1, 1);
;     if (kt + 3 < nk) BLOAD(pf.a1, pf.b1, kt + 3);
;     __syncthreads();
;     BCOMP(1);
;     if (kt + 2 < nk) { BSTORE(pf.a0, pf.b0, 0); if (kt + 4 < nk) BLOAD(pf.a0, pf.b0, kt + 4); }
;     __syncthreads();
;   }
	s_setprio 1
	ds_read_b128 v[224:227], v126 offset:49152
	ds_read_b128 v[232:235], v128 offset:49152
	ds_read_b128 v[236:239], v128 offset:51200
	ds_read_b128 v[228:231], v126 offset:51200
	ds_read_b128 v[240:243], v128 offset:57344
	ds_read_b128 v[244:247], v128 offset:59392
	ds_read_b128 v[248:251], v127 offset:49152
	ds_read_b128 v[160:163], v129 offset:49152
	ds_read_b128 v[164:167], v129 offset:51200
	ds_read_b128 v[156:159], v127 offset:51200
	ds_read_b128 v[168:171], v129 offset:57344
	ds_read_b128 v[122:125], v129 offset:59392
	s_add_u32 m0, s16, 0x6000
	s_add_u32 s42, s42, 0x100000
	s_addc_u32 s43, s43, 0
	global_load_lds_dwordx4 v137, s[42:43]
	global_load_lds_dwordx4 v150, s[42:43] offset:1024
	s_add_u32 m0, s0, 0x6000
	s_add_u32 s30, s30, 0x10000
	s_addc_u32 s31, s31, 0
	global_load_lds_dwordx4 v151, s[30:31]
	global_load_lds_dwordx4 v152, s[30:31] offset:1024
	global_load_lds_dwordx4 v153, s[30:31] offset:2048
	global_load_lds_dwordx4 v154, s[30:31] offset:3072
	s_waitcnt lgkmcnt(10)
	v_mfma_f32_32x32x16_bf16 v[34:49], v[224:227], v[232:235], v[34:49]
	s_waitcnt lgkmcnt(9)
	v_mfma_f32_32x32x16_bf16 v[50:65], v[224:227], v[236:239], v[50:65]
	s_waitcnt lgkmcnt(8)
	v_mfma_f32_32x32x16_bf16 v[2:17], v[228:231], v[232:235], v[2:17]
	v_mfma_f32_32x32x16_bf16 v[18:33], v[228:231], v[236:239], v[18:33]
	s_waitcnt lgkmcnt(7)
	v_mfma_f32_32x32x16_bf16 v[74:89], v[224:227], v[240:243], v[74:89]
	s_waitcnt lgkmcnt(6)
	v_mfma_f32_32x32x16_bf16 v[90:105], v[224:227], v[244:247], v[90:105]
	v_mfma_f32_32x32x16_bf16 v[106:121], v[228:231], v[240:243], v[106:121]
	v_mfma_f32_32x32x16_bf16 v[208:223], v[228:231], v[244:247], v[208:223]
	s_waitcnt lgkmcnt(4)
	v_mfma_f32_32x32x16_bf16 v[34:49], v[248:251], v[160:163], v[34:49]
	s_waitcnt lgkmcnt(3)
	v_mfma_f32_32x32x16_bf16 v[50:65], v[248:251], v[164:167], v[50:65]
	s_waitcnt lgkmcnt(2)
	v_mfma_f32_32x32x16_bf16 v[2:17], v[156:159], v[160:163], v[2:17]
	v_mfma_f32_32x32x16_bf16 v[18:33], v[156:159], v[164:167], v[18:33]
	s_waitcnt lgkmcnt(1)
	v_mfma_f32_32x32x16_bf16 v[74:89], v[248:251], v[168:171], v[74:89]
	s_waitcnt lgkmcnt(0)
	v_mfma_f32_32x32x16_bf16 v[90:105], v[248:251], v[122:125], v[90:105]
	v_mfma_f32_32x32x16_bf16 v[106:121], v[156:159], v[168:171], v[106:121]
	v_mfma_f32_32x32x16_bf16 v[208:223], v[156:159], v[122:125], v[208:223]
	s_setprio 0
	s_waitcnt vmcnt(6)
	s_barrier
	s_setprio 1
	ds_read_b128 v[224:227], v126 offset:0
	ds_read_b128 v[232:235], v128 offset:0
	ds_read_b128 v[236:239], v128 offset:2048
	ds_read_b128 v[228:231], v126 offset:2048
	ds_read_b128 v[240:243], v128 offset:8192
	ds_read_b128 v[244:247], v128 offset:10240
	ds_read_b128 v[248:251], v127 offset:0
	ds_read_b128 v[160:163], v129 offset:0
	ds_read_b128 v[164:167], v129 offset:2048
	ds_read_b128 v[156:159], v127 offset:2048
	ds_read_b128 v[168:171], v129 offset:8192
	ds_read_b128 v[122:125], v129 offset:10240
	s_add_u32 m0, s16, 0xc000
	s_add_u32 s42, s42, 0x100000
	s_addc_u32 s43, s43, 0
	global_load_lds_dwordx4 v137, s[42:43]
	global_load_lds_dwordx4 v150, s[42:43] offset:1024
	s_add_u32 m0, s0, 0xc000
	s_add_u32 s30, s30, 0x10000
	s_addc_u32 s31, s31, 0
	global_load_lds_dwordx4 v151, s[30:31]
	global_load_lds_dwordx4 v152, s[30:31] offset:1024
	global_load_lds_dwordx4 v153, s[30:31] offset:2048
	global_load_lds_dwordx4 v154, s[30:31] offset:3072
	s_waitcnt lgkmcnt(10)
	v_mfma_f32_32x32x16_bf16 v[34:49], v[224:227], v[232:235], v[34:49]
	s_waitcnt lgkmcnt(9)
	v_mfma_f32_32x32x16_bf16 v[50:65], v[224:227], v[236:239], v[50:65]
	s_waitcnt lgkmcnt(8)
	v_mfma_f32_32x32x16_bf16 v[2:17], v[228:231], v[232:235], v[2:17]
	v_mfma_f32_32x32x16_bf16 v[18:33], v[228:231], v[236:239], v[18:33]
	s_waitcnt lgkmcnt(7)
	v_mfma_f32_32x32x16_bf16 v[74:89], v[224:227], v[240:243], v[74:89]
	s_waitcnt lgkmcnt(6)
	v_mfma_f32_32x32x16_bf16 v[90:105], v[224:227], v[244:247], v[90:105]
	v_mfma_f32_32x32x16_bf16 v[106:121], v[228:231], v[240:243], v[106:121]
	v_mfma_f32_32x32x16_bf16 v[208:223], v[228:231], v[244:247], v[208:223]
	s_waitcnt lgkmcnt(4)
	v_mfma_f32_32x32x16_bf16 v[34:49], v[248:251], v[160:163], v[34:49]
	s_waitcnt lgkmcnt(3)
	v_mfma_f32_32x32x16_bf16 v[50:65], v[248:251], v[164:167], v[50:65]
	s_waitcnt lgkmcnt(2)
	v_mfma_f32_32x32x16_bf16 v[2:17], v[156:159], v[160:163], v[2:17]
	v_mfma_f32_32x32x16_bf16 v[18:33], v[156:159], v[164:167], v[18:33]
	s_waitcnt lgkmcnt(1)
	v_mfma_f32_32x32x16_bf16 v[74:89], v[248:251], v[168:171], v[74:89]
	s_waitcnt lgkmcnt(0)
	v_mfma_f32_32x32x16_bf16 v[90:105], v[248:251], v[122:125], v[90:105]
	v_mfma_f32_32x32x16_bf16 v[106:121], v[156:159], v[168:171], v[106:121]
	v_mfma_f32_32x32x16_bf16 v[208:223], v[156:159], v[122:125], v[208:223]
	s_setprio 0
	s_waitcnt vmcnt(6)
	s_barrier
; #define BLOAD(A_, B_, kt) do { _Pragma("unroll") for (int i = 0; i < 4; ++i) { \
;     A_[i] = *(const u32x4*)((const char*)Ap + (aoff + (unsigned)(32 * i * lda + (kt) * 64) * 2u)); B_[i] = *(const u32x4*)((const char*)Wt + (woff + (unsigned)(32 * i * K + (kt) * 64) * 2u)); } } while (0)
; #define BLOAD(A_, B_, kt) do { _Pragma("unroll") for (int i = 0; i < 4; ++i) { \
;     A_[i] = *(const u32x4*)((const char*)Ap + (aoff + (unsigned)(32 * i * lda + (kt) * 64) * 2u)); B_[i] = *(const u32x4*)((const char*)Wt + (woff + (unsigned)(32 * i * K + (kt) * 64) * 2u)); } } while (0)
; #define BSTORE(A_, B_, buf) do { _Pragma("unroll") for (int i = 0; i < 4; ++i) { \
;     *(u32x4*)&As[(buf) * GBUF + (srow + 32 * i) * LDT + sc8] = A_[i]; \
;     *(u32x4*)&Bs[(buf) * GBUF + (srow + 32 * i) * LDT + sc8] = B_[i]; } } while (0)
; template <int NK>
; DI void gemm_run(PF& pf, const u16* __restrict__ Ap, int lda, const u16* __restrict__ Wt, f32x16 (&acc)[2][2], char* smem) {
;     ...
; #pragma unroll
;   for (int kt = 0; kt < nk; kt += 2) {
;     BCOMP(0);
;     BSTORE(pf.a1, pf.b1, 1);
;     if (kt + 3 < nk) BLOAD(pf.a1, pf.b1, kt + 3);
;     __syncthreads();
;     BCOMP(1);
;     if (kt + 2 < nk) { BSTORE(pf.a0, pf.b0, 0); if (kt + 4 < nk) BLOAD(pf.a0, pf.b0, kt + 4); }
;     __syncthreads();
;   }
	s_setprio 1
	ds_read_b128 v[224:227], v126 offset:24576
	ds_read_b128 v[232:235], v128 offset:24576
	ds_read_b128 v[236:239], v128 offset:26624
	ds_read_b128 v[228:231], v126 offset:26624
	ds_read_b128 v[240:243], v128 offset:32768
	ds_read_b128 v[244:247], v128 offset:34816
	ds_read_b128 v[248:251], v127 offset:24576
	ds_read_b128 v[160:163], v129 offset:24576
	ds_read_b128 v[164:167], v129 offset:26624
	ds_read_b128 v[156:159], v127 offset:26624
	ds_read_b128 v[168:171], v129 offset:32768
	ds_read_b128 v[122:125], v129 offset:34816
	s_add_u32 m0, s16, 0x0
	s_add_u32 s42, s42, 0x100000
	s_addc_u32 s43, s43, 0
	global_load_lds_dwordx4 v137, s[42:43]
	global_load_lds_dwordx4 v150, s[42:43] offset:1024
	s_add_u32 m0, s0, 0x0
	s_add_u32 s30, s30, 0x10000
	s_addc_u32 s31, s31, 0
	global_load_lds_dwordx4 v151, s[30:31]
	global_load_lds_dwordx4 v152, s[30:31] offset:1024
	global_load_lds_dwordx4 v153, s[30:31] offset:2048
	global_load_lds_dwordx4 v154, s[30:31] offset:3072
	s_waitcnt lgkmcnt(10)
	v_mfma_f32_32x32x16_bf16 v[34:49], v[224:227], v[232:235], v[34:49]
	s_waitcnt lgkmcnt(9)
	v_mfma_f32_32x32x16_bf16 v[50:65], v[224:227], v[236:239], v[50:65]
	s_waitcnt lgkmcnt(8)
	v_mfma_f32_32x32x16_bf16 v[2:17], v[228:231], v[232:235], v[2:17]
	v_mfma_f32_32x32x16_bf16 v[18:33], v[228:231], v[236:239], v[18:33]
	s_waitcnt lgkmcnt(7)
	v_mfma_f32_32x32x16_bf16 v[74:89], v[224:227], v[240:243], v[74:89]
	s_waitcnt lgkmcnt(6)
	v_mfma_f32_32x32x16_bf16 v[90:105], v[224:227], v[244:247], v[90:105]
	v_mfma_f32_32x32x16_bf16 v[106:121], v[228:231], v[240:243], v[106:121]
	v_mfma_f32_32x32x16_bf16 v[208:223], v[228:231], v[244:247], v[208:223]
	s_waitcnt lgkmcnt(4)
	v_mfma_f32_32x32x16_bf16 v[34:49], v[248:251], v[160:163], v[34:49]
	s_waitcnt lgkmcnt(3)
	v_mfma_f32_32x32x16_bf16 v[50:65], v[248:251], v[164:167], v[50:65]
	s_waitcnt lgkmcnt(2)
	v_mfma_f32_32x32x16_bf16 v[2:17], v[156:159], v[160:163], v[2:17]
	v_mfma_f32_32x32x16_bf16 v[18:33], v[156:159], v[164:167], v[18:33]
	s_waitcnt lgkmcnt(1)
	v_mfma_f32_32x32x16_bf16 v[74:89], v[248:251], v[168:171], v[74:89]
	s_waitcnt lgkmcnt(0)
	v_mfma_f32_32x32x16_bf16 v[90:105], v[248:251], v[122:125], v[90:105]
	v_mfma_f32_32x32x16_bf16 v[106:121], v[156:159], v[168:171], v[106:121]
	v_mfma_f32_32x32x16_bf16 v[208:223], v[156:159], v[122:125], v[208:223]
	s_setprio 0
	s_waitcnt vmcnt(6)
	s_barrier
	s_setprio 1
	ds_read_b128 v[224:227], v126 offset:49152
	ds_read_b128 v[232:235], v128 offset:49152
	ds_read_b128 v[236:239], v128 offset:51200
	ds_read_b128 v[228:231], v126 offset:51200
	ds_read_b128 v[240:243], v128 offset:57344
	ds_read_b128 v[244:247], v128 offset:59392
	ds_read_b128 v[248:251], v127 offset:49152
	ds_read_b128 v[160:163], v129 offset:49152
	ds_read_b128 v[164:167], v129 offset:51200
	ds_read_b128 v[156:159], v127 offset:51200
	ds_read_b128 v[168:171], v129 offset:57344
	ds_read_b128 v[122:125], v129 offset:59392
	s_add_u32 m0, s16, 0x6000
	s_add_u32 s42, s42, 0x100000
	s_addc_u32 s43, s43, 0
	global_load_lds_dwordx4 v137, s[42:43]
	global_load_lds_dwordx4 v150, s[42:43] offset:1024
	s_add_u32 m0, s0, 0x6000
	s_add_u32 s30, s30, 0x10000
	s_addc_u32 s31, s31, 0
	global_load_lds_dwordx4 v151, s[30:31]
	global_load_lds_dwordx4 v152, s[30:31] offset:1024
	global_load_lds_dwordx4 v153, s[30:31] offset:2048
	global_load_lds_dwordx4 v154, s[30:31] offset:3072
	s_waitcnt lgkmcnt(10)
	v_mfma_f32_32x32x16_bf16 v[34:49], v[224:227], v[232:235], v[34:49]
	s_waitcnt lgkmcnt(9)
	v_mfma_f32_32x32x16_bf16 v[50:65], v[224:227], v[236:239], v[50:65]
	s_waitcnt lgkmcnt(8)
	v_mfma_f32_32x32x16_bf16 v[2:17], v[228:231], v[232:235], v[2:17]
	v_mfma_f32_32x32x16_bf16 v[18:33], v[228:231], v[236:239], v[18:33]
	s_waitcnt lgkmcnt(7)
	v_mfma_f32_32x32x16_bf16 v[74:89], v[224:227], v[240:243], v[74:89]
	s_waitcnt lgkmcnt(6)
	v_mfma_f32_32x32x16_bf16 v[90:105], v[224:227], v[244:247], v[90:105]
	v_mfma_f32_32x32x16_bf16 v[106:121], v[228:231], v[240:243], v[106:121]
	v_mfma_f32_32x32x16_bf16 v[208:223], v[228:231], v[244:247], v[208:223]
	s_waitcnt lgkmcnt(4)
	v_mfma_f32_32x32x16_bf16 v[34:49], v[248:251], v[160:163], v[34:49]
	s_waitcnt lgkmcnt(3)
	v_mfma_f32_32x32x16_bf16 v[50:65], v[248:251], v[164:167], v[50:65]
	s_waitcnt lgkmcnt(2)
	v_mfma_f32_32x32x16_bf16 v[2:17], v[156:159], v[160:163], v[2:17]
	v_mfma_f32_32x32x16_bf16 v[18:33], v[156:159], v[164:167], v[18:33]
	s_waitcnt lgkmcnt(1)
	v_mfma_f32_32x32x16_bf16 v[74:89], v[248:251], v[168:171], v[74:89]
	s_waitcnt lgkmcnt(0)
	v_mfma_f32_32x32x16_bf16 v[90:105], v[248:251], v[122:125], v[90:105]
	v_mfma_f32_32x32x16_bf16 v[106:121], v[156:159], v[168:171], v[106:121]
	v_mfma_f32_32x32x16_bf16 v[208:223], v[156:159], v[122:125], v[208:223]
	s_setprio 0
	s_waitcnt vmcnt(6)
	s_barrier
; #define BLOAD(A_, B_, kt) do { _Pragma("unroll") for (int i = 0; i < 4; ++i) { \
;     A_[i] = *(const u32x4*)((const char*)Ap + (aoff + (unsigned)(32 * i * lda + (kt) * 64) * 2u)); B_[i] = *(const u32x4*)((const char*)Wt + (woff + (unsigned)(32 * i * K + (kt) * 64) * 2u)); } } while (0)
; #define BLOAD(A_, B_, kt) do { _Pragma("unroll") for (int i = 0; i < 4; ++i) { \
;     A_[i] = *(const u32x4*)((const char*)Ap + (aoff + (unsigned)(32 * i * lda + (kt) * 64) * 2u)); B_[i] = *(const u32x4*)((const char*)Wt + (woff + (unsigned)(32 * i * K + (kt) * 64) * 2u)); } } while (0)
; #define BSTORE(A_, B_, buf) do { _Pragma("unroll") for (int i = 0; i < 4; ++i) { \
;     *(u32x4*)&As[(buf) * GBUF + (srow + 32 * i) * LDT + sc8] = A_[i]; \
;     *(u32x4*)&Bs[(buf) * GBUF + (srow + 32 * i) * LDT + sc8] = B_[i]; } } while (0)
; template <int NK>
; DI void gemm_run(PF& pf, const u16* __restrict__ Ap, int lda, const u16* __restrict__ Wt, f32x16 (&acc)[2][2], char* smem) {
;     ...
; #pragma unroll
;   for (int kt = 0; kt < nk; kt += 2) {
;     BCOMP(0);
;     BSTORE(pf.a1, pf.b1, 1);
;     if (kt + 3 < nk) BLOAD(pf.a1, pf.b1, kt + 3);
;     __syncthreads();
;     BCOMP(1);
;     if (kt + 2 < nk) { BSTORE(pf.a0, pf.b0, 0); if (kt + 4 < nk) BLOAD(pf.a0, pf.b0, kt + 4); }
;     __syncthreads();
;   }
	s_setprio 1
	ds_read_b128 v[224:227], v126 offset:0
	ds_read_b128 v[232:235], v128 offset:0
	ds_read_b128 v[236:239], v128 offset:2048
	ds_read_b128 v[228:231], v126 offset:2048
	ds_read_b128 v[240:243], v128 offset:8192
	ds_read_b128 v[244:247], v128 offset:10240
	ds_read_b128 v[248:251], v127 offset:0
	ds_read_b128 v[160:163], v129 offset:0
	ds_read_b128 v[164:167], v129 offset:2048
	ds_read_b128 v[156:159], v127 offset:2048
	ds_read_b128 v[168:171], v129 offset:8192
	ds_read_b128 v[122:125], v129 offset:10240
	s_add_u32 m0, s16, 0xc000
	s_add_u32 s42, s42, 0x100000
	s_addc_u32 s43, s43, 0
	global_load_lds_dwordx4 v137, s[42:43]
	global_load_lds_dwordx4 v150, s[42:43] offset:1024
	s_add_u32 m0, s0, 0xc000
	s_add_u32 s30, s30, 0x10000
	s_addc_u32 s31, s31, 0
	global_load_lds_dwordx4 v151, s[30:31]
	global_load_lds_dwordx4 v152, s[30:31] offset:1024
	global_load_lds_dwordx4 v153, s[30:31] offset:2048
	global_load_lds_dwordx4 v154, s[30:31] offset:3072
	s_waitcnt lgkmcnt(10)
	v_mfma_f32_32x32x16_bf16 v[34:49], v[224:227], v[232:235], v[34:49]
	s_waitcnt lgkmcnt(9)
	v_mfma_f32_32x32x16_bf16 v[50:65], v[224:227], v[236:239], v[50:65]
	s_waitcnt lgkmcnt(8)
	v_mfma_f32_32x32x16_bf16 v[2:17], v[228:231], v[232:235], v[2:17]
	v_mfma_f32_32x32x16_bf16 v[18:33], v[228:231], v[236:239], v[18:33]
	s_waitcnt lgkmcnt(7)
	v_mfma_f32_32x32x16_bf16 v[74:89], v[224:227], v[240:243], v[74:89]
	s_waitcnt lgkmcnt(6)
	v_mfma_f32_32x32x16_bf16 v[90:105], v[224:227], v[244:247], v[90:105]
	v_mfma_f32_32x32x16_bf16 v[106:121], v[228:231], v[240:243], v[106:121]
	v_mfma_f32_32x32x16_bf16 v[208:223], v[228:231], v[244:247], v[208:223]
	s_waitcnt lgkmcnt(4)
	v_mfma_f32_32x32x16_bf16 v[34:49], v[248:251], v[160:163], v[34:49]
	s_waitcnt lgkmcnt(3)
	v_mfma_f32_32x32x16_bf16 v[50:65], v[248:251], v[164:167], v[50:65]
	s_waitcnt lgkmcnt(2)
	v_mfma_f32_32x32x16_bf16 v[2:17], v[156:159], v[160:163], v[2:17]
	v_mfma_f32_32x32x16_bf16 v[18:33], v[156:159], v[164:167], v[18:33]
	s_waitcnt lgkmcnt(1)
	v_mfma_f32_32x32x16_bf16 v[74:89], v[248:251], v[168:171], v[74:89]
	s_waitcnt lgkmcnt(0)
	v_mfma_f32_32x32x16_bf16 v[90:105], v[248:251], v[122:125], v[90:105]
	v_mfma_f32_32x32x16_bf16 v[106:121], v[156:159], v[168:171], v[106:121]
	v_mfma_f32_32x32x16_bf16 v[208:223], v[156:159], v[122:125], v[208:223]
	s_setprio 0
	s_waitcnt vmcnt(6)
	s_barrier
	s_setprio 1
	ds_read_b128 v[224:227], v126 offset:24576
	ds_read_b128 v[232:235], v128 offset:24576
	ds_read_b128 v[236:239], v128 offset:26624
	ds_read_b128 v[228:231], v126 offset:26624
	ds_read_b128 v[240:243], v128 offset:32768
	ds_read_b128 v[244:247], v128 offset:34816
	ds_read_b128 v[248:251], v127 offset:24576
	ds_read_b128 v[160:163], v129 offset:24576
	ds_read_b128 v[164:167], v129 offset:26624
	ds_read_b128 v[156:159], v127 offset:26624
	ds_read_b128 v[168:171], v129 offset:32768
	ds_read_b128 v[122:125], v129 offset:34816
	s_add_u32 m0, s16, 0x0
	s_add_u32 s42, s42, 0x100000
	s_addc_u32 s43, s43, 0
	global_load_lds_dwordx4 v137, s[42:43]
	global_load_lds_dwordx4 v150, s[42:43] offset:1024
	s_add_u32 m0, s0, 0x0
	s_add_u32 s30, s30, 0x10000
	s_addc_u32 s31, s31, 0
	global_load_lds_dwordx4 v151, s[30:31]
	global_load_lds_dwordx4 v152, s[30:31] offset:1024
	global_load_lds_dwordx4 v153, s[30:31] offset:2048
	global_load_lds_dwordx4 v154, s[30:31] offset:3072
	s_waitcnt lgkmcnt(10)
	v_mfma_f32_32x32x16_bf16 v[34:49], v[224:227], v[232:235], v[34:49]
	s_waitcnt lgkmcnt(9)
	v_mfma_f32_32x32x16_bf16 v[50:65], v[224:227], v[236:239], v[50:65]
	s_waitcnt lgkmcnt(8)
	v_mfma_f32_32x32x16_bf16 v[2:17], v[228:231], v[232:235], v[2:17]
	v_mfma_f32_32x32x16_bf16 v[18:33], v[228:231], v[236:239], v[18:33]
	s_waitcnt lgkmcnt(7)
	v_mfma_f32_32x32x16_bf16 v[74:89], v[224:227], v[240:243], v[74:89]
	s_waitcnt lgkmcnt(6)
	v_mfma_f32_32x32x16_bf16 v[90:105], v[224:227], v[244:247], v[90:105]
	v_mfma_f32_32x32x16_bf16 v[106:121], v[228:231], v[240:243], v[106:121]
	v_mfma_f32_32x32x16_bf16 v[208:223], v[228:231], v[244:247], v[208:223]
	s_waitcnt lgkmcnt(4)
	v_mfma_f32_32x32x16_bf16 v[34:49], v[248:251], v[160:163], v[34:49]
	s_waitcnt lgkmcnt(3)
	v_mfma_f32_32x32x16_bf16 v[50:65], v[248:251], v[164:167], v[50:65]
	s_waitcnt lgkmcnt(2)
	v_mfma_f32_32x32x16_bf16 v[2:17], v[156:159], v[160:163], v[2:17]
	v_mfma_f32_32x32x16_bf16 v[18:33], v[156:159], v[164:167], v[18:33]
	s_waitcnt lgkmcnt(1)
	v_mfma_f32_32x32x16_bf16 v[74:89], v[248:251], v[168:171], v[74:89]
	s_waitcnt lgkmcnt(0)
	v_mfma_f32_32x32x16_bf16 v[90:105], v[248:251], v[122:125], v[90:105]
	v_mfma_f32_32x32x16_bf16 v[106:121], v[156:159], v[168:171], v[106:121]
	v_mfma_f32_32x32x16_bf16 v[208:223], v[156:159], v[122:125], v[208:223]
	s_setprio 0
	s_waitcnt vmcnt(6)
	s_barrier
; #define BLOAD(A_, B_, kt) do { _Pragma("unroll") for (int i = 0; i < 4; ++i) { \
;     A_[i] = *(const u32x4*)((const char*)Ap + (aoff + (unsigned)(32 * i * lda + (kt) * 64) * 2u)); B_[i] = *(const u32x4*)((const char*)Wt + (woff + (unsigned)(32 * i * K + (kt) * 64) * 2u)); } } while (0)
; #define BLOAD(A_, B_, kt) do { _Pragma("unroll") for (int i = 0; i < 4; ++i) { \
;     A_[i] = *(const u32x4*)((const char*)Ap + (aoff + (unsigned)(32 * i * lda + (kt) * 64) * 2u)); B_[i] = *(const u32x4*)((const char*)Wt + (woff + (unsigned)(32 * i * K + (kt) * 64) * 2u)); } } while (0)
; #define BSTORE(A_, B_, buf) do { _Pragma("unroll") for (int i = 0; i < 4; ++i) { \
;     *(u32x4*)&As[(buf) * GBUF + (srow + 32 * i) * LDT + sc8] = A_[i]; \
;     *(u32x4*)&Bs[(buf) * GBUF + (srow + 32 * i) * LDT + sc8] = B_[i]; } } while (0)
; template <int NK>
; DI void gemm_run(PF& pf, const u16* __restrict__ Ap, int lda, const u16* __restrict__ Wt, f32x16 (&acc)[2][2], char* smem) {
;     ...
; #pragma unroll
;   for (int kt = 0; kt < nk; kt += 2) {
;     BCOMP(0);
;     BSTORE(pf.a1, pf.b1, 1);
;     if (kt + 3 < nk) BLOAD(pf.a1, pf.b1, kt + 3);
;     __syncthreads();
;     BCOMP(1);
;     if (kt + 2 < nk) { BSTORE(pf.a0, pf.b0, 0); if (kt + 4 < nk) BLOAD(pf.a0, pf.b0, kt + 4); }
;     __syncthreads();
;   }
	s_setprio 1
	ds_read_b128 v[224:227], v126 offset:49152
	ds_read_b128 v[232:235], v128 offset:49152
	ds_read_b128 v[236:239], v128 offset:51200
	ds_read_b128 v[228:231], v126 offset:51200
	ds_read_b128 v[240:243], v128 offset:57344
	ds_read_b128 v[244:247], v128 offset:59392
	ds_read_b128 v[248:251], v127 offset:49152
	ds_read_b128 v[160:163], v129 offset:49152
	ds_read_b128 v[164:167], v129 offset:51200
	ds_read_b128 v[156:159], v127 offset:51200
	ds_read_b128 v[168:171], v129 offset:57344
	ds_read_b128 v[122:125], v129 offset:59392
	s_add_u32 m0, s16, 0x6000
	s_add_u32 s42, s42, 0x100000
	s_addc_u32 s43, s43, 0
	global_load_lds_dwordx4 v137, s[42:43]
	global_load_lds_dwordx4 v150, s[42:43] offset:1024
	s_add_u32 m0, s0, 0x6000
	s_add_u32 s30, s30, 0x10000
	s_addc_u32 s31, s31, 0
	global_load_lds_dwordx4 v151, s[30:31]
	global_load_lds_dwordx4 v152, s[30:31] offset:1024
	global_load_lds_dwordx4 v153, s[30:31] offset:2048
	global_load_lds_dwordx4 v154, s[30:31] offset:3072
	s_waitcnt lgkmcnt(10)
	v_mfma_f32_32x32x16_bf16 v[34:49], v[224:227], v[232:235], v[34:49]
	s_waitcnt lgkmcnt(9)
	v_mfma_f32_32x32x16_bf16 v[50:65], v[224:227], v[236:239], v[50:65]
	s_waitcnt lgkmcnt(8)
	v_mfma_f32_32x32x16_bf16 v[2:17], v[228:231], v[232:235], v[2:17]
	v_mfma_f32_32x32x16_bf16 v[18:33], v[228:231], v[236:239], v[18:33]
	s_waitcnt lgkmcnt(7)
	v_mfma_f32_32x32x16_bf16 v[74:89], v[224:227], v[240:243], v[74:89]
	s_waitcnt lgkmcnt(6)
	v_mfma_f32_32x32x16_bf16 v[90:105], v[224:227], v[244:247], v[90:105]
	v_mfma_f32_32x32x16_bf16 v[106:121], v[228:231], v[240:243], v[106:121]
	v_mfma_f32_32x32x16_bf16 v[208:223], v[228:231], v[244:247], v[208:223]
	s_waitcnt lgkmcnt(4)
	v_mfma_f32_32x32x16_bf16 v[34:49], v[248:251], v[160:163], v[34:49]
	s_waitcnt lgkmcnt(3)
	v_mfma_f32_32x32x16_bf16 v[50:65], v[248:251], v[164:167], v[50:65]
	s_waitcnt lgkmcnt(2)
	v_mfma_f32_32x32x16_bf16 v[2:17], v[156:159], v[160:163], v[2:17]
	v_mfma_f32_32x32x16_bf16 v[18:33], v[156:159], v[164:167], v[18:33]
	s_waitcnt lgkmcnt(1)
	v_mfma_f32_32x32x16_bf16 v[74:89], v[248:251], v[168:171], v[74:89]
	s_waitcnt lgkmcnt(0)
	v_mfma_f32_32x32x16_bf16 v[90:105], v[248:251], v[122:125], v[90:105]
	v_mfma_f32_32x32x16_bf16 v[106:121], v[156:159], v[168:171], v[106:121]
	v_mfma_f32_32x32x16_bf16 v[208:223], v[156:159], v[122:125], v[208:223]
	s_setprio 0
	s_waitcnt vmcnt(6)
	s_barrier
	s_setprio 1
	ds_read_b128 v[224:227], v126 offset:0
	ds_read_b128 v[232:235], v128 offset:0
	ds_read_b128 v[236:239], v128 offset:2048
	ds_read_b128 v[228:231], v126 offset:2048
	ds_read_b128 v[240:243], v128 offset:8192
	ds_read_b128 v[244:247], v128 offset:10240
	ds_read_b128 v[248:251], v127 offset:0
	ds_read_b128 v[160:163], v129 offset:0
	ds_read_b128 v[164:167], v129 offset:2048
	ds_read_b128 v[156:159], v127 offset:2048
	ds_read_b128 v[168:171], v129 offset:8192
	ds_read_b128 v[122:125], v129 offset:10240
	s_add_u32 m0, s16, 0xc000
	s_add_u32 s42, s42, 0x100000
	s_addc_u32 s43, s43, 0
	global_load_lds_dwordx4 v137, s[42:43]
	global_load_lds_dwordx4 v150, s[42:43] offset:1024
	s_add_u32 m0, s0, 0xc000
	s_add_u32 s30, s30, 0x10000
	s_addc_u32 s31, s31, 0
	global_load_lds_dwordx4 v151, s[30:31]
	global_load_lds_dwordx4 v152, s[30:31] offset:1024
	global_load_lds_dwordx4 v153, s[30:31] offset:2048
	global_load_lds_dwordx4 v154, s[30:31] offset:3072
	s_waitcnt lgkmcnt(10)
	v_mfma_f32_32x32x16_bf16 v[34:49], v[224:227], v[232:235], v[34:49]
	s_waitcnt lgkmcnt(9)
	v_mfma_f32_32x32x16_bf16 v[50:65], v[224:227], v[236:239], v[50:65]
	s_waitcnt lgkmcnt(8)
	v_mfma_f32_32x32x16_bf16 v[2:17], v[228:231], v[232:235], v[2:17]
	v_mfma_f32_32x32x16_bf16 v[18:33], v[228:231], v[236:239], v[18:33]
	s_waitcnt lgkmcnt(7)
	v_mfma_f32_32x32x16_bf16 v[74:89], v[224:227], v[240:243], v[74:89]
	s_waitcnt lgkmcnt(6)
	v_mfma_f32_32x32x16_bf16 v[90:105], v[224:227], v[244:247], v[90:105]
	v_mfma_f32_32x32x16_bf16 v[106:121], v[228:231], v[240:243], v[106:121]
	v_mfma_f32_32x32x16_bf16 v[208:223], v[228:231], v[244:247], v[208:223]
	s_waitcnt lgkmcnt(4)
	v_mfma_f32_32x32x16_bf16 v[34:49], v[248:251], v[160:163], v[34:49]
	s_waitcnt lgkmcnt(3)
	v_mfma_f32_32x32x16_bf16 v[50:65], v[248:251], v[164:167], v[50:65]
	s_waitcnt lgkmcnt(2)
	v_mfma_f32_32x32x16_bf16 v[2:17], v[156:159], v[160:163], v[2:17]
	v_mfma_f32_32x32x16_bf16 v[18:33], v[156:159], v[164:167], v[18:33]
	s_waitcnt lgkmcnt(1)
	v_mfma_f32_32x32x16_bf16 v[74:89], v[248:251], v[168:171], v[74:89]
	s_waitcnt lgkmcnt(0)
	v_mfma_f32_32x32x16_bf16 v[90:105], v[248:251], v[122:125], v[90:105]
	v_mfma_f32_32x32x16_bf16 v[106:121], v[156:159], v[168:171], v[106:121]
	v_mfma_f32_32x32x16_bf16 v[208:223], v[156:159], v[122:125], v[208:223]
	s_setprio 0
	s_waitcnt vmcnt(6)
	s_barrier
; #define BLOAD(A_, B_, kt) do { _Pragma("unroll") for (int i = 0; i < 4; ++i) { \
;     A_[i] = *(const u32x4*)((const char*)Ap + (aoff + (unsigned)(32 * i * lda + (kt) * 64) * 2u)); B_[i] = *(const u32x4*)((const char*)Wt + (woff + (unsigned)(32 * i * K + (kt) * 64) * 2u)); } } while (0)
; #define BLOAD(A_, B_, kt) do { _Pragma("unroll") for (int i = 0; i < 4; ++i) { \
;     A_[i] = *(const u32x4*)((const char*)Ap + (aoff + (unsigned)(32 * i * lda + (kt) * 64) * 2u)); B_[i] = *(const u32x4*)((const char*)Wt + (woff + (unsigned)(32 * i * K + (kt) * 64) * 2u)); } } while (0)
; #define BSTORE(A_, B_, buf) do { _Pragma("unroll") for (int i = 0; i < 4; ++i) { \
;     *(u32x4*)&As[(buf) * GBUF + (srow + 32 * i) * LDT + sc8] = A_[i]; \
;     *(u32x4*)&Bs[(buf) * GBUF + (srow + 32 * i) * LDT + sc8] = B_[i]; } } while (0)
; template <int NK>
; DI void gemm_run(PF& pf, const u16* __restrict__ Ap, int lda, const u16* __restrict__ Wt, f32x16 (&acc)[2][2], char* smem) {
;     ...
; #pragma unroll
;   for (int kt = 0; kt < nk; kt += 2) {
;     BCOMP(0);
;     BSTORE(pf.a1, pf.b1, 1);
;     if (kt + 3 < nk) BLOAD(pf.a1, pf.b1, kt + 3);
;     __syncthreads();
;     BCOMP(1);
;     if (kt + 2 < nk) { BSTORE(pf.a0, pf.b0, 0); if (kt + 4 < nk) BLOAD(pf.a0, pf.b0, kt + 4); }
;     __syncthreads();
;   }
	s_setprio 1
	ds_read_b128 v[224:227], v126 offset:24576
	ds_read_b128 v[232:235], v128 offset:24576
	ds_read_b128 v[236:239], v128 offset:26624
	ds_read_b128 v[228:231], v126 offset:26624
	ds_read_b128 v[240:243], v128 offset:32768
	ds_read_b128 v[244:247], v128 offset:34816
	ds_read_b128 v[248:251], v127 offset:24576
	ds_read_b128 v[160:163], v129 offset:24576
	ds_read_b128 v[164:167], v129 offset:26624
	ds_read_b128 v[156:159], v127 offset:26624
	ds_read_b128 v[168:171], v129 offset:32768
	ds_read_b128 v[122:125], v129 offset:34816
	s_add_u32 m0, s16, 0x0
	s_add_u32 s42, s42, 0x100000
	s_addc_u32 s43, s43, 0
	global_load_lds_dwordx4 v137, s[42:43]
	global_load_lds_dwordx4 v150, s[42:43] offset:1024
	s_add_u32 m0, s0, 0x0
	s_add_u32 s30, s30, 0x10000
	s_addc_u32 s31, s31, 0
	global_load_lds_dwordx4 v151, s[30:31]
	global_load_lds_dwordx4 v152, s[30:31] offset:1024
	global_load_lds_dwordx4 v153, s[30:31] offset:2048
	global_load_lds_dwordx4 v154, s[30:31] offset:3072
	s_waitcnt lgkmcnt(10)
	v_mfma_f32_32x32x16_bf16 v[34:49], v[224:227], v[232:235], v[34:49]
	s_waitcnt lgkmcnt(9)
	v_mfma_f32_32x32x16_bf16 v[50:65], v[224:227], v[236:239], v[50:65]
	s_waitcnt lgkmcnt(8)
	v_mfma_f32_32x32x16_bf16 v[2:17], v[228:231], v[232:235], v[2:17]
	v_mfma_f32_32x32x16_bf16 v[18:33], v[228:231], v[236:239], v[18:33]
	s_waitcnt lgkmcnt(7)
	v_mfma_f32_32x32x16_bf16 v[74:89], v[224:227], v[240:243], v[74:89]
	s_waitcnt lgkmcnt(6)
	v_mfma_f32_32x32x16_bf16 v[90:105], v[224:227], v[244:247], v[90:105]
	v_mfma_f32_32x32x16_bf16 v[106:121], v[228:231], v[240:243], v[106:121]
	v_mfma_f32_32x32x16_bf16 v[208:223], v[228:231], v[244:247], v[208:223]
	s_waitcnt lgkmcnt(4)
	v_mfma_f32_32x32x16_bf16 v[34:49], v[248:251], v[160:163], v[34:49]
	s_waitcnt lgkmcnt(3)
	v_mfma_f32_32x32x16_bf16 v[50:65], v[248:251], v[164:167], v[50:65]
	s_waitcnt lgkmcnt(2)
	v_mfma_f32_32x32x16_bf16 v[2:17], v[156:159], v[160:163], v[2:17]
	v_mfma_f32_32x32x16_bf16 v[18:33], v[156:159], v[164:167], v[18:33]
	s_waitcnt lgkmcnt(1)
	v_mfma_f32_32x32x16_bf16 v[74:89], v[248:251], v[168:171], v[74:89]
	s_waitcnt lgkmcnt(0)
	v_mfma_f32_32x32x16_bf16 v[90:105], v[248:251], v[122:125], v[90:105]
	v_mfma_f32_32x32x16_bf16 v[106:121], v[156:159], v[168:171], v[106:121]
	v_mfma_f32_32x32x16_bf16 v[208:223], v[156:159], v[122:125], v[208:223]
	s_setprio 0
	s_waitcnt vmcnt(6)
	s_barrier
	s_setprio 1
	ds_read_b128 v[224:227], v126 offset:49152
	ds_read_b128 v[232:235], v128 offset:49152
	ds_read_b128 v[236:239], v128 offset:51200
	ds_read_b128 v[228:231], v126 offset:51200
	ds_read_b128 v[240:243], v128 offset:57344
	ds_read_b128 v[244:247], v128 offset:59392
	ds_read_b128 v[248:251], v127 offset:49152
	ds_read_b128 v[160:163], v129 offset:49152
	ds_read_b128 v[164:167], v129 offset:51200
	ds_read_b128 v[156:159], v127 offset:51200
	ds_read_b128 v[168:171], v129 offset:57344
	ds_read_b128 v[122:125], v129 offset:59392
	s_add_u32 m0, s16, 0x6000
	s_add_u32 s42, s42, 0x100000
	s_addc_u32 s43, s43, 0
	global_load_lds_dwordx4 v137, s[42:43]
	global_load_lds_dwordx4 v150, s[42:43] offset:1024
	s_add_u32 m0, s0, 0x6000
	s_add_u32 s30, s30, 0x10000
	s_addc_u32 s31, s31, 0
	global_load_lds_dwordx4 v151, s[30:31]
	global_load_lds_dwordx4 v152, s[30:31] offset:1024
	global_load_lds_dwordx4 v153, s[30:31] offset:2048
	global_load_lds_dwordx4 v154, s[30:31] offset:3072
	s_waitcnt lgkmcnt(10)
	v_mfma_f32_32x32x16_bf16 v[34:49], v[224:227], v[232:235], v[34:49]
	s_waitcnt lgkmcnt(9)
	v_mfma_f32_32x32x16_bf16 v[50:65], v[224:227], v[236:239], v[50:65]
	s_waitcnt lgkmcnt(8)
	v_mfma_f32_32x32x16_bf16 v[2:17], v[228:231], v[232:235], v[2:17]
	v_mfma_f32_32x32x16_bf16 v[18:33], v[228:231], v[236:239], v[18:33]
	s_waitcnt lgkmcnt(7)
	v_mfma_f32_32x32x16_bf16 v[74:89], v[224:227], v[240:243], v[74:89]
	s_waitcnt lgkmcnt(6)
	v_mfma_f32_32x32x16_bf16 v[90:105], v[224:227], v[244:247], v[90:105]
	v_mfma_f32_32x32x16_bf16 v[106:121], v[228:231], v[240:243], v[106:121]
	v_mfma_f32_32x32x16_bf16 v[208:223], v[228:231], v[244:247], v[208:223]
	s_waitcnt lgkmcnt(4)
	v_mfma_f32_32x32x16_bf16 v[34:49], v[248:251], v[160:163], v[34:49]
	s_waitcnt lgkmcnt(3)
	v_mfma_f32_32x32x16_bf16 v[50:65], v[248:251], v[164:167], v[50:65]
	s_waitcnt lgkmcnt(2)
	v_mfma_f32_32x32x16_bf16 v[2:17], v[156:159], v[160:163], v[2:17]
	v_mfma_f32_32x32x16_bf16 v[18:33], v[156:159], v[164:167], v[18:33]
	s_waitcnt lgkmcnt(1)
	v_mfma_f32_32x32x16_bf16 v[74:89], v[248:251], v[168:171], v[74:89]
	s_waitcnt lgkmcnt(0)
	v_mfma_f32_32x32x16_bf16 v[90:105], v[248:251], v[122:125], v[90:105]
	v_mfma_f32_32x32x16_bf16 v[106:121], v[156:159], v[168:171], v[106:121]
	v_mfma_f32_32x32x16_bf16 v[208:223], v[156:159], v[122:125], v[208:223]
	s_setprio 0
	s_waitcnt vmcnt(6)
	s_barrier
; #define BLOAD(A_, B_, kt) do { _Pragma("unroll") for (int i = 0; i < 4; ++i) { \
;     A_[i] = *(const u32x4*)((const char*)Ap + (aoff + (unsigned)(32 * i * lda + (kt) * 64) * 2u)); B_[i] = *(const u32x4*)((const char*)Wt + (woff + (unsigned)(32 * i * K + (kt) * 64) * 2u)); } } while (0)
; #define BLOAD(A_, B_, kt) do { _Pragma("unroll") for (int i = 0; i < 4; ++i) { \
;     A_[i] = *(const u32x4*)((const char*)Ap + (aoff + (unsigned)(32 * i * lda + (kt) * 64) * 2u)); B_[i] = *(const u32x4*)((const char*)Wt + (woff + (unsigned)(32 * i * K + (kt) * 64) * 2u)); } } while (0)
; #define BSTORE(A_, B_, buf) do { _Pragma("unroll") for (int i = 0; i < 4; ++i) { \
;     *(u32x4*)&As[(buf) * GBUF + (srow + 32 * i) * LDT + sc8] = A_[i]; \
;     *(u32x4*)&Bs[(buf) * GBUF + (srow + 32 * i) * LDT + sc8] = B_[i]; } } while (0)
; template <int NK>
; DI void gemm_run(PF& pf, const u16* __restrict__ Ap, int lda, const u16* __restrict__ Wt, f32x16 (&acc)[2][2], char* smem) {
;     ...
; #pragma unroll
;   for (int kt = 0; kt < nk; kt += 2) {
;     BCOMP(0);
;     BSTORE(pf.a1, pf.b1, 1);
;     if (kt + 3 < nk) BLOAD(pf.a1, pf.b1, kt + 3);
;     __syncthreads();
;     BCOMP(1);
;     if (kt + 2 < nk) { BSTORE(pf.a0, pf.b0, 0); if (kt + 4 < nk) BLOAD(pf.a0, pf.b0, kt + 4); }
;     __syncthreads();
;   }
	s_setprio 1
	ds_read_b128 v[224:227], v126 offset:0
	ds_read_b128 v[232:235], v128 offset:0
	ds_read_b128 v[236:239], v128 offset:2048
	ds_read_b128 v[228:231], v126 offset:2048
	ds_read_b128 v[240:243], v128 offset:8192
	ds_read_b128 v[244:247], v128 offset:10240
	ds_read_b128 v[248:251], v127 offset:0
	ds_read_b128 v[160:163], v129 offset:0
	ds_read_b128 v[164:167], v129 offset:2048
	ds_read_b128 v[156:159], v127 offset:2048
	ds_read_b128 v[168:171], v129 offset:8192
	ds_read_b128 v[122:125], v129 offset:10240
	s_add_u32 m0, s16, 0xc000
	s_add_u32 s42, s42, 0x100000
	s_addc_u32 s43, s43, 0
	global_load_lds_dwordx4 v137, s[42:43]
	global_load_lds_dwordx4 v150, s[42:43] offset:1024
	s_add_u32 m0, s0, 0xc000
	s_add_u32 s30, s30, 0x10000
	s_addc_u32 s31, s31, 0
	global_load_lds_dwordx4 v151, s[30:31]
	global_load_lds_dwordx4 v152, s[30:31] offset:1024
	global_load_lds_dwordx4 v153, s[30:31] offset:2048
	global_load_lds_dwordx4 v154, s[30:31] offset:3072
	s_waitcnt lgkmcnt(10)
	v_mfma_f32_32x32x16_bf16 v[34:49], v[224:227], v[232:235], v[34:49]
	s_waitcnt lgkmcnt(9)
	v_mfma_f32_32x32x16_bf16 v[50:65], v[224:227], v[236:239], v[50:65]
	s_waitcnt lgkmcnt(8)
	v_mfma_f32_32x32x16_bf16 v[2:17], v[228:231], v[232:235], v[2:17]
	v_mfma_f32_32x32x16_bf16 v[18:33], v[228:231], v[236:239], v[18:33]
	s_waitcnt lgkmcnt(7)
	v_mfma_f32_32x32x16_bf16 v[74:89], v[224:227], v[240:243], v[74:89]
	s_waitcnt lgkmcnt(6)
	v_mfma_f32_32x32x16_bf16 v[90:105], v[224:227], v[244:247], v[90:105]
	v_mfma_f32_32x32x16_bf16 v[106:121], v[228:231], v[240:243], v[106:121]
	v_mfma_f32_32x32x16_bf16 v[208:223], v[228:231], v[244:247], v[208:223]
	s_waitcnt lgkmcnt(4)
	v_mfma_f32_32x32x16_bf16 v[34:49], v[248:251], v[160:163], v[34:49]
	s_waitcnt lgkmcnt(3)
	v_mfma_f32_32x32x16_bf16 v[50:65], v[248:251], v[164:167], v[50:65]
	s_waitcnt lgkmcnt(2)
	v_mfma_f32_32x32x16_bf16 v[2:17], v[156:159], v[160:163], v[2:17]
	v_mfma_f32_32x32x16_bf16 v[18:33], v[156:159], v[164:167], v[18:33]
	s_waitcnt lgkmcnt(1)
	v_mfma_f32_32x32x16_bf16 v[74:89], v[248:251], v[168:171], v[74:89]
	s_waitcnt lgkmcnt(0)
	v_mfma_f32_32x32x16_bf16 v[90:105], v[248:251], v[122:125], v[90:105]
	v_mfma_f32_32x32x16_bf16 v[106:121], v[156:159], v[168:171], v[106:121]
	v_mfma_f32_32x32x16_bf16 v[208:223], v[156:159], v[122:125], v[208:223]
	s_setprio 0
	s_waitcnt vmcnt(6)
	s_barrier
	s_setprio 1
	ds_read_b128 v[224:227], v126 offset:24576
	ds_read_b128 v[232:235], v128 offset:24576
	ds_read_b128 v[236:239], v128 offset:26624
	ds_read_b128 v[228:231], v126 offset:26624
	ds_read_b128 v[240:243], v128 offset:32768
	ds_read_b128 v[244:247], v128 offset:34816
	ds_read_b128 v[248:251], v127 offset:24576
	ds_read_b128 v[160:163], v129 offset:24576
	ds_read_b128 v[164:167], v129 offset:26624
	ds_read_b128 v[156:159], v127 offset:26624
	ds_read_b128 v[168:171], v129 offset:32768
	ds_read_b128 v[122:125], v129 offset:34816
	s_add_u32 m0, s16, 0x0
	s_add_u32 s42, s42, 0x100000
	s_addc_u32 s43, s43, 0
	global_load_lds_dwordx4 v137, s[42:43]
	global_load_lds_dwordx4 v150, s[42:43] offset:1024
	s_add_u32 m0, s0, 0x0
	s_add_u32 s30, s30, 0x10000
	s_addc_u32 s31, s31, 0
	global_load_lds_dwordx4 v151, s[30:31]
	global_load_lds_dwordx4 v152, s[30:31] offset:1024
	global_load_lds_dwordx4 v153, s[30:31] offset:2048
	global_load_lds_dwordx4 v154, s[30:31] offset:3072
	s_waitcnt lgkmcnt(10)
	v_mfma_f32_32x32x16_bf16 v[34:49], v[224:227], v[232:235], v[34:49]
	s_waitcnt lgkmcnt(9)
	v_mfma_f32_32x32x16_bf16 v[50:65], v[224:227], v[236:239], v[50:65]
	s_waitcnt lgkmcnt(8)
	v_mfma_f32_32x32x16_bf16 v[2:17], v[228:231], v[232:235], v[2:17]
	v_mfma_f32_32x32x16_bf16 v[18:33], v[228:231], v[236:239], v[18:33]
	s_waitcnt lgkmcnt(7)
	v_mfma_f32_32x32x16_bf16 v[74:89], v[224:227], v[240:243], v[74:89]
	s_waitcnt lgkmcnt(6)
	v_mfma_f32_32x32x16_bf16 v[90:105], v[224:227], v[244:247], v[90:105]
	v_mfma_f32_32x32x16_bf16 v[106:121], v[228:231], v[240:243], v[106:121]
	v_mfma_f32_32x32x16_bf16 v[208:223], v[228:231], v[244:247], v[208:223]
	s_waitcnt lgkmcnt(4)
	v_mfma_f32_32x32x16_bf16 v[34:49], v[248:251], v[160:163], v[34:49]
	s_waitcnt lgkmcnt(3)
	v_mfma_f32_32x32x16_bf16 v[50:65], v[248:251], v[164:167], v[50:65]
	s_waitcnt lgkmcnt(2)
	v_mfma_f32_32x32x16_bf16 v[2:17], v[156:159], v[160:163], v[2:17]
	v_mfma_f32_32x32x16_bf16 v[18:33], v[156:159], v[164:167], v[18:33]
	s_waitcnt lgkmcnt(1)
	v_mfma_f32_32x32x16_bf16 v[74:89], v[248:251], v[168:171], v[74:89]
	s_waitcnt lgkmcnt(0)
	v_mfma_f32_32x32x16_bf16 v[90:105], v[248:251], v[122:125], v[90:105]
	v_mfma_f32_32x32x16_bf16 v[106:121], v[156:159], v[168:171], v[106:121]
	v_mfma_f32_32x32x16_bf16 v[208:223], v[156:159], v[122:125], v[208:223]
	s_setprio 0
	s_waitcnt vmcnt(6)
	s_barrier
; #define BLOAD(A_, B_, kt) do { _Pragma("unroll") for (int i = 0; i < 4; ++i) { \
;     A_[i] = *(const u32x4*)((const char*)Ap + (aoff + (unsigned)(32 * i * lda + (kt) * 64) * 2u)); B_[i] = *(const u32x4*)((const char*)Wt + (woff + (unsigned)(32 * i * K + (kt) * 64) * 2u)); } } while (0)
; #define BLOAD(A_, B_, kt) do { _Pragma("unroll") for (int i = 0; i < 4; ++i) { \
;     A_[i] = *(const u32x4*)((const char*)Ap + (aoff + (unsigned)(32 * i * lda + (kt) * 64) * 2u)); B_[i] = *(const u32x4*)((const char*)Wt + (woff + (unsigned)(32 * i * K + (kt) * 64) * 2u)); } } while (0)
; #define BSTORE(A_, B_, buf) do { _Pragma("unroll") for (int i = 0; i < 4; ++i) { \
;     *(u32x4*)&As[(buf) * GBUF + (srow + 32 * i) * LDT + sc8] = A_[i]; \
;     *(u32x4*)&Bs[(buf) * GBUF + (srow + 32 * i) * LDT + sc8] = B_[i]; } } while (0)
; template <int NK>
; DI void gemm_run(PF& pf, const u16* __restrict__ Ap, int lda, const u16* __restrict__ Wt, f32x16 (&acc)[2][2], char* smem) {
;     ...
; #pragma unroll
;   for (int kt = 0; kt < nk; kt += 2) {
;     BCOMP(0);
;     BSTORE(pf.a1, pf.b1, 1);
;     if (kt + 3 < nk) BLOAD(pf.a1, pf.b1, kt + 3);
;     __syncthreads();
;     BCOMP(1);
;     if (kt + 2 < nk) { BSTORE(pf.a0, pf.b0, 0); if (kt + 4 < nk) BLOAD(pf.a0, pf.b0, kt + 4); }
;     __syncthreads();
;   }
	s_setprio 1
	ds_read_b128 v[224:227], v126 offset:49152
	ds_read_b128 v[232:235], v128 offset:49152
	ds_read_b128 v[236:239], v128 offset:51200
	ds_read_b128 v[228:231], v126 offset:51200
	ds_read_b128 v[240:243], v128 offset:57344
	ds_read_b128 v[244:247], v128 offset:59392
	ds_read_b128 v[248:251], v127 offset:49152
	ds_read_b128 v[160:163], v129 offset:49152
	ds_read_b128 v[164:167], v129 offset:51200
	ds_read_b128 v[156:159], v127 offset:51200
	ds_read_b128 v[168:171], v129 offset:57344
	ds_read_b128 v[122:125], v129 offset:59392
	s_add_u32 m0, s16, 0x6000
	s_add_u32 s42, s42, 0x100000
	s_addc_u32 s43, s43, 0
	global_load_lds_dwordx4 v137, s[42:43]
	global_load_lds_dwordx4 v150, s[42:43] offset:1024
	s_add_u32 m0, s0, 0x6000
	s_add_u32 s30, s30, 0x10000
	s_addc_u32 s31, s31, 0
	global_load_lds_dwordx4 v151, s[30:31]
	global_load_lds_dwordx4 v152, s[30:31] offset:1024
	global_load_lds_dwordx4 v153, s[30:31] offset:2048
	global_load_lds_dwordx4 v154, s[30:31] offset:3072
	s_waitcnt lgkmcnt(10)
	v_mfma_f32_32x32x16_bf16 v[34:49], v[224:227], v[232:235], v[34:49]
	s_waitcnt lgkmcnt(9)
	v_mfma_f32_32x32x16_bf16 v[50:65], v[224:227], v[236:239], v[50:65]
	s_waitcnt lgkmcnt(8)
	v_mfma_f32_32x32x16_bf16 v[2:17], v[228:231], v[232:235], v[2:17]
	v_mfma_f32_32x32x16_bf16 v[18:33], v[228:231], v[236:239], v[18:33]
	s_waitcnt lgkmcnt(7)
	v_mfma_f32_32x32x16_bf16 v[74:89], v[224:227], v[240:243], v[74:89]
	s_waitcnt lgkmcnt(6)
	v_mfma_f32_32x32x16_bf16 v[90:105], v[224:227], v[244:247], v[90:105]
	v_mfma_f32_32x32x16_bf16 v[106:121], v[228:231], v[240:243], v[106:121]
	v_mfma_f32_32x32x16_bf16 v[208:223], v[228:231], v[244:247], v[208:223]
	s_waitcnt lgkmcnt(4)
	v_mfma_f32_32x32x16_bf16 v[34:49], v[248:251], v[160:163], v[34:49]
	s_waitcnt lgkmcnt(3)
	v_mfma_f32_32x32x16_bf16 v[50:65], v[248:251], v[164:167], v[50:65]
	s_waitcnt lgkmcnt(2)
	v_mfma_f32_32x32x16_bf16 v[2:17], v[156:159], v[160:163], v[2:17]
	v_mfma_f32_32x32x16_bf16 v[18:33], v[156:159], v[164:167], v[18:33]
	s_waitcnt lgkmcnt(1)
	v_mfma_f32_32x32x16_bf16 v[74:89], v[248:251], v[168:171], v[74:89]
	s_waitcnt lgkmcnt(0)
	v_mfma_f32_32x32x16_bf16 v[90:105], v[248:251], v[122:125], v[90:105]
	v_mfma_f32_32x32x16_bf16 v[106:121], v[156:159], v[168:171], v[106:121]
	v_mfma_f32_32x32x16_bf16 v[208:223], v[156:159], v[122:125], v[208:223]
	s_setprio 0
	s_waitcnt vmcnt(6)
	s_barrier
	s_setprio 1
	ds_read_b128 v[224:227], v126 offset:0
	ds_read_b128 v[232:235], v128 offset:0
	ds_read_b128 v[236:239], v128 offset:2048
	ds_read_b128 v[228:231], v126 offset:2048
	ds_read_b128 v[240:243], v128 offset:8192
	ds_read_b128 v[244:247], v128 offset:10240
	ds_read_b128 v[248:251], v127 offset:0
	ds_read_b128 v[160:163], v129 offset:0
	ds_read_b128 v[164:167], v129 offset:2048
	ds_read_b128 v[156:159], v127 offset:2048
	ds_read_b128 v[168:171], v129 offset:8192
	ds_read_b128 v[122:125], v129 offset:10240
	s_add_u32 m0, s16, 0xc000
	s_add_u32 s42, s42, 0x100000
	s_addc_u32 s43, s43, 0
	global_load_lds_dwordx4 v137, s[42:43]
	global_load_lds_dwordx4 v150, s[42:43] offset:1024
	s_add_u32 m0, s0, 0xc000
	s_add_u32 s30, s30, 0x10000
	s_addc_u32 s31, s31, 0
	global_load_lds_dwordx4 v151, s[30:31]
	global_load_lds_dwordx4 v152, s[30:31] offset:1024
	global_load_lds_dwordx4 v153, s[30:31] offset:2048
	global_load_lds_dwordx4 v154, s[30:31] offset:3072
	s_waitcnt lgkmcnt(10)
	v_mfma_f32_32x32x16_bf16 v[34:49], v[224:227], v[232:235], v[34:49]
	s_waitcnt lgkmcnt(9)
	v_mfma_f32_32x32x16_bf16 v[50:65], v[224:227], v[236:239], v[50:65]
	s_waitcnt lgkmcnt(8)
	v_mfma_f32_32x32x16_bf16 v[2:17], v[228:231], v[232:235], v[2:17]
	v_mfma_f32_32x32x16_bf16 v[18:33], v[228:231], v[236:239], v[18:33]
	s_waitcnt lgkmcnt(7)
	v_mfma_f32_32x32x16_bf16 v[74:89], v[224:227], v[240:243], v[74:89]
	s_waitcnt lgkmcnt(6)
	v_mfma_f32_32x32x16_bf16 v[90:105], v[224:227], v[244:247], v[90:105]
	v_mfma_f32_32x32x16_bf16 v[106:121], v[228:231], v[240:243], v[106:121]
	v_mfma_f32_32x32x16_bf16 v[208:223], v[228:231], v[244:247], v[208:223]
	s_waitcnt lgkmcnt(4)
	v_mfma_f32_32x32x16_bf16 v[34:49], v[248:251], v[160:163], v[34:49]
	s_waitcnt lgkmcnt(3)
	v_mfma_f32_32x32x16_bf16 v[50:65], v[248:251], v[164:167], v[50:65]
	s_waitcnt lgkmcnt(2)
	v_mfma_f32_32x32x16_bf16 v[2:17], v[156:159], v[160:163], v[2:17]
	v_mfma_f32_32x32x16_bf16 v[18:33], v[156:159], v[164:167], v[18:33]
	s_waitcnt lgkmcnt(1)
	v_mfma_f32_32x32x16_bf16 v[74:89], v[248:251], v[168:171], v[74:89]
	s_waitcnt lgkmcnt(0)
	v_mfma_f32_32x32x16_bf16 v[90:105], v[248:251], v[122:125], v[90:105]
	v_mfma_f32_32x32x16_bf16 v[106:121], v[156:159], v[168:171], v[106:121]
	v_mfma_f32_32x32x16_bf16 v[208:223], v[156:159], v[122:125], v[208:223]
	s_setprio 0
	s_waitcnt vmcnt(6)
	s_barrier
; #define BLOAD(A_, B_, kt) do { _Pragma("unroll") for (int i = 0; i < 4; ++i) { \
;     A_[i] = *(const u32x4*)((const char*)Ap + (aoff + (unsigned)(32 * i * lda + (kt) * 64) * 2u)); B_[i] = *(const u32x4*)((const char*)Wt + (woff + (unsigned)(32 * i * K + (kt) * 64) * 2u)); } } while (0)
; #define BLOAD(A_, B_, kt) do { _Pragma("unroll") for (int i = 0; i < 4; ++i) { \
;     A_[i] = *(const u32x4*)((const char*)Ap + (aoff + (unsigned)(32 * i * lda + (kt) * 64) * 2u)); B_[i] = *(const u32x4*)((const char*)Wt + (woff + (unsigned)(32 * i * K + (kt) * 64) * 2u)); } } while (0)
; #define BSTORE(A_, B_, buf) do { _Pragma("unroll") for (int i = 0; i < 4; ++i) { \
;     *(u32x4*)&As[(buf) * GBUF + (srow + 32 * i) * LDT + sc8] = A_[i]; \
;     *(u32x4*)&Bs[(buf) * GBUF + (srow + 32 * i) * LDT + sc8] = B_[i]; } } while (0)
; template <int NK>
; DI void gemm_run(PF& pf, const u16* __restrict__ Ap, int lda, const u16* __restrict__ Wt, f32x16 (&acc)[2][2], char* smem) {
;     ...
; #pragma unroll
;   for (int kt = 0; kt < nk; kt += 2) {
;     BCOMP(0);
;     BSTORE(pf.a1, pf.b1, 1);
;     if (kt + 3 < nk) BLOAD(pf.a1, pf.b1, kt + 3);
;     __syncthreads();
;     BCOMP(1);
;     if (kt + 2 < nk) { BSTORE(pf.a0, pf.b0, 0); if (kt + 4 < nk) BLOAD(pf.a0, pf.b0, kt + 4); }
;     __syncthreads();
;   }
	s_setprio 1
	ds_read_b128 v[224:227], v126 offset:24576
	ds_read_b128 v[232:235], v128 offset:24576
	ds_read_b128 v[236:239], v128 offset:26624
	ds_read_b128 v[228:231], v126 offset:26624
	ds_read_b128 v[240:243], v128 offset:32768
	ds_read_b128 v[244:247], v128 offset:34816
	ds_read_b128 v[248:251], v127 offset:24576
	ds_read_b128 v[160:163], v129 offset:24576
	ds_read_b128 v[164:167], v129 offset:26624
	ds_read_b128 v[156:159], v127 offset:26624
	ds_read_b128 v[168:171], v129 offset:32768
	ds_read_b128 v[122:125], v129 offset:34816
	s_add_u32 m0, s16, 0x0
	s_add_u32 s42, s42, 0x100000
	s_addc_u32 s43, s43, 0
	global_load_lds_dwordx4 v137, s[42:43]
	global_load_lds_dwordx4 v150, s[42:43] offset:1024
	s_add_u32 m0, s0, 0x0
	s_add_u32 s30, s30, 0x10000
	s_addc_u32 s31, s31, 0
	global_load_lds_dwordx4 v151, s[30:31]
	global_load_lds_dwordx4 v152, s[30:31] offset:1024
	global_load_lds_dwordx4 v153, s[30:31] offset:2048
	global_load_lds_dwordx4 v154, s[30:31] offset:3072
	s_waitcnt lgkmcnt(10)
	v_mfma_f32_32x32x16_bf16 v[34:49], v[224:227], v[232:235], v[34:49]
	s_waitcnt lgkmcnt(9)
	v_mfma_f32_32x32x16_bf16 v[50:65], v[224:227], v[236:239], v[50:65]
	s_waitcnt lgkmcnt(8)
	v_mfma_f32_32x32x16_bf16 v[2:17], v[228:231], v[232:235], v[2:17]
	v_mfma_f32_32x32x16_bf16 v[18:33], v[228:231], v[236:239], v[18:33]
	s_waitcnt lgkmcnt(7)
	v_mfma_f32_32x32x16_bf16 v[74:89], v[224:227], v[240:243], v[74:89]
	s_waitcnt lgkmcnt(6)
	v_mfma_f32_32x32x16_bf16 v[90:105], v[224:227], v[244:247], v[90:105]
	v_mfma_f32_32x32x16_bf16 v[106:121], v[228:231], v[240:243], v[106:121]
	v_mfma_f32_32x32x16_bf16 v[208:223], v[228:231], v[244:247], v[208:223]
	s_waitcnt lgkmcnt(4)
	v_mfma_f32_32x32x16_bf16 v[34:49], v[248:251], v[160:163], v[34:49]
	s_waitcnt lgkmcnt(3)
	v_mfma_f32_32x32x16_bf16 v[50:65], v[248:251], v[164:167], v[50:65]
	s_waitcnt lgkmcnt(2)
	v_mfma_f32_32x32x16_bf16 v[2:17], v[156:159], v[160:163], v[2:17]
	v_mfma_f32_32x32x16_bf16 v[18:33], v[156:159], v[164:167], v[18:33]
	s_waitcnt lgkmcnt(1)
	v_mfma_f32_32x32x16_bf16 v[74:89], v[248:251], v[168:171], v[74:89]
	s_waitcnt lgkmcnt(0)
	v_mfma_f32_32x32x16_bf16 v[90:105], v[248:251], v[122:125], v[90:105]
	v_mfma_f32_32x32x16_bf16 v[106:121], v[156:159], v[168:171], v[106:121]
	v_mfma_f32_32x32x16_bf16 v[208:223], v[156:159], v[122:125], v[208:223]
	s_setprio 0
	s_waitcnt vmcnt(6)
	s_barrier
	s_setprio 1
	ds_read_b128 v[224:227], v126 offset:49152
	ds_read_b128 v[232:235], v128 offset:49152
	ds_read_b128 v[236:239], v128 offset:51200
	ds_read_b128 v[228:231], v126 offset:51200
	ds_read_b128 v[240:243], v128 offset:57344
	ds_read_b128 v[244:247], v128 offset:59392
	ds_read_b128 v[248:251], v127 offset:49152
	ds_read_b128 v[160:163], v129 offset:49152
	ds_read_b128 v[164:167], v129 offset:51200
	ds_read_b128 v[156:159], v127 offset:51200
	ds_read_b128 v[168:171], v129 offset:57344
	ds_read_b128 v[122:125], v129 offset:59392
	s_add_u32 m0, s16, 0x6000
	s_add_u32 s42, s42, 0x100000
	s_addc_u32 s43, s43, 0
	global_load_lds_dwordx4 v137, s[42:43]
	global_load_lds_dwordx4 v150, s[42:43] offset:1024
	s_add_u32 m0, s0, 0x6000
	s_add_u32 s30, s30, 0x10000
	s_addc_u32 s31, s31, 0
	global_load_lds_dwordx4 v151, s[30:31]
	global_load_lds_dwordx4 v152, s[30:31] offset:1024
	global_load_lds_dwordx4 v153, s[30:31] offset:2048
	global_load_lds_dwordx4 v154, s[30:31] offset:3072
	s_waitcnt lgkmcnt(10)
	v_mfma_f32_32x32x16_bf16 v[34:49], v[224:227], v[232:235], v[34:49]
	s_waitcnt lgkmcnt(9)
	v_mfma_f32_32x32x16_bf16 v[50:65], v[224:227], v[236:239], v[50:65]
	s_waitcnt lgkmcnt(8)
	v_mfma_f32_32x32x16_bf16 v[2:17], v[228:231], v[232:235], v[2:17]
	v_mfma_f32_32x32x16_bf16 v[18:33], v[228:231], v[236:239], v[18:33]
	s_waitcnt lgkmcnt(7)
	v_mfma_f32_32x32x16_bf16 v[74:89], v[224:227], v[240:243], v[74:89]
	s_waitcnt lgkmcnt(6)
	v_mfma_f32_32x32x16_bf16 v[90:105], v[224:227], v[244:247], v[90:105]
	v_mfma_f32_32x32x16_bf16 v[106:121], v[228:231], v[240:243], v[106:121]
	v_mfma_f32_32x32x16_bf16 v[208:223], v[228:231], v[244:247], v[208:223]
	s_waitcnt lgkmcnt(4)
	v_mfma_f32_32x32x16_bf16 v[34:49], v[248:251], v[160:163], v[34:49]
	s_waitcnt lgkmcnt(3)
	v_mfma_f32_32x32x16_bf16 v[50:65], v[248:251], v[164:167], v[50:65]
	s_waitcnt lgkmcnt(2)
	v_mfma_f32_32x32x16_bf16 v[2:17], v[156:159], v[160:163], v[2:17]
	v_mfma_f32_32x32x16_bf16 v[18:33], v[156:159], v[164:167], v[18:33]
	s_waitcnt lgkmcnt(1)
	v_mfma_f32_32x32x16_bf16 v[74:89], v[248:251], v[168:171], v[74:89]
	s_waitcnt lgkmcnt(0)
	v_mfma_f32_32x32x16_bf16 v[90:105], v[248:251], v[122:125], v[90:105]
	v_mfma_f32_32x32x16_bf16 v[106:121], v[156:159], v[168:171], v[106:121]
	v_mfma_f32_32x32x16_bf16 v[208:223], v[156:159], v[122:125], v[208:223]
	s_setprio 0
	s_waitcnt vmcnt(6)
	s_barrier
; #define BLOAD(A_, B_, kt) do { _Pragma("unroll") for (int i = 0; i < 4; ++i) { \
;     A_[i] = *(const u32x4*)((const char*)Ap + (aoff + (unsigned)(32 * i * lda + (kt) * 64) * 2u)); B_[i] = *(const u32x4*)((const char*)Wt + (woff + (unsigned)(32 * i * K + (kt) * 64) * 2u)); } } while (0)
; #define BLOAD(A_, B_, kt) do { _Pragma("unroll") for (int i = 0; i < 4; ++i) { \
;     A_[i] = *(const u32x4*)((const char*)Ap + (aoff + (unsigned)(32 * i * lda + (kt) * 64) * 2u)); B_[i] = *(const u32x4*)((const char*)Wt + (woff + (unsigned)(32 * i * K + (kt) * 64) * 2u)); } } while (0)
; #define BSTORE(A_, B_, buf) do { _Pragma("unroll") for (int i = 0; i < 4; ++i) { \
;     *(u32x4*)&As[(buf) * GBUF + (srow + 32 * i) * LDT + sc8] = A_[i]; \
;     *(u32x4*)&Bs[(buf) * GBUF + (srow + 32 * i) * LDT + sc8] = B_[i]; } } while (0)
; template <int NK>
; DI void gemm_run(PF& pf, const u16* __restrict__ Ap, int lda, const u16* __restrict__ Wt, f32x16 (&acc)[2][2], char* smem) {
;     ...
;   __builtin_amdgcn_s_setprio(0);
;   __syncthreads();
;   BSTORE(pf.a0, pf.b0, 0);
;   BLOAD(pf.a0, pf.b0, 2);
;   __syncthreads();
; #pragma unroll
;   for (int kt = 0; kt < nk; kt += 2) {
;     BCOMP(0);
;     BSTORE(pf.a1, pf.b1, 1);
;     if (kt + 3 < nk) BLOAD(pf.a1, pf.b1, kt + 3);
;     __syncthreads();
;     BCOMP(1);
;     if (kt + 2 < nk) { BSTORE(pf.a0, pf.b0, 0); if (kt + 4 < nk) BLOAD(pf.a0, pf.b0, kt + 4); }
;     __syncthreads();
;   }
	s_setprio 1
	ds_read_b128 v[224:227], v126 offset:0
	ds_read_b128 v[232:235], v128 offset:0
	ds_read_b128 v[236:239], v128 offset:2048
	ds_read_b128 v[228:231], v126 offset:2048
	ds_read_b128 v[240:243], v128 offset:8192
	ds_read_b128 v[244:247], v128 offset:10240
	ds_read_b128 v[248:251], v127 offset:0
	ds_read_b128 v[160:163], v129 offset:0
	ds_read_b128 v[164:167], v129 offset:2048
	ds_read_b128 v[156:159], v127 offset:2048
	ds_read_b128 v[168:171], v129 offset:8192
	ds_read_b128 v[122:125], v129 offset:10240
	s_add_u32 m0, s16, 0xc000
	s_add_u32 s42, s42, 0x100000
	s_addc_u32 s43, s43, 0
	global_load_lds_dwordx4 v137, s[42:43]
	global_load_lds_dwordx4 v150, s[42:43] offset:1024
	s_add_u32 m0, s0, 0xc000
	s_add_u32 s30, s30, 0x10000
	s_addc_u32 s31, s31, 0
	global_load_lds_dwordx4 v151, s[30:31]
	global_load_lds_dwordx4 v152, s[30:31] offset:1024
	global_load_lds_dwordx4 v153, s[30:31] offset:2048
	global_load_lds_dwordx4 v154, s[30:31] offset:3072
	s_waitcnt lgkmcnt(10)
	v_mfma_f32_32x32x16_bf16 v[34:49], v[224:227], v[232:235], v[34:49]
	s_waitcnt lgkmcnt(9)
	v_mfma_f32_32x32x16_bf16 v[50:65], v[224:227], v[236:239], v[50:65]
	s_waitcnt lgkmcnt(8)
	v_mfma_f32_32x32x16_bf16 v[2:17], v[228:231], v[232:235], v[2:17]
	v_mfma_f32_32x32x16_bf16 v[18:33], v[228:231], v[236:239], v[18:33]
	s_waitcnt lgkmcnt(7)
	v_mfma_f32_32x32x16_bf16 v[74:89], v[224:227], v[240:243], v[74:89]
	s_waitcnt lgkmcnt(6)
	v_mfma_f32_32x32x16_bf16 v[90:105], v[224:227], v[244:247], v[90:105]
	v_mfma_f32_32x32x16_bf16 v[106:121], v[228:231], v[240:243], v[106:121]
	v_mfma_f32_32x32x16_bf16 v[208:223], v[228:231], v[244:247], v[208:223]
	s_waitcnt lgkmcnt(4)
	v_mfma_f32_32x32x16_bf16 v[34:49], v[248:251], v[160:163], v[34:49]
	s_waitcnt lgkmcnt(3)
	v_mfma_f32_32x32x16_bf16 v[50:65], v[248:251], v[164:167], v[50:65]
	s_waitcnt lgkmcnt(2)
	v_mfma_f32_32x32x16_bf16 v[2:17], v[156:159], v[160:163], v[2:17]
	v_mfma_f32_32x32x16_bf16 v[18:33], v[156:159], v[164:167], v[18:33]
	s_waitcnt lgkmcnt(1)
	v_mfma_f32_32x32x16_bf16 v[74:89], v[248:251], v[168:171], v[74:89]
	s_waitcnt lgkmcnt(0)
	v_mfma_f32_32x32x16_bf16 v[90:105], v[248:251], v[122:125], v[90:105]
	v_mfma_f32_32x32x16_bf16 v[106:121], v[156:159], v[168:171], v[106:121]
	v_mfma_f32_32x32x16_bf16 v[208:223], v[156:159], v[122:125], v[208:223]
	s_setprio 0
	s_waitcnt vmcnt(6)
	s_barrier
	s_setprio 1
	ds_read_b128 v[224:227], v126 offset:24576
	ds_read_b128 v[232:235], v128 offset:24576
	ds_read_b128 v[236:239], v128 offset:26624
	ds_read_b128 v[228:231], v126 offset:26624
	ds_read_b128 v[240:243], v128 offset:32768
	ds_read_b128 v[244:247], v128 offset:34816
	ds_read_b128 v[248:251], v127 offset:24576
	ds_read_b128 v[160:163], v129 offset:24576
	ds_read_b128 v[164:167], v129 offset:26624
	ds_read_b128 v[156:159], v127 offset:26624
	ds_read_b128 v[168:171], v129 offset:32768
	ds_read_b128 v[122:125], v129 offset:34816
	s_add_u32 m0, s16, 0x0
	s_add_u32 s42, s42, 0x100000
	s_addc_u32 s43, s43, 0
	global_load_lds_dwordx4 v137, s[42:43]
	global_load_lds_dwordx4 v150, s[42:43] offset:1024
	s_add_u32 m0, s0, 0x0
	s_add_u32 s30, s30, 0x10000
	s_addc_u32 s31, s31, 0
	global_load_lds_dwordx4 v151, s[30:31]
	global_load_lds_dwordx4 v152, s[30:31] offset:1024
	global_load_lds_dwordx4 v153, s[30:31] offset:2048
	global_load_lds_dwordx4 v154, s[30:31] offset:3072
	s_waitcnt lgkmcnt(10)
	v_mfma_f32_32x32x16_bf16 v[34:49], v[224:227], v[232:235], v[34:49]
	s_waitcnt lgkmcnt(9)
	v_mfma_f32_32x32x16_bf16 v[50:65], v[224:227], v[236:239], v[50:65]
	s_waitcnt lgkmcnt(8)
	v_mfma_f32_32x32x16_bf16 v[2:17], v[228:231], v[232:235], v[2:17]
	v_mfma_f32_32x32x16_bf16 v[18:33], v[228:231], v[236:239], v[18:33]
	s_waitcnt lgkmcnt(7)
	v_mfma_f32_32x32x16_bf16 v[74:89], v[224:227], v[240:243], v[74:89]
	s_waitcnt lgkmcnt(6)
	v_mfma_f32_32x32x16_bf16 v[90:105], v[224:227], v[244:247], v[90:105]
	v_mfma_f32_32x32x16_bf16 v[106:121], v[228:231], v[240:243], v[106:121]
	v_mfma_f32_32x32x16_bf16 v[208:223], v[228:231], v[244:247], v[208:223]
	s_waitcnt lgkmcnt(4)
	v_mfma_f32_32x32x16_bf16 v[34:49], v[248:251], v[160:163], v[34:49]
	s_waitcnt lgkmcnt(3)
	v_mfma_f32_32x32x16_bf16 v[50:65], v[248:251], v[164:167], v[50:65]
	s_waitcnt lgkmcnt(2)
	v_mfma_f32_32x32x16_bf16 v[2:17], v[156:159], v[160:163], v[2:17]
	v_mfma_f32_32x32x16_bf16 v[18:33], v[156:159], v[164:167], v[18:33]
	s_waitcnt lgkmcnt(1)
	v_mfma_f32_32x32x16_bf16 v[74:89], v[248:251], v[168:171], v[74:89]
	s_waitcnt lgkmcnt(0)
	v_mfma_f32_32x32x16_bf16 v[90:105], v[248:251], v[122:125], v[90:105]
	v_mfma_f32_32x32x16_bf16 v[106:121], v[156:159], v[168:171], v[106:121]
	v_mfma_f32_32x32x16_bf16 v[208:223], v[156:159], v[122:125], v[208:223]
	s_setprio 0
	s_waitcnt vmcnt(6)
	s_barrier
; #define BLOAD(A_, B_, kt) do { _Pragma("unroll") for (int i = 0; i < 4; ++i) { \
;     A_[i] = *(const u32x4*)((const char*)Ap + (aoff + (unsigned)(32 * i * lda + (kt) * 64) * 2u)); B_[i] = *(const u32x4*)((const char*)Wt + (woff + (unsigned)(32 * i * K + (kt) * 64) * 2u)); } } while (0)
; #define BLOAD(A_, B_, kt) do { _Pragma("unroll") for (int i = 0; i < 4; ++i) { \
;     A_[i] = *(const u32x4*)((const char*)Ap + (aoff + (unsigned)(32 * i * lda + (kt) * 64) * 2u)); B_[i] = *(const u32x4*)((const char*)Wt + (woff + (unsigned)(32 * i * K + (kt) * 64) * 2u)); } } while (0)
; #define BSTORE(A_, B_, buf) do { _Pragma("unroll") for (int i = 0; i < 4; ++i) { \
;     *(u32x4*)&As[(buf) * GBUF + (srow + 32 * i) * LDT + sc8] = A_[i]; \
;     *(u32x4*)&Bs[(buf) * GBUF + (srow + 32 * i) * LDT + sc8] = B_[i]; } } while (0)
; template <int NK>
; DI void gemm_run(PF& pf, const u16* __restrict__ Ap, int lda, const u16* __restrict__ Wt, f32x16 (&acc)[2][2], char* smem) {
;     ...
;   __builtin_amdgcn_s_setprio(0);
;   __syncthreads();
;   BSTORE(pf.a0, pf.b0, 0);
;   BLOAD(pf.a0, pf.b0, 2);
;   __syncthreads();
; #pragma unroll
;   for (int kt = 0; kt < nk; kt += 2) {
;     BCOMP(0);
;     BSTORE(pf.a1, pf.b1, 1);
;     if (kt + 3 < nk) BLOAD(pf.a1, pf.b1, kt + 3);
;     __syncthreads();
;     BCOMP(1);
;     if (kt + 2 < nk) { BSTORE(pf.a0, pf.b0, 0); if (kt + 4 < nk) BLOAD(pf.a0, pf.b0, kt + 4); }
;     __syncthreads();
;   }
	s_setprio 1
	ds_read_b128 v[224:227], v126 offset:49152
	ds_read_b128 v[232:235], v128 offset:49152
	ds_read_b128 v[236:239], v128 offset:51200
	ds_read_b128 v[228:231], v126 offset:51200
	ds_read_b128 v[240:243], v128 offset:57344
	ds_read_b128 v[244:247], v128 offset:59392
	ds_read_b128 v[248:251], v127 offset:49152
	ds_read_b128 v[160:163], v129 offset:49152
	ds_read_b128 v[164:167], v129 offset:51200
	ds_read_b128 v[156:159], v127 offset:51200
	ds_read_b128 v[168:171], v129 offset:57344
	ds_read_b128 v[122:125], v129 offset:59392
	s_add_u32 m0, s16, 0x6000
	s_add_u32 s42, s42, 0x100000
	s_addc_u32 s43, s43, 0
	global_load_lds_dwordx4 v137, s[42:43]
	global_load_lds_dwordx4 v150, s[42:43] offset:1024
	s_add_u32 m0, s0, 0x6000
	s_add_u32 s30, s30, 0x10000
	s_addc_u32 s31, s31, 0
	global_load_lds_dwordx4 v151, s[30:31]
	global_load_lds_dwordx4 v152, s[30:31] offset:1024
	global_load_lds_dwordx4 v153, s[30:31] offset:2048
	global_load_lds_dwordx4 v154, s[30:31] offset:3072
	s_waitcnt lgkmcnt(10)
	v_mfma_f32_32x32x16_bf16 v[34:49], v[224:227], v[232:235], v[34:49]
	s_waitcnt lgkmcnt(9)
	v_mfma_f32_32x32x16_bf16 v[50:65], v[224:227], v[236:239], v[50:65]
	s_waitcnt lgkmcnt(8)
	v_mfma_f32_32x32x16_bf16 v[2:17], v[228:231], v[232:235], v[2:17]
	v_mfma_f32_32x32x16_bf16 v[18:33], v[228:231], v[236:239], v[18:33]
	s_waitcnt lgkmcnt(7)
	v_mfma_f32_32x32x16_bf16 v[74:89], v[224:227], v[240:243], v[74:89]
	s_waitcnt lgkmcnt(6)
	v_mfma_f32_32x32x16_bf16 v[90:105], v[224:227], v[244:247], v[90:105]
	v_mfma_f32_32x32x16_bf16 v[106:121], v[228:231], v[240:243], v[106:121]
	v_mfma_f32_32x32x16_bf16 v[208:223], v[228:231], v[244:247], v[208:223]
	s_waitcnt lgkmcnt(4)
	v_mfma_f32_32x32x16_bf16 v[34:49], v[248:251], v[160:163], v[34:49]
	s_waitcnt lgkmcnt(3)
	v_mfma_f32_32x32x16_bf16 v[50:65], v[248:251], v[164:167], v[50:65]
	s_waitcnt lgkmcnt(2)
	v_mfma_f32_32x32x16_bf16 v[2:17], v[156:159], v[160:163], v[2:17]
	v_mfma_f32_32x32x16_bf16 v[18:33], v[156:159], v[164:167], v[18:33]
	s_waitcnt lgkmcnt(1)
	v_mfma_f32_32x32x16_bf16 v[74:89], v[248:251], v[168:171], v[74:89]
	s_waitcnt lgkmcnt(0)
	v_mfma_f32_32x32x16_bf16 v[90:105], v[248:251], v[122:125], v[90:105]
	v_mfma_f32_32x32x16_bf16 v[106:121], v[156:159], v[168:171], v[106:121]
	v_mfma_f32_32x32x16_bf16 v[208:223], v[156:159], v[122:125], v[208:223]
	s_setprio 0
	s_waitcnt vmcnt(6)
	s_barrier
	s_setprio 1
	ds_read_b128 v[224:227], v126 offset:0
	ds_read_b128 v[232:235], v128 offset:0
	ds_read_b128 v[236:239], v128 offset:2048
	ds_read_b128 v[228:231], v126 offset:2048
	ds_read_b128 v[240:243], v128 offset:8192
	ds_read_b128 v[244:247], v128 offset:10240
	ds_read_b128 v[248:251], v127 offset:0
	ds_read_b128 v[160:163], v129 offset:0
	ds_read_b128 v[164:167], v129 offset:2048
	ds_read_b128 v[156:159], v127 offset:2048
	ds_read_b128 v[168:171], v129 offset:8192
	ds_read_b128 v[122:125], v129 offset:10240
	s_add_u32 m0, s16, 0xc000
	s_add_u32 s42, s42, 0x100000
	s_addc_u32 s43, s43, 0
	global_load_lds_dwordx4 v137, s[42:43]
	global_load_lds_dwordx4 v150, s[42:43] offset:1024
	s_add_u32 m0, s0, 0xc000
	s_add_u32 s30, s30, 0x10000
	s_addc_u32 s31, s31, 0
	global_load_lds_dwordx4 v151, s[30:31]
	global_load_lds_dwordx4 v152, s[30:31] offset:1024
	global_load_lds_dwordx4 v153, s[30:31] offset:2048
	global_load_lds_dwordx4 v154, s[30:31] offset:3072
	s_waitcnt lgkmcnt(10)
	v_mfma_f32_32x32x16_bf16 v[34:49], v[224:227], v[232:235], v[34:49]
	s_waitcnt lgkmcnt(9)
	v_mfma_f32_32x32x16_bf16 v[50:65], v[224:227], v[236:239], v[50:65]
	s_waitcnt lgkmcnt(8)
	v_mfma_f32_32x32x16_bf16 v[2:17], v[228:231], v[232:235], v[2:17]
	v_mfma_f32_32x32x16_bf16 v[18:33], v[228:231], v[236:239], v[18:33]
	s_waitcnt lgkmcnt(7)
	v_mfma_f32_32x32x16_bf16 v[74:89], v[224:227], v[240:243], v[74:89]
	s_waitcnt lgkmcnt(6)
	v_mfma_f32_32x32x16_bf16 v[90:105], v[224:227], v[244:247], v[90:105]
	v_mfma_f32_32x32x16_bf16 v[106:121], v[228:231], v[240:243], v[106:121]
	v_mfma_f32_32x32x16_bf16 v[208:223], v[228:231], v[244:247], v[208:223]
	s_waitcnt lgkmcnt(4)
	v_mfma_f32_32x32x16_bf16 v[34:49], v[248:251], v[160:163], v[34:49]
	s_waitcnt lgkmcnt(3)
	v_mfma_f32_32x32x16_bf16 v[50:65], v[248:251], v[164:167], v[50:65]
	s_waitcnt lgkmcnt(2)
	v_mfma_f32_32x32x16_bf16 v[2:17], v[156:159], v[160:163], v[2:17]
	v_mfma_f32_32x32x16_bf16 v[18:33], v[156:159], v[164:167], v[18:33]
	s_waitcnt lgkmcnt(1)
	v_mfma_f32_32x32x16_bf16 v[74:89], v[248:251], v[168:171], v[74:89]
	s_waitcnt lgkmcnt(0)
	v_mfma_f32_32x32x16_bf16 v[90:105], v[248:251], v[122:125], v[90:105]
	v_mfma_f32_32x32x16_bf16 v[106:121], v[156:159], v[168:171], v[106:121]
	v_mfma_f32_32x32x16_bf16 v[208:223], v[156:159], v[122:125], v[208:223]
	s_setprio 0
	s_waitcnt vmcnt(6)
	s_barrier
; #define BLOAD(A_, B_, kt) do { _Pragma("unroll") for (int i = 0; i < 4; ++i) { \
;     A_[i] = *(const u32x4*)((const char*)Ap + (aoff + (unsigned)(32 * i * lda + (kt) * 64) * 2u)); B_[i] = *(const u32x4*)((const char*)Wt + (woff + (unsigned)(32 * i * K + (kt) * 64) * 2u)); } } while (0)
; #define BLOAD(A_, B_, kt) do { _Pragma("unroll") for (int i = 0; i < 4; ++i) { \
;     A_[i] = *(const u32x4*)((const char*)Ap + (aoff + (unsigned)(32 * i * lda + (kt) * 64) * 2u)); B_[i] = *(const u32x4*)((const char*)Wt + (woff + (unsigned)(32 * i * K + (kt) * 64) * 2u)); } } while (0)
; #define BSTORE(A_, B_, buf) do { _Pragma("unroll") for (int i = 0; i < 4; ++i) { \
;     *(u32x4*)&As[(buf) * GBUF + (srow + 32 * i) * LDT + sc8] = A_[i]; \
;     *(u32x4*)&Bs[(buf) * GBUF + (srow + 32 * i) * LDT + sc8] = B_[i]; } } while (0)
; template <int NK>
; DI void gemm_run(PF& pf, const u16* __restrict__ Ap, int lda, const u16* __restrict__ Wt, f32x16 (&acc)[2][2], char* smem) {
;     ...
;   __builtin_amdgcn_s_setprio(0);
;   __syncthreads();
;   BSTORE(pf.a0, pf.b0, 0);
;   BLOAD(pf.a0, pf.b0, 2);
;   __syncthreads();
; #pragma unroll
;   for (int kt = 0; kt < nk; kt += 2) {
;     BCOMP(0);
;     BSTORE(pf.a1, pf.b1, 1);
;     if (kt + 3 < nk) BLOAD(pf.a1, pf.b1, kt + 3);
;     __syncthreads();
;     BCOMP(1);
;     if (kt + 2 < nk) { BSTORE(pf.a0, pf.b0, 0); if (kt + 4 < nk) BLOAD(pf.a0, pf.b0, kt + 4); }
;     __syncthreads();
;   }
	s_setprio 1
	ds_read_b128 v[224:227], v126 offset:24576
	ds_read_b128 v[232:235], v128 offset:24576
	ds_read_b128 v[236:239], v128 offset:26624
	ds_read_b128 v[228:231], v126 offset:26624
	ds_read_b128 v[240:243], v128 offset:32768
	ds_read_b128 v[244:247], v128 offset:34816
	ds_read_b128 v[248:251], v127 offset:24576
	ds_read_b128 v[160:163], v129 offset:24576
	ds_read_b128 v[164:167], v129 offset:26624
	ds_read_b128 v[156:159], v127 offset:26624
	ds_read_b128 v[168:171], v129 offset:32768
	ds_read_b128 v[122:125], v129 offset:34816
	s_add_u32 m0, s16, 0x0
	s_add_u32 s42, s42, 0x100000
	s_addc_u32 s43, s43, 0
	global_load_lds_dwordx4 v137, s[42:43]
	global_load_lds_dwordx4 v150, s[42:43] offset:1024
	s_add_u32 m0, s0, 0x0
	s_add_u32 s30, s30, 0x10000
	s_addc_u32 s31, s31, 0
	global_load_lds_dwordx4 v151, s[30:31]
	global_load_lds_dwordx4 v152, s[30:31] offset:1024
	global_load_lds_dwordx4 v153, s[30:31] offset:2048
	global_load_lds_dwordx4 v154, s[30:31] offset:3072
	s_waitcnt lgkmcnt(10)
	v_mfma_f32_32x32x16_bf16 v[34:49], v[224:227], v[232:235], v[34:49]
	s_waitcnt lgkmcnt(9)
	v_mfma_f32_32x32x16_bf16 v[50:65], v[224:227], v[236:239], v[50:65]
	s_waitcnt lgkmcnt(8)
	v_mfma_f32_32x32x16_bf16 v[2:17], v[228:231], v[232:235], v[2:17]
	v_mfma_f32_32x32x16_bf16 v[18:33], v[228:231], v[236:239], v[18:33]
	s_waitcnt lgkmcnt(7)
	v_mfma_f32_32x32x16_bf16 v[74:89], v[224:227], v[240:243], v[74:89]
	s_waitcnt lgkmcnt(6)
	v_mfma_f32_32x32x16_bf16 v[90:105], v[224:227], v[244:247], v[90:105]
	v_mfma_f32_32x32x16_bf16 v[106:121], v[228:231], v[240:243], v[106:121]
	v_mfma_f32_32x32x16_bf16 v[208:223], v[228:231], v[244:247], v[208:223]
	s_waitcnt lgkmcnt(4)
	v_mfma_f32_32x32x16_bf16 v[34:49], v[248:251], v[160:163], v[34:49]
	s_waitcnt lgkmcnt(3)
	v_mfma_f32_32x32x16_bf16 v[50:65], v[248:251], v[164:167], v[50:65]
	s_waitcnt lgkmcnt(2)
	v_mfma_f32_32x32x16_bf16 v[2:17], v[156:159], v[160:163], v[2:17]
	v_mfma_f32_32x32x16_bf16 v[18:33], v[156:159], v[164:167], v[18:33]
	s_waitcnt lgkmcnt(1)
	v_mfma_f32_32x32x16_bf16 v[74:89], v[248:251], v[168:171], v[74:89]
	s_waitcnt lgkmcnt(0)
	v_mfma_f32_32x32x16_bf16 v[90:105], v[248:251], v[122:125], v[90:105]
	v_mfma_f32_32x32x16_bf16 v[106:121], v[156:159], v[168:171], v[106:121]
	v_mfma_f32_32x32x16_bf16 v[208:223], v[156:159], v[122:125], v[208:223]
	s_setprio 0
	s_waitcnt vmcnt(6)
	s_barrier
	s_setprio 1
	ds_read_b128 v[224:227], v126 offset:49152
	ds_read_b128 v[232:235], v128 offset:49152
	ds_read_b128 v[236:239], v128 offset:51200
	ds_read_b128 v[228:231], v126 offset:51200
	ds_read_b128 v[240:243], v128 offset:57344
	ds_read_b128 v[244:247], v128 offset:59392
	ds_read_b128 v[248:251], v127 offset:49152
	ds_read_b128 v[160:163], v129 offset:49152
	ds_read_b128 v[164:167], v129 offset:51200
	ds_read_b128 v[156:159], v127 offset:51200
	ds_read_b128 v[168:171], v129 offset:57344
	ds_read_b128 v[122:125], v129 offset:59392
	s_add_u32 m0, s16, 0x6000
	s_add_u32 s42, s42, 0x100000
	s_addc_u32 s43, s43, 0
	global_load_lds_dwordx4 v137, s[42:43]
	global_load_lds_dwordx4 v150, s[42:43] offset:1024
	s_add_u32 m0, s0, 0x6000
	s_add_u32 s30, s30, 0x10000
	s_addc_u32 s31, s31, 0
	global_load_lds_dwordx4 v151, s[30:31]
	global_load_lds_dwordx4 v152, s[30:31] offset:1024
	global_load_lds_dwordx4 v153, s[30:31] offset:2048
	global_load_lds_dwordx4 v154, s[30:31] offset:3072
	s_waitcnt lgkmcnt(10)
	v_mfma_f32_32x32x16_bf16 v[34:49], v[224:227], v[232:235], v[34:49]
	s_waitcnt lgkmcnt(9)
	v_mfma_f32_32x32x16_bf16 v[50:65], v[224:227], v[236:239], v[50:65]
	s_waitcnt lgkmcnt(8)
	v_mfma_f32_32x32x16_bf16 v[2:17], v[228:231], v[232:235], v[2:17]
	v_mfma_f32_32x32x16_bf16 v[18:33], v[228:231], v[236:239], v[18:33]
	s_waitcnt lgkmcnt(7)
	v_mfma_f32_32x32x16_bf16 v[74:89], v[224:227], v[240:243], v[74:89]
	s_waitcnt lgkmcnt(6)
	v_mfma_f32_32x32x16_bf16 v[90:105], v[224:227], v[244:247], v[90:105]
	v_mfma_f32_32x32x16_bf16 v[106:121], v[228:231], v[240:243], v[106:121]
	v_mfma_f32_32x32x16_bf16 v[208:223], v[228:231], v[244:247], v[208:223]
	s_waitcnt lgkmcnt(4)
	v_mfma_f32_32x32x16_bf16 v[34:49], v[248:251], v[160:163], v[34:49]
	s_waitcnt lgkmcnt(3)
	v_mfma_f32_32x32x16_bf16 v[50:65], v[248:251], v[164:167], v[50:65]
	s_waitcnt lgkmcnt(2)
	v_mfma_f32_32x32x16_bf16 v[2:17], v[156:159], v[160:163], v[2:17]
	v_mfma_f32_32x32x16_bf16 v[18:33], v[156:159], v[164:167], v[18:33]
	s_waitcnt lgkmcnt(1)
	v_mfma_f32_32x32x16_bf16 v[74:89], v[248:251], v[168:171], v[74:89]
	s_waitcnt lgkmcnt(0)
	v_mfma_f32_32x32x16_bf16 v[90:105], v[248:251], v[122:125], v[90:105]
	v_mfma_f32_32x32x16_bf16 v[106:121], v[156:159], v[168:171], v[106:121]
	v_mfma_f32_32x32x16_bf16 v[208:223], v[156:159], v[122:125], v[208:223]
	s_setprio 0
	s_waitcnt vmcnt(6)
	s_barrier
; #define BLOAD(A_, B_, kt) do { _Pragma("unroll") for (int i = 0; i < 4; ++i) { \
;     A_[i] = *(const u32x4*)((const char*)Ap + (aoff + (unsigned)(32 * i * lda + (kt) * 64) * 2u)); B_[i] = *(const u32x4*)((const char*)Wt + (woff + (unsigned)(32 * i * K + (kt) * 64) * 2u)); } } while (0)
; #define BLOAD(A_, B_, kt) do { _Pragma("unroll") for (int i = 0; i < 4; ++i) { \
;     A_[i] = *(const u32x4*)((const char*)Ap + (aoff + (unsigned)(32 * i * lda + (kt) * 64) * 2u)); B_[i] = *(const u32x4*)((const char*)Wt + (woff + (unsigned)(32 * i * K + (kt) * 64) * 2u)); } } while (0)
; #define BSTORE(A_, B_, buf) do { _Pragma("unroll") for (int i = 0; i < 4; ++i) { \
;     *(u32x4*)&As[(buf) * GBUF + (srow + 32 * i) * LDT + sc8] = A_[i]; \
;     *(u32x4*)&Bs[(buf) * GBUF + (srow + 32 * i) * LDT + sc8] = B_[i]; } } while (0)
; template <int NK>
; DI void gemm_run(PF& pf, const u16* __restrict__ Ap, int lda, const u16* __restrict__ Wt, f32x16 (&acc)[2][2], char* smem) {
;     ...
;   __builtin_amdgcn_s_setprio(0);
;   __syncthreads();
;   BSTORE(pf.a0, pf.b0, 0);
;   BLOAD(pf.a0, pf.b0, 2);
;   __syncthreads();
; #pragma unroll
;   for (int kt = 0; kt < nk; kt += 2) {
;     BCOMP(0);
;     BSTORE(pf.a1, pf.b1, 1);
;     if (kt + 3 < nk) BLOAD(pf.a1, pf.b1, kt + 3);
;     __syncthreads();
;     BCOMP(1);
;     if (kt + 2 < nk) { BSTORE(pf.a0, pf.b0, 0); if (kt + 4 < nk) BLOAD(pf.a0, pf.b0, kt + 4); }
;     __syncthreads();
;   }
	s_setprio 1
	ds_read_b128 v[224:227], v126 offset:0
	ds_read_b128 v[232:235], v128 offset:0
	ds_read_b128 v[236:239], v128 offset:2048
	ds_read_b128 v[228:231], v126 offset:2048
	ds_read_b128 v[240:243], v128 offset:8192
	ds_read_b128 v[244:247], v128 offset:10240
	ds_read_b128 v[248:251], v127 offset:0
	ds_read_b128 v[160:163], v129 offset:0
	ds_read_b128 v[164:167], v129 offset:2048
	ds_read_b128 v[156:159], v127 offset:2048
	ds_read_b128 v[168:171], v129 offset:8192
	ds_read_b128 v[122:125], v129 offset:10240
	s_add_u32 m0, s16, 0xc000
	s_add_u32 s42, s42, 0x100000
	s_addc_u32 s43, s43, 0
	global_load_lds_dwordx4 v137, s[42:43]
	global_load_lds_dwordx4 v150, s[42:43] offset:1024
	s_add_u32 m0, s0, 0xc000
	s_add_u32 s30, s30, 0x10000
	s_addc_u32 s31, s31, 0
	global_load_lds_dwordx4 v151, s[30:31]
	global_load_lds_dwordx4 v152, s[30:31] offset:1024
	global_load_lds_dwordx4 v153, s[30:31] offset:2048
	global_load_lds_dwordx4 v154, s[30:31] offset:3072
	s_waitcnt lgkmcnt(10)
	v_mfma_f32_32x32x16_bf16 v[34:49], v[224:227], v[232:235], v[34:49]
	s_waitcnt lgkmcnt(9)
	v_mfma_f32_32x32x16_bf16 v[50:65], v[224:227], v[236:239], v[50:65]
	s_waitcnt lgkmcnt(8)
	v_mfma_f32_32x32x16_bf16 v[2:17], v[228:231], v[232:235], v[2:17]
	v_mfma_f32_32x32x16_bf16 v[18:33], v[228:231], v[236:239], v[18:33]
	s_waitcnt lgkmcnt(7)
	v_mfma_f32_32x32x16_bf16 v[74:89], v[224:227], v[240:243], v[74:89]
	s_waitcnt lgkmcnt(6)
	v_mfma_f32_32x32x16_bf16 v[90:105], v[224:227], v[244:247], v[90:105]
	v_mfma_f32_32x32x16_bf16 v[106:121], v[228:231], v[240:243], v[106:121]
	v_mfma_f32_32x32x16_bf16 v[208:223], v[228:231], v[244:247], v[208:223]
	s_waitcnt lgkmcnt(4)
	v_mfma_f32_32x32x16_bf16 v[34:49], v[248:251], v[160:163], v[34:49]
	s_waitcnt lgkmcnt(3)
	v_mfma_f32_32x32x16_bf16 v[50:65], v[248:251], v[164:167], v[50:65]
	s_waitcnt lgkmcnt(2)
	v_mfma_f32_32x32x16_bf16 v[2:17], v[156:159], v[160:163], v[2:17]
	v_mfma_f32_32x32x16_bf16 v[18:33], v[156:159], v[164:167], v[18:33]
	s_waitcnt lgkmcnt(1)
	v_mfma_f32_32x32x16_bf16 v[74:89], v[248:251], v[168:171], v[74:89]
	s_waitcnt lgkmcnt(0)
	v_mfma_f32_32x32x16_bf16 v[90:105], v[248:251], v[122:125], v[90:105]
	v_mfma_f32_32x32x16_bf16 v[106:121], v[156:159], v[168:171], v[106:121]
	v_mfma_f32_32x32x16_bf16 v[208:223], v[156:159], v[122:125], v[208:223]
	s_setprio 0
	s_waitcnt vmcnt(6)
	s_barrier
	s_setprio 1
	ds_read_b128 v[224:227], v126 offset:24576
	ds_read_b128 v[232:235], v128 offset:24576
	ds_read_b128 v[236:239], v128 offset:26624
	ds_read_b128 v[228:231], v126 offset:26624
	ds_read_b128 v[240:243], v128 offset:32768
	ds_read_b128 v[244:247], v128 offset:34816
	ds_read_b128 v[248:251], v127 offset:24576
	ds_read_b128 v[160:163], v129 offset:24576
	ds_read_b128 v[164:167], v129 offset:26624
	ds_read_b128 v[156:159], v127 offset:26624
	ds_read_b128 v[168:171], v129 offset:32768
	ds_read_b128 v[122:125], v129 offset:34816
	s_add_u32 m0, s16, 0x0
	s_add_u32 s42, s42, 0x100000
	s_addc_u32 s43, s43, 0
	global_load_lds_dwordx4 v137, s[42:43]
	global_load_lds_dwordx4 v150, s[42:43] offset:1024
	s_add_u32 m0, s0, 0x0
	s_add_u32 s30, s30, 0x10000
	s_addc_u32 s31, s31, 0
	global_load_lds_dwordx4 v151, s[30:31]
	global_load_lds_dwordx4 v152, s[30:31] offset:1024
	global_load_lds_dwordx4 v153, s[30:31] offset:2048
	global_load_lds_dwordx4 v154, s[30:31] offset:3072
	s_waitcnt lgkmcnt(10)
	v_mfma_f32_32x32x16_bf16 v[34:49], v[224:227], v[232:235], v[34:49]
	s_waitcnt lgkmcnt(9)
	v_mfma_f32_32x32x16_bf16 v[50:65], v[224:227], v[236:239], v[50:65]
	s_waitcnt lgkmcnt(8)
	v_mfma_f32_32x32x16_bf16 v[2:17], v[228:231], v[232:235], v[2:17]
	v_mfma_f32_32x32x16_bf16 v[18:33], v[228:231], v[236:239], v[18:33]
	s_waitcnt lgkmcnt(7)
	v_mfma_f32_32x32x16_bf16 v[74:89], v[224:227], v[240:243], v[74:89]
	s_waitcnt lgkmcnt(6)
	v_mfma_f32_32x32x16_bf16 v[90:105], v[224:227], v[244:247], v[90:105]
	v_mfma_f32_32x32x16_bf16 v[106:121], v[228:231], v[240:243], v[106:121]
	v_mfma_f32_32x32x16_bf16 v[208:223], v[228:231], v[244:247], v[208:223]
	s_waitcnt lgkmcnt(4)
	v_mfma_f32_32x32x16_bf16 v[34:49], v[248:251], v[160:163], v[34:49]
	s_waitcnt lgkmcnt(3)
	v_mfma_f32_32x32x16_bf16 v[50:65], v[248:251], v[164:167], v[50:65]
	s_waitcnt lgkmcnt(2)
	v_mfma_f32_32x32x16_bf16 v[2:17], v[156:159], v[160:163], v[2:17]
	v_mfma_f32_32x32x16_bf16 v[18:33], v[156:159], v[164:167], v[18:33]
	s_waitcnt lgkmcnt(1)
	v_mfma_f32_32x32x16_bf16 v[74:89], v[248:251], v[168:171], v[74:89]
	s_waitcnt lgkmcnt(0)
	v_mfma_f32_32x32x16_bf16 v[90:105], v[248:251], v[122:125], v[90:105]
	v_mfma_f32_32x32x16_bf16 v[106:121], v[156:159], v[168:171], v[106:121]
	v_mfma_f32_32x32x16_bf16 v[208:223], v[156:159], v[122:125], v[208:223]
	s_setprio 0
	s_waitcnt vmcnt(6)
	s_barrier
; #define BLOAD(A_, B_, kt) do { _Pragma("unroll") for (int i = 0; i < 4; ++i) { \
;     A_[i] = *(const u32x4*)((const char*)Ap + (aoff + (unsigned)(32 * i * lda + (kt) * 64) * 2u)); B_[i] = *(const u32x4*)((const char*)Wt + (woff + (unsigned)(32 * i * K + (kt) * 64) * 2u)); } } while (0)
; #define BLOAD(A_, B_, kt) do { _Pragma("unroll") for (int i = 0; i < 4; ++i) { \
;     A_[i] = *(const u32x4*)((const char*)Ap + (aoff + (unsigned)(32 * i * lda + (kt) * 64) * 2u)); B_[i] = *(const u32x4*)((const char*)Wt + (woff + (unsigned)(32 * i * K + (kt) * 64) * 2u)); } } while (0)
; #define BSTORE(A_, B_, buf) do { _Pragma("unroll") for (int i = 0; i < 4; ++i) { \
;     *(u32x4*)&As[(buf) * GBUF + (srow + 32 * i) * LDT + sc8] = A_[i]; \
;     *(u32x4*)&Bs[(buf) * GBUF + (srow + 32 * i) * LDT + sc8] = B_[i]; } } while (0)
; template <int NK>
; DI void gemm_run(PF& pf, const u16* __restrict__ Ap, int lda, const u16* __restrict__ Wt, f32x16 (&acc)[2][2], char* smem) {
;     ...
;   __builtin_amdgcn_s_setprio(0);
;   __syncthreads();
;   BSTORE(pf.a0, pf.b0, 0);
;   BLOAD(pf.a0, pf.b0, 2);
;   __syncthreads();
; #pragma unroll
;   for (int kt = 0; kt < nk; kt += 2) {
;     BCOMP(0);
;     BSTORE(pf.a1, pf.b1, 1);
;     if (kt + 3 < nk) BLOAD(pf.a1, pf.b1, kt + 3);
;     __syncthreads();
;     BCOMP(1);
;     if (kt + 2 < nk) { BSTORE(pf.a0, pf.b0, 0); if (kt + 4 < nk) BLOAD(pf.a0, pf.b0, kt + 4); }
;     __syncthreads();
;   }
	s_setprio 1
	ds_read_b128 v[224:227], v126 offset:49152
	ds_read_b128 v[232:235], v128 offset:49152
	ds_read_b128 v[236:239], v128 offset:51200
	ds_read_b128 v[228:231], v126 offset:51200
	ds_read_b128 v[240:243], v128 offset:57344
	ds_read_b128 v[244:247], v128 offset:59392
	ds_read_b128 v[248:251], v127 offset:49152
	ds_read_b128 v[160:163], v129 offset:49152
	ds_read_b128 v[164:167], v129 offset:51200
	ds_read_b128 v[156:159], v127 offset:51200
	ds_read_b128 v[168:171], v129 offset:57344
	ds_read_b128 v[122:125], v129 offset:59392
	s_add_u32 m0, s16, 0x6000
	s_add_u32 s42, s42, 0x100000
	s_addc_u32 s43, s43, 0
	global_load_lds_dwordx4 v137, s[42:43]
	global_load_lds_dwordx4 v150, s[42:43] offset:1024
	s_add_u32 m0, s0, 0x6000
	s_add_u32 s30, s30, 0x10000
	s_addc_u32 s31, s31, 0
	global_load_lds_dwordx4 v151, s[30:31]
	global_load_lds_dwordx4 v152, s[30:31] offset:1024
	global_load_lds_dwordx4 v153, s[30:31] offset:2048
	global_load_lds_dwordx4 v154, s[30:31] offset:3072
	s_waitcnt lgkmcnt(10)
	v_mfma_f32_32x32x16_bf16 v[34:49], v[224:227], v[232:235], v[34:49]
	s_waitcnt lgkmcnt(9)
	v_mfma_f32_32x32x16_bf16 v[50:65], v[224:227], v[236:239], v[50:65]
	s_waitcnt lgkmcnt(8)
	v_mfma_f32_32x32x16_bf16 v[2:17], v[228:231], v[232:235], v[2:17]
	v_mfma_f32_32x32x16_bf16 v[18:33], v[228:231], v[236:239], v[18:33]
	s_waitcnt lgkmcnt(7)
	v_mfma_f32_32x32x16_bf16 v[74:89], v[224:227], v[240:243], v[74:89]
	s_waitcnt lgkmcnt(6)
	v_mfma_f32_32x32x16_bf16 v[90:105], v[224:227], v[244:247], v[90:105]
	v_mfma_f32_32x32x16_bf16 v[106:121], v[228:231], v[240:243], v[106:121]
	v_mfma_f32_32x32x16_bf16 v[208:223], v[228:231], v[244:247], v[208:223]
	s_waitcnt lgkmcnt(4)
	v_mfma_f32_32x32x16_bf16 v[34:49], v[248:251], v[160:163], v[34:49]
	s_waitcnt lgkmcnt(3)
	v_mfma_f32_32x32x16_bf16 v[50:65], v[248:251], v[164:167], v[50:65]
	s_waitcnt lgkmcnt(2)
	v_mfma_f32_32x32x16_bf16 v[2:17], v[156:159], v[160:163], v[2:17]
	v_mfma_f32_32x32x16_bf16 v[18:33], v[156:159], v[164:167], v[18:33]
	s_waitcnt lgkmcnt(1)
	v_mfma_f32_32x32x16_bf16 v[74:89], v[248:251], v[168:171], v[74:89]
	s_waitcnt lgkmcnt(0)
	v_mfma_f32_32x32x16_bf16 v[90:105], v[248:251], v[122:125], v[90:105]
	v_mfma_f32_32x32x16_bf16 v[106:121], v[156:159], v[168:171], v[106:121]
	v_mfma_f32_32x32x16_bf16 v[208:223], v[156:159], v[122:125], v[208:223]
	s_setprio 0
	s_waitcnt vmcnt(6)
	s_barrier
	s_setprio 1
	ds_read_b128 v[224:227], v126 offset:0
	ds_read_b128 v[232:235], v128 offset:0
	ds_read_b128 v[236:239], v128 offset:2048
	ds_read_b128 v[228:231], v126 offset:2048
	ds_read_b128 v[240:243], v128 offset:8192
	ds_read_b128 v[244:247], v128 offset:10240
	ds_read_b128 v[248:251], v127 offset:0
	ds_read_b128 v[160:163], v129 offset:0
	ds_read_b128 v[164:167], v129 offset:2048
	ds_read_b128 v[156:159], v127 offset:2048
	ds_read_b128 v[168:171], v129 offset:8192
	ds_read_b128 v[122:125], v129 offset:10240
	s_add_u32 m0, s16, 0xc000
	s_add_u32 s42, s42, 0x100000
	s_addc_u32 s43, s43, 0
	global_load_lds_dwordx4 v137, s[42:43]
	global_load_lds_dwordx4 v150, s[42:43] offset:1024
	s_add_u32 m0, s0, 0xc000
	s_add_u32 s30, s30, 0x10000
	s_addc_u32 s31, s31, 0
	global_load_lds_dwordx4 v151, s[30:31]
	global_load_lds_dwordx4 v152, s[30:31] offset:1024
	global_load_lds_dwordx4 v153, s[30:31] offset:2048
	global_load_lds_dwordx4 v154, s[30:31] offset:3072
	s_waitcnt lgkmcnt(10)
	v_mfma_f32_32x32x16_bf16 v[34:49], v[224:227], v[232:235], v[34:49]
	s_waitcnt lgkmcnt(9)
	v_mfma_f32_32x32x16_bf16 v[50:65], v[224:227], v[236:239], v[50:65]
	s_waitcnt lgkmcnt(8)
	v_mfma_f32_32x32x16_bf16 v[2:17], v[228:231], v[232:235], v[2:17]
	v_mfma_f32_32x32x16_bf16 v[18:33], v[228:231], v[236:239], v[18:33]
	s_waitcnt lgkmcnt(7)
	v_mfma_f32_32x32x16_bf16 v[74:89], v[224:227], v[240:243], v[74:89]
	s_waitcnt lgkmcnt(6)
	v_mfma_f32_32x32x16_bf16 v[90:105], v[224:227], v[244:247], v[90:105]
	v_mfma_f32_32x32x16_bf16 v[106:121], v[228:231], v[240:243], v[106:121]
	v_mfma_f32_32x32x16_bf16 v[208:223], v[228:231], v[244:247], v[208:223]
	s_waitcnt lgkmcnt(4)
	v_mfma_f32_32x32x16_bf16 v[34:49], v[248:251], v[160:163], v[34:49]
	s_waitcnt lgkmcnt(3)
	v_mfma_f32_32x32x16_bf16 v[50:65], v[248:251], v[164:167], v[50:65]
	s_waitcnt lgkmcnt(2)
	v_mfma_f32_32x32x16_bf16 v[2:17], v[156:159], v[160:163], v[2:17]
	v_mfma_f32_32x32x16_bf16 v[18:33], v[156:159], v[164:167], v[18:33]
	s_waitcnt lgkmcnt(1)
	v_mfma_f32_32x32x16_bf16 v[74:89], v[248:251], v[168:171], v[74:89]
	s_waitcnt lgkmcnt(0)
	v_mfma_f32_32x32x16_bf16 v[90:105], v[248:251], v[122:125], v[90:105]
	v_mfma_f32_32x32x16_bf16 v[106:121], v[156:159], v[168:171], v[106:121]
	v_mfma_f32_32x32x16_bf16 v[208:223], v[156:159], v[122:125], v[208:223]
	s_setprio 0
	s_waitcnt vmcnt(6)
	s_barrier
; #define BLOAD(A_, B_, kt) do { _Pragma("unroll") for (int i = 0; i < 4; ++i) { \
;     A_[i] = *(const u32x4*)((const char*)Ap + (aoff + (unsigned)(32 * i * lda + (kt) * 64) * 2u)); B_[i] = *(const u32x4*)((const char*)Wt + (woff + (unsigned)(32 * i * K + (kt) * 64) * 2u)); } } while (0)
; #define BLOAD(A_, B_, kt) do { _Pragma("unroll") for (int i = 0; i < 4; ++i) { \
;     A_[i] = *(const u32x4*)((const char*)Ap + (aoff + (unsigned)(32 * i * lda + (kt) * 64) * 2u)); B_[i] = *(const u32x4*)((const char*)Wt + (woff + (unsigned)(32 * i * K + (kt) * 64) * 2u)); } } while (0)
; #define BSTORE(A_, B_, buf) do { _Pragma("unroll") for (int i = 0; i < 4; ++i) { \
;     *(u32x4*)&As[(buf) * GBUF + (srow + 32 * i) * LDT + sc8] = A_[i]; \
;     *(u32x4*)&Bs[(buf) * GBUF + (srow + 32 * i) * LDT + sc8] = B_[i]; } } while (0)
; template <int NK>
; DI void gemm_run(PF& pf, const u16* __restrict__ Ap, int lda, const u16* __restrict__ Wt, f32x16 (&acc)[2][2], char* smem) {
;     ...
;   __builtin_amdgcn_s_setprio(0);
;   __syncthreads();
;   BSTORE(pf.a0, pf.b0, 0);
;   BLOAD(pf.a0, pf.b0, 2);
;   __syncthreads();
; #pragma unroll
;   for (int kt = 0; kt < nk; kt += 2) {
;     BCOMP(0);
;     BSTORE(pf.a1, pf.b1, 1);
;     if (kt + 3 < nk) BLOAD(pf.a1, pf.b1, kt + 3);
;     __syncthreads();
;     BCOMP(1);
;     if (kt + 2 < nk) { BSTORE(pf.a0, pf.b0, 0); if (kt + 4 < nk) BLOAD(pf.a0, pf.b0, kt + 4); }
;     __syncthreads();
;   }
	s_setprio 1
	ds_read_b128 v[224:227], v126 offset:24576
	ds_read_b128 v[232:235], v128 offset:24576
	ds_read_b128 v[236:239], v128 offset:26624
	ds_read_b128 v[228:231], v126 offset:26624
	ds_read_b128 v[240:243], v128 offset:32768
	ds_read_b128 v[244:247], v128 offset:34816
	ds_read_b128 v[248:251], v127 offset:24576
	ds_read_b128 v[160:163], v129 offset:24576
	ds_read_b128 v[164:167], v129 offset:26624
	ds_read_b128 v[156:159], v127 offset:26624
	ds_read_b128 v[168:171], v129 offset:32768
	ds_read_b128 v[122:125], v129 offset:34816
	s_add_u32 m0, s16, 0x0
	s_add_u32 s42, s42, 0x100000
	s_addc_u32 s43, s43, 0
	global_load_lds_dwordx4 v137, s[42:43]
	global_load_lds_dwordx4 v150, s[42:43] offset:1024
	s_add_u32 m0, s0, 0x0
	s_add_u32 s30, s30, 0x10000
	s_addc_u32 s31, s31, 0
	global_load_lds_dwordx4 v151, s[30:31]
	global_load_lds_dwordx4 v152, s[30:31] offset:1024
	global_load_lds_dwordx4 v153, s[30:31] offset:2048
	global_load_lds_dwordx4 v154, s[30:31] offset:3072
	s_waitcnt lgkmcnt(10)
	v_mfma_f32_32x32x16_bf16 v[34:49], v[224:227], v[232:235], v[34:49]
	s_waitcnt lgkmcnt(9)
	v_mfma_f32_32x32x16_bf16 v[50:65], v[224:227], v[236:239], v[50:65]
	s_waitcnt lgkmcnt(8)
	v_mfma_f32_32x32x16_bf16 v[2:17], v[228:231], v[232:235], v[2:17]
	v_mfma_f32_32x32x16_bf16 v[18:33], v[228:231], v[236:239], v[18:33]
	s_waitcnt lgkmcnt(7)
	v_mfma_f32_32x32x16_bf16 v[74:89], v[224:227], v[240:243], v[74:89]
	s_waitcnt lgkmcnt(6)
	v_mfma_f32_32x32x16_bf16 v[90:105], v[224:227], v[244:247], v[90:105]
	v_mfma_f32_32x32x16_bf16 v[106:121], v[228:231], v[240:243], v[106:121]
	v_mfma_f32_32x32x16_bf16 v[208:223], v[228:231], v[244:247], v[208:223]
	s_waitcnt lgkmcnt(4)
	v_mfma_f32_32x32x16_bf16 v[34:49], v[248:251], v[160:163], v[34:49]
	s_waitcnt lgkmcnt(3)
	v_mfma_f32_32x32x16_bf16 v[50:65], v[248:251], v[164:167], v[50:65]
	s_waitcnt lgkmcnt(2)
	v_mfma_f32_32x32x16_bf16 v[2:17], v[156:159], v[160:163], v[2:17]
	v_mfma_f32_32x32x16_bf16 v[18:33], v[156:159], v[164:167], v[18:33]
	s_waitcnt lgkmcnt(1)
	v_mfma_f32_32x32x16_bf16 v[74:89], v[248:251], v[168:171], v[74:89]
	s_waitcnt lgkmcnt(0)
	v_mfma_f32_32x32x16_bf16 v[90:105], v[248:251], v[122:125], v[90:105]
	v_mfma_f32_32x32x16_bf16 v[106:121], v[156:159], v[168:171], v[106:121]
	v_mfma_f32_32x32x16_bf16 v[208:223], v[156:159], v[122:125], v[208:223]
	s_setprio 0
	s_waitcnt vmcnt(6)
	s_barrier
	s_setprio 1
	ds_read_b128 v[224:227], v126 offset:49152
	ds_read_b128 v[232:235], v128 offset:49152
	ds_read_b128 v[236:239], v128 offset:51200
	ds_read_b128 v[228:231], v126 offset:51200
	ds_read_b128 v[240:243], v128 offset:57344
	ds_read_b128 v[244:247], v128 offset:59392
	ds_read_b128 v[248:251], v127 offset:49152
	ds_read_b128 v[160:163], v129 offset:49152
	ds_read_b128 v[164:167], v129 offset:51200
	ds_read_b128 v[156:159], v127 offset:51200
	ds_read_b128 v[168:171], v129 offset:57344
	ds_read_b128 v[122:125], v129 offset:59392
	s_add_u32 m0, s16, 0x6000
	s_add_u32 s42, s42, 0x100000
	s_addc_u32 s43, s43, 0
	global_load_lds_dwordx4 v137, s[42:43]
	global_load_lds_dwordx4 v150, s[42:43] offset:1024
	s_add_u32 m0, s0, 0x6000
	s_add_u32 s30, s30, 0x10000
	s_addc_u32 s31, s31, 0
	global_load_lds_dwordx4 v151, s[30:31]
	global_load_lds_dwordx4 v152, s[30:31] offset:1024
	global_load_lds_dwordx4 v153, s[30:31] offset:2048
	global_load_lds_dwordx4 v154, s[30:31] offset:3072
	s_waitcnt lgkmcnt(10)
	v_mfma_f32_32x32x16_bf16 v[34:49], v[224:227], v[232:235], v[34:49]
	s_waitcnt lgkmcnt(9)
	v_mfma_f32_32x32x16_bf16 v[50:65], v[224:227], v[236:239], v[50:65]
	s_waitcnt lgkmcnt(8)
	v_mfma_f32_32x32x16_bf16 v[2:17], v[228:231], v[232:235], v[2:17]
	v_mfma_f32_32x32x16_bf16 v[18:33], v[228:231], v[236:239], v[18:33]
	s_waitcnt lgkmcnt(7)
	v_mfma_f32_32x32x16_bf16 v[74:89], v[224:227], v[240:243], v[74:89]
	s_waitcnt lgkmcnt(6)
	v_mfma_f32_32x32x16_bf16 v[90:105], v[224:227], v[244:247], v[90:105]
	v_mfma_f32_32x32x16_bf16 v[106:121], v[228:231], v[240:243], v[106:121]
	v_mfma_f32_32x32x16_bf16 v[208:223], v[228:231], v[244:247], v[208:223]
	s_waitcnt lgkmcnt(4)
	v_mfma_f32_32x32x16_bf16 v[34:49], v[248:251], v[160:163], v[34:49]
	s_waitcnt lgkmcnt(3)
	v_mfma_f32_32x32x16_bf16 v[50:65], v[248:251], v[164:167], v[50:65]
	s_waitcnt lgkmcnt(2)
	v_mfma_f32_32x32x16_bf16 v[2:17], v[156:159], v[160:163], v[2:17]
	v_mfma_f32_32x32x16_bf16 v[18:33], v[156:159], v[164:167], v[18:33]
	s_waitcnt lgkmcnt(1)
	v_mfma_f32_32x32x16_bf16 v[74:89], v[248:251], v[168:171], v[74:89]
	s_waitcnt lgkmcnt(0)
	v_mfma_f32_32x32x16_bf16 v[90:105], v[248:251], v[122:125], v[90:105]
	v_mfma_f32_32x32x16_bf16 v[106:121], v[156:159], v[168:171], v[106:121]
	v_mfma_f32_32x32x16_bf16 v[208:223], v[156:159], v[122:125], v[208:223]
	s_setprio 0
	s_waitcnt vmcnt(6)
	s_barrier
; #define BLOAD(A_, B_, kt) do { _Pragma("unroll") for (int i = 0; i < 4; ++i) { \
;     A_[i] = *(const u32x4*)((const char*)Ap + (aoff + (unsigned)(32 * i * lda + (kt) * 64) * 2u)); B_[i] = *(const u32x4*)((const char*)Wt + (woff + (unsigned)(32 * i * K + (kt) * 64) * 2u)); } } while (0)
; #define BLOAD(A_, B_, kt) do { _Pragma("unroll") for (int i = 0; i < 4; ++i) { \
;     A_[i] = *(const u32x4*)((const char*)Ap + (aoff + (unsigned)(32 * i * lda + (kt) * 64) * 2u)); B_[i] = *(const u32x4*)((const char*)Wt + (woff + (unsigned)(32 * i * K + (kt) * 64) * 2u)); } } while (0)
; #define BSTORE(A_, B_, buf) do { _Pragma("unroll") for (int i = 0; i < 4; ++i) { \
;     *(u32x4*)&As[(buf) * GBUF + (srow + 32 * i) * LDT + sc8] = A_[i]; \
;     *(u32x4*)&Bs[(buf) * GBUF + (srow + 32 * i) * LDT + sc8] = B_[i]; } } while (0)
; template <int NK>
; DI void gemm_run(PF& pf, const u16* __restrict__ Ap, int lda, const u16* __restrict__ Wt, f32x16 (&acc)[2][2], char* smem) {
;     ...
;   __builtin_amdgcn_s_setprio(0);
;   __syncthreads();
;   BSTORE(pf.a0, pf.b0, 0);
;   BLOAD(pf.a0, pf.b0, 2);
;   __syncthreads();
; #pragma unroll
;   for (int kt = 0; kt < nk; kt += 2) {
;     BCOMP(0);
;     BSTORE(pf.a1, pf.b1, 1);
;     if (kt + 3 < nk) BLOAD(pf.a1, pf.b1, kt + 3);
;     __syncthreads();
;     BCOMP(1);
;     if (kt + 2 < nk) { BSTORE(pf.a0, pf.b0, 0); if (kt + 4 < nk) BLOAD(pf.a0, pf.b0, kt + 4); }
;     __syncthreads();
;   }
	s_setprio 1
	ds_read_b128 v[224:227], v126 offset:0
	ds_read_b128 v[232:235], v128 offset:0
	ds_read_b128 v[236:239], v128 offset:2048
	ds_read_b128 v[228:231], v126 offset:2048
	ds_read_b128 v[240:243], v128 offset:8192
	ds_read_b128 v[244:247], v128 offset:10240
	ds_read_b128 v[248:251], v127 offset:0
	ds_read_b128 v[160:163], v129 offset:0
	ds_read_b128 v[164:167], v129 offset:2048
	ds_read_b128 v[156:159], v127 offset:2048
	ds_read_b128 v[168:171], v129 offset:8192
	ds_read_b128 v[122:125], v129 offset:10240
	s_add_u32 m0, s16, 0xc000
	s_add_u32 s42, s42, 0x100000
	s_addc_u32 s43, s43, 0
	global_load_lds_dwordx4 v137, s[42:43]
	global_load_lds_dwordx4 v150, s[42:43] offset:1024
	s_add_u32 m0, s0, 0xc000
	s_add_u32 s30, s30, 0x10000
	s_addc_u32 s31, s31, 0
	global_load_lds_dwordx4 v151, s[30:31]
	global_load_lds_dwordx4 v152, s[30:31] offset:1024
	global_load_lds_dwordx4 v153, s[30:31] offset:2048
	global_load_lds_dwordx4 v154, s[30:31] offset:3072
	s_waitcnt lgkmcnt(10)
	v_mfma_f32_32x32x16_bf16 v[34:49], v[224:227], v[232:235], v[34:49]
	s_waitcnt lgkmcnt(9)
	v_mfma_f32_32x32x16_bf16 v[50:65], v[224:227], v[236:239], v[50:65]
	s_waitcnt lgkmcnt(8)
	v_mfma_f32_32x32x16_bf16 v[2:17], v[228:231], v[232:235], v[2:17]
	v_mfma_f32_32x32x16_bf16 v[18:33], v[228:231], v[236:239], v[18:33]
	s_waitcnt lgkmcnt(7)
	v_mfma_f32_32x32x16_bf16 v[74:89], v[224:227], v[240:243], v[74:89]
	s_waitcnt lgkmcnt(6)
	v_mfma_f32_32x32x16_bf16 v[90:105], v[224:227], v[244:247], v[90:105]
	v_mfma_f32_32x32x16_bf16 v[106:121], v[228:231], v[240:243], v[106:121]
	v_mfma_f32_32x32x16_bf16 v[208:223], v[228:231], v[244:247], v[208:223]
	s_waitcnt lgkmcnt(4)
	v_mfma_f32_32x32x16_bf16 v[34:49], v[248:251], v[160:163], v[34:49]
	s_waitcnt lgkmcnt(3)
	v_mfma_f32_32x32x16_bf16 v[50:65], v[248:251], v[164:167], v[50:65]
	s_waitcnt lgkmcnt(2)
	v_mfma_f32_32x32x16_bf16 v[2:17], v[156:159], v[160:163], v[2:17]
	v_mfma_f32_32x32x16_bf16 v[18:33], v[156:159], v[164:167], v[18:33]
	s_waitcnt lgkmcnt(1)
	v_mfma_f32_32x32x16_bf16 v[74:89], v[248:251], v[168:171], v[74:89]
	s_waitcnt lgkmcnt(0)
	v_mfma_f32_32x32x16_bf16 v[90:105], v[248:251], v[122:125], v[90:105]
	v_mfma_f32_32x32x16_bf16 v[106:121], v[156:159], v[168:171], v[106:121]
	v_mfma_f32_32x32x16_bf16 v[208:223], v[156:159], v[122:125], v[208:223]
	s_setprio 0
	s_waitcnt vmcnt(6)
	s_barrier
	s_setprio 1
	ds_read_b128 v[224:227], v126 offset:24576
	ds_read_b128 v[232:235], v128 offset:24576
	ds_read_b128 v[236:239], v128 offset:26624
	ds_read_b128 v[228:231], v126 offset:26624
	ds_read_b128 v[240:243], v128 offset:32768
	ds_read_b128 v[244:247], v128 offset:34816
	ds_read_b128 v[248:251], v127 offset:24576
	ds_read_b128 v[160:163], v129 offset:24576
	ds_read_b128 v[164:167], v129 offset:26624
	ds_read_b128 v[156:159], v127 offset:26624
	ds_read_b128 v[168:171], v129 offset:32768
	ds_read_b128 v[122:125], v129 offset:34816
	s_add_u32 m0, s16, 0x0
	s_add_u32 s42, s42, 0x100000
	s_addc_u32 s43, s43, 0
	global_load_lds_dwordx4 v137, s[42:43]
	global_load_lds_dwordx4 v150, s[42:43] offset:1024
	s_add_u32 m0, s0, 0x0
	s_add_u32 s30, s30, 0x10000
	s_addc_u32 s31, s31, 0
	global_load_lds_dwordx4 v151, s[30:31]
	global_load_lds_dwordx4 v152, s[30:31] offset:1024
	global_load_lds_dwordx4 v153, s[30:31] offset:2048
	global_load_lds_dwordx4 v154, s[30:31] offset:3072
	s_waitcnt lgkmcnt(10)
	v_mfma_f32_32x32x16_bf16 v[34:49], v[224:227], v[232:235], v[34:49]
	s_waitcnt lgkmcnt(9)
	v_mfma_f32_32x32x16_bf16 v[50:65], v[224:227], v[236:239], v[50:65]
	s_waitcnt lgkmcnt(8)
	v_mfma_f32_32x32x16_bf16 v[2:17], v[228:231], v[232:235], v[2:17]
	v_mfma_f32_32x32x16_bf16 v[18:33], v[228:231], v[236:239], v[18:33]
	s_waitcnt lgkmcnt(7)
	v_mfma_f32_32x32x16_bf16 v[74:89], v[224:227], v[240:243], v[74:89]
	s_waitcnt lgkmcnt(6)
	v_mfma_f32_32x32x16_bf16 v[90:105], v[224:227], v[244:247], v[90:105]
	v_mfma_f32_32x32x16_bf16 v[106:121], v[228:231], v[240:243], v[106:121]
	v_mfma_f32_32x32x16_bf16 v[208:223], v[228:231], v[244:247], v[208:223]
	s_waitcnt lgkmcnt(4)
	v_mfma_f32_32x32x16_bf16 v[34:49], v[248:251], v[160:163], v[34:49]
	s_waitcnt lgkmcnt(3)
	v_mfma_f32_32x32x16_bf16 v[50:65], v[248:251], v[164:167], v[50:65]
	s_waitcnt lgkmcnt(2)
	v_mfma_f32_32x32x16_bf16 v[2:17], v[156:159], v[160:163], v[2:17]
	v_mfma_f32_32x32x16_bf16 v[18:33], v[156:159], v[164:167], v[18:33]
	s_waitcnt lgkmcnt(1)
	v_mfma_f32_32x32x16_bf16 v[74:89], v[248:251], v[168:171], v[74:89]
	s_waitcnt lgkmcnt(0)
	v_mfma_f32_32x32x16_bf16 v[90:105], v[248:251], v[122:125], v[90:105]
	v_mfma_f32_32x32x16_bf16 v[106:121], v[156:159], v[168:171], v[106:121]
	v_mfma_f32_32x32x16_bf16 v[208:223], v[156:159], v[122:125], v[208:223]
	s_setprio 0
	s_waitcnt vmcnt(6)
	s_barrier
; #define BLOAD(A_, B_, kt) do { _Pragma("unroll") for (int i = 0; i < 4; ++i) { \
;     A_[i] = *(const u32x4*)((const char*)Ap + (aoff + (unsigned)(32 * i * lda + (kt) * 64) * 2u)); B_[i] = *(const u32x4*)((const char*)Wt + (woff + (unsigned)(32 * i * K + (kt) * 64) * 2u)); } } while (0)
; #define BLOAD(A_, B_, kt) do { _Pragma("unroll") for (int i = 0; i < 4; ++i) { \
;     A_[i] = *(const u32x4*)((const char*)Ap + (aoff + (unsigned)(32 * i * lda + (kt) * 64) * 2u)); B_[i] = *(const u32x4*)((const char*)Wt + (woff + (unsigned)(32 * i * K + (kt) * 64) * 2u)); } } while (0)
; #define BSTORE(A_, B_, buf) do { _Pragma("unroll") for (int i = 0; i < 4; ++i) { \
;     *(u32x4*)&As[(buf) * GBUF + (srow + 32 * i) * LDT + sc8] = A_[i]; \
;     *(u32x4*)&Bs[(buf) * GBUF + (srow + 32 * i) * LDT + sc8] = B_[i]; } } while (0)
; template <int NK>
; DI void gemm_run(PF& pf, const u16* __restrict__ Ap, int lda, const u16* __restrict__ Wt, f32x16 (&acc)[2][2], char* smem) {
;     ...
;   __builtin_amdgcn_s_setprio(0);
;   __syncthreads();
;   BSTORE(pf.a0, pf.b0, 0);
;   BLOAD(pf.a0, pf.b0, 2);
;   __syncthreads();
; #pragma unroll
;   for (int kt = 0; kt < nk; kt += 2) {
;     BCOMP(0);
;     BSTORE(pf.a1, pf.b1, 1);
;     if (kt + 3 < nk) BLOAD(pf.a1, pf.b1, kt + 3);
;     __syncthreads();
;     BCOMP(1);
;     if (kt + 2 < nk) { BSTORE(pf.a0, pf.b0, 0); if (kt + 4 < nk) BLOAD(pf.a0, pf.b0, kt + 4); }
;     __syncthreads();
;   }
	s_setprio 1
	ds_read_b128 v[224:227], v126 offset:49152
	ds_read_b128 v[232:235], v128 offset:49152
	ds_read_b128 v[236:239], v128 offset:51200
	ds_read_b128 v[228:231], v126 offset:51200
	ds_read_b128 v[240:243], v128 offset:57344
	ds_read_b128 v[244:247], v128 offset:59392
	ds_read_b128 v[248:251], v127 offset:49152
	ds_read_b128 v[160:163], v129 offset:49152
	ds_read_b128 v[164:167], v129 offset:51200
	ds_read_b128 v[156:159], v127 offset:51200
	ds_read_b128 v[168:171], v129 offset:57344
	ds_read_b128 v[122:125], v129 offset:59392
	s_add_u32 m0, s16, 0x6000
	s_add_u32 s42, s42, 0x100000
	s_addc_u32 s43, s43, 0
	global_load_lds_dwordx4 v137, s[42:43]
	global_load_lds_dwordx4 v150, s[42:43] offset:1024
	s_add_u32 m0, s0, 0x6000
	s_add_u32 s30, s30, 0x10000
	s_addc_u32 s31, s31, 0
	global_load_lds_dwordx4 v151, s[30:31]
	global_load_lds_dwordx4 v152, s[30:31] offset:1024
	global_load_lds_dwordx4 v153, s[30:31] offset:2048
	global_load_lds_dwordx4 v154, s[30:31] offset:3072
	s_waitcnt lgkmcnt(10)
	v_mfma_f32_32x32x16_bf16 v[34:49], v[224:227], v[232:235], v[34:49]
	s_waitcnt lgkmcnt(9)
	v_mfma_f32_32x32x16_bf16 v[50:65], v[224:227], v[236:239], v[50:65]
	s_waitcnt lgkmcnt(8)
	v_mfma_f32_32x32x16_bf16 v[2:17], v[228:231], v[232:235], v[2:17]
	v_mfma_f32_32x32x16_bf16 v[18:33], v[228:231], v[236:239], v[18:33]
	s_waitcnt lgkmcnt(7)
	v_mfma_f32_32x32x16_bf16 v[74:89], v[224:227], v[240:243], v[74:89]
	s_waitcnt lgkmcnt(6)
	v_mfma_f32_32x32x16_bf16 v[90:105], v[224:227], v[244:247], v[90:105]
	v_mfma_f32_32x32x16_bf16 v[106:121], v[228:231], v[240:243], v[106:121]
	v_mfma_f32_32x32x16_bf16 v[208:223], v[228:231], v[244:247], v[208:223]
	s_waitcnt lgkmcnt(4)
	v_mfma_f32_32x32x16_bf16 v[34:49], v[248:251], v[160:163], v[34:49]
	s_waitcnt lgkmcnt(3)
	v_mfma_f32_32x32x16_bf16 v[50:65], v[248:251], v[164:167], v[50:65]
	s_waitcnt lgkmcnt(2)
	v_mfma_f32_32x32x16_bf16 v[2:17], v[156:159], v[160:163], v[2:17]
	v_mfma_f32_32x32x16_bf16 v[18:33], v[156:159], v[164:167], v[18:33]
	s_waitcnt lgkmcnt(1)
	v_mfma_f32_32x32x16_bf16 v[74:89], v[248:251], v[168:171], v[74:89]
	s_waitcnt lgkmcnt(0)
	v_mfma_f32_32x32x16_bf16 v[90:105], v[248:251], v[122:125], v[90:105]
	v_mfma_f32_32x32x16_bf16 v[106:121], v[156:159], v[168:171], v[106:121]
	v_mfma_f32_32x32x16_bf16 v[208:223], v[156:159], v[122:125], v[208:223]
	s_setprio 0
	s_waitcnt vmcnt(6)
	s_barrier
	s_setprio 1
	ds_read_b128 v[224:227], v126 offset:0
	ds_read_b128 v[232:235], v128 offset:0
	ds_read_b128 v[236:239], v128 offset:2048
	ds_read_b128 v[228:231], v126 offset:2048
	ds_read_b128 v[240:243], v128 offset:8192
	ds_read_b128 v[244:247], v128 offset:10240
	ds_read_b128 v[248:251], v127 offset:0
	ds_read_b128 v[160:163], v129 offset:0
	ds_read_b128 v[164:167], v129 offset:2048
	ds_read_b128 v[156:159], v127 offset:2048
	ds_read_b128 v[168:171], v129 offset:8192
	ds_read_b128 v[122:125], v129 offset:10240
	s_add_u32 m0, s16, 0xc000
	s_add_u32 s42, s42, 0x100000
	s_addc_u32 s43, s43, 0
	global_load_lds_dwordx4 v137, s[42:43]
	global_load_lds_dwordx4 v150, s[42:43] offset:1024
	s_add_u32 m0, s0, 0xc000
	s_add_u32 s30, s30, 0x10000
	s_addc_u32 s31, s31, 0
	global_load_lds_dwordx4 v151, s[30:31]
	global_load_lds_dwordx4 v152, s[30:31] offset:1024
	global_load_lds_dwordx4 v153, s[30:31] offset:2048
	global_load_lds_dwordx4 v154, s[30:31] offset:3072
	s_waitcnt lgkmcnt(10)
	v_mfma_f32_32x32x16_bf16 v[34:49], v[224:227], v[232:235], v[34:49]
	s_waitcnt lgkmcnt(9)
	v_mfma_f32_32x32x16_bf16 v[50:65], v[224:227], v[236:239], v[50:65]
	s_waitcnt lgkmcnt(8)
	v_mfma_f32_32x32x16_bf16 v[2:17], v[228:231], v[232:235], v[2:17]
	v_mfma_f32_32x32x16_bf16 v[18:33], v[228:231], v[236:239], v[18:33]
	s_waitcnt lgkmcnt(7)
	v_mfma_f32_32x32x16_bf16 v[74:89], v[224:227], v[240:243], v[74:89]
	s_waitcnt lgkmcnt(6)
	v_mfma_f32_32x32x16_bf16 v[90:105], v[224:227], v[244:247], v[90:105]
	v_mfma_f32_32x32x16_bf16 v[106:121], v[228:231], v[240:243], v[106:121]
	v_mfma_f32_32x32x16_bf16 v[208:223], v[228:231], v[244:247], v[208:223]
	s_waitcnt lgkmcnt(4)
	v_mfma_f32_32x32x16_bf16 v[34:49], v[248:251], v[160:163], v[34:49]
	s_waitcnt lgkmcnt(3)
	v_mfma_f32_32x32x16_bf16 v[50:65], v[248:251], v[164:167], v[50:65]
	s_waitcnt lgkmcnt(2)
	v_mfma_f32_32x32x16_bf16 v[2:17], v[156:159], v[160:163], v[2:17]
	v_mfma_f32_32x32x16_bf16 v[18:33], v[156:159], v[164:167], v[18:33]
	s_waitcnt lgkmcnt(1)
	v_mfma_f32_32x32x16_bf16 v[74:89], v[248:251], v[168:171], v[74:89]
	s_waitcnt lgkmcnt(0)
	v_mfma_f32_32x32x16_bf16 v[90:105], v[248:251], v[122:125], v[90:105]
	v_mfma_f32_32x32x16_bf16 v[106:121], v[156:159], v[168:171], v[106:121]
	v_mfma_f32_32x32x16_bf16 v[208:223], v[156:159], v[122:125], v[208:223]
	s_setprio 0
	s_waitcnt vmcnt(6)
	s_barrier
; #define BLOAD(A_, B_, kt) do { _Pragma("unroll") for (int i = 0; i < 4; ++i) { \
;     A_[i] = *(const u32x4*)((const char*)Ap + (aoff + (unsigned)(32 * i * lda + (kt) * 64) * 2u)); B_[i] = *(const u32x4*)((const char*)Wt + (woff + (unsigned)(32 * i * K + (kt) * 64) * 2u)); } } while (0)
; #define BLOAD(A_, B_, kt) do { _Pragma("unroll") for (int i = 0; i < 4; ++i) { \
;     A_[i] = *(const u32x4*)((const char*)Ap + (aoff + (unsigned)(32 * i * lda + (kt) * 64) * 2u)); B_[i] = *(const u32x4*)((const char*)Wt + (woff + (unsigned)(32 * i * K + (kt) * 64) * 2u)); } } while (0)
; #define BSTORE(A_, B_, buf) do { _Pragma("unroll") for (int i = 0; i < 4; ++i) { \
;     *(u32x4*)&As[(buf) * GBUF + (srow + 32 * i) * LDT + sc8] = A_[i]; \
;     *(u32x4*)&Bs[(buf) * GBUF + (srow + 32 * i) * LDT + sc8] = B_[i]; } } while (0)
; template <int NK>
; DI void gemm_run(PF& pf, const u16* __restrict__ Ap, int lda, const u16* __restrict__ Wt, f32x16 (&acc)[2][2], char* smem) {
;     ...
;   __builtin_amdgcn_s_setprio(0);
;   __syncthreads();
;   BSTORE(pf.a0, pf.b0, 0);
;   BLOAD(pf.a0, pf.b0, 2);
;   __syncthreads();
; #pragma unroll
;   for (int kt = 0; kt < nk; kt += 2) {
;     BCOMP(0);
;     BSTORE(pf.a1, pf.b1, 1);
;     if (kt + 3 < nk) BLOAD(pf.a1, pf.b1, kt + 3);
;     __syncthreads();
;     BCOMP(1);
;     if (kt + 2 < nk) { BSTORE(pf.a0, pf.b0, 0); if (kt + 4 < nk) BLOAD(pf.a0, pf.b0, kt + 4); }
;     __syncthreads();
;   }
	s_setprio 1
	ds_read_b128 v[224:227], v126 offset:24576
	ds_read_b128 v[232:235], v128 offset:24576
	ds_read_b128 v[236:239], v128 offset:26624
	ds_read_b128 v[228:231], v126 offset:26624
	ds_read_b128 v[240:243], v128 offset:32768
	ds_read_b128 v[244:247], v128 offset:34816
	ds_read_b128 v[248:251], v127 offset:24576
	ds_read_b128 v[160:163], v129 offset:24576
	ds_read_b128 v[164:167], v129 offset:26624
	ds_read_b128 v[156:159], v127 offset:26624
	ds_read_b128 v[168:171], v129 offset:32768
	ds_read_b128 v[122:125], v129 offset:34816
	s_add_u32 m0, s16, 0x0
	s_add_u32 s42, s42, 0x100000
	s_addc_u32 s43, s43, 0
	global_load_lds_dwordx4 v137, s[42:43]
	global_load_lds_dwordx4 v150, s[42:43] offset:1024
	s_add_u32 m0, s0, 0x0
	s_add_u32 s30, s30, 0x10000
	s_addc_u32 s31, s31, 0
	global_load_lds_dwordx4 v151, s[30:31]
	global_load_lds_dwordx4 v152, s[30:31] offset:1024
	global_load_lds_dwordx4 v153, s[30:31] offset:2048
	global_load_lds_dwordx4 v154, s[30:31] offset:3072
	s_waitcnt lgkmcnt(10)
	v_mfma_f32_32x32x16_bf16 v[34:49], v[224:227], v[232:235], v[34:49]
	s_waitcnt lgkmcnt(9)
	v_mfma_f32_32x32x16_bf16 v[50:65], v[224:227], v[236:239], v[50:65]
	s_waitcnt lgkmcnt(8)
	v_mfma_f32_32x32x16_bf16 v[2:17], v[228:231], v[232:235], v[2:17]
	v_mfma_f32_32x32x16_bf16 v[18:33], v[228:231], v[236:239], v[18:33]
	s_waitcnt lgkmcnt(7)
	v_mfma_f32_32x32x16_bf16 v[74:89], v[224:227], v[240:243], v[74:89]
	s_waitcnt lgkmcnt(6)
	v_mfma_f32_32x32x16_bf16 v[90:105], v[224:227], v[244:247], v[90:105]
	v_mfma_f32_32x32x16_bf16 v[106:121], v[228:231], v[240:243], v[106:121]
	v_mfma_f32_32x32x16_bf16 v[208:223], v[228:231], v[244:247], v[208:223]
	s_waitcnt lgkmcnt(4)
	v_mfma_f32_32x32x16_bf16 v[34:49], v[248:251], v[160:163], v[34:49]
	s_waitcnt lgkmcnt(3)
	v_mfma_f32_32x32x16_bf16 v[50:65], v[248:251], v[164:167], v[50:65]
	s_waitcnt lgkmcnt(2)
	v_mfma_f32_32x32x16_bf16 v[2:17], v[156:159], v[160:163], v[2:17]
	v_mfma_f32_32x32x16_bf16 v[18:33], v[156:159], v[164:167], v[18:33]
	s_waitcnt lgkmcnt(1)
	v_mfma_f32_32x32x16_bf16 v[74:89], v[248:251], v[168:171], v[74:89]
	s_waitcnt lgkmcnt(0)
	v_mfma_f32_32x32x16_bf16 v[90:105], v[248:251], v[122:125], v[90:105]
	v_mfma_f32_32x32x16_bf16 v[106:121], v[156:159], v[168:171], v[106:121]
	v_mfma_f32_32x32x16_bf16 v[208:223], v[156:159], v[122:125], v[208:223]
	s_setprio 0
	s_waitcnt vmcnt(6)
	s_barrier
	s_setprio 1
	ds_read_b128 v[224:227], v126 offset:49152
	ds_read_b128 v[232:235], v128 offset:49152
	ds_read_b128 v[236:239], v128 offset:51200
	ds_read_b128 v[228:231], v126 offset:51200
	ds_read_b128 v[240:243], v128 offset:57344
	ds_read_b128 v[244:247], v128 offset:59392
	ds_read_b128 v[248:251], v127 offset:49152
	ds_read_b128 v[160:163], v129 offset:49152
	ds_read_b128 v[164:167], v129 offset:51200
	ds_read_b128 v[156:159], v127 offset:51200
	ds_read_b128 v[168:171], v129 offset:57344
	ds_read_b128 v[122:125], v129 offset:59392
	s_add_u32 m0, s16, 0x6000
	s_add_u32 s42, s42, 0x100000
	s_addc_u32 s43, s43, 0
	global_load_lds_dwordx4 v137, s[42:43]
	global_load_lds_dwordx4 v150, s[42:43] offset:1024
	s_add_u32 m0, s0, 0x6000
	s_add_u32 s30, s30, 0x10000
	s_addc_u32 s31, s31, 0
	global_load_lds_dwordx4 v151, s[30:31]
	global_load_lds_dwordx4 v152, s[30:31] offset:1024
	global_load_lds_dwordx4 v153, s[30:31] offset:2048
	global_load_lds_dwordx4 v154, s[30:31] offset:3072
	s_waitcnt lgkmcnt(10)
	v_mfma_f32_32x32x16_bf16 v[34:49], v[224:227], v[232:235], v[34:49]
	s_waitcnt lgkmcnt(9)
	v_mfma_f32_32x32x16_bf16 v[50:65], v[224:227], v[236:239], v[50:65]
	s_waitcnt lgkmcnt(8)
	v_mfma_f32_32x32x16_bf16 v[2:17], v[228:231], v[232:235], v[2:17]
	v_mfma_f32_32x32x16_bf16 v[18:33], v[228:231], v[236:239], v[18:33]
	s_waitcnt lgkmcnt(7)
	v_mfma_f32_32x32x16_bf16 v[74:89], v[224:227], v[240:243], v[74:89]
	s_waitcnt lgkmcnt(6)
	v_mfma_f32_32x32x16_bf16 v[90:105], v[224:227], v[244:247], v[90:105]
	v_mfma_f32_32x32x16_bf16 v[106:121], v[228:231], v[240:243], v[106:121]
	v_mfma_f32_32x32x16_bf16 v[208:223], v[228:231], v[244:247], v[208:223]
	s_waitcnt lgkmcnt(4)
	v_mfma_f32_32x32x16_bf16 v[34:49], v[248:251], v[160:163], v[34:49]
	s_waitcnt lgkmcnt(3)
	v_mfma_f32_32x32x16_bf16 v[50:65], v[248:251], v[164:167], v[50:65]
	s_waitcnt lgkmcnt(2)
	v_mfma_f32_32x32x16_bf16 v[2:17], v[156:159], v[160:163], v[2:17]
	v_mfma_f32_32x32x16_bf16 v[18:33], v[156:159], v[164:167], v[18:33]
	s_waitcnt lgkmcnt(1)
	v_mfma_f32_32x32x16_bf16 v[74:89], v[248:251], v[168:171], v[74:89]
	s_waitcnt lgkmcnt(0)
	v_mfma_f32_32x32x16_bf16 v[90:105], v[248:251], v[122:125], v[90:105]
	v_mfma_f32_32x32x16_bf16 v[106:121], v[156:159], v[168:171], v[106:121]
	v_mfma_f32_32x32x16_bf16 v[208:223], v[156:159], v[122:125], v[208:223]
	s_setprio 0
	s_waitcnt vmcnt(6)
	s_barrier
; #define BLOAD(A_, B_, kt) do { _Pragma("unroll") for (int i = 0; i < 4; ++i) { \
;     A_[i] = *(const u32x4*)((const char*)Ap + (aoff + (unsigned)(32 * i * lda + (kt) * 64) * 2u)); B_[i] = *(const u32x4*)((const char*)Wt + (woff + (unsigned)(32 * i * K + (kt) * 64) * 2u)); } } while (0)
; #define BLOAD(A_, B_, kt) do { _Pragma("unroll") for (int i = 0; i < 4; ++i) { \
;     A_[i] = *(const u32x4*)((const char*)Ap + (aoff + (unsigned)(32 * i * lda + (kt) * 64) * 2u)); B_[i] = *(const u32x4*)((const char*)Wt + (woff + (unsigned)(32 * i * K + (kt) * 64) * 2u)); } } while (0)
; #define BSTORE(A_, B_, buf) do { _Pragma("unroll") for (int i = 0; i < 4; ++i) { \
;     *(u32x4*)&As[(buf) * GBUF + (srow + 32 * i) * LDT + sc8] = A_[i]; \
;     *(u32x4*)&Bs[(buf) * GBUF + (srow + 32 * i) * LDT + sc8] = B_[i]; } } while (0)
; template <int NK>
; DI void gemm_run(PF& pf, const u16* __restrict__ Ap, int lda, const u16* __restrict__ Wt, f32x16 (&acc)[2][2], char* smem) {
;     ...
;   __builtin_amdgcn_s_setprio(0);
;   __syncthreads();
;   BSTORE(pf.a0, pf.b0, 0);
;   BLOAD(pf.a0, pf.b0, 2);
;   __syncthreads();
; #pragma unroll
;   for (int kt = 0; kt < nk; kt += 2) {
;     BCOMP(0);
;     BSTORE(pf.a1, pf.b1, 1);
;     if (kt + 3 < nk) BLOAD(pf.a1, pf.b1, kt + 3);
;     __syncthreads();
;     BCOMP(1);
;     if (kt + 2 < nk) { BSTORE(pf.a0, pf.b0, 0); if (kt + 4 < nk) BLOAD(pf.a0, pf.b0, kt + 4); }
;     __syncthreads();
;   }
	s_setprio 1
	ds_read_b128 v[224:227], v126 offset:0
	ds_read_b128 v[232:235], v128 offset:0
	ds_read_b128 v[236:239], v128 offset:2048
	ds_read_b128 v[228:231], v126 offset:2048
	ds_read_b128 v[240:243], v128 offset:8192
	ds_read_b128 v[244:247], v128 offset:10240
	ds_read_b128 v[248:251], v127 offset:0
	ds_read_b128 v[160:163], v129 offset:0
	ds_read_b128 v[164:167], v129 offset:2048
	ds_read_b128 v[156:159], v127 offset:2048
	ds_read_b128 v[168:171], v129 offset:8192
	ds_read_b128 v[122:125], v129 offset:10240
	s_add_u32 m0, s16, 0xc000
	s_add_u32 s42, s42, 0x100000
	s_addc_u32 s43, s43, 0
	global_load_lds_dwordx4 v137, s[42:43]
	global_load_lds_dwordx4 v150, s[42:43] offset:1024
	s_add_u32 m0, s0, 0xc000
	s_add_u32 s30, s30, 0x10000
	s_addc_u32 s31, s31, 0
	global_load_lds_dwordx4 v151, s[30:31]
	global_load_lds_dwordx4 v152, s[30:31] offset:1024
	global_load_lds_dwordx4 v153, s[30:31] offset:2048
	global_load_lds_dwordx4 v154, s[30:31] offset:3072
	s_waitcnt lgkmcnt(10)
	v_mfma_f32_32x32x16_bf16 v[34:49], v[224:227], v[232:235], v[34:49]
	s_waitcnt lgkmcnt(9)
	v_mfma_f32_32x32x16_bf16 v[50:65], v[224:227], v[236:239], v[50:65]
	s_waitcnt lgkmcnt(8)
	v_mfma_f32_32x32x16_bf16 v[2:17], v[228:231], v[232:235], v[2:17]
	v_mfma_f32_32x32x16_bf16 v[18:33], v[228:231], v[236:239], v[18:33]
	s_waitcnt lgkmcnt(7)
	v_mfma_f32_32x32x16_bf16 v[74:89], v[224:227], v[240:243], v[74:89]
	s_waitcnt lgkmcnt(6)
	v_mfma_f32_32x32x16_bf16 v[90:105], v[224:227], v[244:247], v[90:105]
	v_mfma_f32_32x32x16_bf16 v[106:121], v[228:231], v[240:243], v[106:121]
	v_mfma_f32_32x32x16_bf16 v[208:223], v[228:231], v[244:247], v[208:223]
	s_waitcnt lgkmcnt(4)
	v_mfma_f32_32x32x16_bf16 v[34:49], v[248:251], v[160:163], v[34:49]
	s_waitcnt lgkmcnt(3)
	v_mfma_f32_32x32x16_bf16 v[50:65], v[248:251], v[164:167], v[50:65]
	s_waitcnt lgkmcnt(2)
	v_mfma_f32_32x32x16_bf16 v[2:17], v[156:159], v[160:163], v[2:17]
	v_mfma_f32_32x32x16_bf16 v[18:33], v[156:159], v[164:167], v[18:33]
	s_waitcnt lgkmcnt(1)
	v_mfma_f32_32x32x16_bf16 v[74:89], v[248:251], v[168:171], v[74:89]
	s_waitcnt lgkmcnt(0)
	v_mfma_f32_32x32x16_bf16 v[90:105], v[248:251], v[122:125], v[90:105]
	v_mfma_f32_32x32x16_bf16 v[106:121], v[156:159], v[168:171], v[106:121]
	v_mfma_f32_32x32x16_bf16 v[208:223], v[156:159], v[122:125], v[208:223]
	s_setprio 0
	s_waitcnt vmcnt(6)
	s_barrier
	s_setprio 1
	ds_read_b128 v[224:227], v126 offset:24576
	ds_read_b128 v[232:235], v128 offset:24576
	ds_read_b128 v[236:239], v128 offset:26624
	ds_read_b128 v[228:231], v126 offset:26624
	ds_read_b128 v[240:243], v128 offset:32768
	ds_read_b128 v[244:247], v128 offset:34816
	ds_read_b128 v[248:251], v127 offset:24576
	ds_read_b128 v[160:163], v129 offset:24576
	ds_read_b128 v[164:167], v129 offset:26624
	ds_read_b128 v[156:159], v127 offset:26624
	ds_read_b128 v[168:171], v129 offset:32768
	ds_read_b128 v[122:125], v129 offset:34816
	s_add_u32 m0, s16, 0x0
	s_add_u32 s42, s42, 0x100000
	s_addc_u32 s43, s43, 0
	global_load_lds_dwordx4 v137, s[42:43]
	global_load_lds_dwordx4 v150, s[42:43] offset:1024
	s_add_u32 m0, s0, 0x0
	s_add_u32 s30, s30, 0x10000
	s_addc_u32 s31, s31, 0
	global_load_lds_dwordx4 v151, s[30:31]
	global_load_lds_dwordx4 v152, s[30:31] offset:1024
	global_load_lds_dwordx4 v153, s[30:31] offset:2048
	global_load_lds_dwordx4 v154, s[30:31] offset:3072
	s_waitcnt lgkmcnt(10)
	v_mfma_f32_32x32x16_bf16 v[34:49], v[224:227], v[232:235], v[34:49]
	s_waitcnt lgkmcnt(9)
	v_mfma_f32_32x32x16_bf16 v[50:65], v[224:227], v[236:239], v[50:65]
	s_waitcnt lgkmcnt(8)
	v_mfma_f32_32x32x16_bf16 v[2:17], v[228:231], v[232:235], v[2:17]
	v_mfma_f32_32x32x16_bf16 v[18:33], v[228:231], v[236:239], v[18:33]
	s_waitcnt lgkmcnt(7)
	v_mfma_f32_32x32x16_bf16 v[74:89], v[224:227], v[240:243], v[74:89]
	s_waitcnt lgkmcnt(6)
	v_mfma_f32_32x32x16_bf16 v[90:105], v[224:227], v[244:247], v[90:105]
	v_mfma_f32_32x32x16_bf16 v[106:121], v[228:231], v[240:243], v[106:121]
	v_mfma_f32_32x32x16_bf16 v[208:223], v[228:231], v[244:247], v[208:223]
	s_waitcnt lgkmcnt(4)
	v_mfma_f32_32x32x16_bf16 v[34:49], v[248:251], v[160:163], v[34:49]
	s_waitcnt lgkmcnt(3)
	v_mfma_f32_32x32x16_bf16 v[50:65], v[248:251], v[164:167], v[50:65]
	s_waitcnt lgkmcnt(2)
	v_mfma_f32_32x32x16_bf16 v[2:17], v[156:159], v[160:163], v[2:17]
	v_mfma_f32_32x32x16_bf16 v[18:33], v[156:159], v[164:167], v[18:33]
	s_waitcnt lgkmcnt(1)
	v_mfma_f32_32x32x16_bf16 v[74:89], v[248:251], v[168:171], v[74:89]
	s_waitcnt lgkmcnt(0)
	v_mfma_f32_32x32x16_bf16 v[90:105], v[248:251], v[122:125], v[90:105]
	v_mfma_f32_32x32x16_bf16 v[106:121], v[156:159], v[168:171], v[106:121]
	v_mfma_f32_32x32x16_bf16 v[208:223], v[156:159], v[122:125], v[208:223]
	s_setprio 0
	s_waitcnt vmcnt(6)
	s_barrier
; #define BLOAD(A_, B_, kt) do { _Pragma("unroll") for (int i = 0; i < 4; ++i) { \
;     A_[i] = *(const u32x4*)((const char*)Ap + (aoff + (unsigned)(32 * i * lda + (kt) * 64) * 2u)); B_[i] = *(const u32x4*)((const char*)Wt + (woff + (unsigned)(32 * i * K + (kt) * 64) * 2u)); } } while (0)
; #define BLOAD(A_, B_, kt) do { _Pragma("unroll") for (int i = 0; i < 4; ++i) { \
;     A_[i] = *(const u32x4*)((const char*)Ap + (aoff + (unsigned)(32 * i * lda + (kt) * 64) * 2u)); B_[i] = *(const u32x4*)((const char*)Wt + (woff + (unsigned)(32 * i * K + (kt) * 64) * 2u)); } } while (0)
; #define BSTORE(A_, B_, buf) do { _Pragma("unroll") for (int i = 0; i < 4; ++i) { \
;     *(u32x4*)&As[(buf) * GBUF + (srow + 32 * i) * LDT + sc8] = A_[i]; \
;     *(u32x4*)&Bs[(buf) * GBUF + (srow + 32 * i) * LDT + sc8] = B_[i]; } } while (0)
; template <int NK>
; DI void gemm_run(PF& pf, const u16* __restrict__ Ap, int lda, const u16* __restrict__ Wt, f32x16 (&acc)[2][2], char* smem) {
;     ...
;   __builtin_amdgcn_s_setprio(0);
;   __syncthreads();
;   BSTORE(pf.a0, pf.b0, 0);
;   BLOAD(pf.a0, pf.b0, 2);
;   __syncthreads();
; #pragma unroll
;   for (int kt = 0; kt < nk; kt += 2) {
;     BCOMP(0);
;     BSTORE(pf.a1, pf.b1, 1);
;     if (kt + 3 < nk) BLOAD(pf.a1, pf.b1, kt + 3);
;     __syncthreads();
;     BCOMP(1);
;     if (kt + 2 < nk) { BSTORE(pf.a0, pf.b0, 0); if (kt + 4 < nk) BLOAD(pf.a0, pf.b0, kt + 4); }
;     __syncthreads();
;   }
	s_setprio 1
	ds_read_b128 v[224:227], v126 offset:49152
	ds_read_b128 v[232:235], v128 offset:49152
	ds_read_b128 v[236:239], v128 offset:51200
	ds_read_b128 v[228:231], v126 offset:51200
	ds_read_b128 v[240:243], v128 offset:57344
	ds_read_b128 v[244:247], v128 offset:59392
	ds_read_b128 v[248:251], v127 offset:49152
	ds_read_b128 v[160:163], v129 offset:49152
	ds_read_b128 v[164:167], v129 offset:51200
	ds_read_b128 v[156:159], v127 offset:51200
	ds_read_b128 v[168:171], v129 offset:57344
	ds_read_b128 v[122:125], v129 offset:59392
	s_add_u32 m0, s16, 0x6000
	s_add_u32 s42, s42, 0x100000
	s_addc_u32 s43, s43, 0
	global_load_lds_dwordx4 v137, s[42:43]
	global_load_lds_dwordx4 v150, s[42:43] offset:1024
	s_add_u32 m0, s0, 0x6000
	s_add_u32 s30, s30, 0x10000
	s_addc_u32 s31, s31, 0
	global_load_lds_dwordx4 v151, s[30:31]
	global_load_lds_dwordx4 v152, s[30:31] offset:1024
	global_load_lds_dwordx4 v153, s[30:31] offset:2048
	global_load_lds_dwordx4 v154, s[30:31] offset:3072
	s_waitcnt lgkmcnt(10)
	v_mfma_f32_32x32x16_bf16 v[34:49], v[224:227], v[232:235], v[34:49]
	s_waitcnt lgkmcnt(9)
	v_mfma_f32_32x32x16_bf16 v[50:65], v[224:227], v[236:239], v[50:65]
	s_waitcnt lgkmcnt(8)
	v_mfma_f32_32x32x16_bf16 v[2:17], v[228:231], v[232:235], v[2:17]
	v_mfma_f32_32x32x16_bf16 v[18:33], v[228:231], v[236:239], v[18:33]
	s_waitcnt lgkmcnt(7)
	v_mfma_f32_32x32x16_bf16 v[74:89], v[224:227], v[240:243], v[74:89]
	s_waitcnt lgkmcnt(6)
	v_mfma_f32_32x32x16_bf16 v[90:105], v[224:227], v[244:247], v[90:105]
	v_mfma_f32_32x32x16_bf16 v[106:121], v[228:231], v[240:243], v[106:121]
	v_mfma_f32_32x32x16_bf16 v[208:223], v[228:231], v[244:247], v[208:223]
	s_waitcnt lgkmcnt(4)
	v_mfma_f32_32x32x16_bf16 v[34:49], v[248:251], v[160:163], v[34:49]
	s_waitcnt lgkmcnt(3)
	v_mfma_f32_32x32x16_bf16 v[50:65], v[248:251], v[164:167], v[50:65]
	s_waitcnt lgkmcnt(2)
	v_mfma_f32_32x32x16_bf16 v[2:17], v[156:159], v[160:163], v[2:17]
	v_mfma_f32_32x32x16_bf16 v[18:33], v[156:159], v[164:167], v[18:33]
	s_waitcnt lgkmcnt(1)
	v_mfma_f32_32x32x16_bf16 v[74:89], v[248:251], v[168:171], v[74:89]
	s_waitcnt lgkmcnt(0)
	v_mfma_f32_32x32x16_bf16 v[90:105], v[248:251], v[122:125], v[90:105]
	v_mfma_f32_32x32x16_bf16 v[106:121], v[156:159], v[168:171], v[106:121]
	v_mfma_f32_32x32x16_bf16 v[208:223], v[156:159], v[122:125], v[208:223]
	s_setprio 0
	s_waitcnt vmcnt(6)
	s_barrier
	s_setprio 1
	ds_read_b128 v[224:227], v126 offset:0
	ds_read_b128 v[232:235], v128 offset:0
	ds_read_b128 v[236:239], v128 offset:2048
	ds_read_b128 v[228:231], v126 offset:2048
	ds_read_b128 v[240:243], v128 offset:8192
	ds_read_b128 v[244:247], v128 offset:10240
	ds_read_b128 v[248:251], v127 offset:0
	ds_read_b128 v[160:163], v129 offset:0
	ds_read_b128 v[164:167], v129 offset:2048
	ds_read_b128 v[156:159], v127 offset:2048
	ds_read_b128 v[168:171], v129 offset:8192
	ds_read_b128 v[122:125], v129 offset:10240
	s_add_u32 m0, s16, 0xc000
	s_add_u32 s42, s42, 0x100000
	s_addc_u32 s43, s43, 0
	global_load_lds_dwordx4 v137, s[42:43]
	global_load_lds_dwordx4 v150, s[42:43] offset:1024
	s_add_u32 m0, s0, 0xc000
	s_add_u32 s30, s30, 0x10000
	s_addc_u32 s31, s31, 0
	global_load_lds_dwordx4 v151, s[30:31]
	global_load_lds_dwordx4 v152, s[30:31] offset:1024
	global_load_lds_dwordx4 v153, s[30:31] offset:2048
	global_load_lds_dwordx4 v154, s[30:31] offset:3072
	s_waitcnt lgkmcnt(10)
	v_mfma_f32_32x32x16_bf16 v[34:49], v[224:227], v[232:235], v[34:49]
	s_waitcnt lgkmcnt(9)
	v_mfma_f32_32x32x16_bf16 v[50:65], v[224:227], v[236:239], v[50:65]
	s_waitcnt lgkmcnt(8)
	v_mfma_f32_32x32x16_bf16 v[2:17], v[228:231], v[232:235], v[2:17]
	v_mfma_f32_32x32x16_bf16 v[18:33], v[228:231], v[236:239], v[18:33]
	s_waitcnt lgkmcnt(7)
	v_mfma_f32_32x32x16_bf16 v[74:89], v[224:227], v[240:243], v[74:89]
	s_waitcnt lgkmcnt(6)
	v_mfma_f32_32x32x16_bf16 v[90:105], v[224:227], v[244:247], v[90:105]
	v_mfma_f32_32x32x16_bf16 v[106:121], v[228:231], v[240:243], v[106:121]
	v_mfma_f32_32x32x16_bf16 v[208:223], v[228:231], v[244:247], v[208:223]
	s_waitcnt lgkmcnt(4)
	v_mfma_f32_32x32x16_bf16 v[34:49], v[248:251], v[160:163], v[34:49]
	s_waitcnt lgkmcnt(3)
	v_mfma_f32_32x32x16_bf16 v[50:65], v[248:251], v[164:167], v[50:65]
	s_waitcnt lgkmcnt(2)
	v_mfma_f32_32x32x16_bf16 v[2:17], v[156:159], v[160:163], v[2:17]
	v_mfma_f32_32x32x16_bf16 v[18:33], v[156:159], v[164:167], v[18:33]
	s_waitcnt lgkmcnt(1)
	v_mfma_f32_32x32x16_bf16 v[74:89], v[248:251], v[168:171], v[74:89]
	s_waitcnt lgkmcnt(0)
	v_mfma_f32_32x32x16_bf16 v[90:105], v[248:251], v[122:125], v[90:105]
	v_mfma_f32_32x32x16_bf16 v[106:121], v[156:159], v[168:171], v[106:121]
	v_mfma_f32_32x32x16_bf16 v[208:223], v[156:159], v[122:125], v[208:223]
	s_setprio 0
	s_waitcnt vmcnt(6)
	s_barrier
; #define BLOAD(A_, B_, kt) do { _Pragma("unroll") for (int i = 0; i < 4; ++i) { \
;     A_[i] = *(const u32x4*)((const char*)Ap + (aoff + (unsigned)(32 * i * lda + (kt) * 64) * 2u)); B_[i] = *(const u32x4*)((const char*)Wt + (woff + (unsigned)(32 * i * K + (kt) * 64) * 2u)); } } while (0)
; #define BLOAD(A_, B_, kt) do { _Pragma("unroll") for (int i = 0; i < 4; ++i) { \
;     A_[i] = *(const u32x4*)((const char*)Ap + (aoff + (unsigned)(32 * i * lda + (kt) * 64) * 2u)); B_[i] = *(const u32x4*)((const char*)Wt + (woff + (unsigned)(32 * i * K + (kt) * 64) * 2u)); } } while (0)
; #define BSTORE(A_, B_, buf) do { _Pragma("unroll") for (int i = 0; i < 4; ++i) { \
;     *(u32x4*)&As[(buf) * GBUF + (srow + 32 * i) * LDT + sc8] = A_[i]; \
;     *(u32x4*)&Bs[(buf) * GBUF + (srow + 32 * i) * LDT + sc8] = B_[i]; } } while (0)
; template <int NK>
; DI void gemm_run(PF& pf, const u16* __restrict__ Ap, int lda, const u16* __restrict__ Wt, f32x16 (&acc)[2][2], char* smem) {
;     ...
;   __builtin_amdgcn_s_setprio(0);
;   __syncthreads();
;   BSTORE(pf.a0, pf.b0, 0);
;   BLOAD(pf.a0, pf.b0, 2);
;   __syncthreads();
; #pragma unroll
;   for (int kt = 0; kt < nk; kt += 2) {
;     BCOMP(0);
;     BSTORE(pf.a1, pf.b1, 1);
;     if (kt + 3 < nk) BLOAD(pf.a1, pf.b1, kt + 3);
;     __syncthreads();
;     BCOMP(1);
;     if (kt + 2 < nk) { BSTORE(pf.a0, pf.b0, 0); if (kt + 4 < nk) BLOAD(pf.a0, pf.b0, kt + 4); }
;     __syncthreads();
;   }
	s_setprio 1
	ds_read_b128 v[224:227], v126 offset:24576
	ds_read_b128 v[232:235], v128 offset:24576
	ds_read_b128 v[236:239], v128 offset:26624
	ds_read_b128 v[228:231], v126 offset:26624
	ds_read_b128 v[240:243], v128 offset:32768
	ds_read_b128 v[244:247], v128 offset:34816
	ds_read_b128 v[248:251], v127 offset:24576
	ds_read_b128 v[160:163], v129 offset:24576
	ds_read_b128 v[164:167], v129 offset:26624
	ds_read_b128 v[156:159], v127 offset:26624
	ds_read_b128 v[168:171], v129 offset:32768
	ds_read_b128 v[122:125], v129 offset:34816
	s_add_u32 m0, s16, 0x0
	s_add_u32 s42, s42, 0x100000
	s_addc_u32 s43, s43, 0
	global_load_lds_dwordx4 v137, s[42:43]
	global_load_lds_dwordx4 v150, s[42:43] offset:1024
	s_add_u32 m0, s0, 0x0
	s_add_u32 s30, s30, 0x10000
	s_addc_u32 s31, s31, 0
	global_load_lds_dwordx4 v151, s[30:31]
	global_load_lds_dwordx4 v152, s[30:31] offset:1024
	global_load_lds_dwordx4 v153, s[30:31] offset:2048
	global_load_lds_dwordx4 v154, s[30:31] offset:3072
	s_waitcnt lgkmcnt(10)
	v_mfma_f32_32x32x16_bf16 v[34:49], v[224:227], v[232:235], v[34:49]
	s_waitcnt lgkmcnt(9)
	v_mfma_f32_32x32x16_bf16 v[50:65], v[224:227], v[236:239], v[50:65]
	s_waitcnt lgkmcnt(8)
	v_mfma_f32_32x32x16_bf16 v[2:17], v[228:231], v[232:235], v[2:17]
	v_mfma_f32_32x32x16_bf16 v[18:33], v[228:231], v[236:239], v[18:33]
	s_waitcnt lgkmcnt(7)
	v_mfma_f32_32x32x16_bf16 v[74:89], v[224:227], v[240:243], v[74:89]
	s_waitcnt lgkmcnt(6)
	v_mfma_f32_32x32x16_bf16 v[90:105], v[224:227], v[244:247], v[90:105]
	v_mfma_f32_32x32x16_bf16 v[106:121], v[228:231], v[240:243], v[106:121]
	v_mfma_f32_32x32x16_bf16 v[208:223], v[228:231], v[244:247], v[208:223]
	s_waitcnt lgkmcnt(4)
	v_mfma_f32_32x32x16_bf16 v[34:49], v[248:251], v[160:163], v[34:49]
	s_waitcnt lgkmcnt(3)
	v_mfma_f32_32x32x16_bf16 v[50:65], v[248:251], v[164:167], v[50:65]
	s_waitcnt lgkmcnt(2)
	v_mfma_f32_32x32x16_bf16 v[2:17], v[156:159], v[160:163], v[2:17]
	v_mfma_f32_32x32x16_bf16 v[18:33], v[156:159], v[164:167], v[18:33]
	s_waitcnt lgkmcnt(1)
	v_mfma_f32_32x32x16_bf16 v[74:89], v[248:251], v[168:171], v[74:89]
	s_waitcnt lgkmcnt(0)
	v_mfma_f32_32x32x16_bf16 v[90:105], v[248:251], v[122:125], v[90:105]
	v_mfma_f32_32x32x16_bf16 v[106:121], v[156:159], v[168:171], v[106:121]
	v_mfma_f32_32x32x16_bf16 v[208:223], v[156:159], v[122:125], v[208:223]
	s_setprio 0
	s_waitcnt vmcnt(6)
	s_barrier
	s_setprio 1
	ds_read_b128 v[224:227], v126 offset:49152
	ds_read_b128 v[232:235], v128 offset:49152
	ds_read_b128 v[236:239], v128 offset:51200
	ds_read_b128 v[228:231], v126 offset:51200
	ds_read_b128 v[240:243], v128 offset:57344
	ds_read_b128 v[244:247], v128 offset:59392
	ds_read_b128 v[248:251], v127 offset:49152
	ds_read_b128 v[160:163], v129 offset:49152
	ds_read_b128 v[164:167], v129 offset:51200
	ds_read_b128 v[156:159], v127 offset:51200
	ds_read_b128 v[168:171], v129 offset:57344
	ds_read_b128 v[122:125], v129 offset:59392
	s_add_u32 m0, s16, 0x6000
	s_add_u32 s42, s42, 0x100000
	s_addc_u32 s43, s43, 0
	global_load_lds_dwordx4 v137, s[42:43]
	global_load_lds_dwordx4 v150, s[42:43] offset:1024
	s_add_u32 m0, s0, 0x6000
	s_add_u32 s30, s30, 0x10000
	s_addc_u32 s31, s31, 0
	global_load_lds_dwordx4 v151, s[30:31]
	global_load_lds_dwordx4 v152, s[30:31] offset:1024
	global_load_lds_dwordx4 v153, s[30:31] offset:2048
	global_load_lds_dwordx4 v154, s[30:31] offset:3072
	s_waitcnt lgkmcnt(10)
	v_mfma_f32_32x32x16_bf16 v[34:49], v[224:227], v[232:235], v[34:49]
	s_waitcnt lgkmcnt(9)
	v_mfma_f32_32x32x16_bf16 v[50:65], v[224:227], v[236:239], v[50:65]
	s_waitcnt lgkmcnt(8)
	v_mfma_f32_32x32x16_bf16 v[2:17], v[228:231], v[232:235], v[2:17]
	v_mfma_f32_32x32x16_bf16 v[18:33], v[228:231], v[236:239], v[18:33]
	s_waitcnt lgkmcnt(7)
	v_mfma_f32_32x32x16_bf16 v[74:89], v[224:227], v[240:243], v[74:89]
	s_waitcnt lgkmcnt(6)
	v_mfma_f32_32x32x16_bf16 v[90:105], v[224:227], v[244:247], v[90:105]
	v_mfma_f32_32x32x16_bf16 v[106:121], v[228:231], v[240:243], v[106:121]
	v_mfma_f32_32x32x16_bf16 v[208:223], v[228:231], v[244:247], v[208:223]
	s_waitcnt lgkmcnt(4)
	v_mfma_f32_32x32x16_bf16 v[34:49], v[248:251], v[160:163], v[34:49]
	s_waitcnt lgkmcnt(3)
	v_mfma_f32_32x32x16_bf16 v[50:65], v[248:251], v[164:167], v[50:65]
	s_waitcnt lgkmcnt(2)
	v_mfma_f32_32x32x16_bf16 v[2:17], v[156:159], v[160:163], v[2:17]
	v_mfma_f32_32x32x16_bf16 v[18:33], v[156:159], v[164:167], v[18:33]
	s_waitcnt lgkmcnt(1)
	v_mfma_f32_32x32x16_bf16 v[74:89], v[248:251], v[168:171], v[74:89]
	s_waitcnt lgkmcnt(0)
	v_mfma_f32_32x32x16_bf16 v[90:105], v[248:251], v[122:125], v[90:105]
	v_mfma_f32_32x32x16_bf16 v[106:121], v[156:159], v[168:171], v[106:121]
	v_mfma_f32_32x32x16_bf16 v[208:223], v[156:159], v[122:125], v[208:223]
	s_setprio 0
	s_waitcnt vmcnt(6)
	s_barrier
; #define BLOAD(A_, B_, kt) do { _Pragma("unroll") for (int i = 0; i < 4; ++i) { \
;     A_[i] = *(const u32x4*)((const char*)Ap + (aoff + (unsigned)(32 * i * lda + (kt) * 64) * 2u)); B_[i] = *(const u32x4*)((const char*)Wt + (woff + (unsigned)(32 * i * K + (kt) * 64) * 2u)); } } while (0)
; #define BLOAD(A_, B_, kt) do { _Pragma("unroll") for (int i = 0; i < 4; ++i) { \
;     A_[i] = *(const u32x4*)((const char*)Ap + (aoff + (unsigned)(32 * i * lda + (kt) * 64) * 2u)); B_[i] = *(const u32x4*)((const char*)Wt + (woff + (unsigned)(32 * i * K + (kt) * 64) * 2u)); } } while (0)
; #define BSTORE(A_, B_, buf) do { _Pragma("unroll") for (int i = 0; i < 4; ++i) { \
;     *(u32x4*)&As[(buf) * GBUF + (srow + 32 * i) * LDT + sc8] = A_[i]; \
;     *(u32x4*)&Bs[(buf) * GBUF + (srow + 32 * i) * LDT + sc8] = B_[i]; } } while (0)
; template <int NK>
; DI void gemm_run(PF& pf, const u16* __restrict__ Ap, int lda, const u16* __restrict__ Wt, f32x16 (&acc)[2][2], char* smem) {
;     ...
;   __builtin_amdgcn_s_setprio(0);
;   __syncthreads();
;   BSTORE(pf.a0, pf.b0, 0);
;   BLOAD(pf.a0, pf.b0, 2);
;   __syncthreads();
; #pragma unroll
;   for (int kt = 0; kt < nk; kt += 2) {
;     BCOMP(0);
;     BSTORE(pf.a1, pf.b1, 1);
;     if (kt + 3 < nk) BLOAD(pf.a1, pf.b1, kt + 3);
;     __syncthreads();
;     BCOMP(1);
;     if (kt + 2 < nk) { BSTORE(pf.a0, pf.b0, 0); if (kt + 4 < nk) BLOAD(pf.a0, pf.b0, kt + 4); }
;     __syncthreads();
;   }
	s_setprio 1
	ds_read_b128 v[224:227], v126 offset:0
	ds_read_b128 v[232:235], v128 offset:0
	ds_read_b128 v[236:239], v128 offset:2048
	ds_read_b128 v[228:231], v126 offset:2048
	ds_read_b128 v[240:243], v128 offset:8192
	ds_read_b128 v[244:247], v128 offset:10240
	ds_read_b128 v[248:251], v127 offset:0
	ds_read_b128 v[160:163], v129 offset:0
	ds_read_b128 v[164:167], v129 offset:2048
	ds_read_b128 v[156:159], v127 offset:2048
	ds_read_b128 v[168:171], v129 offset:8192
	ds_read_b128 v[122:125], v129 offset:10240
	s_add_u32 m0, s16, 0xc000
	s_add_u32 s42, s42, 0x100000
	s_addc_u32 s43, s43, 0
	global_load_lds_dwordx4 v137, s[42:43]
	global_load_lds_dwordx4 v150, s[42:43] offset:1024
	s_add_u32 m0, s0, 0xc000
	s_add_u32 s30, s30, 0x10000
	s_addc_u32 s31, s31, 0
	global_load_lds_dwordx4 v151, s[30:31]
	global_load_lds_dwordx4 v152, s[30:31] offset:1024
	global_load_lds_dwordx4 v153, s[30:31] offset:2048
	global_load_lds_dwordx4 v154, s[30:31] offset:3072
	s_waitcnt lgkmcnt(10)
	v_mfma_f32_32x32x16_bf16 v[34:49], v[224:227], v[232:235], v[34:49]
	s_waitcnt lgkmcnt(9)
	v_mfma_f32_32x32x16_bf16 v[50:65], v[224:227], v[236:239], v[50:65]
	s_waitcnt lgkmcnt(8)
	v_mfma_f32_32x32x16_bf16 v[2:17], v[228:231], v[232:235], v[2:17]
	v_mfma_f32_32x32x16_bf16 v[18:33], v[228:231], v[236:239], v[18:33]
	s_waitcnt lgkmcnt(7)
	v_mfma_f32_32x32x16_bf16 v[74:89], v[224:227], v[240:243], v[74:89]
	s_waitcnt lgkmcnt(6)
	v_mfma_f32_32x32x16_bf16 v[90:105], v[224:227], v[244:247], v[90:105]
	v_mfma_f32_32x32x16_bf16 v[106:121], v[228:231], v[240:243], v[106:121]
	v_mfma_f32_32x32x16_bf16 v[208:223], v[228:231], v[244:247], v[208:223]
	s_waitcnt lgkmcnt(4)
	v_mfma_f32_32x32x16_bf16 v[34:49], v[248:251], v[160:163], v[34:49]
	s_waitcnt lgkmcnt(3)
	v_mfma_f32_32x32x16_bf16 v[50:65], v[248:251], v[164:167], v[50:65]
	s_waitcnt lgkmcnt(2)
	v_mfma_f32_32x32x16_bf16 v[2:17], v[156:159], v[160:163], v[2:17]
	v_mfma_f32_32x32x16_bf16 v[18:33], v[156:159], v[164:167], v[18:33]
	s_waitcnt lgkmcnt(1)
	v_mfma_f32_32x32x16_bf16 v[74:89], v[248:251], v[168:171], v[74:89]
	s_waitcnt lgkmcnt(0)
	v_mfma_f32_32x32x16_bf16 v[90:105], v[248:251], v[122:125], v[90:105]
	v_mfma_f32_32x32x16_bf16 v[106:121], v[156:159], v[168:171], v[106:121]
	v_mfma_f32_32x32x16_bf16 v[208:223], v[156:159], v[122:125], v[208:223]
	s_setprio 0
	s_waitcnt vmcnt(6)
	s_barrier
	s_setprio 1
	ds_read_b128 v[224:227], v126 offset:24576
	ds_read_b128 v[232:235], v128 offset:24576
	ds_read_b128 v[236:239], v128 offset:26624
	ds_read_b128 v[228:231], v126 offset:26624
	ds_read_b128 v[240:243], v128 offset:32768
	ds_read_b128 v[244:247], v128 offset:34816
	ds_read_b128 v[248:251], v127 offset:24576
	ds_read_b128 v[160:163], v129 offset:24576
	ds_read_b128 v[164:167], v129 offset:26624
	ds_read_b128 v[156:159], v127 offset:26624
	ds_read_b128 v[168:171], v129 offset:32768
	ds_read_b128 v[122:125], v129 offset:34816
	s_add_u32 m0, s16, 0x0
	s_add_u32 s42, s42, 0x100000
	s_addc_u32 s43, s43, 0
	global_load_lds_dwordx4 v137, s[42:43]
	global_load_lds_dwordx4 v150, s[42:43] offset:1024
	s_add_u32 m0, s0, 0x0
	s_add_u32 s30, s30, 0x10000
	s_addc_u32 s31, s31, 0
	global_load_lds_dwordx4 v151, s[30:31]
	global_load_lds_dwordx4 v152, s[30:31] offset:1024
	global_load_lds_dwordx4 v153, s[30:31] offset:2048
	global_load_lds_dwordx4 v154, s[30:31] offset:3072
	s_waitcnt lgkmcnt(10)
	v_mfma_f32_32x32x16_bf16 v[34:49], v[224:227], v[232:235], v[34:49]
	s_waitcnt lgkmcnt(9)
	v_mfma_f32_32x32x16_bf16 v[50:65], v[224:227], v[236:239], v[50:65]
	s_waitcnt lgkmcnt(8)
	v_mfma_f32_32x32x16_bf16 v[2:17], v[228:231], v[232:235], v[2:17]
	v_mfma_f32_32x32x16_bf16 v[18:33], v[228:231], v[236:239], v[18:33]
	s_waitcnt lgkmcnt(7)
	v_mfma_f32_32x32x16_bf16 v[74:89], v[224:227], v[240:243], v[74:89]
	s_waitcnt lgkmcnt(6)
	v_mfma_f32_32x32x16_bf16 v[90:105], v[224:227], v[244:247], v[90:105]
	v_mfma_f32_32x32x16_bf16 v[106:121], v[228:231], v[240:243], v[106:121]
	v_mfma_f32_32x32x16_bf16 v[208:223], v[228:231], v[244:247], v[208:223]
	s_waitcnt lgkmcnt(4)
	v_mfma_f32_32x32x16_bf16 v[34:49], v[248:251], v[160:163], v[34:49]
	s_waitcnt lgkmcnt(3)
	v_mfma_f32_32x32x16_bf16 v[50:65], v[248:251], v[164:167], v[50:65]
	s_waitcnt lgkmcnt(2)
	v_mfma_f32_32x32x16_bf16 v[2:17], v[156:159], v[160:163], v[2:17]
	v_mfma_f32_32x32x16_bf16 v[18:33], v[156:159], v[164:167], v[18:33]
	s_waitcnt lgkmcnt(1)
	v_mfma_f32_32x32x16_bf16 v[74:89], v[248:251], v[168:171], v[74:89]
	s_waitcnt lgkmcnt(0)
	v_mfma_f32_32x32x16_bf16 v[90:105], v[248:251], v[122:125], v[90:105]
	v_mfma_f32_32x32x16_bf16 v[106:121], v[156:159], v[168:171], v[106:121]
	v_mfma_f32_32x32x16_bf16 v[208:223], v[156:159], v[122:125], v[208:223]
	s_setprio 0
	s_waitcnt vmcnt(6)
	s_barrier
; #define BLOAD(A_, B_, kt) do { _Pragma("unroll") for (int i = 0; i < 4; ++i) { \
;     A_[i] = *(const u32x4*)((const char*)Ap + (aoff + (unsigned)(32 * i * lda + (kt) * 64) * 2u)); B_[i] = *(const u32x4*)((const char*)Wt + (woff + (unsigned)(32 * i * K + (kt) * 64) * 2u)); } } while (0)
; #define BLOAD(A_, B_, kt) do { _Pragma("unroll") for (int i = 0; i < 4; ++i) { \
;     A_[i] = *(const u32x4*)((const char*)Ap + (aoff + (unsigned)(32 * i * lda + (kt) * 64) * 2u)); B_[i] = *(const u32x4*)((const char*)Wt + (woff + (unsigned)(32 * i * K + (kt) * 64) * 2u)); } } while (0)
; #define BSTORE(A_, B_, buf) do { _Pragma("unroll") for (int i = 0; i < 4; ++i) { \
;     *(u32x4*)&As[(buf) * GBUF + (srow + 32 * i) * LDT + sc8] = A_[i]; \
;     *(u32x4*)&Bs[(buf) * GBUF + (srow + 32 * i) * LDT + sc8] = B_[i]; } } while (0)
; template <int NK>
; DI void gemm_run(PF& pf, const u16* __restrict__ Ap, int lda, const u16* __restrict__ Wt, f32x16 (&acc)[2][2], char* smem) {
;     ...
;   __builtin_amdgcn_s_setprio(0);
;   __syncthreads();
;   BSTORE(pf.a0, pf.b0, 0);
;   BLOAD(pf.a0, pf.b0, 2);
;   __syncthreads();
; #pragma unroll
;   for (int kt = 0; kt < nk; kt += 2) {
;     BCOMP(0);
;     BSTORE(pf.a1, pf.b1, 1);
;     if (kt + 3 < nk) BLOAD(pf.a1, pf.b1, kt + 3);
;     __syncthreads();
;     BCOMP(1);
;     if (kt + 2 < nk) { BSTORE(pf.a0, pf.b0, 0); if (kt + 4 < nk) BLOAD(pf.a0, pf.b0, kt + 4); }
;     __syncthreads();
;   }
	s_setprio 1
	ds_read_b128 v[224:227], v126 offset:49152
	ds_read_b128 v[232:235], v128 offset:49152
	ds_read_b128 v[236:239], v128 offset:51200
	ds_read_b128 v[228:231], v126 offset:51200
	ds_read_b128 v[240:243], v128 offset:57344
	ds_read_b128 v[244:247], v128 offset:59392
	ds_read_b128 v[248:251], v127 offset:49152
	ds_read_b128 v[160:163], v129 offset:49152
	ds_read_b128 v[164:167], v129 offset:51200
	ds_read_b128 v[156:159], v127 offset:51200
	ds_read_b128 v[168:171], v129 offset:57344
	ds_read_b128 v[122:125], v129 offset:59392
	s_add_u32 m0, s16, 0x6000
	s_add_u32 s42, s42, 0x100000
	s_addc_u32 s43, s43, 0
	global_load_lds_dwordx4 v137, s[42:43]
	global_load_lds_dwordx4 v150, s[42:43] offset:1024
	s_add_u32 m0, s0, 0x6000
	s_add_u32 s30, s30, 0x10000
	s_addc_u32 s31, s31, 0
	global_load_lds_dwordx4 v151, s[30:31]
	global_load_lds_dwordx4 v152, s[30:31] offset:1024
	global_load_lds_dwordx4 v153, s[30:31] offset:2048
	global_load_lds_dwordx4 v154, s[30:31] offset:3072
	s_waitcnt lgkmcnt(10)
	v_mfma_f32_32x32x16_bf16 v[34:49], v[224:227], v[232:235], v[34:49]
	s_waitcnt lgkmcnt(9)
	v_mfma_f32_32x32x16_bf16 v[50:65], v[224:227], v[236:239], v[50:65]
	s_waitcnt lgkmcnt(8)
	v_mfma_f32_32x32x16_bf16 v[2:17], v[228:231], v[232:235], v[2:17]
	v_mfma_f32_32x32x16_bf16 v[18:33], v[228:231], v[236:239], v[18:33]
	s_waitcnt lgkmcnt(7)
	v_mfma_f32_32x32x16_bf16 v[74:89], v[224:227], v[240:243], v[74:89]
	s_waitcnt lgkmcnt(6)
	v_mfma_f32_32x32x16_bf16 v[90:105], v[224:227], v[244:247], v[90:105]
	v_mfma_f32_32x32x16_bf16 v[106:121], v[228:231], v[240:243], v[106:121]
	v_mfma_f32_32x32x16_bf16 v[208:223], v[228:231], v[244:247], v[208:223]
	s_waitcnt lgkmcnt(4)
	v_mfma_f32_32x32x16_bf16 v[34:49], v[248:251], v[160:163], v[34:49]
	s_waitcnt lgkmcnt(3)
	v_mfma_f32_32x32x16_bf16 v[50:65], v[248:251], v[164:167], v[50:65]
	s_waitcnt lgkmcnt(2)
	v_mfma_f32_32x32x16_bf16 v[2:17], v[156:159], v[160:163], v[2:17]
	v_mfma_f32_32x32x16_bf16 v[18:33], v[156:159], v[164:167], v[18:33]
	s_waitcnt lgkmcnt(1)
	v_mfma_f32_32x32x16_bf16 v[74:89], v[248:251], v[168:171], v[74:89]
	s_waitcnt lgkmcnt(0)
	v_mfma_f32_32x32x16_bf16 v[90:105], v[248:251], v[122:125], v[90:105]
	v_mfma_f32_32x32x16_bf16 v[106:121], v[156:159], v[168:171], v[106:121]
	v_mfma_f32_32x32x16_bf16 v[208:223], v[156:159], v[122:125], v[208:223]
	s_setprio 0
	s_waitcnt vmcnt(6)
	s_barrier
	s_setprio 1
	ds_read_b128 v[224:227], v126 offset:0
	ds_read_b128 v[232:235], v128 offset:0
	ds_read_b128 v[236:239], v128 offset:2048
	ds_read_b128 v[228:231], v126 offset:2048
	ds_read_b128 v[240:243], v128 offset:8192
	ds_read_b128 v[244:247], v128 offset:10240
	ds_read_b128 v[248:251], v127 offset:0
	ds_read_b128 v[160:163], v129 offset:0
	ds_read_b128 v[164:167], v129 offset:2048
	ds_read_b128 v[156:159], v127 offset:2048
	ds_read_b128 v[168:171], v129 offset:8192
	ds_read_b128 v[122:125], v129 offset:10240
	s_add_u32 m0, s16, 0xc000
	s_add_u32 s42, s42, 0x100000
	s_addc_u32 s43, s43, 0
	global_load_lds_dwordx4 v137, s[42:43]
	global_load_lds_dwordx4 v150, s[42:43] offset:1024
	s_add_u32 m0, s0, 0xc000
	s_add_u32 s30, s30, 0x10000
	s_addc_u32 s31, s31, 0
	global_load_lds_dwordx4 v151, s[30:31]
	global_load_lds_dwordx4 v152, s[30:31] offset:1024
	global_load_lds_dwordx4 v153, s[30:31] offset:2048
	global_load_lds_dwordx4 v154, s[30:31] offset:3072
	s_waitcnt lgkmcnt(10)
	v_mfma_f32_32x32x16_bf16 v[34:49], v[224:227], v[232:235], v[34:49]
	s_waitcnt lgkmcnt(9)
	v_mfma_f32_32x32x16_bf16 v[50:65], v[224:227], v[236:239], v[50:65]
	s_waitcnt lgkmcnt(8)
	v_mfma_f32_32x32x16_bf16 v[2:17], v[228:231], v[232:235], v[2:17]
	v_mfma_f32_32x32x16_bf16 v[18:33], v[228:231], v[236:239], v[18:33]
	s_waitcnt lgkmcnt(7)
	v_mfma_f32_32x32x16_bf16 v[74:89], v[224:227], v[240:243], v[74:89]
	s_waitcnt lgkmcnt(6)
	v_mfma_f32_32x32x16_bf16 v[90:105], v[224:227], v[244:247], v[90:105]
	v_mfma_f32_32x32x16_bf16 v[106:121], v[228:231], v[240:243], v[106:121]
	v_mfma_f32_32x32x16_bf16 v[208:223], v[228:231], v[244:247], v[208:223]
	s_waitcnt lgkmcnt(4)
	v_mfma_f32_32x32x16_bf16 v[34:49], v[248:251], v[160:163], v[34:49]
	s_waitcnt lgkmcnt(3)
	v_mfma_f32_32x32x16_bf16 v[50:65], v[248:251], v[164:167], v[50:65]
	s_waitcnt lgkmcnt(2)
	v_mfma_f32_32x32x16_bf16 v[2:17], v[156:159], v[160:163], v[2:17]
	v_mfma_f32_32x32x16_bf16 v[18:33], v[156:159], v[164:167], v[18:33]
	s_waitcnt lgkmcnt(1)
	v_mfma_f32_32x32x16_bf16 v[74:89], v[248:251], v[168:171], v[74:89]
	s_waitcnt lgkmcnt(0)
	v_mfma_f32_32x32x16_bf16 v[90:105], v[248:251], v[122:125], v[90:105]
	v_mfma_f32_32x32x16_bf16 v[106:121], v[156:159], v[168:171], v[106:121]
	v_mfma_f32_32x32x16_bf16 v[208:223], v[156:159], v[122:125], v[208:223]
	s_setprio 0
	s_waitcnt vmcnt(6)
	s_barrier
; #define BLOAD(A_, B_, kt) do { _Pragma("unroll") for (int i = 0; i < 4; ++i) { \
;     A_[i] = *(const u32x4*)((const char*)Ap + (aoff + (unsigned)(32 * i * lda + (kt) * 64) * 2u)); B_[i] = *(const u32x4*)((const char*)Wt + (woff + (unsigned)(32 * i * K + (kt) * 64) * 2u)); } } while (0)
; #define BLOAD(A_, B_, kt) do { _Pragma("unroll") for (int i = 0; i < 4; ++i) { \
;     A_[i] = *(const u32x4*)((const char*)Ap + (aoff + (unsigned)(32 * i * lda + (kt) * 64) * 2u)); B_[i] = *(const u32x4*)((const char*)Wt + (woff + (unsigned)(32 * i * K + (kt) * 64) * 2u)); } } while (0)
; #define BSTORE(A_, B_, buf) do { _Pragma("unroll") for (int i = 0; i < 4; ++i) { \
;     *(u32x4*)&As[(buf) * GBUF + (srow + 32 * i) * LDT + sc8] = A_[i]; \
;     *(u32x4*)&Bs[(buf) * GBUF + (srow + 32 * i) * LDT + sc8] = B_[i]; } } while (0)
; template <int NK>
; DI void gemm_run(PF& pf, const u16* __restrict__ Ap, int lda, const u16* __restrict__ Wt, f32x16 (&acc)[2][2], char* smem) {
;     ...
;   __builtin_amdgcn_s_setprio(0);
;   __syncthreads();
;   BSTORE(pf.a0, pf.b0, 0);
;   BLOAD(pf.a0, pf.b0, 2);
;   __syncthreads();
; #pragma unroll
;   for (int kt = 0; kt < nk; kt += 2) {
;     BCOMP(0);
;     BSTORE(pf.a1, pf.b1, 1);
;     if (kt + 3 < nk) BLOAD(pf.a1, pf.b1, kt + 3);
;     __syncthreads();
;     BCOMP(1);
;     if (kt + 2 < nk) { BSTORE(pf.a0, pf.b0, 0); if (kt + 4 < nk) BLOAD(pf.a0, pf.b0, kt + 4); }
;     __syncthreads();
;   }
	s_setprio 1
	ds_read_b128 v[224:227], v126 offset:24576
	ds_read_b128 v[232:235], v128 offset:24576
	ds_read_b128 v[236:239], v128 offset:26624
	ds_read_b128 v[228:231], v126 offset:26624
	ds_read_b128 v[240:243], v128 offset:32768
	ds_read_b128 v[244:247], v128 offset:34816
	ds_read_b128 v[248:251], v127 offset:24576
	ds_read_b128 v[160:163], v129 offset:24576
	ds_read_b128 v[164:167], v129 offset:26624
	ds_read_b128 v[156:159], v127 offset:26624
	ds_read_b128 v[168:171], v129 offset:32768
	ds_read_b128 v[122:125], v129 offset:34816
	s_add_u32 m0, s16, 0x0
	s_add_u32 s42, s42, 0x100000
	s_addc_u32 s43, s43, 0
	global_load_lds_dwordx4 v137, s[42:43]
	global_load_lds_dwordx4 v150, s[42:43] offset:1024
	s_add_u32 m0, s0, 0x0
	s_add_u32 s30, s30, 0x10000
	s_addc_u32 s31, s31, 0
	global_load_lds_dwordx4 v151, s[30:31]
	global_load_lds_dwordx4 v152, s[30:31] offset:1024
	global_load_lds_dwordx4 v153, s[30:31] offset:2048
	global_load_lds_dwordx4 v154, s[30:31] offset:3072
	s_waitcnt lgkmcnt(10)
	v_mfma_f32_32x32x16_bf16 v[34:49], v[224:227], v[232:235], v[34:49]
	s_waitcnt lgkmcnt(9)
	v_mfma_f32_32x32x16_bf16 v[50:65], v[224:227], v[236:239], v[50:65]
	s_waitcnt lgkmcnt(8)
	v_mfma_f32_32x32x16_bf16 v[2:17], v[228:231], v[232:235], v[2:17]
	v_mfma_f32_32x32x16_bf16 v[18:33], v[228:231], v[236:239], v[18:33]
	s_waitcnt lgkmcnt(7)
	v_mfma_f32_32x32x16_bf16 v[74:89], v[224:227], v[240:243], v[74:89]
	s_waitcnt lgkmcnt(6)
	v_mfma_f32_32x32x16_bf16 v[90:105], v[224:227], v[244:247], v[90:105]
	v_mfma_f32_32x32x16_bf16 v[106:121], v[228:231], v[240:243], v[106:121]
	v_mfma_f32_32x32x16_bf16 v[208:223], v[228:231], v[244:247], v[208:223]
	s_waitcnt lgkmcnt(4)
	v_mfma_f32_32x32x16_bf16 v[34:49], v[248:251], v[160:163], v[34:49]
	s_waitcnt lgkmcnt(3)
	v_mfma_f32_32x32x16_bf16 v[50:65], v[248:251], v[164:167], v[50:65]
	s_waitcnt lgkmcnt(2)
	v_mfma_f32_32x32x16_bf16 v[2:17], v[156:159], v[160:163], v[2:17]
	v_mfma_f32_32x32x16_bf16 v[18:33], v[156:159], v[164:167], v[18:33]
	s_waitcnt lgkmcnt(1)
	v_mfma_f32_32x32x16_bf16 v[74:89], v[248:251], v[168:171], v[74:89]
	s_waitcnt lgkmcnt(0)
	v_mfma_f32_32x32x16_bf16 v[90:105], v[248:251], v[122:125], v[90:105]
	v_mfma_f32_32x32x16_bf16 v[106:121], v[156:159], v[168:171], v[106:121]
	v_mfma_f32_32x32x16_bf16 v[208:223], v[156:159], v[122:125], v[208:223]
	s_setprio 0
	s_waitcnt vmcnt(6)
	s_barrier
	s_setprio 1
	ds_read_b128 v[224:227], v126 offset:49152
	ds_read_b128 v[232:235], v128 offset:49152
	ds_read_b128 v[236:239], v128 offset:51200
	ds_read_b128 v[228:231], v126 offset:51200
	ds_read_b128 v[240:243], v128 offset:57344
	ds_read_b128 v[244:247], v128 offset:59392
	ds_read_b128 v[248:251], v127 offset:49152
	ds_read_b128 v[160:163], v129 offset:49152
	ds_read_b128 v[164:167], v129 offset:51200
	ds_read_b128 v[156:159], v127 offset:51200
	ds_read_b128 v[168:171], v129 offset:57344
	ds_read_b128 v[122:125], v129 offset:59392
	s_add_u32 m0, s16, 0x6000
	s_add_u32 s42, s42, 0x100000
	s_addc_u32 s43, s43, 0
	global_load_lds_dwordx4 v137, s[42:43]
	global_load_lds_dwordx4 v150, s[42:43] offset:1024
	s_add_u32 m0, s0, 0x6000
	s_add_u32 s30, s30, 0x10000
	s_addc_u32 s31, s31, 0
	global_load_lds_dwordx4 v151, s[30:31]
	global_load_lds_dwordx4 v152, s[30:31] offset:1024
	global_load_lds_dwordx4 v153, s[30:31] offset:2048
	global_load_lds_dwordx4 v154, s[30:31] offset:3072
	s_waitcnt lgkmcnt(10)
	v_mfma_f32_32x32x16_bf16 v[34:49], v[224:227], v[232:235], v[34:49]
	s_waitcnt lgkmcnt(9)
	v_mfma_f32_32x32x16_bf16 v[50:65], v[224:227], v[236:239], v[50:65]
	s_waitcnt lgkmcnt(8)
	v_mfma_f32_32x32x16_bf16 v[2:17], v[228:231], v[232:235], v[2:17]
	v_mfma_f32_32x32x16_bf16 v[18:33], v[228:231], v[236:239], v[18:33]
	s_waitcnt lgkmcnt(7)
	v_mfma_f32_32x32x16_bf16 v[74:89], v[224:227], v[240:243], v[74:89]
	s_waitcnt lgkmcnt(6)
	v_mfma_f32_32x32x16_bf16 v[90:105], v[224:227], v[244:247], v[90:105]
	v_mfma_f32_32x32x16_bf16 v[106:121], v[228:231], v[240:243], v[106:121]
	v_mfma_f32_32x32x16_bf16 v[208:223], v[228:231], v[244:247], v[208:223]
	s_waitcnt lgkmcnt(4)
	v_mfma_f32_32x32x16_bf16 v[34:49], v[248:251], v[160:163], v[34:49]
	s_waitcnt lgkmcnt(3)
	v_mfma_f32_32x32x16_bf16 v[50:65], v[248:251], v[164:167], v[50:65]
	s_waitcnt lgkmcnt(2)
	v_mfma_f32_32x32x16_bf16 v[2:17], v[156:159], v[160:163], v[2:17]
	v_mfma_f32_32x32x16_bf16 v[18:33], v[156:159], v[164:167], v[18:33]
	s_waitcnt lgkmcnt(1)
	v_mfma_f32_32x32x16_bf16 v[74:89], v[248:251], v[168:171], v[74:89]
	s_waitcnt lgkmcnt(0)
	v_mfma_f32_32x32x16_bf16 v[90:105], v[248:251], v[122:125], v[90:105]
	v_mfma_f32_32x32x16_bf16 v[106:121], v[156:159], v[168:171], v[106:121]
	v_mfma_f32_32x32x16_bf16 v[208:223], v[156:159], v[122:125], v[208:223]
	s_setprio 0
	s_waitcnt vmcnt(6)
	s_barrier
; #define BLOAD(A_, B_, kt) do { _Pragma("unroll") for (int i = 0; i < 4; ++i) { \
;     A_[i] = *(const u32x4*)((const char*)Ap + (aoff + (unsigned)(32 * i * lda + (kt) * 64) * 2u)); B_[i] = *(const u32x4*)((const char*)Wt + (woff + (unsigned)(32 * i * K + (kt) * 64) * 2u)); } } while (0)
; #define BLOAD(A_, B_, kt) do { _Pragma("unroll") for (int i = 0; i < 4; ++i) { \
;     A_[i] = *(const u32x4*)((const char*)Ap + (aoff + (unsigned)(32 * i * lda + (kt) * 64) * 2u)); B_[i] = *(const u32x4*)((const char*)Wt + (woff + (unsigned)(32 * i * K + (kt) * 64) * 2u)); } } while (0)
; #define BSTORE(A_, B_, buf) do { _Pragma("unroll") for (int i = 0; i < 4; ++i) { \
;     *(u32x4*)&As[(buf) * GBUF + (srow + 32 * i) * LDT + sc8] = A_[i]; \
;     *(u32x4*)&Bs[(buf) * GBUF + (srow + 32 * i) * LDT + sc8] = B_[i]; } } while (0)
; template <int NK>
; DI void gemm_run(PF& pf, const u16* __restrict__ Ap, int lda, const u16* __restrict__ Wt, f32x16 (&acc)[2][2], char* smem) {
;     ...
;   __builtin_amdgcn_s_setprio(0);
;   __syncthreads();
;   BSTORE(pf.a0, pf.b0, 0);
;   BLOAD(pf.a0, pf.b0, 2);
;   __syncthreads();
; #pragma unroll
;   for (int kt = 0; kt < nk; kt += 2) {
;     BCOMP(0);
;     BSTORE(pf.a1, pf.b1, 1);
;     if (kt + 3 < nk) BLOAD(pf.a1, pf.b1, kt + 3);
;     __syncthreads();
;     BCOMP(1);
;     if (kt + 2 < nk) { BSTORE(pf.a0, pf.b0, 0); if (kt + 4 < nk) BLOAD(pf.a0, pf.b0, kt + 4); }
;     __syncthreads();
;   }
	s_setprio 1
	ds_read_b128 v[224:227], v126 offset:0
	ds_read_b128 v[232:235], v128 offset:0
	ds_read_b128 v[236:239], v128 offset:2048
	ds_read_b128 v[228:231], v126 offset:2048
	ds_read_b128 v[240:243], v128 offset:8192
	ds_read_b128 v[244:247], v128 offset:10240
	ds_read_b128 v[248:251], v127 offset:0
	ds_read_b128 v[160:163], v129 offset:0
	ds_read_b128 v[164:167], v129 offset:2048
	ds_read_b128 v[156:159], v127 offset:2048
	ds_read_b128 v[168:171], v129 offset:8192
	ds_read_b128 v[122:125], v129 offset:10240
	s_add_u32 m0, s16, 0xc000
	s_add_u32 s42, s42, 0x100000
	s_addc_u32 s43, s43, 0
	global_load_lds_dwordx4 v137, s[42:43]
	global_load_lds_dwordx4 v150, s[42:43] offset:1024
	s_add_u32 m0, s0, 0xc000
	s_add_u32 s30, s30, 0x10000
	s_addc_u32 s31, s31, 0
	global_load_lds_dwordx4 v151, s[30:31]
	global_load_lds_dwordx4 v152, s[30:31] offset:1024
	global_load_lds_dwordx4 v153, s[30:31] offset:2048
	global_load_lds_dwordx4 v154, s[30:31] offset:3072
	s_waitcnt lgkmcnt(10)
	v_mfma_f32_32x32x16_bf16 v[34:49], v[224:227], v[232:235], v[34:49]
	s_waitcnt lgkmcnt(9)
	v_mfma_f32_32x32x16_bf16 v[50:65], v[224:227], v[236:239], v[50:65]
	s_waitcnt lgkmcnt(8)
	v_mfma_f32_32x32x16_bf16 v[2:17], v[228:231], v[232:235], v[2:17]
	v_mfma_f32_32x32x16_bf16 v[18:33], v[228:231], v[236:239], v[18:33]
	s_waitcnt lgkmcnt(7)
	v_mfma_f32_32x32x16_bf16 v[74:89], v[224:227], v[240:243], v[74:89]
	s_waitcnt lgkmcnt(6)
	v_mfma_f32_32x32x16_bf16 v[90:105], v[224:227], v[244:247], v[90:105]
	v_mfma_f32_32x32x16_bf16 v[106:121], v[228:231], v[240:243], v[106:121]
	v_mfma_f32_32x32x16_bf16 v[208:223], v[228:231], v[244:247], v[208:223]
	s_waitcnt lgkmcnt(4)
	v_mfma_f32_32x32x16_bf16 v[34:49], v[248:251], v[160:163], v[34:49]
	s_waitcnt lgkmcnt(3)
	v_mfma_f32_32x32x16_bf16 v[50:65], v[248:251], v[164:167], v[50:65]
	s_waitcnt lgkmcnt(2)
	v_mfma_f32_32x32x16_bf16 v[2:17], v[156:159], v[160:163], v[2:17]
	v_mfma_f32_32x32x16_bf16 v[18:33], v[156:159], v[164:167], v[18:33]
	s_waitcnt lgkmcnt(1)
	v_mfma_f32_32x32x16_bf16 v[74:89], v[248:251], v[168:171], v[74:89]
	s_waitcnt lgkmcnt(0)
	v_mfma_f32_32x32x16_bf16 v[90:105], v[248:251], v[122:125], v[90:105]
	v_mfma_f32_32x32x16_bf16 v[106:121], v[156:159], v[168:171], v[106:121]
	v_mfma_f32_32x32x16_bf16 v[208:223], v[156:159], v[122:125], v[208:223]
	s_setprio 0
	s_waitcnt vmcnt(6)
	s_barrier
	s_setprio 1
	ds_read_b128 v[224:227], v126 offset:24576
	ds_read_b128 v[232:235], v128 offset:24576
	ds_read_b128 v[236:239], v128 offset:26624
	ds_read_b128 v[228:231], v126 offset:26624
	ds_read_b128 v[240:243], v128 offset:32768
	ds_read_b128 v[244:247], v128 offset:34816
	ds_read_b128 v[248:251], v127 offset:24576
	ds_read_b128 v[160:163], v129 offset:24576
	ds_read_b128 v[164:167], v129 offset:26624
	ds_read_b128 v[156:159], v127 offset:26624
	ds_read_b128 v[168:171], v129 offset:32768
	ds_read_b128 v[122:125], v129 offset:34816
	s_add_u32 m0, s16, 0x0
	s_add_u32 s42, s42, 0x100000
	s_addc_u32 s43, s43, 0
	global_load_lds_dwordx4 v137, s[42:43]
	global_load_lds_dwordx4 v150, s[42:43] offset:1024
	s_add_u32 m0, s0, 0x0
	s_add_u32 s30, s30, 0x10000
	s_addc_u32 s31, s31, 0
	global_load_lds_dwordx4 v151, s[30:31]
	global_load_lds_dwordx4 v152, s[30:31] offset:1024
	global_load_lds_dwordx4 v153, s[30:31] offset:2048
	global_load_lds_dwordx4 v154, s[30:31] offset:3072
	s_waitcnt lgkmcnt(10)
	v_mfma_f32_32x32x16_bf16 v[34:49], v[224:227], v[232:235], v[34:49]
	s_waitcnt lgkmcnt(9)
	v_mfma_f32_32x32x16_bf16 v[50:65], v[224:227], v[236:239], v[50:65]
	s_waitcnt lgkmcnt(8)
	v_mfma_f32_32x32x16_bf16 v[2:17], v[228:231], v[232:235], v[2:17]
	v_mfma_f32_32x32x16_bf16 v[18:33], v[228:231], v[236:239], v[18:33]
	s_waitcnt lgkmcnt(7)
	v_mfma_f32_32x32x16_bf16 v[74:89], v[224:227], v[240:243], v[74:89]
	s_waitcnt lgkmcnt(6)
	v_mfma_f32_32x32x16_bf16 v[90:105], v[224:227], v[244:247], v[90:105]
	v_mfma_f32_32x32x16_bf16 v[106:121], v[228:231], v[240:243], v[106:121]
	v_mfma_f32_32x32x16_bf16 v[208:223], v[228:231], v[244:247], v[208:223]
	s_waitcnt lgkmcnt(4)
	v_mfma_f32_32x32x16_bf16 v[34:49], v[248:251], v[160:163], v[34:49]
	s_waitcnt lgkmcnt(3)
	v_mfma_f32_32x32x16_bf16 v[50:65], v[248:251], v[164:167], v[50:65]
	s_waitcnt lgkmcnt(2)
	v_mfma_f32_32x32x16_bf16 v[2:17], v[156:159], v[160:163], v[2:17]
	v_mfma_f32_32x32x16_bf16 v[18:33], v[156:159], v[164:167], v[18:33]
	s_waitcnt lgkmcnt(1)
	v_mfma_f32_32x32x16_bf16 v[74:89], v[248:251], v[168:171], v[74:89]
	s_waitcnt lgkmcnt(0)
	v_mfma_f32_32x32x16_bf16 v[90:105], v[248:251], v[122:125], v[90:105]
	v_mfma_f32_32x32x16_bf16 v[106:121], v[156:159], v[168:171], v[106:121]
	v_mfma_f32_32x32x16_bf16 v[208:223], v[156:159], v[122:125], v[208:223]
	s_setprio 0
	s_waitcnt vmcnt(6)
	s_barrier
; #define BLOAD(A_, B_, kt) do { _Pragma("unroll") for (int i = 0; i < 4; ++i) { \
;     A_[i] = *(const u32x4*)((const char*)Ap + (aoff + (unsigned)(32 * i * lda + (kt) * 64) * 2u)); B_[i] = *(const u32x4*)((const char*)Wt + (woff + (unsigned)(32 * i * K + (kt) * 64) * 2u)); } } while (0)
; #define BLOAD(A_, B_, kt) do { _Pragma("unroll") for (int i = 0; i < 4; ++i) { \
;     A_[i] = *(const u32x4*)((const char*)Ap + (aoff + (unsigned)(32 * i * lda + (kt) * 64) * 2u)); B_[i] = *(const u32x4*)((const char*)Wt + (woff + (unsigned)(32 * i * K + (kt) * 64) * 2u)); } } while (0)
; #define BSTORE(A_, B_, buf) do { _Pragma("unroll") for (int i = 0; i < 4; ++i) { \
;     *(u32x4*)&As[(buf) * GBUF + (srow + 32 * i) * LDT + sc8] = A_[i]; \
;     *(u32x4*)&Bs[(buf) * GBUF + (srow + 32 * i) * LDT + sc8] = B_[i]; } } while (0)
; template <int NK>
; DI void gemm_run(PF& pf, const u16* __restrict__ Ap, int lda, const u16* __restrict__ Wt, f32x16 (&acc)[2][2], char* smem) {
;     ...
;   __builtin_amdgcn_s_setprio(0);
;   __syncthreads();
;   BSTORE(pf.a0, pf.b0, 0);
;   BLOAD(pf.a0, pf.b0, 2);
;   __syncthreads();
; #pragma unroll
;   for (int kt = 0; kt < nk; kt += 2) {
;     BCOMP(0);
;     BSTORE(pf.a1, pf.b1, 1);
;     if (kt + 3 < nk) BLOAD(pf.a1, pf.b1, kt + 3);
;     __syncthreads();
;     BCOMP(1);
;     if (kt + 2 < nk) { BSTORE(pf.a0, pf.b0, 0); if (kt + 4 < nk) BLOAD(pf.a0, pf.b0, kt + 4); }
;     __syncthreads();
;   }
	s_setprio 1
	ds_read_b128 v[224:227], v126 offset:49152
	ds_read_b128 v[232:235], v128 offset:49152
	ds_read_b128 v[236:239], v128 offset:51200
	ds_read_b128 v[228:231], v126 offset:51200
	ds_read_b128 v[240:243], v128 offset:57344
	ds_read_b128 v[244:247], v128 offset:59392
	ds_read_b128 v[248:251], v127 offset:49152
	ds_read_b128 v[160:163], v129 offset:49152
	ds_read_b128 v[164:167], v129 offset:51200
	ds_read_b128 v[156:159], v127 offset:51200
	ds_read_b128 v[168:171], v129 offset:57344
	ds_read_b128 v[122:125], v129 offset:59392
	s_add_u32 m0, s16, 0x6000
	s_add_u32 s42, s42, 0x100000
	s_addc_u32 s43, s43, 0
	global_load_lds_dwordx4 v137, s[42:43]
	global_load_lds_dwordx4 v150, s[42:43] offset:1024
	s_add_u32 m0, s0, 0x6000
	s_add_u32 s30, s30, 0x10000
	s_addc_u32 s31, s31, 0
	global_load_lds_dwordx4 v151, s[30:31]
	global_load_lds_dwordx4 v152, s[30:31] offset:1024
	global_load_lds_dwordx4 v153, s[30:31] offset:2048
	global_load_lds_dwordx4 v154, s[30:31] offset:3072
	s_waitcnt lgkmcnt(10)
	v_mfma_f32_32x32x16_bf16 v[34:49], v[224:227], v[232:235], v[34:49]
	s_waitcnt lgkmcnt(9)
	v_mfma_f32_32x32x16_bf16 v[50:65], v[224:227], v[236:239], v[50:65]
	s_waitcnt lgkmcnt(8)
	v_mfma_f32_32x32x16_bf16 v[2:17], v[228:231], v[232:235], v[2:17]
	v_mfma_f32_32x32x16_bf16 v[18:33], v[228:231], v[236:239], v[18:33]
	s_waitcnt lgkmcnt(7)
	v_mfma_f32_32x32x16_bf16 v[74:89], v[224:227], v[240:243], v[74:89]
	s_waitcnt lgkmcnt(6)
	v_mfma_f32_32x32x16_bf16 v[90:105], v[224:227], v[244:247], v[90:105]
	v_mfma_f32_32x32x16_bf16 v[106:121], v[228:231], v[240:243], v[106:121]
	v_mfma_f32_32x32x16_bf16 v[208:223], v[228:231], v[244:247], v[208:223]
	s_waitcnt lgkmcnt(4)
	v_mfma_f32_32x32x16_bf16 v[34:49], v[248:251], v[160:163], v[34:49]
	s_waitcnt lgkmcnt(3)
	v_mfma_f32_32x32x16_bf16 v[50:65], v[248:251], v[164:167], v[50:65]
	s_waitcnt lgkmcnt(2)
	v_mfma_f32_32x32x16_bf16 v[2:17], v[156:159], v[160:163], v[2:17]
	v_mfma_f32_32x32x16_bf16 v[18:33], v[156:159], v[164:167], v[18:33]
	s_waitcnt lgkmcnt(1)
	v_mfma_f32_32x32x16_bf16 v[74:89], v[248:251], v[168:171], v[74:89]
	s_waitcnt lgkmcnt(0)
	v_mfma_f32_32x32x16_bf16 v[90:105], v[248:251], v[122:125], v[90:105]
	v_mfma_f32_32x32x16_bf16 v[106:121], v[156:159], v[168:171], v[106:121]
	v_mfma_f32_32x32x16_bf16 v[208:223], v[156:159], v[122:125], v[208:223]
	s_setprio 0
	s_waitcnt vmcnt(6)
	s_barrier
	s_setprio 1
	ds_read_b128 v[224:227], v126 offset:0
	ds_read_b128 v[232:235], v128 offset:0
	ds_read_b128 v[236:239], v128 offset:2048
	ds_read_b128 v[228:231], v126 offset:2048
	ds_read_b128 v[240:243], v128 offset:8192
	ds_read_b128 v[244:247], v128 offset:10240
	ds_read_b128 v[248:251], v127 offset:0
	ds_read_b128 v[160:163], v129 offset:0
	ds_read_b128 v[164:167], v129 offset:2048
	ds_read_b128 v[156:159], v127 offset:2048
	ds_read_b128 v[168:171], v129 offset:8192
	ds_read_b128 v[122:125], v129 offset:10240
	s_add_u32 m0, s16, 0xc000
	s_add_u32 s42, s42, 0x100000
	s_addc_u32 s43, s43, 0
	global_load_lds_dwordx4 v137, s[42:43]
	global_load_lds_dwordx4 v150, s[42:43] offset:1024
	s_add_u32 m0, s0, 0xc000
	s_add_u32 s30, s30, 0x10000
	s_addc_u32 s31, s31, 0
	global_load_lds_dwordx4 v151, s[30:31]
	global_load_lds_dwordx4 v152, s[30:31] offset:1024
	global_load_lds_dwordx4 v153, s[30:31] offset:2048
	global_load_lds_dwordx4 v154, s[30:31] offset:3072
	s_waitcnt lgkmcnt(10)
	v_mfma_f32_32x32x16_bf16 v[34:49], v[224:227], v[232:235], v[34:49]
	s_waitcnt lgkmcnt(9)
	v_mfma_f32_32x32x16_bf16 v[50:65], v[224:227], v[236:239], v[50:65]
	s_waitcnt lgkmcnt(8)
	v_mfma_f32_32x32x16_bf16 v[2:17], v[228:231], v[232:235], v[2:17]
	v_mfma_f32_32x32x16_bf16 v[18:33], v[228:231], v[236:239], v[18:33]
	s_waitcnt lgkmcnt(7)
	v_mfma_f32_32x32x16_bf16 v[74:89], v[224:227], v[240:243], v[74:89]
	s_waitcnt lgkmcnt(6)
	v_mfma_f32_32x32x16_bf16 v[90:105], v[224:227], v[244:247], v[90:105]
	v_mfma_f32_32x32x16_bf16 v[106:121], v[228:231], v[240:243], v[106:121]
	v_mfma_f32_32x32x16_bf16 v[208:223], v[228:231], v[244:247], v[208:223]
	s_waitcnt lgkmcnt(4)
	v_mfma_f32_32x32x16_bf16 v[34:49], v[248:251], v[160:163], v[34:49]
	s_waitcnt lgkmcnt(3)
	v_mfma_f32_32x32x16_bf16 v[50:65], v[248:251], v[164:167], v[50:65]
	s_waitcnt lgkmcnt(2)
	v_mfma_f32_32x32x16_bf16 v[2:17], v[156:159], v[160:163], v[2:17]
	v_mfma_f32_32x32x16_bf16 v[18:33], v[156:159], v[164:167], v[18:33]
	s_waitcnt lgkmcnt(1)
	v_mfma_f32_32x32x16_bf16 v[74:89], v[248:251], v[168:171], v[74:89]
	s_waitcnt lgkmcnt(0)
	v_mfma_f32_32x32x16_bf16 v[90:105], v[248:251], v[122:125], v[90:105]
	v_mfma_f32_32x32x16_bf16 v[106:121], v[156:159], v[168:171], v[106:121]
	v_mfma_f32_32x32x16_bf16 v[208:223], v[156:159], v[122:125], v[208:223]
	s_setprio 0
	s_waitcnt vmcnt(6)
	s_barrier
; #define BLOAD(A_, B_, kt) do { _Pragma("unroll") for (int i = 0; i < 4; ++i) { \
;     A_[i] = *(const u32x4*)((const char*)Ap + (aoff + (unsigned)(32 * i * lda + (kt) * 64) * 2u)); B_[i] = *(const u32x4*)((const char*)Wt + (woff + (unsigned)(32 * i * K + (kt) * 64) * 2u)); } } while (0)
; #define BLOAD(A_, B_, kt) do { _Pragma("unroll") for (int i = 0; i < 4; ++i) { \
;     A_[i] = *(const u32x4*)((const char*)Ap + (aoff + (unsigned)(32 * i * lda + (kt) * 64) * 2u)); B_[i] = *(const u32x4*)((const char*)Wt + (woff + (unsigned)(32 * i * K + (kt) * 64) * 2u)); } } while (0)
; #define BSTORE(A_, B_, buf) do { _Pragma("unroll") for (int i = 0; i < 4; ++i) { \
;     *(u32x4*)&As[(buf) * GBUF + (srow + 32 * i) * LDT + sc8] = A_[i]; \
;     *(u32x4*)&Bs[(buf) * GBUF + (srow + 32 * i) * LDT + sc8] = B_[i]; } } while (0)
; template <int NK>
; DI void gemm_run(PF& pf, const u16* __restrict__ Ap, int lda, const u16* __restrict__ Wt, f32x16 (&acc)[2][2], char* smem) {
;     ...
;   __builtin_amdgcn_s_setprio(0);
;   __syncthreads();
;   BSTORE(pf.a0, pf.b0, 0);
;   BLOAD(pf.a0, pf.b0, 2);
;   __syncthreads();
; #pragma unroll
;   for (int kt = 0; kt < nk; kt += 2) {
;     BCOMP(0);
;     BSTORE(pf.a1, pf.b1, 1);
;     if (kt + 3 < nk) BLOAD(pf.a1, pf.b1, kt + 3);
;     __syncthreads();
;     BCOMP(1);
;     if (kt + 2 < nk) { BSTORE(pf.a0, pf.b0, 0); if (kt + 4 < nk) BLOAD(pf.a0, pf.b0, kt + 4); }
;     __syncthreads();
;   }
	s_setprio 1
	ds_read_b128 v[224:227], v126 offset:24576
	ds_read_b128 v[232:235], v128 offset:24576
	ds_read_b128 v[236:239], v128 offset:26624
	ds_read_b128 v[228:231], v126 offset:26624
	ds_read_b128 v[240:243], v128 offset:32768
	ds_read_b128 v[244:247], v128 offset:34816
	ds_read_b128 v[248:251], v127 offset:24576
	ds_read_b128 v[160:163], v129 offset:24576
	ds_read_b128 v[164:167], v129 offset:26624
	ds_read_b128 v[156:159], v127 offset:26624
	ds_read_b128 v[168:171], v129 offset:32768
	ds_read_b128 v[122:125], v129 offset:34816
	s_add_u32 m0, s16, 0x0
	s_add_u32 s42, s42, 0x100000
	s_addc_u32 s43, s43, 0
	global_load_lds_dwordx4 v137, s[42:43]
	global_load_lds_dwordx4 v150, s[42:43] offset:1024
	s_add_u32 m0, s0, 0x0
	s_add_u32 s30, s30, 0x10000
	s_addc_u32 s31, s31, 0
	global_load_lds_dwordx4 v151, s[30:31]
	global_load_lds_dwordx4 v152, s[30:31] offset:1024
	global_load_lds_dwordx4 v153, s[30:31] offset:2048
	global_load_lds_dwordx4 v154, s[30:31] offset:3072
	s_waitcnt lgkmcnt(10)
	v_mfma_f32_32x32x16_bf16 v[34:49], v[224:227], v[232:235], v[34:49]
	s_waitcnt lgkmcnt(9)
	v_mfma_f32_32x32x16_bf16 v[50:65], v[224:227], v[236:239], v[50:65]
	s_waitcnt lgkmcnt(8)
	v_mfma_f32_32x32x16_bf16 v[2:17], v[228:231], v[232:235], v[2:17]
	v_mfma_f32_32x32x16_bf16 v[18:33], v[228:231], v[236:239], v[18:33]
	s_waitcnt lgkmcnt(7)
	v_mfma_f32_32x32x16_bf16 v[74:89], v[224:227], v[240:243], v[74:89]
	s_waitcnt lgkmcnt(6)
	v_mfma_f32_32x32x16_bf16 v[90:105], v[224:227], v[244:247], v[90:105]
	v_mfma_f32_32x32x16_bf16 v[106:121], v[228:231], v[240:243], v[106:121]
	v_mfma_f32_32x32x16_bf16 v[208:223], v[228:231], v[244:247], v[208:223]
	s_waitcnt lgkmcnt(4)
	v_mfma_f32_32x32x16_bf16 v[34:49], v[248:251], v[160:163], v[34:49]
	s_waitcnt lgkmcnt(3)
	v_mfma_f32_32x32x16_bf16 v[50:65], v[248:251], v[164:167], v[50:65]
	s_waitcnt lgkmcnt(2)
	v_mfma_f32_32x32x16_bf16 v[2:17], v[156:159], v[160:163], v[2:17]
	v_mfma_f32_32x32x16_bf16 v[18:33], v[156:159], v[164:167], v[18:33]
	s_waitcnt lgkmcnt(1)
	v_mfma_f32_32x32x16_bf16 v[74:89], v[248:251], v[168:171], v[74:89]
	s_waitcnt lgkmcnt(0)
	v_mfma_f32_32x32x16_bf16 v[90:105], v[248:251], v[122:125], v[90:105]
	v_mfma_f32_32x32x16_bf16 v[106:121], v[156:159], v[168:171], v[106:121]
	v_mfma_f32_32x32x16_bf16 v[208:223], v[156:159], v[122:125], v[208:223]
	s_setprio 0
	s_waitcnt vmcnt(6)
	s_barrier
	s_setprio 1
	ds_read_b128 v[224:227], v126 offset:49152
	ds_read_b128 v[232:235], v128 offset:49152
	ds_read_b128 v[236:239], v128 offset:51200
	ds_read_b128 v[228:231], v126 offset:51200
	ds_read_b128 v[240:243], v128 offset:57344
	ds_read_b128 v[244:247], v128 offset:59392
	ds_read_b128 v[248:251], v127 offset:49152
	ds_read_b128 v[160:163], v129 offset:49152
	ds_read_b128 v[164:167], v129 offset:51200
	ds_read_b128 v[156:159], v127 offset:51200
	ds_read_b128 v[168:171], v129 offset:57344
	ds_read_b128 v[122:125], v129 offset:59392
	s_add_u32 m0, s16, 0x6000
	s_add_u32 s42, s42, 0x100000
	s_addc_u32 s43, s43, 0
	global_load_lds_dwordx4 v137, s[42:43]
	global_load_lds_dwordx4 v150, s[42:43] offset:1024
	s_add_u32 m0, s0, 0x6000
	s_add_u32 s30, s30, 0x10000
	s_addc_u32 s31, s31, 0
	global_load_lds_dwordx4 v151, s[30:31]
	global_load_lds_dwordx4 v152, s[30:31] offset:1024
	global_load_lds_dwordx4 v153, s[30:31] offset:2048
	global_load_lds_dwordx4 v154, s[30:31] offset:3072
	s_waitcnt lgkmcnt(10)
	v_mfma_f32_32x32x16_bf16 v[34:49], v[224:227], v[232:235], v[34:49]
	s_waitcnt lgkmcnt(9)
	v_mfma_f32_32x32x16_bf16 v[50:65], v[224:227], v[236:239], v[50:65]
	s_waitcnt lgkmcnt(8)
	v_mfma_f32_32x32x16_bf16 v[2:17], v[228:231], v[232:235], v[2:17]
	v_mfma_f32_32x32x16_bf16 v[18:33], v[228:231], v[236:239], v[18:33]
	s_waitcnt lgkmcnt(7)
	v_mfma_f32_32x32x16_bf16 v[74:89], v[224:227], v[240:243], v[74:89]
	s_waitcnt lgkmcnt(6)
	v_mfma_f32_32x32x16_bf16 v[90:105], v[224:227], v[244:247], v[90:105]
	v_mfma_f32_32x32x16_bf16 v[106:121], v[228:231], v[240:243], v[106:121]
	v_mfma_f32_32x32x16_bf16 v[208:223], v[228:231], v[244:247], v[208:223]
	s_waitcnt lgkmcnt(4)
	v_mfma_f32_32x32x16_bf16 v[34:49], v[248:251], v[160:163], v[34:49]
	s_waitcnt lgkmcnt(3)
	v_mfma_f32_32x32x16_bf16 v[50:65], v[248:251], v[164:167], v[50:65]
	s_waitcnt lgkmcnt(2)
	v_mfma_f32_32x32x16_bf16 v[2:17], v[156:159], v[160:163], v[2:17]
	v_mfma_f32_32x32x16_bf16 v[18:33], v[156:159], v[164:167], v[18:33]
	s_waitcnt lgkmcnt(1)
	v_mfma_f32_32x32x16_bf16 v[74:89], v[248:251], v[168:171], v[74:89]
	s_waitcnt lgkmcnt(0)
	v_mfma_f32_32x32x16_bf16 v[90:105], v[248:251], v[122:125], v[90:105]
	v_mfma_f32_32x32x16_bf16 v[106:121], v[156:159], v[168:171], v[106:121]
	v_mfma_f32_32x32x16_bf16 v[208:223], v[156:159], v[122:125], v[208:223]
	s_setprio 0
	s_waitcnt vmcnt(6)
	s_barrier
; #define BLOAD(A_, B_, kt) do { _Pragma("unroll") for (int i = 0; i < 4; ++i) { \
;     A_[i] = *(const u32x4*)((const char*)Ap + (aoff + (unsigned)(32 * i * lda + (kt) * 64) * 2u)); B_[i] = *(const u32x4*)((const char*)Wt + (woff + (unsigned)(32 * i * K + (kt) * 64) * 2u)); } } while (0)
; #define BLOAD(A_, B_, kt) do { _Pragma("unroll") for (int i = 0; i < 4; ++i) { \
;     A_[i] = *(const u32x4*)((const char*)Ap + (aoff + (unsigned)(32 * i * lda + (kt) * 64) * 2u)); B_[i] = *(const u32x4*)((const char*)Wt + (woff + (unsigned)(32 * i * K + (kt) * 64) * 2u)); } } while (0)
; #define BSTORE(A_, B_, buf) do { _Pragma("unroll") for (int i = 0; i < 4; ++i) { \
;     *(u32x4*)&As[(buf) * GBUF + (srow + 32 * i) * LDT + sc8] = A_[i]; \
;     *(u32x4*)&Bs[(buf) * GBUF + (srow + 32 * i) * LDT + sc8] = B_[i]; } } while (0)
; template <int NK>
; DI void gemm_run(PF& pf, const u16* __restrict__ Ap, int lda, const u16* __restrict__ Wt, f32x16 (&acc)[2][2], char* smem) {
;     ...
;   __builtin_amdgcn_s_setprio(0);
;   __syncthreads();
;   BSTORE(pf.a0, pf.b0, 0);
;   BLOAD(pf.a0, pf.b0, 2);
;   __syncthreads();
; #pragma unroll
;   for (int kt = 0; kt < nk; kt += 2) {
;     BCOMP(0);
;     BSTORE(pf.a1, pf.b1, 1);
;     if (kt + 3 < nk) BLOAD(pf.a1, pf.b1, kt + 3);
;     __syncthreads();
;     BCOMP(1);
;     if (kt + 2 < nk) { BSTORE(pf.a0, pf.b0, 0); if (kt + 4 < nk) BLOAD(pf.a0, pf.b0, kt + 4); }
;     __syncthreads();
;   }
	s_setprio 1
	ds_read_b128 v[224:227], v126 offset:0
	ds_read_b128 v[232:235], v128 offset:0
	ds_read_b128 v[236:239], v128 offset:2048
	ds_read_b128 v[228:231], v126 offset:2048
	ds_read_b128 v[240:243], v128 offset:8192
	ds_read_b128 v[244:247], v128 offset:10240
	ds_read_b128 v[248:251], v127 offset:0
	ds_read_b128 v[160:163], v129 offset:0
	ds_read_b128 v[164:167], v129 offset:2048
	ds_read_b128 v[156:159], v127 offset:2048
	ds_read_b128 v[168:171], v129 offset:8192
	ds_read_b128 v[122:125], v129 offset:10240
	s_add_u32 m0, s16, 0xc000
	s_add_u32 s42, s42, 0x100000
	s_addc_u32 s43, s43, 0
	global_load_lds_dwordx4 v137, s[42:43]
	global_load_lds_dwordx4 v150, s[42:43] offset:1024
	s_add_u32 m0, s0, 0xc000
	s_add_u32 s30, s30, 0x10000
	s_addc_u32 s31, s31, 0
	global_load_lds_dwordx4 v151, s[30:31]
	global_load_lds_dwordx4 v152, s[30:31] offset:1024
	global_load_lds_dwordx4 v153, s[30:31] offset:2048
	global_load_lds_dwordx4 v154, s[30:31] offset:3072
	s_waitcnt lgkmcnt(10)
	v_mfma_f32_32x32x16_bf16 v[34:49], v[224:227], v[232:235], v[34:49]
	s_waitcnt lgkmcnt(9)
	v_mfma_f32_32x32x16_bf16 v[50:65], v[224:227], v[236:239], v[50:65]
	s_waitcnt lgkmcnt(8)
	v_mfma_f32_32x32x16_bf16 v[2:17], v[228:231], v[232:235], v[2:17]
	v_mfma_f32_32x32x16_bf16 v[18:33], v[228:231], v[236:239], v[18:33]
	s_waitcnt lgkmcnt(7)
	v_mfma_f32_32x32x16_bf16 v[74:89], v[224:227], v[240:243], v[74:89]
	s_waitcnt lgkmcnt(6)
	v_mfma_f32_32x32x16_bf16 v[90:105], v[224:227], v[244:247], v[90:105]
	v_mfma_f32_32x32x16_bf16 v[106:121], v[228:231], v[240:243], v[106:121]
	v_mfma_f32_32x32x16_bf16 v[208:223], v[228:231], v[244:247], v[208:223]
	s_waitcnt lgkmcnt(4)
	v_mfma_f32_32x32x16_bf16 v[34:49], v[248:251], v[160:163], v[34:49]
	s_waitcnt lgkmcnt(3)
	v_mfma_f32_32x32x16_bf16 v[50:65], v[248:251], v[164:167], v[50:65]
	s_waitcnt lgkmcnt(2)
	v_mfma_f32_32x32x16_bf16 v[2:17], v[156:159], v[160:163], v[2:17]
	v_mfma_f32_32x32x16_bf16 v[18:33], v[156:159], v[164:167], v[18:33]
	s_waitcnt lgkmcnt(1)
	v_mfma_f32_32x32x16_bf16 v[74:89], v[248:251], v[168:171], v[74:89]
	s_waitcnt lgkmcnt(0)
	v_mfma_f32_32x32x16_bf16 v[90:105], v[248:251], v[122:125], v[90:105]
	v_mfma_f32_32x32x16_bf16 v[106:121], v[156:159], v[168:171], v[106:121]
	v_mfma_f32_32x32x16_bf16 v[208:223], v[156:159], v[122:125], v[208:223]
	s_setprio 0
	s_waitcnt vmcnt(6)
	s_barrier
	s_setprio 1
	ds_read_b128 v[224:227], v126 offset:24576
	ds_read_b128 v[232:235], v128 offset:24576
	ds_read_b128 v[236:239], v128 offset:26624
	ds_read_b128 v[228:231], v126 offset:26624
	ds_read_b128 v[240:243], v128 offset:32768
	ds_read_b128 v[244:247], v128 offset:34816
	ds_read_b128 v[248:251], v127 offset:24576
	ds_read_b128 v[160:163], v129 offset:24576
	ds_read_b128 v[164:167], v129 offset:26624
	ds_read_b128 v[156:159], v127 offset:26624
	ds_read_b128 v[168:171], v129 offset:32768
	ds_read_b128 v[122:125], v129 offset:34816
	s_add_u32 m0, s16, 0x0
	s_add_u32 s42, s42, 0x100000
	s_addc_u32 s43, s43, 0
	global_load_lds_dwordx4 v137, s[42:43]
	global_load_lds_dwordx4 v150, s[42:43] offset:1024
	s_add_u32 m0, s0, 0x0
	s_add_u32 s30, s30, 0x10000
	s_addc_u32 s31, s31, 0
	global_load_lds_dwordx4 v151, s[30:31]
	global_load_lds_dwordx4 v152, s[30:31] offset:1024
	global_load_lds_dwordx4 v153, s[30:31] offset:2048
	global_load_lds_dwordx4 v154, s[30:31] offset:3072
	s_waitcnt lgkmcnt(10)
	v_mfma_f32_32x32x16_bf16 v[34:49], v[224:227], v[232:235], v[34:49]
	s_waitcnt lgkmcnt(9)
	v_mfma_f32_32x32x16_bf16 v[50:65], v[224:227], v[236:239], v[50:65]
	s_waitcnt lgkmcnt(8)
	v_mfma_f32_32x32x16_bf16 v[2:17], v[228:231], v[232:235], v[2:17]
	v_mfma_f32_32x32x16_bf16 v[18:33], v[228:231], v[236:239], v[18:33]
	s_waitcnt lgkmcnt(7)
	v_mfma_f32_32x32x16_bf16 v[74:89], v[224:227], v[240:243], v[74:89]
	s_waitcnt lgkmcnt(6)
	v_mfma_f32_32x32x16_bf16 v[90:105], v[224:227], v[244:247], v[90:105]
	v_mfma_f32_32x32x16_bf16 v[106:121], v[228:231], v[240:243], v[106:121]
	v_mfma_f32_32x32x16_bf16 v[208:223], v[228:231], v[244:247], v[208:223]
	s_waitcnt lgkmcnt(4)
	v_mfma_f32_32x32x16_bf16 v[34:49], v[248:251], v[160:163], v[34:49]
	s_waitcnt lgkmcnt(3)
	v_mfma_f32_32x32x16_bf16 v[50:65], v[248:251], v[164:167], v[50:65]
	s_waitcnt lgkmcnt(2)
	v_mfma_f32_32x32x16_bf16 v[2:17], v[156:159], v[160:163], v[2:17]
	v_mfma_f32_32x32x16_bf16 v[18:33], v[156:159], v[164:167], v[18:33]
	s_waitcnt lgkmcnt(1)
	v_mfma_f32_32x32x16_bf16 v[74:89], v[248:251], v[168:171], v[74:89]
	s_waitcnt lgkmcnt(0)
	v_mfma_f32_32x32x16_bf16 v[90:105], v[248:251], v[122:125], v[90:105]
	v_mfma_f32_32x32x16_bf16 v[106:121], v[156:159], v[168:171], v[106:121]
	v_mfma_f32_32x32x16_bf16 v[208:223], v[156:159], v[122:125], v[208:223]
	s_setprio 0
	s_waitcnt vmcnt(6)
	s_barrier
; #define BLOAD(A_, B_, kt) do { _Pragma("unroll") for (int i = 0; i < 4; ++i) { \
;     A_[i] = *(const u32x4*)((const char*)Ap + (aoff + (unsigned)(32 * i * lda + (kt) * 64) * 2u)); B_[i] = *(const u32x4*)((const char*)Wt + (woff + (unsigned)(32 * i * K + (kt) * 64) * 2u)); } } while (0)
; #define BLOAD(A_, B_, kt) do { _Pragma("unroll") for (int i = 0; i < 4; ++i) { \
;     A_[i] = *(const u32x4*)((const char*)Ap + (aoff + (unsigned)(32 * i * lda + (kt) * 64) * 2u)); B_[i] = *(const u32x4*)((const char*)Wt + (woff + (unsigned)(32 * i * K + (kt) * 64) * 2u)); } } while (0)
; #define BSTORE(A_, B_, buf) do { _Pragma("unroll") for (int i = 0; i < 4; ++i) { \
;     *(u32x4*)&As[(buf) * GBUF + (srow + 32 * i) * LDT + sc8] = A_[i]; \
;     *(u32x4*)&Bs[(buf) * GBUF + (srow + 32 * i) * LDT + sc8] = B_[i]; } } while (0)
; template <int NK>
; DI void gemm_run(PF& pf, const u16* __restrict__ Ap, int lda, const u16* __restrict__ Wt, f32x16 (&acc)[2][2], char* smem) {
;     ...
;   __builtin_amdgcn_s_setprio(0);
;   __syncthreads();
;   BSTORE(pf.a0, pf.b0, 0);
;   BLOAD(pf.a0, pf.b0, 2);
;   __syncthreads();
; #pragma unroll
;   for (int kt = 0; kt < nk; kt += 2) {
;     BCOMP(0);
;     BSTORE(pf.a1, pf.b1, 1);
;     if (kt + 3 < nk) BLOAD(pf.a1, pf.b1, kt + 3);
;     __syncthreads();
;     BCOMP(1);
;     if (kt + 2 < nk) { BSTORE(pf.a0, pf.b0, 0); if (kt + 4 < nk) BLOAD(pf.a0, pf.b0, kt + 4); }
;     __syncthreads();
;   }
	s_setprio 1
	ds_read_b128 v[224:227], v126 offset:49152
	ds_read_b128 v[232:235], v128 offset:49152
	ds_read_b128 v[236:239], v128 offset:51200
	ds_read_b128 v[228:231], v126 offset:51200
	ds_read_b128 v[240:243], v128 offset:57344
	ds_read_b128 v[244:247], v128 offset:59392
	ds_read_b128 v[248:251], v127 offset:49152
	ds_read_b128 v[160:163], v129 offset:49152
	ds_read_b128 v[164:167], v129 offset:51200
	ds_read_b128 v[156:159], v127 offset:51200
	ds_read_b128 v[168:171], v129 offset:57344
	ds_read_b128 v[122:125], v129 offset:59392
	s_add_u32 m0, s16, 0x6000
	s_add_u32 s42, s42, 0x100000
	s_addc_u32 s43, s43, 0
	global_load_lds_dwordx4 v137, s[42:43]
	global_load_lds_dwordx4 v150, s[42:43] offset:1024
	s_add_u32 m0, s0, 0x6000
	s_add_u32 s30, s30, 0x10000
	s_addc_u32 s31, s31, 0
	global_load_lds_dwordx4 v151, s[30:31]
	global_load_lds_dwordx4 v152, s[30:31] offset:1024
	global_load_lds_dwordx4 v153, s[30:31] offset:2048
	global_load_lds_dwordx4 v154, s[30:31] offset:3072
	s_waitcnt lgkmcnt(10)
	v_mfma_f32_32x32x16_bf16 v[34:49], v[224:227], v[232:235], v[34:49]
	s_waitcnt lgkmcnt(9)
	v_mfma_f32_32x32x16_bf16 v[50:65], v[224:227], v[236:239], v[50:65]
	s_waitcnt lgkmcnt(8)
	v_mfma_f32_32x32x16_bf16 v[2:17], v[228:231], v[232:235], v[2:17]
	v_mfma_f32_32x32x16_bf16 v[18:33], v[228:231], v[236:239], v[18:33]
	s_waitcnt lgkmcnt(7)
	v_mfma_f32_32x32x16_bf16 v[74:89], v[224:227], v[240:243], v[74:89]
	s_waitcnt lgkmcnt(6)
	v_mfma_f32_32x32x16_bf16 v[90:105], v[224:227], v[244:247], v[90:105]
	v_mfma_f32_32x32x16_bf16 v[106:121], v[228:231], v[240:243], v[106:121]
	v_mfma_f32_32x32x16_bf16 v[208:223], v[228:231], v[244:247], v[208:223]
	s_waitcnt lgkmcnt(4)
	v_mfma_f32_32x32x16_bf16 v[34:49], v[248:251], v[160:163], v[34:49]
	s_waitcnt lgkmcnt(3)
	v_mfma_f32_32x32x16_bf16 v[50:65], v[248:251], v[164:167], v[50:65]
	s_waitcnt lgkmcnt(2)
	v_mfma_f32_32x32x16_bf16 v[2:17], v[156:159], v[160:163], v[2:17]
	v_mfma_f32_32x32x16_bf16 v[18:33], v[156:159], v[164:167], v[18:33]
	s_waitcnt lgkmcnt(1)
	v_mfma_f32_32x32x16_bf16 v[74:89], v[248:251], v[168:171], v[74:89]
	s_waitcnt lgkmcnt(0)
	v_mfma_f32_32x32x16_bf16 v[90:105], v[248:251], v[122:125], v[90:105]
	v_mfma_f32_32x32x16_bf16 v[106:121], v[156:159], v[168:171], v[106:121]
	v_mfma_f32_32x32x16_bf16 v[208:223], v[156:159], v[122:125], v[208:223]
	s_setprio 0
	s_waitcnt vmcnt(6)
	s_barrier
	s_setprio 1
	ds_read_b128 v[224:227], v126 offset:0
	ds_read_b128 v[232:235], v128 offset:0
	ds_read_b128 v[236:239], v128 offset:2048
	ds_read_b128 v[228:231], v126 offset:2048
	ds_read_b128 v[240:243], v128 offset:8192
	ds_read_b128 v[244:247], v128 offset:10240
	ds_read_b128 v[248:251], v127 offset:0
	ds_read_b128 v[160:163], v129 offset:0
	ds_read_b128 v[164:167], v129 offset:2048
	ds_read_b128 v[156:159], v127 offset:2048
	ds_read_b128 v[168:171], v129 offset:8192
	ds_read_b128 v[122:125], v129 offset:10240
	s_add_u32 m0, s16, 0xc000
	s_add_u32 s42, s42, 0x100000
	s_addc_u32 s43, s43, 0
	global_load_lds_dwordx4 v137, s[42:43]
	global_load_lds_dwordx4 v150, s[42:43] offset:1024
	s_add_u32 m0, s0, 0xc000
	s_add_u32 s30, s30, 0x10000
	s_addc_u32 s31, s31, 0
	global_load_lds_dwordx4 v151, s[30:31]
	global_load_lds_dwordx4 v152, s[30:31] offset:1024
	global_load_lds_dwordx4 v153, s[30:31] offset:2048
	global_load_lds_dwordx4 v154, s[30:31] offset:3072
	s_waitcnt lgkmcnt(10)
	v_mfma_f32_32x32x16_bf16 v[34:49], v[224:227], v[232:235], v[34:49]
	s_waitcnt lgkmcnt(9)
	v_mfma_f32_32x32x16_bf16 v[50:65], v[224:227], v[236:239], v[50:65]
	s_waitcnt lgkmcnt(8)
	v_mfma_f32_32x32x16_bf16 v[2:17], v[228:231], v[232:235], v[2:17]
	v_mfma_f32_32x32x16_bf16 v[18:33], v[228:231], v[236:239], v[18:33]
	s_waitcnt lgkmcnt(7)
	v_mfma_f32_32x32x16_bf16 v[74:89], v[224:227], v[240:243], v[74:89]
	s_waitcnt lgkmcnt(6)
	v_mfma_f32_32x32x16_bf16 v[90:105], v[224:227], v[244:247], v[90:105]
	v_mfma_f32_32x32x16_bf16 v[106:121], v[228:231], v[240:243], v[106:121]
	v_mfma_f32_32x32x16_bf16 v[208:223], v[228:231], v[244:247], v[208:223]
	s_waitcnt lgkmcnt(4)
	v_mfma_f32_32x32x16_bf16 v[34:49], v[248:251], v[160:163], v[34:49]
	s_waitcnt lgkmcnt(3)
	v_mfma_f32_32x32x16_bf16 v[50:65], v[248:251], v[164:167], v[50:65]
	s_waitcnt lgkmcnt(2)
	v_mfma_f32_32x32x16_bf16 v[2:17], v[156:159], v[160:163], v[2:17]
	v_mfma_f32_32x32x16_bf16 v[18:33], v[156:159], v[164:167], v[18:33]
	s_waitcnt lgkmcnt(1)
	v_mfma_f32_32x32x16_bf16 v[74:89], v[248:251], v[168:171], v[74:89]
	s_waitcnt lgkmcnt(0)
	v_mfma_f32_32x32x16_bf16 v[90:105], v[248:251], v[122:125], v[90:105]
	v_mfma_f32_32x32x16_bf16 v[106:121], v[156:159], v[168:171], v[106:121]
	v_mfma_f32_32x32x16_bf16 v[208:223], v[156:159], v[122:125], v[208:223]
	s_setprio 0
	s_waitcnt vmcnt(6)
	s_barrier
; #define BLOAD(A_, B_, kt) do { _Pragma("unroll") for (int i = 0; i < 4; ++i) { \
;     A_[i] = *(const u32x4*)((const char*)Ap + (aoff + (unsigned)(32 * i * lda + (kt) * 64) * 2u)); B_[i] = *(const u32x4*)((const char*)Wt + (woff + (unsigned)(32 * i * K + (kt) * 64) * 2u)); } } while (0)
; #define BLOAD(A_, B_, kt) do { _Pragma("unroll") for (int i = 0; i < 4; ++i) { \
;     A_[i] = *(const u32x4*)((const char*)Ap + (aoff + (unsigned)(32 * i * lda + (kt) * 64) * 2u)); B_[i] = *(const u32x4*)((const char*)Wt + (woff + (unsigned)(32 * i * K + (kt) * 64) * 2u)); } } while (0)
; #define BSTORE(A_, B_, buf) do { _Pragma("unroll") for (int i = 0; i < 4; ++i) { \
;     *(u32x4*)&As[(buf) * GBUF + (srow + 32 * i) * LDT + sc8] = A_[i]; \
;     *(u32x4*)&Bs[(buf) * GBUF + (srow + 32 * i) * LDT + sc8] = B_[i]; } } while (0)
; template <int NK>
; DI void gemm_run(PF& pf, const u16* __restrict__ Ap, int lda, const u16* __restrict__ Wt, f32x16 (&acc)[2][2], char* smem) {
;     ...
;   __builtin_amdgcn_s_setprio(0);
;   __syncthreads();
;   BSTORE(pf.a0, pf.b0, 0);
;   BLOAD(pf.a0, pf.b0, 2);
;   __syncthreads();
; #pragma unroll
;   for (int kt = 0; kt < nk; kt += 2) {
;     BCOMP(0);
;     BSTORE(pf.a1, pf.b1, 1);
;     if (kt + 3 < nk) BLOAD(pf.a1, pf.b1, kt + 3);
;     __syncthreads();
;     BCOMP(1);
;     if (kt + 2 < nk) { BSTORE(pf.a0, pf.b0, 0); if (kt + 4 < nk) BLOAD(pf.a0, pf.b0, kt + 4); }
;     __syncthreads();
;   }
	s_setprio 1
	ds_read_b128 v[224:227], v126 offset:24576
	ds_read_b128 v[232:235], v128 offset:24576
	ds_read_b128 v[236:239], v128 offset:26624
	ds_read_b128 v[228:231], v126 offset:26624
	ds_read_b128 v[240:243], v128 offset:32768
	ds_read_b128 v[244:247], v128 offset:34816
	ds_read_b128 v[248:251], v127 offset:24576
	ds_read_b128 v[160:163], v129 offset:24576
	ds_read_b128 v[164:167], v129 offset:26624
	ds_read_b128 v[156:159], v127 offset:26624
	ds_read_b128 v[168:171], v129 offset:32768
	ds_read_b128 v[122:125], v129 offset:34816
	s_add_u32 m0, s16, 0x0
	s_add_u32 s42, s42, 0x100000
	s_addc_u32 s43, s43, 0
	global_load_lds_dwordx4 v137, s[42:43]
	global_load_lds_dwordx4 v150, s[42:43] offset:1024
	s_add_u32 m0, s0, 0x0
	s_add_u32 s30, s30, 0x10000
	s_addc_u32 s31, s31, 0
	global_load_lds_dwordx4 v151, s[30:31]
	global_load_lds_dwordx4 v152, s[30:31] offset:1024
	global_load_lds_dwordx4 v153, s[30:31] offset:2048
	global_load_lds_dwordx4 v154, s[30:31] offset:3072
	s_waitcnt lgkmcnt(10)
	v_mfma_f32_32x32x16_bf16 v[34:49], v[224:227], v[232:235], v[34:49]
	s_waitcnt lgkmcnt(9)
	v_mfma_f32_32x32x16_bf16 v[50:65], v[224:227], v[236:239], v[50:65]
	s_waitcnt lgkmcnt(8)
	v_mfma_f32_32x32x16_bf16 v[2:17], v[228:231], v[232:235], v[2:17]
	v_mfma_f32_32x32x16_bf16 v[18:33], v[228:231], v[236:239], v[18:33]
	s_waitcnt lgkmcnt(7)
	v_mfma_f32_32x32x16_bf16 v[74:89], v[224:227], v[240:243], v[74:89]
	s_waitcnt lgkmcnt(6)
	v_mfma_f32_32x32x16_bf16 v[90:105], v[224:227], v[244:247], v[90:105]
	v_mfma_f32_32x32x16_bf16 v[106:121], v[228:231], v[240:243], v[106:121]
	v_mfma_f32_32x32x16_bf16 v[208:223], v[228:231], v[244:247], v[208:223]
	s_waitcnt lgkmcnt(4)
	v_mfma_f32_32x32x16_bf16 v[34:49], v[248:251], v[160:163], v[34:49]
	s_waitcnt lgkmcnt(3)
	v_mfma_f32_32x32x16_bf16 v[50:65], v[248:251], v[164:167], v[50:65]
	s_waitcnt lgkmcnt(2)
	v_mfma_f32_32x32x16_bf16 v[2:17], v[156:159], v[160:163], v[2:17]
	v_mfma_f32_32x32x16_bf16 v[18:33], v[156:159], v[164:167], v[18:33]
	s_waitcnt lgkmcnt(1)
	v_mfma_f32_32x32x16_bf16 v[74:89], v[248:251], v[168:171], v[74:89]
	s_waitcnt lgkmcnt(0)
	v_mfma_f32_32x32x16_bf16 v[90:105], v[248:251], v[122:125], v[90:105]
	v_mfma_f32_32x32x16_bf16 v[106:121], v[156:159], v[168:171], v[106:121]
	v_mfma_f32_32x32x16_bf16 v[208:223], v[156:159], v[122:125], v[208:223]
	s_setprio 0
	s_waitcnt vmcnt(6)
	s_barrier
	s_setprio 1
	ds_read_b128 v[224:227], v126 offset:49152
	ds_read_b128 v[232:235], v128 offset:49152
	ds_read_b128 v[236:239], v128 offset:51200
	ds_read_b128 v[228:231], v126 offset:51200
	ds_read_b128 v[240:243], v128 offset:57344
	ds_read_b128 v[244:247], v128 offset:59392
	ds_read_b128 v[248:251], v127 offset:49152
	ds_read_b128 v[160:163], v129 offset:49152
	ds_read_b128 v[164:167], v129 offset:51200
	ds_read_b128 v[156:159], v127 offset:51200
	ds_read_b128 v[168:171], v129 offset:57344
	ds_read_b128 v[122:125], v129 offset:59392
	s_add_u32 m0, s16, 0x6000
	s_add_u32 s42, s42, 0x100000
	s_addc_u32 s43, s43, 0
	global_load_lds_dwordx4 v137, s[42:43]
	global_load_lds_dwordx4 v150, s[42:43] offset:1024
	s_add_u32 m0, s0, 0x6000
	s_add_u32 s30, s30, 0x10000
	s_addc_u32 s31, s31, 0
	global_load_lds_dwordx4 v151, s[30:31]
	global_load_lds_dwordx4 v152, s[30:31] offset:1024
	global_load_lds_dwordx4 v153, s[30:31] offset:2048
	global_load_lds_dwordx4 v154, s[30:31] offset:3072
	s_waitcnt lgkmcnt(10)
	v_mfma_f32_32x32x16_bf16 v[34:49], v[224:227], v[232:235], v[34:49]
	s_waitcnt lgkmcnt(9)
	v_mfma_f32_32x32x16_bf16 v[50:65], v[224:227], v[236:239], v[50:65]
	s_waitcnt lgkmcnt(8)
	v_mfma_f32_32x32x16_bf16 v[2:17], v[228:231], v[232:235], v[2:17]
	v_mfma_f32_32x32x16_bf16 v[18:33], v[228:231], v[236:239], v[18:33]
	s_waitcnt lgkmcnt(7)
	v_mfma_f32_32x32x16_bf16 v[74:89], v[224:227], v[240:243], v[74:89]
	s_waitcnt lgkmcnt(6)
	v_mfma_f32_32x32x16_bf16 v[90:105], v[224:227], v[244:247], v[90:105]
	v_mfma_f32_32x32x16_bf16 v[106:121], v[228:231], v[240:243], v[106:121]
	v_mfma_f32_32x32x16_bf16 v[208:223], v[228:231], v[244:247], v[208:223]
	s_waitcnt lgkmcnt(4)
	v_mfma_f32_32x32x16_bf16 v[34:49], v[248:251], v[160:163], v[34:49]
	s_waitcnt lgkmcnt(3)
	v_mfma_f32_32x32x16_bf16 v[50:65], v[248:251], v[164:167], v[50:65]
	s_waitcnt lgkmcnt(2)
	v_mfma_f32_32x32x16_bf16 v[2:17], v[156:159], v[160:163], v[2:17]
	v_mfma_f32_32x32x16_bf16 v[18:33], v[156:159], v[164:167], v[18:33]
	s_waitcnt lgkmcnt(1)
	v_mfma_f32_32x32x16_bf16 v[74:89], v[248:251], v[168:171], v[74:89]
	s_waitcnt lgkmcnt(0)
	v_mfma_f32_32x32x16_bf16 v[90:105], v[248:251], v[122:125], v[90:105]
	v_mfma_f32_32x32x16_bf16 v[106:121], v[156:159], v[168:171], v[106:121]
	v_mfma_f32_32x32x16_bf16 v[208:223], v[156:159], v[122:125], v[208:223]
	s_setprio 0
	s_waitcnt vmcnt(6)
	s_barrier
; #define BLOAD(A_, B_, kt) do { _Pragma("unroll") for (int i = 0; i < 4; ++i) { \
;     A_[i] = *(const u32x4*)((const char*)Ap + (aoff + (unsigned)(32 * i * lda + (kt) * 64) * 2u)); B_[i] = *(const u32x4*)((const char*)Wt + (woff + (unsigned)(32 * i * K + (kt) * 64) * 2u)); } } while (0)
; #define BLOAD(A_, B_, kt) do { _Pragma("unroll") for (int i = 0; i < 4; ++i) { \
;     A_[i] = *(const u32x4*)((const char*)Ap + (aoff + (unsigned)(32 * i * lda + (kt) * 64) * 2u)); B_[i] = *(const u32x4*)((const char*)Wt + (woff + (unsigned)(32 * i * K + (kt) * 64) * 2u)); } } while (0)
; #define BSTORE(A_, B_, buf) do { _Pragma("unroll") for (int i = 0; i < 4; ++i) { \
;     *(u32x4*)&As[(buf) * GBUF + (srow + 32 * i) * LDT + sc8] = A_[i]; \
;     *(u32x4*)&Bs[(buf) * GBUF + (srow + 32 * i) * LDT + sc8] = B_[i]; } } while (0)
; template <int NK>
; DI void gemm_run(PF& pf, const u16* __restrict__ Ap, int lda, const u16* __restrict__ Wt, f32x16 (&acc)[2][2], char* smem) {
;     ...
;   __builtin_amdgcn_s_setprio(0);
;   __syncthreads();
;   BSTORE(pf.a0, pf.b0, 0);
;   BLOAD(pf.a0, pf.b0, 2);
;   __syncthreads();
; #pragma unroll
;   for (int kt = 0; kt < nk; kt += 2) {
;     BCOMP(0);
;     BSTORE(pf.a1, pf.b1, 1);
;     if (kt + 3 < nk) BLOAD(pf.a1, pf.b1, kt + 3);
;     __syncthreads();
;     BCOMP(1);
;     if (kt + 2 < nk) { BSTORE(pf.a0, pf.b0, 0); if (kt + 4 < nk) BLOAD(pf.a0, pf.b0, kt + 4); }
;     __syncthreads();
;   }
	s_setprio 1
	ds_read_b128 v[224:227], v126 offset:0
	ds_read_b128 v[232:235], v128 offset:0
	ds_read_b128 v[236:239], v128 offset:2048
	ds_read_b128 v[228:231], v126 offset:2048
	ds_read_b128 v[240:243], v128 offset:8192
	ds_read_b128 v[244:247], v128 offset:10240
	ds_read_b128 v[248:251], v127 offset:0
	ds_read_b128 v[160:163], v129 offset:0
	ds_read_b128 v[164:167], v129 offset:2048
	ds_read_b128 v[156:159], v127 offset:2048
	ds_read_b128 v[168:171], v129 offset:8192
	ds_read_b128 v[122:125], v129 offset:10240
	s_add_u32 m0, s16, 0xc000
	s_add_u32 s42, s42, 0x100000
	s_addc_u32 s43, s43, 0
	global_load_lds_dwordx4 v137, s[42:43]
	global_load_lds_dwordx4 v150, s[42:43] offset:1024
	s_add_u32 m0, s0, 0xc000
	s_add_u32 s30, s30, 0x10000
	s_addc_u32 s31, s31, 0
	global_load_lds_dwordx4 v151, s[30:31]
	global_load_lds_dwordx4 v152, s[30:31] offset:1024
	global_load_lds_dwordx4 v153, s[30:31] offset:2048
	global_load_lds_dwordx4 v154, s[30:31] offset:3072
	s_waitcnt lgkmcnt(10)
	v_mfma_f32_32x32x16_bf16 v[34:49], v[224:227], v[232:235], v[34:49]
	s_waitcnt lgkmcnt(9)
	v_mfma_f32_32x32x16_bf16 v[50:65], v[224:227], v[236:239], v[50:65]
	s_waitcnt lgkmcnt(8)
	v_mfma_f32_32x32x16_bf16 v[2:17], v[228:231], v[232:235], v[2:17]
	v_mfma_f32_32x32x16_bf16 v[18:33], v[228:231], v[236:239], v[18:33]
	s_waitcnt lgkmcnt(7)
	v_mfma_f32_32x32x16_bf16 v[74:89], v[224:227], v[240:243], v[74:89]
	s_waitcnt lgkmcnt(6)
	v_mfma_f32_32x32x16_bf16 v[90:105], v[224:227], v[244:247], v[90:105]
	v_mfma_f32_32x32x16_bf16 v[106:121], v[228:231], v[240:243], v[106:121]
	v_mfma_f32_32x32x16_bf16 v[208:223], v[228:231], v[244:247], v[208:223]
	s_waitcnt lgkmcnt(4)
	v_mfma_f32_32x32x16_bf16 v[34:49], v[248:251], v[160:163], v[34:49]
	s_waitcnt lgkmcnt(3)
	v_mfma_f32_32x32x16_bf16 v[50:65], v[248:251], v[164:167], v[50:65]
	s_waitcnt lgkmcnt(2)
	v_mfma_f32_32x32x16_bf16 v[2:17], v[156:159], v[160:163], v[2:17]
	v_mfma_f32_32x32x16_bf16 v[18:33], v[156:159], v[164:167], v[18:33]
	s_waitcnt lgkmcnt(1)
	v_mfma_f32_32x32x16_bf16 v[74:89], v[248:251], v[168:171], v[74:89]
	s_waitcnt lgkmcnt(0)
	v_mfma_f32_32x32x16_bf16 v[90:105], v[248:251], v[122:125], v[90:105]
	v_mfma_f32_32x32x16_bf16 v[106:121], v[156:159], v[168:171], v[106:121]
	v_mfma_f32_32x32x16_bf16 v[208:223], v[156:159], v[122:125], v[208:223]
	s_setprio 0
	s_waitcnt vmcnt(6)
	s_barrier
	s_setprio 1
	ds_read_b128 v[224:227], v126 offset:24576
	ds_read_b128 v[232:235], v128 offset:24576
	ds_read_b128 v[236:239], v128 offset:26624
	ds_read_b128 v[228:231], v126 offset:26624
	ds_read_b128 v[240:243], v128 offset:32768
	ds_read_b128 v[244:247], v128 offset:34816
	ds_read_b128 v[248:251], v127 offset:24576
	ds_read_b128 v[160:163], v129 offset:24576
	ds_read_b128 v[164:167], v129 offset:26624
	ds_read_b128 v[156:159], v127 offset:26624
	ds_read_b128 v[168:171], v129 offset:32768
	ds_read_b128 v[122:125], v129 offset:34816
	s_add_u32 m0, s16, 0x0
	s_add_u32 s42, s42, 0x100000
	s_addc_u32 s43, s43, 0
	global_load_lds_dwordx4 v137, s[42:43]
	global_load_lds_dwordx4 v150, s[42:43] offset:1024
	s_add_u32 m0, s0, 0x0
	s_add_u32 s30, s30, 0x10000
	s_addc_u32 s31, s31, 0
	global_load_lds_dwordx4 v151, s[30:31]
	global_load_lds_dwordx4 v152, s[30:31] offset:1024
	global_load_lds_dwordx4 v153, s[30:31] offset:2048
	global_load_lds_dwordx4 v154, s[30:31] offset:3072
	s_waitcnt lgkmcnt(10)
	v_mfma_f32_32x32x16_bf16 v[34:49], v[224:227], v[232:235], v[34:49]
	s_waitcnt lgkmcnt(9)
	v_mfma_f32_32x32x16_bf16 v[50:65], v[224:227], v[236:239], v[50:65]
	s_waitcnt lgkmcnt(8)
	v_mfma_f32_32x32x16_bf16 v[2:17], v[228:231], v[232:235], v[2:17]
	v_mfma_f32_32x32x16_bf16 v[18:33], v[228:231], v[236:239], v[18:33]
	s_waitcnt lgkmcnt(7)
	v_mfma_f32_32x32x16_bf16 v[74:89], v[224:227], v[240:243], v[74:89]
	s_waitcnt lgkmcnt(6)
	v_mfma_f32_32x32x16_bf16 v[90:105], v[224:227], v[244:247], v[90:105]
	v_mfma_f32_32x32x16_bf16 v[106:121], v[228:231], v[240:243], v[106:121]
	v_mfma_f32_32x32x16_bf16 v[208:223], v[228:231], v[244:247], v[208:223]
	s_waitcnt lgkmcnt(4)
	v_mfma_f32_32x32x16_bf16 v[34:49], v[248:251], v[160:163], v[34:49]
	s_waitcnt lgkmcnt(3)
	v_mfma_f32_32x32x16_bf16 v[50:65], v[248:251], v[164:167], v[50:65]
	s_waitcnt lgkmcnt(2)
	v_mfma_f32_32x32x16_bf16 v[2:17], v[156:159], v[160:163], v[2:17]
	v_mfma_f32_32x32x16_bf16 v[18:33], v[156:159], v[164:167], v[18:33]
	s_waitcnt lgkmcnt(1)
	v_mfma_f32_32x32x16_bf16 v[74:89], v[248:251], v[168:171], v[74:89]
	s_waitcnt lgkmcnt(0)
	v_mfma_f32_32x32x16_bf16 v[90:105], v[248:251], v[122:125], v[90:105]
	v_mfma_f32_32x32x16_bf16 v[106:121], v[156:159], v[168:171], v[106:121]
	v_mfma_f32_32x32x16_bf16 v[208:223], v[156:159], v[122:125], v[208:223]
	s_setprio 0
	s_waitcnt vmcnt(6)
	s_barrier
; #define BLOAD(A_, B_, kt) do { _Pragma("unroll") for (int i = 0; i < 4; ++i) { \
;     A_[i] = *(const u32x4*)((const char*)Ap + (aoff + (unsigned)(32 * i * lda + (kt) * 64) * 2u)); B_[i] = *(const u32x4*)((const char*)Wt + (woff + (unsigned)(32 * i * K + (kt) * 64) * 2u)); } } while (0)
; #define BLOAD(A_, B_, kt) do { _Pragma("unroll") for (int i = 0; i < 4; ++i) { \
;     A_[i] = *(const u32x4*)((const char*)Ap + (aoff + (unsigned)(32 * i * lda + (kt) * 64) * 2u)); B_[i] = *(const u32x4*)((const char*)Wt + (woff + (unsigned)(32 * i * K + (kt) * 64) * 2u)); } } while (0)
; #define BSTORE(A_, B_, buf) do { _Pragma("unroll") for (int i = 0; i < 4; ++i) { \
;     *(u32x4*)&As[(buf) * GBUF + (srow + 32 * i) * LDT + sc8] = A_[i]; \
;     *(u32x4*)&Bs[(buf) * GBUF + (srow + 32 * i) * LDT + sc8] = B_[i]; } } while (0)
; template <int NK>
; DI void gemm_run(PF& pf, const u16* __restrict__ Ap, int lda, const u16* __restrict__ Wt, f32x16 (&acc)[2][2], char* smem) {
;     ...
;   __builtin_amdgcn_s_setprio(0);
;   __syncthreads();
;   BSTORE(pf.a0, pf.b0, 0);
;   BLOAD(pf.a0, pf.b0, 2);
;   __syncthreads();
; #pragma unroll
;   for (int kt = 0; kt < nk; kt += 2) {
;     BCOMP(0);
;     BSTORE(pf.a1, pf.b1, 1);
;     if (kt + 3 < nk) BLOAD(pf.a1, pf.b1, kt + 3);
;     __syncthreads();
;     BCOMP(1);
;     if (kt + 2 < nk) { BSTORE(pf.a0, pf.b0, 0); if (kt + 4 < nk) BLOAD(pf.a0, pf.b0, kt + 4); }
;     __syncthreads();
;   }
	s_setprio 1
	ds_read_b128 v[224:227], v126 offset:49152
	ds_read_b128 v[232:235], v128 offset:49152
	ds_read_b128 v[236:239], v128 offset:51200
	ds_read_b128 v[228:231], v126 offset:51200
	ds_read_b128 v[240:243], v128 offset:57344
	ds_read_b128 v[244:247], v128 offset:59392
	ds_read_b128 v[248:251], v127 offset:49152
	ds_read_b128 v[160:163], v129 offset:49152
	ds_read_b128 v[164:167], v129 offset:51200
	ds_read_b128 v[156:159], v127 offset:51200
	ds_read_b128 v[168:171], v129 offset:57344
	ds_read_b128 v[122:125], v129 offset:59392
	s_add_u32 m0, s16, 0x6000
	s_add_u32 s42, s42, 0x100000
	s_addc_u32 s43, s43, 0
	global_load_lds_dwordx4 v137, s[42:43]
	global_load_lds_dwordx4 v150, s[42:43] offset:1024
	s_add_u32 m0, s0, 0x6000
	s_add_u32 s30, s30, 0x10000
	s_addc_u32 s31, s31, 0
	global_load_lds_dwordx4 v151, s[30:31]
	global_load_lds_dwordx4 v152, s[30:31] offset:1024
	global_load_lds_dwordx4 v153, s[30:31] offset:2048
	global_load_lds_dwordx4 v154, s[30:31] offset:3072
	s_waitcnt lgkmcnt(10)
	v_mfma_f32_32x32x16_bf16 v[34:49], v[224:227], v[232:235], v[34:49]
	s_waitcnt lgkmcnt(9)
	v_mfma_f32_32x32x16_bf16 v[50:65], v[224:227], v[236:239], v[50:65]
	s_waitcnt lgkmcnt(8)
	v_mfma_f32_32x32x16_bf16 v[2:17], v[228:231], v[232:235], v[2:17]
	v_mfma_f32_32x32x16_bf16 v[18:33], v[228:231], v[236:239], v[18:33]
	s_waitcnt lgkmcnt(7)
	v_mfma_f32_32x32x16_bf16 v[74:89], v[224:227], v[240:243], v[74:89]
	s_waitcnt lgkmcnt(6)
	v_mfma_f32_32x32x16_bf16 v[90:105], v[224:227], v[244:247], v[90:105]
	v_mfma_f32_32x32x16_bf16 v[106:121], v[228:231], v[240:243], v[106:121]
	v_mfma_f32_32x32x16_bf16 v[208:223], v[228:231], v[244:247], v[208:223]
	s_waitcnt lgkmcnt(4)
	v_mfma_f32_32x32x16_bf16 v[34:49], v[248:251], v[160:163], v[34:49]
	s_waitcnt lgkmcnt(3)
	v_mfma_f32_32x32x16_bf16 v[50:65], v[248:251], v[164:167], v[50:65]
	s_waitcnt lgkmcnt(2)
	v_mfma_f32_32x32x16_bf16 v[2:17], v[156:159], v[160:163], v[2:17]
	v_mfma_f32_32x32x16_bf16 v[18:33], v[156:159], v[164:167], v[18:33]
	s_waitcnt lgkmcnt(1)
	v_mfma_f32_32x32x16_bf16 v[74:89], v[248:251], v[168:171], v[74:89]
	s_waitcnt lgkmcnt(0)
	v_mfma_f32_32x32x16_bf16 v[90:105], v[248:251], v[122:125], v[90:105]
	v_mfma_f32_32x32x16_bf16 v[106:121], v[156:159], v[168:171], v[106:121]
	v_mfma_f32_32x32x16_bf16 v[208:223], v[156:159], v[122:125], v[208:223]
	s_setprio 0
	s_waitcnt vmcnt(6)
	s_barrier
	s_setprio 1
	ds_read_b128 v[224:227], v126 offset:0
	ds_read_b128 v[232:235], v128 offset:0
	ds_read_b128 v[236:239], v128 offset:2048
	ds_read_b128 v[228:231], v126 offset:2048
	ds_read_b128 v[240:243], v128 offset:8192
	ds_read_b128 v[244:247], v128 offset:10240
	ds_read_b128 v[248:251], v127 offset:0
	ds_read_b128 v[160:163], v129 offset:0
	ds_read_b128 v[164:167], v129 offset:2048
	ds_read_b128 v[156:159], v127 offset:2048
	ds_read_b128 v[168:171], v129 offset:8192
	ds_read_b128 v[122:125], v129 offset:10240
	s_add_u32 m0, s16, 0xc000
	s_add_u32 s42, s42, 0x100000
	s_addc_u32 s43, s43, 0
	global_load_lds_dwordx4 v137, s[42:43]
	global_load_lds_dwordx4 v150, s[42:43] offset:1024
	s_add_u32 m0, s0, 0xc000
	s_add_u32 s30, s30, 0x10000
	s_addc_u32 s31, s31, 0
	global_load_lds_dwordx4 v151, s[30:31]
	global_load_lds_dwordx4 v152, s[30:31] offset:1024
	global_load_lds_dwordx4 v153, s[30:31] offset:2048
	global_load_lds_dwordx4 v154, s[30:31] offset:3072
	s_waitcnt lgkmcnt(10)
	v_mfma_f32_32x32x16_bf16 v[34:49], v[224:227], v[232:235], v[34:49]
	s_waitcnt lgkmcnt(9)
	v_mfma_f32_32x32x16_bf16 v[50:65], v[224:227], v[236:239], v[50:65]
	s_waitcnt lgkmcnt(8)
	v_mfma_f32_32x32x16_bf16 v[2:17], v[228:231], v[232:235], v[2:17]
	v_mfma_f32_32x32x16_bf16 v[18:33], v[228:231], v[236:239], v[18:33]
	s_waitcnt lgkmcnt(7)
	v_mfma_f32_32x32x16_bf16 v[74:89], v[224:227], v[240:243], v[74:89]
	s_waitcnt lgkmcnt(6)
	v_mfma_f32_32x32x16_bf16 v[90:105], v[224:227], v[244:247], v[90:105]
	v_mfma_f32_32x32x16_bf16 v[106:121], v[228:231], v[240:243], v[106:121]
	v_mfma_f32_32x32x16_bf16 v[208:223], v[228:231], v[244:247], v[208:223]
	s_waitcnt lgkmcnt(4)
	v_mfma_f32_32x32x16_bf16 v[34:49], v[248:251], v[160:163], v[34:49]
	s_waitcnt lgkmcnt(3)
	v_mfma_f32_32x32x16_bf16 v[50:65], v[248:251], v[164:167], v[50:65]
	s_waitcnt lgkmcnt(2)
	v_mfma_f32_32x32x16_bf16 v[2:17], v[156:159], v[160:163], v[2:17]
	v_mfma_f32_32x32x16_bf16 v[18:33], v[156:159], v[164:167], v[18:33]
	s_waitcnt lgkmcnt(1)
	v_mfma_f32_32x32x16_bf16 v[74:89], v[248:251], v[168:171], v[74:89]
	s_waitcnt lgkmcnt(0)
	v_mfma_f32_32x32x16_bf16 v[90:105], v[248:251], v[122:125], v[90:105]
	v_mfma_f32_32x32x16_bf16 v[106:121], v[156:159], v[168:171], v[106:121]
	v_mfma_f32_32x32x16_bf16 v[208:223], v[156:159], v[122:125], v[208:223]
	s_setprio 0
	s_waitcnt vmcnt(6)
	s_barrier
; #define BLOAD(A_, B_, kt) do { _Pragma("unroll") for (int i = 0; i < 4; ++i) { \
;     A_[i] = *(const u32x4*)((const char*)Ap + (aoff + (unsigned)(32 * i * lda + (kt) * 64) * 2u)); B_[i] = *(const u32x4*)((const char*)Wt + (woff + (unsigned)(32 * i * K + (kt) * 64) * 2u)); } } while (0)
; #define BLOAD(A_, B_, kt) do { _Pragma("unroll") for (int i = 0; i < 4; ++i) { \
;     A_[i] = *(const u32x4*)((const char*)Ap + (aoff + (unsigned)(32 * i * lda + (kt) * 64) * 2u)); B_[i] = *(const u32x4*)((const char*)Wt + (woff + (unsigned)(32 * i * K + (kt) * 64) * 2u)); } } while (0)
; #define BSTORE(A_, B_, buf) do { _Pragma("unroll") for (int i = 0; i < 4; ++i) { \
;     *(u32x4*)&As[(buf) * GBUF + (srow + 32 * i) * LDT + sc8] = A_[i]; \
;     *(u32x4*)&Bs[(buf) * GBUF + (srow + 32 * i) * LDT + sc8] = B_[i]; } } while (0)
; template <int NK>
; DI void gemm_run(PF& pf, const u16* __restrict__ Ap, int lda, const u16* __restrict__ Wt, f32x16 (&acc)[2][2], char* smem) {
;     ...
;   __builtin_amdgcn_s_setprio(0);
;   __syncthreads();
;   BSTORE(pf.a0, pf.b0, 0);
;   BLOAD(pf.a0, pf.b0, 2);
;   __syncthreads();
; #pragma unroll
;   for (int kt = 0; kt < nk; kt += 2) {
;     BCOMP(0);
;     BSTORE(pf.a1, pf.b1, 1);
;     if (kt + 3 < nk) BLOAD(pf.a1, pf.b1, kt + 3);
;     __syncthreads();
;     BCOMP(1);
;     if (kt + 2 < nk) { BSTORE(pf.a0, pf.b0, 0); if (kt + 4 < nk) BLOAD(pf.a0, pf.b0, kt + 4); }
;     __syncthreads();
;   }
	s_setprio 1
	ds_read_b128 v[224:227], v126 offset:24576
	ds_read_b128 v[232:235], v128 offset:24576
	ds_read_b128 v[236:239], v128 offset:26624
	ds_read_b128 v[228:231], v126 offset:26624
	ds_read_b128 v[240:243], v128 offset:32768
	ds_read_b128 v[244:247], v128 offset:34816
	ds_read_b128 v[248:251], v127 offset:24576
	ds_read_b128 v[160:163], v129 offset:24576
	ds_read_b128 v[164:167], v129 offset:26624
	ds_read_b128 v[156:159], v127 offset:26624
	ds_read_b128 v[168:171], v129 offset:32768
	ds_read_b128 v[122:125], v129 offset:34816
	s_add_u32 m0, s16, 0x0
	s_add_u32 s42, s42, 0x100000
	s_addc_u32 s43, s43, 0
	global_load_lds_dwordx4 v137, s[42:43]
	global_load_lds_dwordx4 v150, s[42:43] offset:1024
	s_add_u32 m0, s0, 0x0
	s_add_u32 s30, s30, 0x10000
	s_addc_u32 s31, s31, 0
	global_load_lds_dwordx4 v151, s[30:31]
	global_load_lds_dwordx4 v152, s[30:31] offset:1024
	global_load_lds_dwordx4 v153, s[30:31] offset:2048
	global_load_lds_dwordx4 v154, s[30:31] offset:3072
	s_waitcnt lgkmcnt(10)
	v_mfma_f32_32x32x16_bf16 v[34:49], v[224:227], v[232:235], v[34:49]
	s_waitcnt lgkmcnt(9)
	v_mfma_f32_32x32x16_bf16 v[50:65], v[224:227], v[236:239], v[50:65]
	s_waitcnt lgkmcnt(8)
	v_mfma_f32_32x32x16_bf16 v[2:17], v[228:231], v[232:235], v[2:17]
	v_mfma_f32_32x32x16_bf16 v[18:33], v[228:231], v[236:239], v[18:33]
	s_waitcnt lgkmcnt(7)
	v_mfma_f32_32x32x16_bf16 v[74:89], v[224:227], v[240:243], v[74:89]
	s_waitcnt lgkmcnt(6)
	v_mfma_f32_32x32x16_bf16 v[90:105], v[224:227], v[244:247], v[90:105]
	v_mfma_f32_32x32x16_bf16 v[106:121], v[228:231], v[240:243], v[106:121]
	v_mfma_f32_32x32x16_bf16 v[208:223], v[228:231], v[244:247], v[208:223]
	s_waitcnt lgkmcnt(4)
	v_mfma_f32_32x32x16_bf16 v[34:49], v[248:251], v[160:163], v[34:49]
	s_waitcnt lgkmcnt(3)
	v_mfma_f32_32x32x16_bf16 v[50:65], v[248:251], v[164:167], v[50:65]
	s_waitcnt lgkmcnt(2)
	v_mfma_f32_32x32x16_bf16 v[2:17], v[156:159], v[160:163], v[2:17]
	v_mfma_f32_32x32x16_bf16 v[18:33], v[156:159], v[164:167], v[18:33]
	s_waitcnt lgkmcnt(1)
	v_mfma_f32_32x32x16_bf16 v[74:89], v[248:251], v[168:171], v[74:89]
	s_waitcnt lgkmcnt(0)
	v_mfma_f32_32x32x16_bf16 v[90:105], v[248:251], v[122:125], v[90:105]
	v_mfma_f32_32x32x16_bf16 v[106:121], v[156:159], v[168:171], v[106:121]
	v_mfma_f32_32x32x16_bf16 v[208:223], v[156:159], v[122:125], v[208:223]
	s_setprio 0
	s_waitcnt vmcnt(6)
	s_barrier
	s_setprio 1
	ds_read_b128 v[224:227], v126 offset:49152
	ds_read_b128 v[232:235], v128 offset:49152
	ds_read_b128 v[236:239], v128 offset:51200
	ds_read_b128 v[228:231], v126 offset:51200
	ds_read_b128 v[240:243], v128 offset:57344
	ds_read_b128 v[244:247], v128 offset:59392
	ds_read_b128 v[248:251], v127 offset:49152
	ds_read_b128 v[160:163], v129 offset:49152
	ds_read_b128 v[164:167], v129 offset:51200
	ds_read_b128 v[156:159], v127 offset:51200
	ds_read_b128 v[168:171], v129 offset:57344
	ds_read_b128 v[122:125], v129 offset:59392
	s_add_u32 m0, s16, 0x6000
	s_add_u32 s42, s42, 0x100000
	s_addc_u32 s43, s43, 0
	global_load_lds_dwordx4 v137, s[42:43]
	global_load_lds_dwordx4 v150, s[42:43] offset:1024
	s_add_u32 m0, s0, 0x6000
	s_add_u32 s30, s30, 0x10000
	s_addc_u32 s31, s31, 0
	global_load_lds_dwordx4 v151, s[30:31]
	global_load_lds_dwordx4 v152, s[30:31] offset:1024
	global_load_lds_dwordx4 v153, s[30:31] offset:2048
	global_load_lds_dwordx4 v154, s[30:31] offset:3072
	s_waitcnt lgkmcnt(10)
	v_mfma_f32_32x32x16_bf16 v[34:49], v[224:227], v[232:235], v[34:49]
	s_waitcnt lgkmcnt(9)
	v_mfma_f32_32x32x16_bf16 v[50:65], v[224:227], v[236:239], v[50:65]
	s_waitcnt lgkmcnt(8)
	v_mfma_f32_32x32x16_bf16 v[2:17], v[228:231], v[232:235], v[2:17]
	v_mfma_f32_32x32x16_bf16 v[18:33], v[228:231], v[236:239], v[18:33]
	s_waitcnt lgkmcnt(7)
	v_mfma_f32_32x32x16_bf16 v[74:89], v[224:227], v[240:243], v[74:89]
	s_waitcnt lgkmcnt(6)
	v_mfma_f32_32x32x16_bf16 v[90:105], v[224:227], v[244:247], v[90:105]
	v_mfma_f32_32x32x16_bf16 v[106:121], v[228:231], v[240:243], v[106:121]
	v_mfma_f32_32x32x16_bf16 v[208:223], v[228:231], v[244:247], v[208:223]
	s_waitcnt lgkmcnt(4)
	v_mfma_f32_32x32x16_bf16 v[34:49], v[248:251], v[160:163], v[34:49]
	s_waitcnt lgkmcnt(3)
	v_mfma_f32_32x32x16_bf16 v[50:65], v[248:251], v[164:167], v[50:65]
	s_waitcnt lgkmcnt(2)
	v_mfma_f32_32x32x16_bf16 v[2:17], v[156:159], v[160:163], v[2:17]
	v_mfma_f32_32x32x16_bf16 v[18:33], v[156:159], v[164:167], v[18:33]
	s_waitcnt lgkmcnt(1)
	v_mfma_f32_32x32x16_bf16 v[74:89], v[248:251], v[168:171], v[74:89]
	s_waitcnt lgkmcnt(0)
	v_mfma_f32_32x32x16_bf16 v[90:105], v[248:251], v[122:125], v[90:105]
	v_mfma_f32_32x32x16_bf16 v[106:121], v[156:159], v[168:171], v[106:121]
	v_mfma_f32_32x32x16_bf16 v[208:223], v[156:159], v[122:125], v[208:223]
	s_setprio 0
	s_waitcnt vmcnt(6)
	s_barrier
; #define BLOAD(A_, B_, kt) do { _Pragma("unroll") for (int i = 0; i < 4; ++i) { \
;     A_[i] = *(const u32x4*)((const char*)Ap + (aoff + (unsigned)(32 * i * lda + (kt) * 64) * 2u)); B_[i] = *(const u32x4*)((const char*)Wt + (woff + (unsigned)(32 * i * K + (kt) * 64) * 2u)); } } while (0)
; #define BLOAD(A_, B_, kt) do { _Pragma("unroll") for (int i = 0; i < 4; ++i) { \
;     A_[i] = *(const u32x4*)((const char*)Ap + (aoff + (unsigned)(32 * i * lda + (kt) * 64) * 2u)); B_[i] = *(const u32x4*)((const char*)Wt + (woff + (unsigned)(32 * i * K + (kt) * 64) * 2u)); } } while (0)
; #define BSTORE(A_, B_, buf) do { _Pragma("unroll") for (int i = 0; i < 4; ++i) { \
;     *(u32x4*)&As[(buf) * GBUF + (srow + 32 * i) * LDT + sc8] = A_[i]; \
;     *(u32x4*)&Bs[(buf) * GBUF + (srow + 32 * i) * LDT + sc8] = B_[i]; } } while (0)
; template <int NK>
; DI void gemm_run(PF& pf, const u16* __restrict__ Ap, int lda, const u16* __restrict__ Wt, f32x16 (&acc)[2][2], char* smem) {
;     ...
;   __builtin_amdgcn_s_setprio(0);
;   __syncthreads();
;   BSTORE(pf.a0, pf.b0, 0);
;   BLOAD(pf.a0, pf.b0, 2);
;   __syncthreads();
; #pragma unroll
;   for (int kt = 0; kt < nk; kt += 2) {
;     BCOMP(0);
;     BSTORE(pf.a1, pf.b1, 1);
;     if (kt + 3 < nk) BLOAD(pf.a1, pf.b1, kt + 3);
;     __syncthreads();
;     BCOMP(1);
;     if (kt + 2 < nk) { BSTORE(pf.a0, pf.b0, 0); if (kt + 4 < nk) BLOAD(pf.a0, pf.b0, kt + 4); }
;     __syncthreads();
;   }
	s_setprio 1
	ds_read_b128 v[224:227], v126 offset:0
	ds_read_b128 v[232:235], v128 offset:0
	ds_read_b128 v[236:239], v128 offset:2048
	ds_read_b128 v[228:231], v126 offset:2048
	ds_read_b128 v[240:243], v128 offset:8192
	ds_read_b128 v[244:247], v128 offset:10240
	ds_read_b128 v[248:251], v127 offset:0
	ds_read_b128 v[160:163], v129 offset:0
	ds_read_b128 v[164:167], v129 offset:2048
	ds_read_b128 v[156:159], v127 offset:2048
	ds_read_b128 v[168:171], v129 offset:8192
	ds_read_b128 v[122:125], v129 offset:10240
	s_add_u32 m0, s16, 0xc000
	s_add_u32 s42, s42, 0x100000
	s_addc_u32 s43, s43, 0
	global_load_lds_dwordx4 v137, s[42:43]
	global_load_lds_dwordx4 v150, s[42:43] offset:1024
	s_add_u32 m0, s0, 0xc000
	s_add_u32 s30, s30, 0x10000
	s_addc_u32 s31, s31, 0
	global_load_lds_dwordx4 v151, s[30:31]
	global_load_lds_dwordx4 v152, s[30:31] offset:1024
	global_load_lds_dwordx4 v153, s[30:31] offset:2048
	global_load_lds_dwordx4 v154, s[30:31] offset:3072
	s_waitcnt lgkmcnt(10)
	v_mfma_f32_32x32x16_bf16 v[34:49], v[224:227], v[232:235], v[34:49]
	s_waitcnt lgkmcnt(9)
	v_mfma_f32_32x32x16_bf16 v[50:65], v[224:227], v[236:239], v[50:65]
	s_waitcnt lgkmcnt(8)
	v_mfma_f32_32x32x16_bf16 v[2:17], v[228:231], v[232:235], v[2:17]
	v_mfma_f32_32x32x16_bf16 v[18:33], v[228:231], v[236:239], v[18:33]
	s_waitcnt lgkmcnt(7)
	v_mfma_f32_32x32x16_bf16 v[74:89], v[224:227], v[240:243], v[74:89]
	s_waitcnt lgkmcnt(6)
	v_mfma_f32_32x32x16_bf16 v[90:105], v[224:227], v[244:247], v[90:105]
	v_mfma_f32_32x32x16_bf16 v[106:121], v[228:231], v[240:243], v[106:121]
	v_mfma_f32_32x32x16_bf16 v[208:223], v[228:231], v[244:247], v[208:223]
	s_waitcnt lgkmcnt(4)
	v_mfma_f32_32x32x16_bf16 v[34:49], v[248:251], v[160:163], v[34:49]
	s_waitcnt lgkmcnt(3)
	v_mfma_f32_32x32x16_bf16 v[50:65], v[248:251], v[164:167], v[50:65]
	s_waitcnt lgkmcnt(2)
	v_mfma_f32_32x32x16_bf16 v[2:17], v[156:159], v[160:163], v[2:17]
	v_mfma_f32_32x32x16_bf16 v[18:33], v[156:159], v[164:167], v[18:33]
	s_waitcnt lgkmcnt(1)
	v_mfma_f32_32x32x16_bf16 v[74:89], v[248:251], v[168:171], v[74:89]
	s_waitcnt lgkmcnt(0)
	v_mfma_f32_32x32x16_bf16 v[90:105], v[248:251], v[122:125], v[90:105]
	v_mfma_f32_32x32x16_bf16 v[106:121], v[156:159], v[168:171], v[106:121]
	v_mfma_f32_32x32x16_bf16 v[208:223], v[156:159], v[122:125], v[208:223]
	s_setprio 0
	s_waitcnt vmcnt(6)
	s_barrier
	s_setprio 1
	ds_read_b128 v[224:227], v126 offset:24576
	ds_read_b128 v[232:235], v128 offset:24576
	ds_read_b128 v[236:239], v128 offset:26624
	ds_read_b128 v[228:231], v126 offset:26624
	ds_read_b128 v[240:243], v128 offset:32768
	ds_read_b128 v[244:247], v128 offset:34816
	ds_read_b128 v[248:251], v127 offset:24576
	ds_read_b128 v[160:163], v129 offset:24576
	ds_read_b128 v[164:167], v129 offset:26624
	ds_read_b128 v[156:159], v127 offset:26624
	ds_read_b128 v[168:171], v129 offset:32768
	ds_read_b128 v[122:125], v129 offset:34816
	s_add_u32 m0, s16, 0x0
	s_add_u32 s42, s42, 0x100000
	s_addc_u32 s43, s43, 0
	global_load_lds_dwordx4 v137, s[42:43]
	global_load_lds_dwordx4 v150, s[42:43] offset:1024
	s_add_u32 m0, s0, 0x0
	s_add_u32 s30, s30, 0x10000
	s_addc_u32 s31, s31, 0
	global_load_lds_dwordx4 v151, s[30:31]
	global_load_lds_dwordx4 v152, s[30:31] offset:1024
	global_load_lds_dwordx4 v153, s[30:31] offset:2048
	global_load_lds_dwordx4 v154, s[30:31] offset:3072
	s_waitcnt lgkmcnt(10)
	v_mfma_f32_32x32x16_bf16 v[34:49], v[224:227], v[232:235], v[34:49]
	s_waitcnt lgkmcnt(9)
	v_mfma_f32_32x32x16_bf16 v[50:65], v[224:227], v[236:239], v[50:65]
	s_waitcnt lgkmcnt(8)
	v_mfma_f32_32x32x16_bf16 v[2:17], v[228:231], v[232:235], v[2:17]
	v_mfma_f32_32x32x16_bf16 v[18:33], v[228:231], v[236:239], v[18:33]
	s_waitcnt lgkmcnt(7)
	v_mfma_f32_32x32x16_bf16 v[74:89], v[224:227], v[240:243], v[74:89]
	s_waitcnt lgkmcnt(6)
	v_mfma_f32_32x32x16_bf16 v[90:105], v[224:227], v[244:247], v[90:105]
	v_mfma_f32_32x32x16_bf16 v[106:121], v[228:231], v[240:243], v[106:121]
	v_mfma_f32_32x32x16_bf16 v[208:223], v[228:231], v[244:247], v[208:223]
	s_waitcnt lgkmcnt(4)
	v_mfma_f32_32x32x16_bf16 v[34:49], v[248:251], v[160:163], v[34:49]
	s_waitcnt lgkmcnt(3)
	v_mfma_f32_32x32x16_bf16 v[50:65], v[248:251], v[164:167], v[50:65]
	s_waitcnt lgkmcnt(2)
	v_mfma_f32_32x32x16_bf16 v[2:17], v[156:159], v[160:163], v[2:17]
	v_mfma_f32_32x32x16_bf16 v[18:33], v[156:159], v[164:167], v[18:33]
	s_waitcnt lgkmcnt(1)
	v_mfma_f32_32x32x16_bf16 v[74:89], v[248:251], v[168:171], v[74:89]
	s_waitcnt lgkmcnt(0)
	v_mfma_f32_32x32x16_bf16 v[90:105], v[248:251], v[122:125], v[90:105]
	v_mfma_f32_32x32x16_bf16 v[106:121], v[156:159], v[168:171], v[106:121]
	v_mfma_f32_32x32x16_bf16 v[208:223], v[156:159], v[122:125], v[208:223]
	s_setprio 0
	s_waitcnt vmcnt(6)
	s_barrier
; #define BLOAD(A_, B_, kt) do { _Pragma("unroll") for (int i = 0; i < 4; ++i) { \
;     A_[i] = *(const u32x4*)((const char*)Ap + (aoff + (unsigned)(32 * i * lda + (kt) * 64) * 2u)); B_[i] = *(const u32x4*)((const char*)Wt + (woff + (unsigned)(32 * i * K + (kt) * 64) * 2u)); } } while (0)
; #define BLOAD(A_, B_, kt) do { _Pragma("unroll") for (int i = 0; i < 4; ++i) { \
;     A_[i] = *(const u32x4*)((const char*)Ap + (aoff + (unsigned)(32 * i * lda + (kt) * 64) * 2u)); B_[i] = *(const u32x4*)((const char*)Wt + (woff + (unsigned)(32 * i * K + (kt) * 64) * 2u)); } } while (0)
; #define BSTORE(A_, B_, buf) do { _Pragma("unroll") for (int i = 0; i < 4; ++i) { \
;     *(u32x4*)&As[(buf) * GBUF + (srow + 32 * i) * LDT + sc8] = A_[i]; \
;     *(u32x4*)&Bs[(buf) * GBUF + (srow + 32 * i) * LDT + sc8] = B_[i]; } } while (0)
; template <int NK>
; DI void gemm_run(PF& pf, const u16* __restrict__ Ap, int lda, const u16* __restrict__ Wt, f32x16 (&acc)[2][2], char* smem) {
;     ...
;   __builtin_amdgcn_s_setprio(0);
;   __syncthreads();
;   BSTORE(pf.a0, pf.b0, 0);
;   BLOAD(pf.a0, pf.b0, 2);
;   __syncthreads();
; #pragma unroll
;   for (int kt = 0; kt < nk; kt += 2) {
;     BCOMP(0);
;     BSTORE(pf.a1, pf.b1, 1);
;     if (kt + 3 < nk) BLOAD(pf.a1, pf.b1, kt + 3);
;     __syncthreads();
;     BCOMP(1);
;     if (kt + 2 < nk) { BSTORE(pf.a0, pf.b0, 0); if (kt + 4 < nk) BLOAD(pf.a0, pf.b0, kt + 4); }
;     __syncthreads();
;   }
	s_setprio 1
	ds_read_b128 v[224:227], v126 offset:49152
	ds_read_b128 v[232:235], v128 offset:49152
	ds_read_b128 v[236:239], v128 offset:51200
	ds_read_b128 v[228:231], v126 offset:51200
	ds_read_b128 v[240:243], v128 offset:57344
	ds_read_b128 v[244:247], v128 offset:59392
	ds_read_b128 v[248:251], v127 offset:49152
	ds_read_b128 v[160:163], v129 offset:49152
	ds_read_b128 v[164:167], v129 offset:51200
	ds_read_b128 v[156:159], v127 offset:51200
	ds_read_b128 v[168:171], v129 offset:57344
	ds_read_b128 v[122:125], v129 offset:59392
	s_add_u32 m0, s16, 0x6000
	s_add_u32 s42, s42, 0x100000
	s_addc_u32 s43, s43, 0
	global_load_lds_dwordx4 v137, s[42:43]
	global_load_lds_dwordx4 v150, s[42:43] offset:1024
	s_add_u32 m0, s0, 0x6000
	s_add_u32 s30, s30, 0x10000
	s_addc_u32 s31, s31, 0
	global_load_lds_dwordx4 v151, s[30:31]
	global_load_lds_dwordx4 v152, s[30:31] offset:1024
	global_load_lds_dwordx4 v153, s[30:31] offset:2048
	global_load_lds_dwordx4 v154, s[30:31] offset:3072
	s_waitcnt lgkmcnt(10)
	v_mfma_f32_32x32x16_bf16 v[34:49], v[224:227], v[232:235], v[34:49]
	s_waitcnt lgkmcnt(9)
	v_mfma_f32_32x32x16_bf16 v[50:65], v[224:227], v[236:239], v[50:65]
	s_waitcnt lgkmcnt(8)
	v_mfma_f32_32x32x16_bf16 v[2:17], v[228:231], v[232:235], v[2:17]
	v_mfma_f32_32x32x16_bf16 v[18:33], v[228:231], v[236:239], v[18:33]
	s_waitcnt lgkmcnt(7)
	v_mfma_f32_32x32x16_bf16 v[74:89], v[224:227], v[240:243], v[74:89]
	s_waitcnt lgkmcnt(6)
	v_mfma_f32_32x32x16_bf16 v[90:105], v[224:227], v[244:247], v[90:105]
	v_mfma_f32_32x32x16_bf16 v[106:121], v[228:231], v[240:243], v[106:121]
	v_mfma_f32_32x32x16_bf16 v[208:223], v[228:231], v[244:247], v[208:223]
	s_waitcnt lgkmcnt(4)
	v_mfma_f32_32x32x16_bf16 v[34:49], v[248:251], v[160:163], v[34:49]
	s_waitcnt lgkmcnt(3)
	v_mfma_f32_32x32x16_bf16 v[50:65], v[248:251], v[164:167], v[50:65]
	s_waitcnt lgkmcnt(2)
	v_mfma_f32_32x32x16_bf16 v[2:17], v[156:159], v[160:163], v[2:17]
	v_mfma_f32_32x32x16_bf16 v[18:33], v[156:159], v[164:167], v[18:33]
	s_waitcnt lgkmcnt(1)
	v_mfma_f32_32x32x16_bf16 v[74:89], v[248:251], v[168:171], v[74:89]
	s_waitcnt lgkmcnt(0)
	v_mfma_f32_32x32x16_bf16 v[90:105], v[248:251], v[122:125], v[90:105]
	v_mfma_f32_32x32x16_bf16 v[106:121], v[156:159], v[168:171], v[106:121]
	v_mfma_f32_32x32x16_bf16 v[208:223], v[156:159], v[122:125], v[208:223]
	s_setprio 0
	s_waitcnt vmcnt(6)
	s_barrier
	s_setprio 1
	ds_read_b128 v[224:227], v126 offset:0
	ds_read_b128 v[232:235], v128 offset:0
	ds_read_b128 v[236:239], v128 offset:2048
	ds_read_b128 v[228:231], v126 offset:2048
	ds_read_b128 v[240:243], v128 offset:8192
	ds_read_b128 v[244:247], v128 offset:10240
	ds_read_b128 v[248:251], v127 offset:0
	ds_read_b128 v[160:163], v129 offset:0
	ds_read_b128 v[164:167], v129 offset:2048
	ds_read_b128 v[156:159], v127 offset:2048
	ds_read_b128 v[168:171], v129 offset:8192
	ds_read_b128 v[122:125], v129 offset:10240
	s_add_u32 m0, s16, 0xc000
	s_add_u32 s42, s42, 0x100000
	s_addc_u32 s43, s43, 0
	global_load_lds_dwordx4 v137, s[42:43]
	global_load_lds_dwordx4 v150, s[42:43] offset:1024
	s_add_u32 m0, s0, 0xc000
	s_add_u32 s30, s30, 0x10000
	s_addc_u32 s31, s31, 0
	global_load_lds_dwordx4 v151, s[30:31]
	global_load_lds_dwordx4 v152, s[30:31] offset:1024
	global_load_lds_dwordx4 v153, s[30:31] offset:2048
	global_load_lds_dwordx4 v154, s[30:31] offset:3072
	s_waitcnt lgkmcnt(10)
	v_mfma_f32_32x32x16_bf16 v[34:49], v[224:227], v[232:235], v[34:49]
	s_waitcnt lgkmcnt(9)
	v_mfma_f32_32x32x16_bf16 v[50:65], v[224:227], v[236:239], v[50:65]
	s_waitcnt lgkmcnt(8)
	v_mfma_f32_32x32x16_bf16 v[2:17], v[228:231], v[232:235], v[2:17]
	v_mfma_f32_32x32x16_bf16 v[18:33], v[228:231], v[236:239], v[18:33]
	s_waitcnt lgkmcnt(7)
	v_mfma_f32_32x32x16_bf16 v[74:89], v[224:227], v[240:243], v[74:89]
	s_waitcnt lgkmcnt(6)
	v_mfma_f32_32x32x16_bf16 v[90:105], v[224:227], v[244:247], v[90:105]
	v_mfma_f32_32x32x16_bf16 v[106:121], v[228:231], v[240:243], v[106:121]
	v_mfma_f32_32x32x16_bf16 v[208:223], v[228:231], v[244:247], v[208:223]
	s_waitcnt lgkmcnt(4)
	v_mfma_f32_32x32x16_bf16 v[34:49], v[248:251], v[160:163], v[34:49]
	s_waitcnt lgkmcnt(3)
	v_mfma_f32_32x32x16_bf16 v[50:65], v[248:251], v[164:167], v[50:65]
	s_waitcnt lgkmcnt(2)
	v_mfma_f32_32x32x16_bf16 v[2:17], v[156:159], v[160:163], v[2:17]
	v_mfma_f32_32x32x16_bf16 v[18:33], v[156:159], v[164:167], v[18:33]
	s_waitcnt lgkmcnt(1)
	v_mfma_f32_32x32x16_bf16 v[74:89], v[248:251], v[168:171], v[74:89]
	s_waitcnt lgkmcnt(0)
	v_mfma_f32_32x32x16_bf16 v[90:105], v[248:251], v[122:125], v[90:105]
	v_mfma_f32_32x32x16_bf16 v[106:121], v[156:159], v[168:171], v[106:121]
	v_mfma_f32_32x32x16_bf16 v[208:223], v[156:159], v[122:125], v[208:223]
	s_setprio 0
	s_waitcnt vmcnt(6)
	s_barrier
; #define BLOAD(A_, B_, kt) do { _Pragma("unroll") for (int i = 0; i < 4; ++i) { \
;     A_[i] = *(const u32x4*)((const char*)Ap + (aoff + (unsigned)(32 * i * lda + (kt) * 64) * 2u)); B_[i] = *(const u32x4*)((const char*)Wt + (woff + (unsigned)(32 * i * K + (kt) * 64) * 2u)); } } while (0)
; #define BLOAD(A_, B_, kt) do { _Pragma("unroll") for (int i = 0; i < 4; ++i) { \
;     A_[i] = *(const u32x4*)((const char*)Ap + (aoff + (unsigned)(32 * i * lda + (kt) * 64) * 2u)); B_[i] = *(const u32x4*)((const char*)Wt + (woff + (unsigned)(32 * i * K + (kt) * 64) * 2u)); } } while (0)
; #define BSTORE(A_, B_, buf) do { _Pragma("unroll") for (int i = 0; i < 4; ++i) { \
;     *(u32x4*)&As[(buf) * GBUF + (srow + 32 * i) * LDT + sc8] = A_[i]; \
;     *(u32x4*)&Bs[(buf) * GBUF + (srow + 32 * i) * LDT + sc8] = B_[i]; } } while (0)
; template <int NK>
; DI void gemm_run(PF& pf, const u16* __restrict__ Ap, int lda, const u16* __restrict__ Wt, f32x16 (&acc)[2][2], char* smem) {
;     ...
;   __builtin_amdgcn_s_setprio(0);
;   __syncthreads();
;   BSTORE(pf.a0, pf.b0, 0);
;   BLOAD(pf.a0, pf.b0, 2);
;   __syncthreads();
; #pragma unroll
;   for (int kt = 0; kt < nk; kt += 2) {
;     BCOMP(0);
;     BSTORE(pf.a1, pf.b1, 1);
;     if (kt + 3 < nk) BLOAD(pf.a1, pf.b1, kt + 3);
;     __syncthreads();
;     BCOMP(1);
;     if (kt + 2 < nk) { BSTORE(pf.a0, pf.b0, 0); if (kt + 4 < nk) BLOAD(pf.a0, pf.b0, kt + 4); }
;     __syncthreads();
;   }
	s_setprio 1
	ds_read_b128 v[224:227], v126 offset:24576
	ds_read_b128 v[232:235], v128 offset:24576
	ds_read_b128 v[236:239], v128 offset:26624
	ds_read_b128 v[228:231], v126 offset:26624
	ds_read_b128 v[240:243], v128 offset:32768
	ds_read_b128 v[244:247], v128 offset:34816
	ds_read_b128 v[248:251], v127 offset:24576
	ds_read_b128 v[160:163], v129 offset:24576
	ds_read_b128 v[164:167], v129 offset:26624
	ds_read_b128 v[156:159], v127 offset:26624
	ds_read_b128 v[168:171], v129 offset:32768
	ds_read_b128 v[122:125], v129 offset:34816
	s_add_u32 m0, s16, 0x0
	s_add_u32 s42, s42, 0x100000
	s_addc_u32 s43, s43, 0
	global_load_lds_dwordx4 v137, s[42:43]
	global_load_lds_dwordx4 v150, s[42:43] offset:1024
	s_add_u32 m0, s0, 0x0
	s_add_u32 s30, s30, 0x10000
	s_addc_u32 s31, s31, 0
	global_load_lds_dwordx4 v151, s[30:31]
	global_load_lds_dwordx4 v152, s[30:31] offset:1024
	global_load_lds_dwordx4 v153, s[30:31] offset:2048
	global_load_lds_dwordx4 v154, s[30:31] offset:3072
	s_waitcnt lgkmcnt(10)
	v_mfma_f32_32x32x16_bf16 v[34:49], v[224:227], v[232:235], v[34:49]
	s_waitcnt lgkmcnt(9)
	v_mfma_f32_32x32x16_bf16 v[50:65], v[224:227], v[236:239], v[50:65]
	s_waitcnt lgkmcnt(8)
	v_mfma_f32_32x32x16_bf16 v[2:17], v[228:231], v[232:235], v[2:17]
	v_mfma_f32_32x32x16_bf16 v[18:33], v[228:231], v[236:239], v[18:33]
	s_waitcnt lgkmcnt(7)
	v_mfma_f32_32x32x16_bf16 v[74:89], v[224:227], v[240:243], v[74:89]
	s_waitcnt lgkmcnt(6)
	v_mfma_f32_32x32x16_bf16 v[90:105], v[224:227], v[244:247], v[90:105]
	v_mfma_f32_32x32x16_bf16 v[106:121], v[228:231], v[240:243], v[106:121]
	v_mfma_f32_32x32x16_bf16 v[208:223], v[228:231], v[244:247], v[208:223]
	s_waitcnt lgkmcnt(4)
	v_mfma_f32_32x32x16_bf16 v[34:49], v[248:251], v[160:163], v[34:49]
	s_waitcnt lgkmcnt(3)
	v_mfma_f32_32x32x16_bf16 v[50:65], v[248:251], v[164:167], v[50:65]
	s_waitcnt lgkmcnt(2)
	v_mfma_f32_32x32x16_bf16 v[2:17], v[156:159], v[160:163], v[2:17]
	v_mfma_f32_32x32x16_bf16 v[18:33], v[156:159], v[164:167], v[18:33]
	s_waitcnt lgkmcnt(1)
	v_mfma_f32_32x32x16_bf16 v[74:89], v[248:251], v[168:171], v[74:89]
	s_waitcnt lgkmcnt(0)
	v_mfma_f32_32x32x16_bf16 v[90:105], v[248:251], v[122:125], v[90:105]
	v_mfma_f32_32x32x16_bf16 v[106:121], v[156:159], v[168:171], v[106:121]
	v_mfma_f32_32x32x16_bf16 v[208:223], v[156:159], v[122:125], v[208:223]
	s_setprio 0
	s_waitcnt vmcnt(6)
	s_barrier
	s_setprio 1
	ds_read_b128 v[224:227], v126 offset:49152
	ds_read_b128 v[232:235], v128 offset:49152
	ds_read_b128 v[236:239], v128 offset:51200
	ds_read_b128 v[228:231], v126 offset:51200
	ds_read_b128 v[240:243], v128 offset:57344
	ds_read_b128 v[244:247], v128 offset:59392
	ds_read_b128 v[248:251], v127 offset:49152
	ds_read_b128 v[160:163], v129 offset:49152
	ds_read_b128 v[164:167], v129 offset:51200
	ds_read_b128 v[156:159], v127 offset:51200
	ds_read_b128 v[168:171], v129 offset:57344
	ds_read_b128 v[122:125], v129 offset:59392
	s_add_u32 m0, s16, 0x6000
	s_add_u32 s42, s42, 0x100000
	s_addc_u32 s43, s43, 0
	global_load_lds_dwordx4 v137, s[42:43]
	global_load_lds_dwordx4 v150, s[42:43] offset:1024
	s_add_u32 m0, s0, 0x6000
	s_add_u32 s30, s30, 0x10000
	s_addc_u32 s31, s31, 0
	global_load_lds_dwordx4 v151, s[30:31]
	global_load_lds_dwordx4 v152, s[30:31] offset:1024
	global_load_lds_dwordx4 v153, s[30:31] offset:2048
	global_load_lds_dwordx4 v154, s[30:31] offset:3072
	s_waitcnt lgkmcnt(10)
	v_mfma_f32_32x32x16_bf16 v[34:49], v[224:227], v[232:235], v[34:49]
	s_waitcnt lgkmcnt(9)
	v_mfma_f32_32x32x16_bf16 v[50:65], v[224:227], v[236:239], v[50:65]
	s_waitcnt lgkmcnt(8)
	v_mfma_f32_32x32x16_bf16 v[2:17], v[228:231], v[232:235], v[2:17]
	v_mfma_f32_32x32x16_bf16 v[18:33], v[228:231], v[236:239], v[18:33]
	s_waitcnt lgkmcnt(7)
	v_mfma_f32_32x32x16_bf16 v[74:89], v[224:227], v[240:243], v[74:89]
	s_waitcnt lgkmcnt(6)
	v_mfma_f32_32x32x16_bf16 v[90:105], v[224:227], v[244:247], v[90:105]
	v_mfma_f32_32x32x16_bf16 v[106:121], v[228:231], v[240:243], v[106:121]
	v_mfma_f32_32x32x16_bf16 v[208:223], v[228:231], v[244:247], v[208:223]
	s_waitcnt lgkmcnt(4)
	v_mfma_f32_32x32x16_bf16 v[34:49], v[248:251], v[160:163], v[34:49]
	s_waitcnt lgkmcnt(3)
	v_mfma_f32_32x32x16_bf16 v[50:65], v[248:251], v[164:167], v[50:65]
	s_waitcnt lgkmcnt(2)
	v_mfma_f32_32x32x16_bf16 v[2:17], v[156:159], v[160:163], v[2:17]
	v_mfma_f32_32x32x16_bf16 v[18:33], v[156:159], v[164:167], v[18:33]
	s_waitcnt lgkmcnt(1)
	v_mfma_f32_32x32x16_bf16 v[74:89], v[248:251], v[168:171], v[74:89]
	s_waitcnt lgkmcnt(0)
	v_mfma_f32_32x32x16_bf16 v[90:105], v[248:251], v[122:125], v[90:105]
	v_mfma_f32_32x32x16_bf16 v[106:121], v[156:159], v[168:171], v[106:121]
	v_mfma_f32_32x32x16_bf16 v[208:223], v[156:159], v[122:125], v[208:223]
	s_setprio 0
	s_waitcnt vmcnt(6)
	s_barrier
; #define BLOAD(A_, B_, kt) do { _Pragma("unroll") for (int i = 0; i < 4; ++i) { \
;     A_[i] = *(const u32x4*)((const char*)Ap + (aoff + (unsigned)(32 * i * lda + (kt) * 64) * 2u)); B_[i] = *(const u32x4*)((const char*)Wt + (woff + (unsigned)(32 * i * K + (kt) * 64) * 2u)); } } while (0)
; #define BLOAD(A_, B_, kt) do { _Pragma("unroll") for (int i = 0; i < 4; ++i) { \
;     A_[i] = *(const u32x4*)((const char*)Ap + (aoff + (unsigned)(32 * i * lda + (kt) * 64) * 2u)); B_[i] = *(const u32x4*)((const char*)Wt + (woff + (unsigned)(32 * i * K + (kt) * 64) * 2u)); } } while (0)
; #define BSTORE(A_, B_, buf) do { _Pragma("unroll") for (int i = 0; i < 4; ++i) { \
;     *(u32x4*)&As[(buf) * GBUF + (srow + 32 * i) * LDT + sc8] = A_[i]; \
;     *(u32x4*)&Bs[(buf) * GBUF + (srow + 32 * i) * LDT + sc8] = B_[i]; } } while (0)
; template <int NK>
; DI void gemm_run(PF& pf, const u16* __restrict__ Ap, int lda, const u16* __restrict__ Wt, f32x16 (&acc)[2][2], char* smem) {
;     ...
;   __builtin_amdgcn_s_setprio(0);
;   __syncthreads();
;   BSTORE(pf.a0, pf.b0, 0);
;   BLOAD(pf.a0, pf.b0, 2);
;   __syncthreads();
; #pragma unroll
;   for (int kt = 0; kt < nk; kt += 2) {
;     BCOMP(0);
;     BSTORE(pf.a1, pf.b1, 1);
;     if (kt + 3 < nk) BLOAD(pf.a1, pf.b1, kt + 3);
;     __syncthreads();
;     BCOMP(1);
;     if (kt + 2 < nk) { BSTORE(pf.a0, pf.b0, 0); if (kt + 4 < nk) BLOAD(pf.a0, pf.b0, kt + 4); }
;     __syncthreads();
	s_setprio 1
	ds_read_b128 v[224:227], v126 offset:0
	ds_read_b128 v[232:235], v128 offset:0
	ds_read_b128 v[236:239], v128 offset:2048
	ds_read_b128 v[228:231], v126 offset:2048
	ds_read_b128 v[240:243], v128 offset:8192
	ds_read_b128 v[244:247], v128 offset:10240
	ds_read_b128 v[248:251], v127 offset:0
	ds_read_b128 v[160:163], v129 offset:0
	ds_read_b128 v[164:167], v129 offset:2048
	ds_read_b128 v[156:159], v127 offset:2048
	ds_read_b128 v[168:171], v129 offset:8192
	ds_read_b128 v[122:125], v129 offset:10240
	s_add_u32 m0, s16, 0xc000
	s_add_u32 s42, s42, 0x100000
	s_addc_u32 s43, s43, 0
	global_load_lds_dwordx4 v137, s[42:43]
	global_load_lds_dwordx4 v150, s[42:43] offset:1024
	s_add_u32 m0, s0, 0xc000
	s_add_u32 s30, s30, 0x10000
	s_addc_u32 s31, s31, 0
	global_load_lds_dwordx4 v151, s[30:31]
	global_load_lds_dwordx4 v152, s[30:31] offset:1024
	global_load_lds_dwordx4 v153, s[30:31] offset:2048
	global_load_lds_dwordx4 v154, s[30:31] offset:3072
	s_waitcnt lgkmcnt(10)
	v_mfma_f32_32x32x16_bf16 v[34:49], v[224:227], v[232:235], v[34:49]
	s_waitcnt lgkmcnt(9)
	v_mfma_f32_32x32x16_bf16 v[50:65], v[224:227], v[236:239], v[50:65]
	s_waitcnt lgkmcnt(8)
	v_mfma_f32_32x32x16_bf16 v[2:17], v[228:231], v[232:235], v[2:17]
	v_mfma_f32_32x32x16_bf16 v[18:33], v[228:231], v[236:239], v[18:33]
	s_waitcnt lgkmcnt(7)
	v_mfma_f32_32x32x16_bf16 v[74:89], v[224:227], v[240:243], v[74:89]
	s_waitcnt lgkmcnt(6)
	v_mfma_f32_32x32x16_bf16 v[90:105], v[224:227], v[244:247], v[90:105]
	v_mfma_f32_32x32x16_bf16 v[106:121], v[228:231], v[240:243], v[106:121]
	v_mfma_f32_32x32x16_bf16 v[208:223], v[228:231], v[244:247], v[208:223]
	s_waitcnt lgkmcnt(4)
	v_mfma_f32_32x32x16_bf16 v[34:49], v[248:251], v[160:163], v[34:49]
	s_waitcnt lgkmcnt(3)
	v_mfma_f32_32x32x16_bf16 v[50:65], v[248:251], v[164:167], v[50:65]
	s_waitcnt lgkmcnt(2)
	v_mfma_f32_32x32x16_bf16 v[2:17], v[156:159], v[160:163], v[2:17]
	v_mfma_f32_32x32x16_bf16 v[18:33], v[156:159], v[164:167], v[18:33]
	s_waitcnt lgkmcnt(1)
	v_mfma_f32_32x32x16_bf16 v[74:89], v[248:251], v[168:171], v[74:89]
	s_waitcnt lgkmcnt(0)
	v_mfma_f32_32x32x16_bf16 v[90:105], v[248:251], v[122:125], v[90:105]
	v_mfma_f32_32x32x16_bf16 v[106:121], v[156:159], v[168:171], v[106:121]
	v_mfma_f32_32x32x16_bf16 v[208:223], v[156:159], v[122:125], v[208:223]
	s_setprio 0
	s_waitcnt vmcnt(6)
	s_barrier
	s_setprio 1
	ds_read_b128 v[224:227], v126 offset:24576
	ds_read_b128 v[232:235], v128 offset:24576
	ds_read_b128 v[236:239], v128 offset:26624
	ds_read_b128 v[228:231], v126 offset:26624
	ds_read_b128 v[240:243], v128 offset:32768
	ds_read_b128 v[244:247], v128 offset:34816
	ds_read_b128 v[248:251], v127 offset:24576
	ds_read_b128 v[160:163], v129 offset:24576
	ds_read_b128 v[164:167], v129 offset:26624
	ds_read_b128 v[156:159], v127 offset:26624
	ds_read_b128 v[168:171], v129 offset:32768
	ds_read_b128 v[122:125], v129 offset:34816
	s_add_u32 m0, s16, 0x0
	s_add_u32 s42, s42, 0x100000
	s_addc_u32 s43, s43, 0
	global_load_lds_dwordx4 v137, s[42:43]
	global_load_lds_dwordx4 v150, s[42:43] offset:1024
	s_add_u32 m0, s0, 0x0
	s_add_u32 s30, s30, 0x10000
	s_addc_u32 s31, s31, 0
	global_load_lds_dwordx4 v151, s[30:31]
	global_load_lds_dwordx4 v152, s[30:31] offset:1024
	global_load_lds_dwordx4 v153, s[30:31] offset:2048
	global_load_lds_dwordx4 v154, s[30:31] offset:3072
	s_waitcnt lgkmcnt(10)
	v_mfma_f32_32x32x16_bf16 v[34:49], v[224:227], v[232:235], v[34:49]
	s_waitcnt lgkmcnt(9)
	v_mfma_f32_32x32x16_bf16 v[50:65], v[224:227], v[236:239], v[50:65]
	s_waitcnt lgkmcnt(8)
	v_mfma_f32_32x32x16_bf16 v[2:17], v[228:231], v[232:235], v[2:17]
	v_mfma_f32_32x32x16_bf16 v[18:33], v[228:231], v[236:239], v[18:33]
	s_waitcnt lgkmcnt(7)
	v_mfma_f32_32x32x16_bf16 v[74:89], v[224:227], v[240:243], v[74:89]
	s_waitcnt lgkmcnt(6)
	v_mfma_f32_32x32x16_bf16 v[90:105], v[224:227], v[244:247], v[90:105]
	v_mfma_f32_32x32x16_bf16 v[106:121], v[228:231], v[240:243], v[106:121]
	v_mfma_f32_32x32x16_bf16 v[208:223], v[228:231], v[244:247], v[208:223]
	s_waitcnt lgkmcnt(4)
	v_mfma_f32_32x32x16_bf16 v[34:49], v[248:251], v[160:163], v[34:49]
	s_waitcnt lgkmcnt(3)
	v_mfma_f32_32x32x16_bf16 v[50:65], v[248:251], v[164:167], v[50:65]
	s_waitcnt lgkmcnt(2)
	v_mfma_f32_32x32x16_bf16 v[2:17], v[156:159], v[160:163], v[2:17]
	v_mfma_f32_32x32x16_bf16 v[18:33], v[156:159], v[164:167], v[18:33]
	s_waitcnt lgkmcnt(1)
	v_mfma_f32_32x32x16_bf16 v[74:89], v[248:251], v[168:171], v[74:89]
	s_waitcnt lgkmcnt(0)
	v_mfma_f32_32x32x16_bf16 v[90:105], v[248:251], v[122:125], v[90:105]
	v_mfma_f32_32x32x16_bf16 v[106:121], v[156:159], v[168:171], v[106:121]
	v_mfma_f32_32x32x16_bf16 v[208:223], v[156:159], v[122:125], v[208:223]
	s_setprio 0
	s_waitcnt vmcnt(6)
	s_barrier
; #define BLOAD(A_, B_, kt) do { _Pragma("unroll") for (int i = 0; i < 4; ++i) { \
;     A_[i] = *(const u32x4*)((const char*)Ap + (aoff + (unsigned)(32 * i * lda + (kt) * 64) * 2u)); B_[i] = *(const u32x4*)((const char*)Wt + (woff + (unsigned)(32 * i * K + (kt) * 64) * 2u)); } } while (0)
; #define BLOAD(A_, B_, kt) do { _Pragma("unroll") for (int i = 0; i < 4; ++i) { \
;     A_[i] = *(const u32x4*)((const char*)Ap + (aoff + (unsigned)(32 * i * lda + (kt) * 64) * 2u)); B_[i] = *(const u32x4*)((const char*)Wt + (woff + (unsigned)(32 * i * K + (kt) * 64) * 2u)); } } while (0)
; #define BSTORE(A_, B_, buf) do { _Pragma("unroll") for (int i = 0; i < 4; ++i) { \
;     *(u32x4*)&As[(buf) * GBUF + (srow + 32 * i) * LDT + sc8] = A_[i]; \
;     *(u32x4*)&Bs[(buf) * GBUF + (srow + 32 * i) * LDT + sc8] = B_[i]; } } while (0)
; template <int NK>
; DI void gemm_run(PF& pf, const u16* __restrict__ Ap, int lda, const u16* __restrict__ Wt, f32x16 (&acc)[2][2], char* smem) {
;     ...
;   __builtin_amdgcn_s_setprio(0);
;   __syncthreads();
;   BSTORE(pf.a0, pf.b0, 0);
;   BLOAD(pf.a0, pf.b0, 2);
;   __syncthreads();
; #pragma unroll
;   for (int kt = 0; kt < nk; kt += 2) {
;     BCOMP(0);
;     BSTORE(pf.a1, pf.b1, 1);
;     if (kt + 3 < nk) BLOAD(pf.a1, pf.b1, kt + 3);
;     __syncthreads();
;     BCOMP(1);
;     if (kt + 2 < nk) { BSTORE(pf.a0, pf.b0, 0); if (kt + 4 < nk) BLOAD(pf.a0, pf.b0, kt + 4); }
;     __syncthreads();
	s_setprio 1
	ds_read_b128 v[224:227], v126 offset:49152
	ds_read_b128 v[232:235], v128 offset:49152
	ds_read_b128 v[236:239], v128 offset:51200
	ds_read_b128 v[228:231], v126 offset:51200
	ds_read_b128 v[240:243], v128 offset:57344
	ds_read_b128 v[244:247], v128 offset:59392
	ds_read_b128 v[248:251], v127 offset:49152
	ds_read_b128 v[160:163], v129 offset:49152
	ds_read_b128 v[164:167], v129 offset:51200
	ds_read_b128 v[156:159], v127 offset:51200
	ds_read_b128 v[168:171], v129 offset:57344
	ds_read_b128 v[122:125], v129 offset:59392
	s_add_u32 m0, s16, 0x6000
	s_add_u32 s42, s42, 0x100000
	s_addc_u32 s43, s43, 0
	global_load_lds_dwordx4 v137, s[42:43]
	global_load_lds_dwordx4 v150, s[42:43] offset:1024
	s_add_u32 m0, s0, 0x6000
	s_add_u32 s30, s30, 0x10000
	s_addc_u32 s31, s31, 0
	global_load_lds_dwordx4 v151, s[30:31]
	global_load_lds_dwordx4 v152, s[30:31] offset:1024
	global_load_lds_dwordx4 v153, s[30:31] offset:2048
	global_load_lds_dwordx4 v154, s[30:31] offset:3072
	s_waitcnt lgkmcnt(10)
	v_mfma_f32_32x32x16_bf16 v[34:49], v[224:227], v[232:235], v[34:49]
	s_waitcnt lgkmcnt(9)
	v_mfma_f32_32x32x16_bf16 v[50:65], v[224:227], v[236:239], v[50:65]
	s_waitcnt lgkmcnt(8)
	v_mfma_f32_32x32x16_bf16 v[2:17], v[228:231], v[232:235], v[2:17]
	v_mfma_f32_32x32x16_bf16 v[18:33], v[228:231], v[236:239], v[18:33]
	s_waitcnt lgkmcnt(7)
	v_mfma_f32_32x32x16_bf16 v[74:89], v[224:227], v[240:243], v[74:89]
	s_waitcnt lgkmcnt(6)
	v_mfma_f32_32x32x16_bf16 v[90:105], v[224:227], v[244:247], v[90:105]
	v_mfma_f32_32x32x16_bf16 v[106:121], v[228:231], v[240:243], v[106:121]
	v_mfma_f32_32x32x16_bf16 v[208:223], v[228:231], v[244:247], v[208:223]
	s_waitcnt lgkmcnt(4)
	v_mfma_f32_32x32x16_bf16 v[34:49], v[248:251], v[160:163], v[34:49]
	s_waitcnt lgkmcnt(3)
	v_mfma_f32_32x32x16_bf16 v[50:65], v[248:251], v[164:167], v[50:65]
	s_waitcnt lgkmcnt(2)
	v_mfma_f32_32x32x16_bf16 v[2:17], v[156:159], v[160:163], v[2:17]
	v_mfma_f32_32x32x16_bf16 v[18:33], v[156:159], v[164:167], v[18:33]
	s_waitcnt lgkmcnt(1)
	v_mfma_f32_32x32x16_bf16 v[74:89], v[248:251], v[168:171], v[74:89]
	s_waitcnt lgkmcnt(0)
	v_mfma_f32_32x32x16_bf16 v[90:105], v[248:251], v[122:125], v[90:105]
	v_mfma_f32_32x32x16_bf16 v[106:121], v[156:159], v[168:171], v[106:121]
	v_mfma_f32_32x32x16_bf16 v[208:223], v[156:159], v[122:125], v[208:223]
	s_setprio 0
	s_waitcnt vmcnt(6)
	s_barrier
	s_setprio 1
	ds_read_b128 v[224:227], v126 offset:0
	ds_read_b128 v[232:235], v128 offset:0
	ds_read_b128 v[236:239], v128 offset:2048
	ds_read_b128 v[228:231], v126 offset:2048
	ds_read_b128 v[240:243], v128 offset:8192
	ds_read_b128 v[244:247], v128 offset:10240
	ds_read_b128 v[248:251], v127 offset:0
	ds_read_b128 v[160:163], v129 offset:0
	ds_read_b128 v[164:167], v129 offset:2048
	ds_read_b128 v[156:159], v127 offset:2048
	ds_read_b128 v[168:171], v129 offset:8192
	ds_read_b128 v[122:125], v129 offset:10240
	s_add_u32 m0, s16, 0xc000
	s_add_u32 s42, s42, 0x100000
	s_addc_u32 s43, s43, 0
	global_load_lds_dwordx4 v137, s[42:43]
	global_load_lds_dwordx4 v150, s[42:43] offset:1024
	s_add_u32 m0, s0, 0xc000
	s_add_u32 s30, s30, 0x10000
	s_addc_u32 s31, s31, 0
	global_load_lds_dwordx4 v151, s[30:31]
	global_load_lds_dwordx4 v152, s[30:31] offset:1024
	global_load_lds_dwordx4 v153, s[30:31] offset:2048
	global_load_lds_dwordx4 v154, s[30:31] offset:3072
	s_waitcnt lgkmcnt(10)
	v_mfma_f32_32x32x16_bf16 v[34:49], v[224:227], v[232:235], v[34:49]
	s_waitcnt lgkmcnt(9)
	v_mfma_f32_32x32x16_bf16 v[50:65], v[224:227], v[236:239], v[50:65]
	s_waitcnt lgkmcnt(8)
	v_mfma_f32_32x32x16_bf16 v[2:17], v[228:231], v[232:235], v[2:17]
	v_mfma_f32_32x32x16_bf16 v[18:33], v[228:231], v[236:239], v[18:33]
	s_waitcnt lgkmcnt(7)
	v_mfma_f32_32x32x16_bf16 v[74:89], v[224:227], v[240:243], v[74:89]
	s_waitcnt lgkmcnt(6)
	v_mfma_f32_32x32x16_bf16 v[90:105], v[224:227], v[244:247], v[90:105]
	v_mfma_f32_32x32x16_bf16 v[106:121], v[228:231], v[240:243], v[106:121]
	v_mfma_f32_32x32x16_bf16 v[208:223], v[228:231], v[244:247], v[208:223]
	s_waitcnt lgkmcnt(4)
	v_mfma_f32_32x32x16_bf16 v[34:49], v[248:251], v[160:163], v[34:49]
	s_waitcnt lgkmcnt(3)
	v_mfma_f32_32x32x16_bf16 v[50:65], v[248:251], v[164:167], v[50:65]
	s_waitcnt lgkmcnt(2)
	v_mfma_f32_32x32x16_bf16 v[2:17], v[156:159], v[160:163], v[2:17]
	v_mfma_f32_32x32x16_bf16 v[18:33], v[156:159], v[164:167], v[18:33]
	s_waitcnt lgkmcnt(1)
	v_mfma_f32_32x32x16_bf16 v[74:89], v[248:251], v[168:171], v[74:89]
	s_waitcnt lgkmcnt(0)
	v_mfma_f32_32x32x16_bf16 v[90:105], v[248:251], v[122:125], v[90:105]
	v_mfma_f32_32x32x16_bf16 v[106:121], v[156:159], v[168:171], v[106:121]
	v_mfma_f32_32x32x16_bf16 v[208:223], v[156:159], v[122:125], v[208:223]
	s_setprio 0
	s_waitcnt vmcnt(6)
	s_barrier
; #define BLOAD(A_, B_, kt) do { _Pragma("unroll") for (int i = 0; i < 4; ++i) { \
;     A_[i] = *(const u32x4*)((const char*)Ap + (aoff + (unsigned)(32 * i * lda + (kt) * 64) * 2u)); B_[i] = *(const u32x4*)((const char*)Wt + (woff + (unsigned)(32 * i * K + (kt) * 64) * 2u)); } } while (0)
; #define BLOAD(A_, B_, kt) do { _Pragma("unroll") for (int i = 0; i < 4; ++i) { \
;     A_[i] = *(const u32x4*)((const char*)Ap + (aoff + (unsigned)(32 * i * lda + (kt) * 64) * 2u)); B_[i] = *(const u32x4*)((const char*)Wt + (woff + (unsigned)(32 * i * K + (kt) * 64) * 2u)); } } while (0)
; #define BSTORE(A_, B_, buf) do { _Pragma("unroll") for (int i = 0; i < 4; ++i) { \
;     *(u32x4*)&As[(buf) * GBUF + (srow + 32 * i) * LDT + sc8] = A_[i]; \
;     *(u32x4*)&Bs[(buf) * GBUF + (srow + 32 * i) * LDT + sc8] = B_[i]; } } while (0)
; template <int NK>
; DI void gemm_run(PF& pf, const u16* __restrict__ Ap, int lda, const u16* __restrict__ Wt, f32x16 (&acc)[2][2], char* smem) {
;     ...
;   __builtin_amdgcn_s_setprio(0);
;   __syncthreads();
;   BSTORE(pf.a0, pf.b0, 0);
;   BLOAD(pf.a0, pf.b0, 2);
;   __syncthreads();
; #pragma unroll
;   for (int kt = 0; kt < nk; kt += 2) {
;     BCOMP(0);
;     BSTORE(pf.a1, pf.b1, 1);
;     if (kt + 3 < nk) BLOAD(pf.a1, pf.b1, kt + 3);
;     __syncthreads();
;     BCOMP(1);
;     if (kt + 2 < nk) { BSTORE(pf.a0, pf.b0, 0); if (kt + 4 < nk) BLOAD(pf.a0, pf.b0, kt + 4); }
;     __syncthreads();
	s_setprio 1
	ds_read_b128 v[224:227], v126 offset:24576
	ds_read_b128 v[232:235], v128 offset:24576
	ds_read_b128 v[236:239], v128 offset:26624
	ds_read_b128 v[228:231], v126 offset:26624
	ds_read_b128 v[240:243], v128 offset:32768
	ds_read_b128 v[244:247], v128 offset:34816
	ds_read_b128 v[248:251], v127 offset:24576
	ds_read_b128 v[160:163], v129 offset:24576
	ds_read_b128 v[164:167], v129 offset:26624
	ds_read_b128 v[156:159], v127 offset:26624
	ds_read_b128 v[168:171], v129 offset:32768
	ds_read_b128 v[122:125], v129 offset:34816
	s_add_u32 m0, s16, 0x0
	s_add_u32 s42, s42, 0x100000
	s_addc_u32 s43, s43, 0
	global_load_lds_dwordx4 v137, s[42:43]
	global_load_lds_dwordx4 v150, s[42:43] offset:1024
	s_add_u32 m0, s0, 0x0
	s_add_u32 s30, s30, 0x10000
	s_addc_u32 s31, s31, 0
	global_load_lds_dwordx4 v151, s[30:31]
	global_load_lds_dwordx4 v152, s[30:31] offset:1024
	global_load_lds_dwordx4 v153, s[30:31] offset:2048
	global_load_lds_dwordx4 v154, s[30:31] offset:3072
	s_waitcnt lgkmcnt(10)
	v_mfma_f32_32x32x16_bf16 v[34:49], v[224:227], v[232:235], v[34:49]
	s_waitcnt lgkmcnt(9)
	v_mfma_f32_32x32x16_bf16 v[50:65], v[224:227], v[236:239], v[50:65]
	s_waitcnt lgkmcnt(8)
	v_mfma_f32_32x32x16_bf16 v[2:17], v[228:231], v[232:235], v[2:17]
	v_mfma_f32_32x32x16_bf16 v[18:33], v[228:231], v[236:239], v[18:33]
	s_waitcnt lgkmcnt(7)
	v_mfma_f32_32x32x16_bf16 v[74:89], v[224:227], v[240:243], v[74:89]
	s_waitcnt lgkmcnt(6)
	v_mfma_f32_32x32x16_bf16 v[90:105], v[224:227], v[244:247], v[90:105]
	v_mfma_f32_32x32x16_bf16 v[106:121], v[228:231], v[240:243], v[106:121]
	v_mfma_f32_32x32x16_bf16 v[208:223], v[228:231], v[244:247], v[208:223]
	s_waitcnt lgkmcnt(4)
	v_mfma_f32_32x32x16_bf16 v[34:49], v[248:251], v[160:163], v[34:49]
	s_waitcnt lgkmcnt(3)
	v_mfma_f32_32x32x16_bf16 v[50:65], v[248:251], v[164:167], v[50:65]
	s_waitcnt lgkmcnt(2)
	v_mfma_f32_32x32x16_bf16 v[2:17], v[156:159], v[160:163], v[2:17]
	v_mfma_f32_32x32x16_bf16 v[18:33], v[156:159], v[164:167], v[18:33]
	s_waitcnt lgkmcnt(1)
	v_mfma_f32_32x32x16_bf16 v[74:89], v[248:251], v[168:171], v[74:89]
	s_waitcnt lgkmcnt(0)
	v_mfma_f32_32x32x16_bf16 v[90:105], v[248:251], v[122:125], v[90:105]
	v_mfma_f32_32x32x16_bf16 v[106:121], v[156:159], v[168:171], v[106:121]
	v_mfma_f32_32x32x16_bf16 v[208:223], v[156:159], v[122:125], v[208:223]
	s_setprio 0
	s_waitcnt vmcnt(6)
	s_barrier
	s_setprio 1
	ds_read_b128 v[224:227], v126 offset:49152
	ds_read_b128 v[232:235], v128 offset:49152
	ds_read_b128 v[236:239], v128 offset:51200
	ds_read_b128 v[228:231], v126 offset:51200
	ds_read_b128 v[240:243], v128 offset:57344
	ds_read_b128 v[244:247], v128 offset:59392
	ds_read_b128 v[248:251], v127 offset:49152
	ds_read_b128 v[160:163], v129 offset:49152
	ds_read_b128 v[164:167], v129 offset:51200
	ds_read_b128 v[156:159], v127 offset:51200
	ds_read_b128 v[168:171], v129 offset:57344
	ds_read_b128 v[122:125], v129 offset:59392
	s_add_u32 m0, s16, 0x6000
	s_add_u32 s42, s42, 0x100000
	s_addc_u32 s43, s43, 0
	global_load_lds_dwordx4 v137, s[42:43]
	global_load_lds_dwordx4 v150, s[42:43] offset:1024
	s_add_u32 m0, s0, 0x6000
	s_add_u32 s30, s30, 0x10000
	s_addc_u32 s31, s31, 0
	global_load_lds_dwordx4 v151, s[30:31]
	global_load_lds_dwordx4 v152, s[30:31] offset:1024
	global_load_lds_dwordx4 v153, s[30:31] offset:2048
	global_load_lds_dwordx4 v154, s[30:31] offset:3072
	s_waitcnt lgkmcnt(10)
	v_mfma_f32_32x32x16_bf16 v[34:49], v[224:227], v[232:235], v[34:49]
	s_waitcnt lgkmcnt(9)
	v_mfma_f32_32x32x16_bf16 v[50:65], v[224:227], v[236:239], v[50:65]
	s_waitcnt lgkmcnt(8)
	v_mfma_f32_32x32x16_bf16 v[2:17], v[228:231], v[232:235], v[2:17]
	v_mfma_f32_32x32x16_bf16 v[18:33], v[228:231], v[236:239], v[18:33]
	s_waitcnt lgkmcnt(7)
	v_mfma_f32_32x32x16_bf16 v[74:89], v[224:227], v[240:243], v[74:89]
	s_waitcnt lgkmcnt(6)
	v_mfma_f32_32x32x16_bf16 v[90:105], v[224:227], v[244:247], v[90:105]
	v_mfma_f32_32x32x16_bf16 v[106:121], v[228:231], v[240:243], v[106:121]
	v_mfma_f32_32x32x16_bf16 v[208:223], v[228:231], v[244:247], v[208:223]
	s_waitcnt lgkmcnt(4)
	v_mfma_f32_32x32x16_bf16 v[34:49], v[248:251], v[160:163], v[34:49]
	s_waitcnt lgkmcnt(3)
	v_mfma_f32_32x32x16_bf16 v[50:65], v[248:251], v[164:167], v[50:65]
	s_waitcnt lgkmcnt(2)
	v_mfma_f32_32x32x16_bf16 v[2:17], v[156:159], v[160:163], v[2:17]
	v_mfma_f32_32x32x16_bf16 v[18:33], v[156:159], v[164:167], v[18:33]
	s_waitcnt lgkmcnt(1)
	v_mfma_f32_32x32x16_bf16 v[74:89], v[248:251], v[168:171], v[74:89]
	s_waitcnt lgkmcnt(0)
	v_mfma_f32_32x32x16_bf16 v[90:105], v[248:251], v[122:125], v[90:105]
	v_mfma_f32_32x32x16_bf16 v[106:121], v[156:159], v[168:171], v[106:121]
	v_mfma_f32_32x32x16_bf16 v[208:223], v[156:159], v[122:125], v[208:223]
	s_setprio 0
	s_waitcnt vmcnt(6)
	s_barrier
; #define BLOAD(A_, B_, kt) do { _Pragma("unroll") for (int i = 0; i < 4; ++i) { \
;     A_[i] = *(const u32x4*)((const char*)Ap + (aoff + (unsigned)(32 * i * lda + (kt) * 64) * 2u)); B_[i] = *(const u32x4*)((const char*)Wt + (woff + (unsigned)(32 * i * K + (kt) * 64) * 2u)); } } while (0)
; #define BLOAD(A_, B_, kt) do { _Pragma("unroll") for (int i = 0; i < 4; ++i) { \
;     A_[i] = *(const u32x4*)((const char*)Ap + (aoff + (unsigned)(32 * i * lda + (kt) * 64) * 2u)); B_[i] = *(const u32x4*)((const char*)Wt + (woff + (unsigned)(32 * i * K + (kt) * 64) * 2u)); } } while (0)
; #define BSTORE(A_, B_, buf) do { _Pragma("unroll") for (int i = 0; i < 4; ++i) { \
;     *(u32x4*)&As[(buf) * GBUF + (srow + 32 * i) * LDT + sc8] = A_[i]; \
;     *(u32x4*)&Bs[(buf) * GBUF + (srow + 32 * i) * LDT + sc8] = B_[i]; } } while (0)
; template <int NK>
; DI void gemm_run(PF& pf, const u16* __restrict__ Ap, int lda, const u16* __restrict__ Wt, f32x16 (&acc)[2][2], char* smem) {
;     ...
;   __builtin_amdgcn_s_setprio(0);
;   __syncthreads();
;   BSTORE(pf.a0, pf.b0, 0);
;   BLOAD(pf.a0, pf.b0, 2);
;   __syncthreads();
; #pragma unroll
;   for (int kt = 0; kt < nk; kt += 2) {
;     BCOMP(0);
;     BSTORE(pf.a1, pf.b1, 1);
;     if (kt + 3 < nk) BLOAD(pf.a1, pf.b1, kt + 3);
;     __syncthreads();
;     BCOMP(1);
;     if (kt + 2 < nk) { BSTORE(pf.a0, pf.b0, 0); if (kt + 4 < nk) BLOAD(pf.a0, pf.b0, kt + 4); }
;     __syncthreads();
	s_setprio 1
	ds_read_b128 v[224:227], v126 offset:0
	ds_read_b128 v[232:235], v128 offset:0
	ds_read_b128 v[236:239], v128 offset:2048
	ds_read_b128 v[228:231], v126 offset:2048
	ds_read_b128 v[240:243], v128 offset:8192
	ds_read_b128 v[244:247], v128 offset:10240
	ds_read_b128 v[248:251], v127 offset:0
	ds_read_b128 v[160:163], v129 offset:0
	ds_read_b128 v[164:167], v129 offset:2048
	ds_read_b128 v[156:159], v127 offset:2048
	ds_read_b128 v[168:171], v129 offset:8192
	ds_read_b128 v[122:125], v129 offset:10240
	s_add_u32 m0, s16, 0xc000
	s_add_u32 s42, s42, 0x100000
	s_addc_u32 s43, s43, 0
	global_load_lds_dwordx4 v137, s[42:43]
	global_load_lds_dwordx4 v150, s[42:43] offset:1024
	s_add_u32 m0, s0, 0xc000
	s_add_u32 s30, s30, 0x10000
	s_addc_u32 s31, s31, 0
	global_load_lds_dwordx4 v151, s[30:31]
	global_load_lds_dwordx4 v152, s[30:31] offset:1024
	global_load_lds_dwordx4 v153, s[30:31] offset:2048
	global_load_lds_dwordx4 v154, s[30:31] offset:3072
	s_waitcnt lgkmcnt(10)
	v_mfma_f32_32x32x16_bf16 v[34:49], v[224:227], v[232:235], v[34:49]
	s_waitcnt lgkmcnt(9)
	v_mfma_f32_32x32x16_bf16 v[50:65], v[224:227], v[236:239], v[50:65]
	s_waitcnt lgkmcnt(8)
	v_mfma_f32_32x32x16_bf16 v[2:17], v[228:231], v[232:235], v[2:17]
	v_mfma_f32_32x32x16_bf16 v[18:33], v[228:231], v[236:239], v[18:33]
	s_waitcnt lgkmcnt(7)
	v_mfma_f32_32x32x16_bf16 v[74:89], v[224:227], v[240:243], v[74:89]
	s_waitcnt lgkmcnt(6)
	v_mfma_f32_32x32x16_bf16 v[90:105], v[224:227], v[244:247], v[90:105]
	v_mfma_f32_32x32x16_bf16 v[106:121], v[228:231], v[240:243], v[106:121]
	v_mfma_f32_32x32x16_bf16 v[208:223], v[228:231], v[244:247], v[208:223]
	s_waitcnt lgkmcnt(4)
	v_mfma_f32_32x32x16_bf16 v[34:49], v[248:251], v[160:163], v[34:49]
	s_waitcnt lgkmcnt(3)
	v_mfma_f32_32x32x16_bf16 v[50:65], v[248:251], v[164:167], v[50:65]
	s_waitcnt lgkmcnt(2)
	v_mfma_f32_32x32x16_bf16 v[2:17], v[156:159], v[160:163], v[2:17]
	v_mfma_f32_32x32x16_bf16 v[18:33], v[156:159], v[164:167], v[18:33]
	s_waitcnt lgkmcnt(1)
	v_mfma_f32_32x32x16_bf16 v[74:89], v[248:251], v[168:171], v[74:89]
	s_waitcnt lgkmcnt(0)
	v_mfma_f32_32x32x16_bf16 v[90:105], v[248:251], v[122:125], v[90:105]
	v_mfma_f32_32x32x16_bf16 v[106:121], v[156:159], v[168:171], v[106:121]
	v_mfma_f32_32x32x16_bf16 v[208:223], v[156:159], v[122:125], v[208:223]
	s_setprio 0
	s_waitcnt vmcnt(6)
	s_barrier
	s_setprio 1
	ds_read_b128 v[224:227], v126 offset:24576
	ds_read_b128 v[232:235], v128 offset:24576
	ds_read_b128 v[236:239], v128 offset:26624
	ds_read_b128 v[228:231], v126 offset:26624
	ds_read_b128 v[240:243], v128 offset:32768
	ds_read_b128 v[244:247], v128 offset:34816
	ds_read_b128 v[248:251], v127 offset:24576
	ds_read_b128 v[160:163], v129 offset:24576
	ds_read_b128 v[164:167], v129 offset:26624
	ds_read_b128 v[156:159], v127 offset:26624
	ds_read_b128 v[168:171], v129 offset:32768
	ds_read_b128 v[122:125], v129 offset:34816
	s_add_u32 m0, s16, 0x0
	s_add_u32 s42, s42, 0x100000
	s_addc_u32 s43, s43, 0
	global_load_lds_dwordx4 v137, s[42:43]
	global_load_lds_dwordx4 v150, s[42:43] offset:1024
	s_add_u32 m0, s0, 0x0
	s_add_u32 s30, s30, 0x10000
	s_addc_u32 s31, s31, 0
	global_load_lds_dwordx4 v151, s[30:31]
	global_load_lds_dwordx4 v152, s[30:31] offset:1024
	global_load_lds_dwordx4 v153, s[30:31] offset:2048
	global_load_lds_dwordx4 v154, s[30:31] offset:3072
	s_waitcnt lgkmcnt(10)
	v_mfma_f32_32x32x16_bf16 v[34:49], v[224:227], v[232:235], v[34:49]
	s_waitcnt lgkmcnt(9)
	v_mfma_f32_32x32x16_bf16 v[50:65], v[224:227], v[236:239], v[50:65]
	s_waitcnt lgkmcnt(8)
	v_mfma_f32_32x32x16_bf16 v[2:17], v[228:231], v[232:235], v[2:17]
	v_mfma_f32_32x32x16_bf16 v[18:33], v[228:231], v[236:239], v[18:33]
	s_waitcnt lgkmcnt(7)
	v_mfma_f32_32x32x16_bf16 v[74:89], v[224:227], v[240:243], v[74:89]
	s_waitcnt lgkmcnt(6)
	v_mfma_f32_32x32x16_bf16 v[90:105], v[224:227], v[244:247], v[90:105]
	v_mfma_f32_32x32x16_bf16 v[106:121], v[228:231], v[240:243], v[106:121]
	v_mfma_f32_32x32x16_bf16 v[208:223], v[228:231], v[244:247], v[208:223]
	s_waitcnt lgkmcnt(4)
	v_mfma_f32_32x32x16_bf16 v[34:49], v[248:251], v[160:163], v[34:49]
	s_waitcnt lgkmcnt(3)
	v_mfma_f32_32x32x16_bf16 v[50:65], v[248:251], v[164:167], v[50:65]
	s_waitcnt lgkmcnt(2)
	v_mfma_f32_32x32x16_bf16 v[2:17], v[156:159], v[160:163], v[2:17]
	v_mfma_f32_32x32x16_bf16 v[18:33], v[156:159], v[164:167], v[18:33]
	s_waitcnt lgkmcnt(1)
	v_mfma_f32_32x32x16_bf16 v[74:89], v[248:251], v[168:171], v[74:89]
	s_waitcnt lgkmcnt(0)
	v_mfma_f32_32x32x16_bf16 v[90:105], v[248:251], v[122:125], v[90:105]
	v_mfma_f32_32x32x16_bf16 v[106:121], v[156:159], v[168:171], v[106:121]
	v_mfma_f32_32x32x16_bf16 v[208:223], v[156:159], v[122:125], v[208:223]
	s_setprio 0
	s_waitcnt vmcnt(6)
	s_barrier
; #define BLOAD(A_, B_, kt) do { _Pragma("unroll") for (int i = 0; i < 4; ++i) { \
;     A_[i] = *(const u32x4*)((const char*)Ap + (aoff + (unsigned)(32 * i * lda + (kt) * 64) * 2u)); B_[i] = *(const u32x4*)((const char*)Wt + (woff + (unsigned)(32 * i * K + (kt) * 64) * 2u)); } } while (0)
; #define BLOAD(A_, B_, kt) do { _Pragma("unroll") for (int i = 0; i < 4; ++i) { \
;     A_[i] = *(const u32x4*)((const char*)Ap + (aoff + (unsigned)(32 * i * lda + (kt) * 64) * 2u)); B_[i] = *(const u32x4*)((const char*)Wt + (woff + (unsigned)(32 * i * K + (kt) * 64) * 2u)); } } while (0)
; #define BSTORE(A_, B_, buf) do { _Pragma("unroll") for (int i = 0; i < 4; ++i) { \
;     *(u32x4*)&As[(buf) * GBUF + (srow + 32 * i) * LDT + sc8] = A_[i]; \
;     *(u32x4*)&Bs[(buf) * GBUF + (srow + 32 * i) * LDT + sc8] = B_[i]; } } while (0)
; template <int NK>
; DI void gemm_run(PF& pf, const u16* __restrict__ Ap, int lda, const u16* __restrict__ Wt, f32x16 (&acc)[2][2], char* smem) {
;     ...
;   __builtin_amdgcn_s_setprio(0);
;   __syncthreads();
;   BSTORE(pf.a0, pf.b0, 0);
;   BLOAD(pf.a0, pf.b0, 2);
;   __syncthreads();
; #pragma unroll
;   for (int kt = 0; kt < nk; kt += 2) {
;     BCOMP(0);
;     BSTORE(pf.a1, pf.b1, 1);
;     if (kt + 3 < nk) BLOAD(pf.a1, pf.b1, kt + 3);
;     __syncthreads();
;     BCOMP(1);
;     if (kt + 2 < nk) { BSTORE(pf.a0, pf.b0, 0); if (kt + 4 < nk) BLOAD(pf.a0, pf.b0, kt + 4); }
;     __syncthreads();
	s_setprio 1
	ds_read_b128 v[224:227], v126 offset:49152
	ds_read_b128 v[232:235], v128 offset:49152
	ds_read_b128 v[236:239], v128 offset:51200
	ds_read_b128 v[228:231], v126 offset:51200
	ds_read_b128 v[240:243], v128 offset:57344
	ds_read_b128 v[244:247], v128 offset:59392
	ds_read_b128 v[248:251], v127 offset:49152
	ds_read_b128 v[160:163], v129 offset:49152
	ds_read_b128 v[164:167], v129 offset:51200
	ds_read_b128 v[156:159], v127 offset:51200
	ds_read_b128 v[168:171], v129 offset:57344
	ds_read_b128 v[122:125], v129 offset:59392
	s_add_u32 m0, s16, 0x6000
	s_add_u32 s42, s42, 0x100000
	s_addc_u32 s43, s43, 0
	global_load_lds_dwordx4 v137, s[42:43]
	global_load_lds_dwordx4 v150, s[42:43] offset:1024
	s_add_u32 m0, s0, 0x6000
	s_add_u32 s30, s30, 0x10000
	s_addc_u32 s31, s31, 0
	global_load_lds_dwordx4 v151, s[30:31]
	global_load_lds_dwordx4 v152, s[30:31] offset:1024
	global_load_lds_dwordx4 v153, s[30:31] offset:2048
	global_load_lds_dwordx4 v154, s[30:31] offset:3072
	s_waitcnt lgkmcnt(10)
	v_mfma_f32_32x32x16_bf16 v[34:49], v[224:227], v[232:235], v[34:49]
	s_waitcnt lgkmcnt(9)
	v_mfma_f32_32x32x16_bf16 v[50:65], v[224:227], v[236:239], v[50:65]
	s_waitcnt lgkmcnt(8)
	v_mfma_f32_32x32x16_bf16 v[2:17], v[228:231], v[232:235], v[2:17]
	v_mfma_f32_32x32x16_bf16 v[18:33], v[228:231], v[236:239], v[18:33]
	s_waitcnt lgkmcnt(7)
	v_mfma_f32_32x32x16_bf16 v[74:89], v[224:227], v[240:243], v[74:89]
	s_waitcnt lgkmcnt(6)
	v_mfma_f32_32x32x16_bf16 v[90:105], v[224:227], v[244:247], v[90:105]
	v_mfma_f32_32x32x16_bf16 v[106:121], v[228:231], v[240:243], v[106:121]
	v_mfma_f32_32x32x16_bf16 v[208:223], v[228:231], v[244:247], v[208:223]
	s_waitcnt lgkmcnt(4)
	v_mfma_f32_32x32x16_bf16 v[34:49], v[248:251], v[160:163], v[34:49]
	s_waitcnt lgkmcnt(3)
	v_mfma_f32_32x32x16_bf16 v[50:65], v[248:251], v[164:167], v[50:65]
	s_waitcnt lgkmcnt(2)
	v_mfma_f32_32x32x16_bf16 v[2:17], v[156:159], v[160:163], v[2:17]
	v_mfma_f32_32x32x16_bf16 v[18:33], v[156:159], v[164:167], v[18:33]
	s_waitcnt lgkmcnt(1)
	v_mfma_f32_32x32x16_bf16 v[74:89], v[248:251], v[168:171], v[74:89]
	s_waitcnt lgkmcnt(0)
	v_mfma_f32_32x32x16_bf16 v[90:105], v[248:251], v[122:125], v[90:105]
	v_mfma_f32_32x32x16_bf16 v[106:121], v[156:159], v[168:171], v[106:121]
	v_mfma_f32_32x32x16_bf16 v[208:223], v[156:159], v[122:125], v[208:223]
	s_setprio 0
	s_waitcnt vmcnt(6)
	s_barrier
	s_setprio 1
	ds_read_b128 v[224:227], v126 offset:0
	ds_read_b128 v[232:235], v128 offset:0
	ds_read_b128 v[236:239], v128 offset:2048
	ds_read_b128 v[228:231], v126 offset:2048
	ds_read_b128 v[240:243], v128 offset:8192
	ds_read_b128 v[244:247], v128 offset:10240
	ds_read_b128 v[248:251], v127 offset:0
	ds_read_b128 v[160:163], v129 offset:0
	ds_read_b128 v[164:167], v129 offset:2048
	ds_read_b128 v[156:159], v127 offset:2048
	ds_read_b128 v[168:171], v129 offset:8192
	ds_read_b128 v[122:125], v129 offset:10240
	s_add_u32 m0, s16, 0xc000
	s_add_u32 s42, s42, 0x100000
	s_addc_u32 s43, s43, 0
	global_load_lds_dwordx4 v137, s[42:43]
	global_load_lds_dwordx4 v150, s[42:43] offset:1024
	s_add_u32 m0, s0, 0xc000
	s_add_u32 s30, s30, 0x10000
	s_addc_u32 s31, s31, 0
	global_load_lds_dwordx4 v151, s[30:31]
	global_load_lds_dwordx4 v152, s[30:31] offset:1024
	global_load_lds_dwordx4 v153, s[30:31] offset:2048
	global_load_lds_dwordx4 v154, s[30:31] offset:3072
	s_waitcnt lgkmcnt(10)
	v_mfma_f32_32x32x16_bf16 v[34:49], v[224:227], v[232:235], v[34:49]
	s_waitcnt lgkmcnt(9)
	v_mfma_f32_32x32x16_bf16 v[50:65], v[224:227], v[236:239], v[50:65]
	s_waitcnt lgkmcnt(8)
	v_mfma_f32_32x32x16_bf16 v[2:17], v[228:231], v[232:235], v[2:17]
	v_mfma_f32_32x32x16_bf16 v[18:33], v[228:231], v[236:239], v[18:33]
	s_waitcnt lgkmcnt(7)
	v_mfma_f32_32x32x16_bf16 v[74:89], v[224:227], v[240:243], v[74:89]
	s_waitcnt lgkmcnt(6)
	v_mfma_f32_32x32x16_bf16 v[90:105], v[224:227], v[244:247], v[90:105]
	v_mfma_f32_32x32x16_bf16 v[106:121], v[228:231], v[240:243], v[106:121]
	v_mfma_f32_32x32x16_bf16 v[208:223], v[228:231], v[244:247], v[208:223]
	s_waitcnt lgkmcnt(4)
	v_mfma_f32_32x32x16_bf16 v[34:49], v[248:251], v[160:163], v[34:49]
	s_waitcnt lgkmcnt(3)
	v_mfma_f32_32x32x16_bf16 v[50:65], v[248:251], v[164:167], v[50:65]
	s_waitcnt lgkmcnt(2)
	v_mfma_f32_32x32x16_bf16 v[2:17], v[156:159], v[160:163], v[2:17]
	v_mfma_f32_32x32x16_bf16 v[18:33], v[156:159], v[164:167], v[18:33]
	s_waitcnt lgkmcnt(1)
	v_mfma_f32_32x32x16_bf16 v[74:89], v[248:251], v[168:171], v[74:89]
	s_waitcnt lgkmcnt(0)
	v_mfma_f32_32x32x16_bf16 v[90:105], v[248:251], v[122:125], v[90:105]
	v_mfma_f32_32x32x16_bf16 v[106:121], v[156:159], v[168:171], v[106:121]
	v_mfma_f32_32x32x16_bf16 v[208:223], v[156:159], v[122:125], v[208:223]
	s_setprio 0
	s_waitcnt vmcnt(6)
	s_barrier
; #define BLOAD(A_, B_, kt) do { _Pragma("unroll") for (int i = 0; i < 4; ++i) { \
;     A_[i] = *(const u32x4*)((const char*)Ap + (aoff + (unsigned)(32 * i * lda + (kt) * 64) * 2u)); B_[i] = *(const u32x4*)((const char*)Wt + (woff + (unsigned)(32 * i * K + (kt) * 64) * 2u)); } } while (0)
; #define BLOAD(A_, B_, kt) do { _Pragma("unroll") for (int i = 0; i < 4; ++i) { \
;     A_[i] = *(const u32x4*)((const char*)Ap + (aoff + (unsigned)(32 * i * lda + (kt) * 64) * 2u)); B_[i] = *(const u32x4*)((const char*)Wt + (woff + (unsigned)(32 * i * K + (kt) * 64) * 2u)); } } while (0)
; #define BSTORE(A_, B_, buf) do { _Pragma("unroll") for (int i = 0; i < 4; ++i) { \
;     *(u32x4*)&As[(buf) * GBUF + (srow + 32 * i) * LDT + sc8] = A_[i]; \
;     *(u32x4*)&Bs[(buf) * GBUF + (srow + 32 * i) * LDT + sc8] = B_[i]; } } while (0)
; template <int NK>
; DI void gemm_run(PF& pf, const u16* __restrict__ Ap, int lda, const u16* __restrict__ Wt, f32x16 (&acc)[2][2], char* smem) {
;     ...
;   __builtin_amdgcn_s_setprio(0);
;   __syncthreads();
;   BSTORE(pf.a0, pf.b0, 0);
;   BLOAD(pf.a0, pf.b0, 2);
;   __syncthreads();
; #pragma unroll
;   for (int kt = 0; kt < nk; kt += 2) {
;     BCOMP(0);
;     BSTORE(pf.a1, pf.b1, 1);
;     if (kt + 3 < nk) BLOAD(pf.a1, pf.b1, kt + 3);
;     __syncthreads();
;     BCOMP(1);
;     if (kt + 2 < nk) { BSTORE(pf.a0, pf.b0, 0); if (kt + 4 < nk) BLOAD(pf.a0, pf.b0, kt + 4); }
;     __syncthreads();
	s_setprio 1
	ds_read_b128 v[224:227], v126 offset:24576
	ds_read_b128 v[232:235], v128 offset:24576
	ds_read_b128 v[236:239], v128 offset:26624
	ds_read_b128 v[228:231], v126 offset:26624
	ds_read_b128 v[240:243], v128 offset:32768
	ds_read_b128 v[244:247], v128 offset:34816
	ds_read_b128 v[248:251], v127 offset:24576
	ds_read_b128 v[160:163], v129 offset:24576
	ds_read_b128 v[164:167], v129 offset:26624
	ds_read_b128 v[156:159], v127 offset:26624
	ds_read_b128 v[168:171], v129 offset:32768
	ds_read_b128 v[122:125], v129 offset:34816
	s_add_u32 m0, s16, 0x0
	s_add_u32 s42, s42, 0x100000
	s_addc_u32 s43, s43, 0
	global_load_lds_dwordx4 v137, s[42:43]
	global_load_lds_dwordx4 v150, s[42:43] offset:1024
	s_add_u32 m0, s0, 0x0
	s_add_u32 s30, s30, 0x10000
	s_addc_u32 s31, s31, 0
	global_load_lds_dwordx4 v151, s[30:31]
	global_load_lds_dwordx4 v152, s[30:31] offset:1024
	global_load_lds_dwordx4 v153, s[30:31] offset:2048
	global_load_lds_dwordx4 v154, s[30:31] offset:3072
	s_waitcnt lgkmcnt(10)
	v_mfma_f32_32x32x16_bf16 v[34:49], v[224:227], v[232:235], v[34:49]
	s_waitcnt lgkmcnt(9)
	v_mfma_f32_32x32x16_bf16 v[50:65], v[224:227], v[236:239], v[50:65]
	s_waitcnt lgkmcnt(8)
	v_mfma_f32_32x32x16_bf16 v[2:17], v[228:231], v[232:235], v[2:17]
	v_mfma_f32_32x32x16_bf16 v[18:33], v[228:231], v[236:239], v[18:33]
	s_waitcnt lgkmcnt(7)
	v_mfma_f32_32x32x16_bf16 v[74:89], v[224:227], v[240:243], v[74:89]
	s_waitcnt lgkmcnt(6)
	v_mfma_f32_32x32x16_bf16 v[90:105], v[224:227], v[244:247], v[90:105]
	v_mfma_f32_32x32x16_bf16 v[106:121], v[228:231], v[240:243], v[106:121]
	v_mfma_f32_32x32x16_bf16 v[208:223], v[228:231], v[244:247], v[208:223]
	s_waitcnt lgkmcnt(4)
	v_mfma_f32_32x32x16_bf16 v[34:49], v[248:251], v[160:163], v[34:49]
	s_waitcnt lgkmcnt(3)
	v_mfma_f32_32x32x16_bf16 v[50:65], v[248:251], v[164:167], v[50:65]
	s_waitcnt lgkmcnt(2)
	v_mfma_f32_32x32x16_bf16 v[2:17], v[156:159], v[160:163], v[2:17]
	v_mfma_f32_32x32x16_bf16 v[18:33], v[156:159], v[164:167], v[18:33]
	s_waitcnt lgkmcnt(1)
	v_mfma_f32_32x32x16_bf16 v[74:89], v[248:251], v[168:171], v[74:89]
	s_waitcnt lgkmcnt(0)
	v_mfma_f32_32x32x16_bf16 v[90:105], v[248:251], v[122:125], v[90:105]
	v_mfma_f32_32x32x16_bf16 v[106:121], v[156:159], v[168:171], v[106:121]
	v_mfma_f32_32x32x16_bf16 v[208:223], v[156:159], v[122:125], v[208:223]
	s_setprio 0
	s_waitcnt vmcnt(6)
	s_barrier
	s_setprio 1
	ds_read_b128 v[224:227], v126 offset:49152
	ds_read_b128 v[232:235], v128 offset:49152
	ds_read_b128 v[236:239], v128 offset:51200
	ds_read_b128 v[228:231], v126 offset:51200
	ds_read_b128 v[240:243], v128 offset:57344
	ds_read_b128 v[244:247], v128 offset:59392
	ds_read_b128 v[248:251], v127 offset:49152
	ds_read_b128 v[160:163], v129 offset:49152
	ds_read_b128 v[164:167], v129 offset:51200
	ds_read_b128 v[156:159], v127 offset:51200
	ds_read_b128 v[168:171], v129 offset:57344
	ds_read_b128 v[122:125], v129 offset:59392
	s_add_u32 m0, s16, 0x6000
	s_add_u32 s42, s42, 0x100000
	s_addc_u32 s43, s43, 0
	global_load_lds_dwordx4 v137, s[42:43]
	global_load_lds_dwordx4 v150, s[42:43] offset:1024
	s_add_u32 m0, s0, 0x6000
	s_add_u32 s30, s30, 0x10000
	s_addc_u32 s31, s31, 0
	global_load_lds_dwordx4 v151, s[30:31]
	global_load_lds_dwordx4 v152, s[30:31] offset:1024
	global_load_lds_dwordx4 v153, s[30:31] offset:2048
	global_load_lds_dwordx4 v154, s[30:31] offset:3072
	s_waitcnt lgkmcnt(10)
	v_mfma_f32_32x32x16_bf16 v[34:49], v[224:227], v[232:235], v[34:49]
	s_waitcnt lgkmcnt(9)
	v_mfma_f32_32x32x16_bf16 v[50:65], v[224:227], v[236:239], v[50:65]
	s_waitcnt lgkmcnt(8)
	v_mfma_f32_32x32x16_bf16 v[2:17], v[228:231], v[232:235], v[2:17]
	v_mfma_f32_32x32x16_bf16 v[18:33], v[228:231], v[236:239], v[18:33]
	s_waitcnt lgkmcnt(7)
	v_mfma_f32_32x32x16_bf16 v[74:89], v[224:227], v[240:243], v[74:89]
	s_waitcnt lgkmcnt(6)
	v_mfma_f32_32x32x16_bf16 v[90:105], v[224:227], v[244:247], v[90:105]
	v_mfma_f32_32x32x16_bf16 v[106:121], v[228:231], v[240:243], v[106:121]
	v_mfma_f32_32x32x16_bf16 v[208:223], v[228:231], v[244:247], v[208:223]
	s_waitcnt lgkmcnt(4)
	v_mfma_f32_32x32x16_bf16 v[34:49], v[248:251], v[160:163], v[34:49]
	s_waitcnt lgkmcnt(3)
	v_mfma_f32_32x32x16_bf16 v[50:65], v[248:251], v[164:167], v[50:65]
	s_waitcnt lgkmcnt(2)
	v_mfma_f32_32x32x16_bf16 v[2:17], v[156:159], v[160:163], v[2:17]
	v_mfma_f32_32x32x16_bf16 v[18:33], v[156:159], v[164:167], v[18:33]
	s_waitcnt lgkmcnt(1)
	v_mfma_f32_32x32x16_bf16 v[74:89], v[248:251], v[168:171], v[74:89]
	s_waitcnt lgkmcnt(0)
	v_mfma_f32_32x32x16_bf16 v[90:105], v[248:251], v[122:125], v[90:105]
	v_mfma_f32_32x32x16_bf16 v[106:121], v[156:159], v[168:171], v[106:121]
	v_mfma_f32_32x32x16_bf16 v[208:223], v[156:159], v[122:125], v[208:223]
	s_setprio 0
	s_waitcnt vmcnt(6)
	s_barrier
; #define BLOAD(A_, B_, kt) do { _Pragma("unroll") for (int i = 0; i < 4; ++i) { \
;     A_[i] = *(const u32x4*)((const char*)Ap + (aoff + (unsigned)(32 * i * lda + (kt) * 64) * 2u)); B_[i] = *(const u32x4*)((const char*)Wt + (woff + (unsigned)(32 * i * K + (kt) * 64) * 2u)); } } while (0)
; #define BLOAD(A_, B_, kt) do { _Pragma("unroll") for (int i = 0; i < 4; ++i) { \
;     A_[i] = *(const u32x4*)((const char*)Ap + (aoff + (unsigned)(32 * i * lda + (kt) * 64) * 2u)); B_[i] = *(const u32x4*)((const char*)Wt + (woff + (unsigned)(32 * i * K + (kt) * 64) * 2u)); } } while (0)
; #define BSTORE(A_, B_, buf) do { _Pragma("unroll") for (int i = 0; i < 4; ++i) { \
;     *(u32x4*)&As[(buf) * GBUF + (srow + 32 * i) * LDT + sc8] = A_[i]; \
;     *(u32x4*)&Bs[(buf) * GBUF + (srow + 32 * i) * LDT + sc8] = B_[i]; } } while (0)
; template <int NK>
; DI void gemm_run(PF& pf, const u16* __restrict__ Ap, int lda, const u16* __restrict__ Wt, f32x16 (&acc)[2][2], char* smem) {
;     ...
;   __builtin_amdgcn_s_setprio(0);
;   __syncthreads();
;   BSTORE(pf.a0, pf.b0, 0);
;   BLOAD(pf.a0, pf.b0, 2);
;   __syncthreads();
; #pragma unroll
;   for (int kt = 0; kt < nk; kt += 2) {
;     BCOMP(0);
;     BSTORE(pf.a1, pf.b1, 1);
;     if (kt + 3 < nk) BLOAD(pf.a1, pf.b1, kt + 3);
;     __syncthreads();
;     BCOMP(1);
;     if (kt + 2 < nk) { BSTORE(pf.a0, pf.b0, 0); if (kt + 4 < nk) BLOAD(pf.a0, pf.b0, kt + 4); }
;     __syncthreads();
	s_setprio 1
	ds_read_b128 v[224:227], v126 offset:0
	ds_read_b128 v[232:235], v128 offset:0
	ds_read_b128 v[236:239], v128 offset:2048
	ds_read_b128 v[228:231], v126 offset:2048
	ds_read_b128 v[240:243], v128 offset:8192
	ds_read_b128 v[244:247], v128 offset:10240
	ds_read_b128 v[248:251], v127 offset:0
	ds_read_b128 v[160:163], v129 offset:0
	ds_read_b128 v[164:167], v129 offset:2048
	ds_read_b128 v[156:159], v127 offset:2048
	ds_read_b128 v[168:171], v129 offset:8192
	ds_read_b128 v[122:125], v129 offset:10240
	s_add_u32 m0, s16, 0xc000
	s_add_u32 s42, s42, 0x100000
	s_addc_u32 s43, s43, 0
	global_load_lds_dwordx4 v137, s[42:43]
	global_load_lds_dwordx4 v150, s[42:43] offset:1024
	s_add_u32 m0, s0, 0xc000
	s_add_u32 s30, s30, 0x10000
	s_addc_u32 s31, s31, 0
	global_load_lds_dwordx4 v151, s[30:31]
	global_load_lds_dwordx4 v152, s[30:31] offset:1024
	global_load_lds_dwordx4 v153, s[30:31] offset:2048
	global_load_lds_dwordx4 v154, s[30:31] offset:3072
	s_waitcnt lgkmcnt(10)
	v_mfma_f32_32x32x16_bf16 v[34:49], v[224:227], v[232:235], v[34:49]
	s_waitcnt lgkmcnt(9)
	v_mfma_f32_32x32x16_bf16 v[50:65], v[224:227], v[236:239], v[50:65]
	s_waitcnt lgkmcnt(8)
	v_mfma_f32_32x32x16_bf16 v[2:17], v[228:231], v[232:235], v[2:17]
	v_mfma_f32_32x32x16_bf16 v[18:33], v[228:231], v[236:239], v[18:33]
	s_waitcnt lgkmcnt(7)
	v_mfma_f32_32x32x16_bf16 v[74:89], v[224:227], v[240:243], v[74:89]
	s_waitcnt lgkmcnt(6)
	v_mfma_f32_32x32x16_bf16 v[90:105], v[224:227], v[244:247], v[90:105]
	v_mfma_f32_32x32x16_bf16 v[106:121], v[228:231], v[240:243], v[106:121]
	v_mfma_f32_32x32x16_bf16 v[208:223], v[228:231], v[244:247], v[208:223]
	s_waitcnt lgkmcnt(4)
	v_mfma_f32_32x32x16_bf16 v[34:49], v[248:251], v[160:163], v[34:49]
	s_waitcnt lgkmcnt(3)
	v_mfma_f32_32x32x16_bf16 v[50:65], v[248:251], v[164:167], v[50:65]
	s_waitcnt lgkmcnt(2)
	v_mfma_f32_32x32x16_bf16 v[2:17], v[156:159], v[160:163], v[2:17]
	v_mfma_f32_32x32x16_bf16 v[18:33], v[156:159], v[164:167], v[18:33]
	s_waitcnt lgkmcnt(1)
	v_mfma_f32_32x32x16_bf16 v[74:89], v[248:251], v[168:171], v[74:89]
	s_waitcnt lgkmcnt(0)
	v_mfma_f32_32x32x16_bf16 v[90:105], v[248:251], v[122:125], v[90:105]
	v_mfma_f32_32x32x16_bf16 v[106:121], v[156:159], v[168:171], v[106:121]
	v_mfma_f32_32x32x16_bf16 v[208:223], v[156:159], v[122:125], v[208:223]
	s_setprio 0
	s_waitcnt vmcnt(6)
	s_barrier
	s_setprio 1
	ds_read_b128 v[224:227], v126 offset:24576
	ds_read_b128 v[232:235], v128 offset:24576
	ds_read_b128 v[236:239], v128 offset:26624
	ds_read_b128 v[228:231], v126 offset:26624
	ds_read_b128 v[240:243], v128 offset:32768
	ds_read_b128 v[244:247], v128 offset:34816
	ds_read_b128 v[248:251], v127 offset:24576
	ds_read_b128 v[160:163], v129 offset:24576
	ds_read_b128 v[164:167], v129 offset:26624
	ds_read_b128 v[156:159], v127 offset:26624
	ds_read_b128 v[168:171], v129 offset:32768
	ds_read_b128 v[122:125], v129 offset:34816
	s_add_u32 m0, s16, 0x0
	s_add_u32 s42, s42, 0x100000
	s_addc_u32 s43, s43, 0
	global_load_lds_dwordx4 v137, s[42:43]
	global_load_lds_dwordx4 v150, s[42:43] offset:1024
	s_add_u32 m0, s0, 0x0
	s_add_u32 s30, s30, 0x10000
	s_addc_u32 s31, s31, 0
	global_load_lds_dwordx4 v151, s[30:31]
	global_load_lds_dwordx4 v152, s[30:31] offset:1024
	global_load_lds_dwordx4 v153, s[30:31] offset:2048
	global_load_lds_dwordx4 v154, s[30:31] offset:3072
	s_waitcnt lgkmcnt(10)
	v_mfma_f32_32x32x16_bf16 v[34:49], v[224:227], v[232:235], v[34:49]
	s_waitcnt lgkmcnt(9)
	v_mfma_f32_32x32x16_bf16 v[50:65], v[224:227], v[236:239], v[50:65]
	s_waitcnt lgkmcnt(8)
	v_mfma_f32_32x32x16_bf16 v[2:17], v[228:231], v[232:235], v[2:17]
	v_mfma_f32_32x32x16_bf16 v[18:33], v[228:231], v[236:239], v[18:33]
	s_waitcnt lgkmcnt(7)
	v_mfma_f32_32x32x16_bf16 v[74:89], v[224:227], v[240:243], v[74:89]
	s_waitcnt lgkmcnt(6)
	v_mfma_f32_32x32x16_bf16 v[90:105], v[224:227], v[244:247], v[90:105]
	v_mfma_f32_32x32x16_bf16 v[106:121], v[228:231], v[240:243], v[106:121]
	v_mfma_f32_32x32x16_bf16 v[208:223], v[228:231], v[244:247], v[208:223]
	s_waitcnt lgkmcnt(4)
	v_mfma_f32_32x32x16_bf16 v[34:49], v[248:251], v[160:163], v[34:49]
	s_waitcnt lgkmcnt(3)
	v_mfma_f32_32x32x16_bf16 v[50:65], v[248:251], v[164:167], v[50:65]
	s_waitcnt lgkmcnt(2)
	v_mfma_f32_32x32x16_bf16 v[2:17], v[156:159], v[160:163], v[2:17]
	v_mfma_f32_32x32x16_bf16 v[18:33], v[156:159], v[164:167], v[18:33]
	s_waitcnt lgkmcnt(1)
	v_mfma_f32_32x32x16_bf16 v[74:89], v[248:251], v[168:171], v[74:89]
	s_waitcnt lgkmcnt(0)
	v_mfma_f32_32x32x16_bf16 v[90:105], v[248:251], v[122:125], v[90:105]
	v_mfma_f32_32x32x16_bf16 v[106:121], v[156:159], v[168:171], v[106:121]
	v_mfma_f32_32x32x16_bf16 v[208:223], v[156:159], v[122:125], v[208:223]
	s_setprio 0
	s_waitcnt vmcnt(6)
	s_barrier
; #define BLOAD(A_, B_, kt) do { _Pragma("unroll") for (int i = 0; i < 4; ++i) { \
;     A_[i] = *(const u32x4*)((const char*)Ap + (aoff + (unsigned)(32 * i * lda + (kt) * 64) * 2u)); B_[i] = *(const u32x4*)((const char*)Wt + (woff + (unsigned)(32 * i * K + (kt) * 64) * 2u)); } } while (0)
; #define BLOAD(A_, B_, kt) do { _Pragma("unroll") for (int i = 0; i < 4; ++i) { \
;     A_[i] = *(const u32x4*)((const char*)Ap + (aoff + (unsigned)(32 * i * lda + (kt) * 64) * 2u)); B_[i] = *(const u32x4*)((const char*)Wt + (woff + (unsigned)(32 * i * K + (kt) * 64) * 2u)); } } while (0)
; #define BSTORE(A_, B_, buf) do { _Pragma("unroll") for (int i = 0; i < 4; ++i) { \
;     *(u32x4*)&As[(buf) * GBUF + (srow + 32 * i) * LDT + sc8] = A_[i]; \
;     *(u32x4*)&Bs[(buf) * GBUF + (srow + 32 * i) * LDT + sc8] = B_[i]; } } while (0)
; template <int NK>
; DI void gemm_run(PF& pf, const u16* __restrict__ Ap, int lda, const u16* __restrict__ Wt, f32x16 (&acc)[2][2], char* smem) {
;     ...
;   __builtin_amdgcn_s_setprio(0);
;   __syncthreads();
;   BSTORE(pf.a0, pf.b0, 0);
;   BLOAD(pf.a0, pf.b0, 2);
;   __syncthreads();
; #pragma unroll
;   for (int kt = 0; kt < nk; kt += 2) {
;     BCOMP(0);
;     BSTORE(pf.a1, pf.b1, 1);
;     if (kt + 3 < nk) BLOAD(pf.a1, pf.b1, kt + 3);
;     __syncthreads();
;     BCOMP(1);
;     if (kt + 2 < nk) { BSTORE(pf.a0, pf.b0, 0); if (kt + 4 < nk) BLOAD(pf.a0, pf.b0, kt + 4); }
;     __syncthreads();
	s_setprio 1
	ds_read_b128 v[224:227], v126 offset:49152
	ds_read_b128 v[232:235], v128 offset:49152
	ds_read_b128 v[236:239], v128 offset:51200
	ds_read_b128 v[228:231], v126 offset:51200
	ds_read_b128 v[240:243], v128 offset:57344
	ds_read_b128 v[244:247], v128 offset:59392
	ds_read_b128 v[248:251], v127 offset:49152
	ds_read_b128 v[160:163], v129 offset:49152
	ds_read_b128 v[164:167], v129 offset:51200
	ds_read_b128 v[156:159], v127 offset:51200
	ds_read_b128 v[168:171], v129 offset:57344
	ds_read_b128 v[122:125], v129 offset:59392
	s_add_u32 m0, s16, 0x6000
	s_add_u32 s42, s42, 0x100000
	s_addc_u32 s43, s43, 0
	global_load_lds_dwordx4 v137, s[42:43]
	global_load_lds_dwordx4 v150, s[42:43] offset:1024
	s_add_u32 m0, s0, 0x6000
	s_add_u32 s30, s30, 0x10000
	s_addc_u32 s31, s31, 0
	global_load_lds_dwordx4 v151, s[30:31]
	global_load_lds_dwordx4 v152, s[30:31] offset:1024
	global_load_lds_dwordx4 v153, s[30:31] offset:2048
	global_load_lds_dwordx4 v154, s[30:31] offset:3072
	s_waitcnt lgkmcnt(10)
	v_mfma_f32_32x32x16_bf16 v[34:49], v[224:227], v[232:235], v[34:49]
	s_waitcnt lgkmcnt(9)
	v_mfma_f32_32x32x16_bf16 v[50:65], v[224:227], v[236:239], v[50:65]
	s_waitcnt lgkmcnt(8)
	v_mfma_f32_32x32x16_bf16 v[2:17], v[228:231], v[232:235], v[2:17]
	v_mfma_f32_32x32x16_bf16 v[18:33], v[228:231], v[236:239], v[18:33]
	s_waitcnt lgkmcnt(7)
	v_mfma_f32_32x32x16_bf16 v[74:89], v[224:227], v[240:243], v[74:89]
	s_waitcnt lgkmcnt(6)
	v_mfma_f32_32x32x16_bf16 v[90:105], v[224:227], v[244:247], v[90:105]
	v_mfma_f32_32x32x16_bf16 v[106:121], v[228:231], v[240:243], v[106:121]
	v_mfma_f32_32x32x16_bf16 v[208:223], v[228:231], v[244:247], v[208:223]
	s_waitcnt lgkmcnt(4)
	v_mfma_f32_32x32x16_bf16 v[34:49], v[248:251], v[160:163], v[34:49]
	s_waitcnt lgkmcnt(3)
	v_mfma_f32_32x32x16_bf16 v[50:65], v[248:251], v[164:167], v[50:65]
	s_waitcnt lgkmcnt(2)
	v_mfma_f32_32x32x16_bf16 v[2:17], v[156:159], v[160:163], v[2:17]
	v_mfma_f32_32x32x16_bf16 v[18:33], v[156:159], v[164:167], v[18:33]
	s_waitcnt lgkmcnt(1)
	v_mfma_f32_32x32x16_bf16 v[74:89], v[248:251], v[168:171], v[74:89]
	s_waitcnt lgkmcnt(0)
	v_mfma_f32_32x32x16_bf16 v[90:105], v[248:251], v[122:125], v[90:105]
	v_mfma_f32_32x32x16_bf16 v[106:121], v[156:159], v[168:171], v[106:121]
	v_mfma_f32_32x32x16_bf16 v[208:223], v[156:159], v[122:125], v[208:223]
	s_setprio 0
	s_waitcnt vmcnt(6)
	s_barrier
	s_setprio 1
	ds_read_b128 v[224:227], v126 offset:0
	ds_read_b128 v[232:235], v128 offset:0
	ds_read_b128 v[236:239], v128 offset:2048
	ds_read_b128 v[228:231], v126 offset:2048
	ds_read_b128 v[240:243], v128 offset:8192
	ds_read_b128 v[244:247], v128 offset:10240
	ds_read_b128 v[248:251], v127 offset:0
	ds_read_b128 v[160:163], v129 offset:0
	ds_read_b128 v[164:167], v129 offset:2048
	ds_read_b128 v[156:159], v127 offset:2048
	ds_read_b128 v[168:171], v129 offset:8192
	ds_read_b128 v[122:125], v129 offset:10240
	s_add_u32 m0, s16, 0xc000
	s_add_u32 s42, s42, 0x100000
	s_addc_u32 s43, s43, 0
	global_load_lds_dwordx4 v137, s[42:43]
	global_load_lds_dwordx4 v150, s[42:43] offset:1024
	s_add_u32 m0, s0, 0xc000
	s_add_u32 s30, s30, 0x10000
	s_addc_u32 s31, s31, 0
	global_load_lds_dwordx4 v151, s[30:31]
	global_load_lds_dwordx4 v152, s[30:31] offset:1024
	global_load_lds_dwordx4 v153, s[30:31] offset:2048
	global_load_lds_dwordx4 v154, s[30:31] offset:3072
	s_waitcnt lgkmcnt(10)
	v_mfma_f32_32x32x16_bf16 v[34:49], v[224:227], v[232:235], v[34:49]
	s_waitcnt lgkmcnt(9)
	v_mfma_f32_32x32x16_bf16 v[50:65], v[224:227], v[236:239], v[50:65]
	s_waitcnt lgkmcnt(8)
	v_mfma_f32_32x32x16_bf16 v[2:17], v[228:231], v[232:235], v[2:17]
	v_mfma_f32_32x32x16_bf16 v[18:33], v[228:231], v[236:239], v[18:33]
	s_waitcnt lgkmcnt(7)
	v_mfma_f32_32x32x16_bf16 v[74:89], v[224:227], v[240:243], v[74:89]
	s_waitcnt lgkmcnt(6)
	v_mfma_f32_32x32x16_bf16 v[90:105], v[224:227], v[244:247], v[90:105]
	v_mfma_f32_32x32x16_bf16 v[106:121], v[228:231], v[240:243], v[106:121]
	v_mfma_f32_32x32x16_bf16 v[208:223], v[228:231], v[244:247], v[208:223]
	s_waitcnt lgkmcnt(4)
	v_mfma_f32_32x32x16_bf16 v[34:49], v[248:251], v[160:163], v[34:49]
	s_waitcnt lgkmcnt(3)
	v_mfma_f32_32x32x16_bf16 v[50:65], v[248:251], v[164:167], v[50:65]
	s_waitcnt lgkmcnt(2)
	v_mfma_f32_32x32x16_bf16 v[2:17], v[156:159], v[160:163], v[2:17]
	v_mfma_f32_32x32x16_bf16 v[18:33], v[156:159], v[164:167], v[18:33]
	s_waitcnt lgkmcnt(1)
	v_mfma_f32_32x32x16_bf16 v[74:89], v[248:251], v[168:171], v[74:89]
	s_waitcnt lgkmcnt(0)
	v_mfma_f32_32x32x16_bf16 v[90:105], v[248:251], v[122:125], v[90:105]
	v_mfma_f32_32x32x16_bf16 v[106:121], v[156:159], v[168:171], v[106:121]
	v_mfma_f32_32x32x16_bf16 v[208:223], v[156:159], v[122:125], v[208:223]
	s_setprio 0
	s_waitcnt vmcnt(6)
	s_barrier
; #define BLOAD(A_, B_, kt) do { _Pragma("unroll") for (int i = 0; i < 4; ++i) { \
;     A_[i] = *(const u32x4*)((const char*)Ap + (aoff + (unsigned)(32 * i * lda + (kt) * 64) * 2u)); B_[i] = *(const u32x4*)((const char*)Wt + (woff + (unsigned)(32 * i * K + (kt) * 64) * 2u)); } } while (0)
; #define BLOAD(A_, B_, kt) do { _Pragma("unroll") for (int i = 0; i < 4; ++i) { \
;     A_[i] = *(const u32x4*)((const char*)Ap + (aoff + (unsigned)(32 * i * lda + (kt) * 64) * 2u)); B_[i] = *(const u32x4*)((const char*)Wt + (woff + (unsigned)(32 * i * K + (kt) * 64) * 2u)); } } while (0)
; #define BSTORE(A_, B_, buf) do { _Pragma("unroll") for (int i = 0; i < 4; ++i) { \
;     *(u32x4*)&As[(buf) * GBUF + (srow + 32 * i) * LDT + sc8] = A_[i]; \
;     *(u32x4*)&Bs[(buf) * GBUF + (srow + 32 * i) * LDT + sc8] = B_[i]; } } while (0)
; template <int NK>
; DI void gemm_run(PF& pf, const u16* __restrict__ Ap, int lda, const u16* __restrict__ Wt, f32x16 (&acc)[2][2], char* smem) {
;     ...
;   __builtin_amdgcn_s_setprio(0);
;   __syncthreads();
;   BSTORE(pf.a0, pf.b0, 0);
;   BLOAD(pf.a0, pf.b0, 2);
;   __syncthreads();
; #pragma unroll
;   for (int kt = 0; kt < nk; kt += 2) {
;     BCOMP(0);
;     BSTORE(pf.a1, pf.b1, 1);
;     if (kt + 3 < nk) BLOAD(pf.a1, pf.b1, kt + 3);
;     __syncthreads();
;     BCOMP(1);
;     if (kt + 2 < nk) { BSTORE(pf.a0, pf.b0, 0); if (kt + 4 < nk) BLOAD(pf.a0, pf.b0, kt + 4); }
;     __syncthreads();
	s_setprio 1
	ds_read_b128 v[224:227], v126 offset:24576
	ds_read_b128 v[232:235], v128 offset:24576
	ds_read_b128 v[236:239], v128 offset:26624
	ds_read_b128 v[228:231], v126 offset:26624
	ds_read_b128 v[240:243], v128 offset:32768
	ds_read_b128 v[244:247], v128 offset:34816
	ds_read_b128 v[248:251], v127 offset:24576
	ds_read_b128 v[160:163], v129 offset:24576
	ds_read_b128 v[164:167], v129 offset:26624
	ds_read_b128 v[156:159], v127 offset:26624
	ds_read_b128 v[168:171], v129 offset:32768
	ds_read_b128 v[122:125], v129 offset:34816
	s_add_u32 m0, s16, 0x0
	s_add_u32 s42, s42, 0x100000
	s_addc_u32 s43, s43, 0
	global_load_lds_dwordx4 v137, s[42:43]
	global_load_lds_dwordx4 v150, s[42:43] offset:1024
	s_add_u32 m0, s0, 0x0
	s_add_u32 s30, s30, 0x10000
	s_addc_u32 s31, s31, 0
	global_load_lds_dwordx4 v151, s[30:31]
	global_load_lds_dwordx4 v152, s[30:31] offset:1024
	global_load_lds_dwordx4 v153, s[30:31] offset:2048
	global_load_lds_dwordx4 v154, s[30:31] offset:3072
	s_waitcnt lgkmcnt(10)
	v_mfma_f32_32x32x16_bf16 v[34:49], v[224:227], v[232:235], v[34:49]
	s_waitcnt lgkmcnt(9)
	v_mfma_f32_32x32x16_bf16 v[50:65], v[224:227], v[236:239], v[50:65]
	s_waitcnt lgkmcnt(8)
	v_mfma_f32_32x32x16_bf16 v[2:17], v[228:231], v[232:235], v[2:17]
	v_mfma_f32_32x32x16_bf16 v[18:33], v[228:231], v[236:239], v[18:33]
	s_waitcnt lgkmcnt(7)
	v_mfma_f32_32x32x16_bf16 v[74:89], v[224:227], v[240:243], v[74:89]
	s_waitcnt lgkmcnt(6)
	v_mfma_f32_32x32x16_bf16 v[90:105], v[224:227], v[244:247], v[90:105]
	v_mfma_f32_32x32x16_bf16 v[106:121], v[228:231], v[240:243], v[106:121]
	v_mfma_f32_32x32x16_bf16 v[208:223], v[228:231], v[244:247], v[208:223]
	s_waitcnt lgkmcnt(4)
	v_mfma_f32_32x32x16_bf16 v[34:49], v[248:251], v[160:163], v[34:49]
	s_waitcnt lgkmcnt(3)
	v_mfma_f32_32x32x16_bf16 v[50:65], v[248:251], v[164:167], v[50:65]
	s_waitcnt lgkmcnt(2)
	v_mfma_f32_32x32x16_bf16 v[2:17], v[156:159], v[160:163], v[2:17]
	v_mfma_f32_32x32x16_bf16 v[18:33], v[156:159], v[164:167], v[18:33]
	s_waitcnt lgkmcnt(1)
	v_mfma_f32_32x32x16_bf16 v[74:89], v[248:251], v[168:171], v[74:89]
	s_waitcnt lgkmcnt(0)
	v_mfma_f32_32x32x16_bf16 v[90:105], v[248:251], v[122:125], v[90:105]
	v_mfma_f32_32x32x16_bf16 v[106:121], v[156:159], v[168:171], v[106:121]
	v_mfma_f32_32x32x16_bf16 v[208:223], v[156:159], v[122:125], v[208:223]
	s_setprio 0
	s_waitcnt vmcnt(6)
	s_barrier
	s_setprio 1
	ds_read_b128 v[224:227], v126 offset:49152
	ds_read_b128 v[232:235], v128 offset:49152
	ds_read_b128 v[236:239], v128 offset:51200
	ds_read_b128 v[228:231], v126 offset:51200
	ds_read_b128 v[240:243], v128 offset:57344
	ds_read_b128 v[244:247], v128 offset:59392
	ds_read_b128 v[248:251], v127 offset:49152
	ds_read_b128 v[160:163], v129 offset:49152
	ds_read_b128 v[164:167], v129 offset:51200
	ds_read_b128 v[156:159], v127 offset:51200
	ds_read_b128 v[168:171], v129 offset:57344
	ds_read_b128 v[122:125], v129 offset:59392
	s_add_u32 m0, s16, 0x6000
	s_add_u32 s42, s42, 0x100000
	s_addc_u32 s43, s43, 0
	global_load_lds_dwordx4 v137, s[42:43]
	global_load_lds_dwordx4 v150, s[42:43] offset:1024
	s_add_u32 m0, s0, 0x6000
	s_add_u32 s30, s30, 0x10000
	s_addc_u32 s31, s31, 0
	global_load_lds_dwordx4 v151, s[30:31]
	global_load_lds_dwordx4 v152, s[30:31] offset:1024
	global_load_lds_dwordx4 v153, s[30:31] offset:2048
	global_load_lds_dwordx4 v154, s[30:31] offset:3072
	s_waitcnt lgkmcnt(10)
	v_mfma_f32_32x32x16_bf16 v[34:49], v[224:227], v[232:235], v[34:49]
	s_waitcnt lgkmcnt(9)
	v_mfma_f32_32x32x16_bf16 v[50:65], v[224:227], v[236:239], v[50:65]
	s_waitcnt lgkmcnt(8)
	v_mfma_f32_32x32x16_bf16 v[2:17], v[228:231], v[232:235], v[2:17]
	v_mfma_f32_32x32x16_bf16 v[18:33], v[228:231], v[236:239], v[18:33]
	s_waitcnt lgkmcnt(7)
	v_mfma_f32_32x32x16_bf16 v[74:89], v[224:227], v[240:243], v[74:89]
	s_waitcnt lgkmcnt(6)
	v_mfma_f32_32x32x16_bf16 v[90:105], v[224:227], v[244:247], v[90:105]
	v_mfma_f32_32x32x16_bf16 v[106:121], v[228:231], v[240:243], v[106:121]
	v_mfma_f32_32x32x16_bf16 v[208:223], v[228:231], v[244:247], v[208:223]
	s_waitcnt lgkmcnt(4)
	v_mfma_f32_32x32x16_bf16 v[34:49], v[248:251], v[160:163], v[34:49]
	s_waitcnt lgkmcnt(3)
	v_mfma_f32_32x32x16_bf16 v[50:65], v[248:251], v[164:167], v[50:65]
	s_waitcnt lgkmcnt(2)
	v_mfma_f32_32x32x16_bf16 v[2:17], v[156:159], v[160:163], v[2:17]
	v_mfma_f32_32x32x16_bf16 v[18:33], v[156:159], v[164:167], v[18:33]
	s_waitcnt lgkmcnt(1)
	v_mfma_f32_32x32x16_bf16 v[74:89], v[248:251], v[168:171], v[74:89]
	s_waitcnt lgkmcnt(0)
	v_mfma_f32_32x32x16_bf16 v[90:105], v[248:251], v[122:125], v[90:105]
	v_mfma_f32_32x32x16_bf16 v[106:121], v[156:159], v[168:171], v[106:121]
	v_mfma_f32_32x32x16_bf16 v[208:223], v[156:159], v[122:125], v[208:223]
	s_setprio 0
	s_waitcnt vmcnt(6)
	s_barrier
; #define BLOAD(A_, B_, kt) do { _Pragma("unroll") for (int i = 0; i < 4; ++i) { \
;     A_[i] = *(const u32x4*)((const char*)Ap + (aoff + (unsigned)(32 * i * lda + (kt) * 64) * 2u)); B_[i] = *(const u32x4*)((const char*)Wt + (woff + (unsigned)(32 * i * K + (kt) * 64) * 2u)); } } while (0)
; #define BLOAD(A_, B_, kt) do { _Pragma("unroll") for (int i = 0; i < 4; ++i) { \
;     A_[i] = *(const u32x4*)((const char*)Ap + (aoff + (unsigned)(32 * i * lda + (kt) * 64) * 2u)); B_[i] = *(const u32x4*)((const char*)Wt + (woff + (unsigned)(32 * i * K + (kt) * 64) * 2u)); } } while (0)
; #define BSTORE(A_, B_, buf) do { _Pragma("unroll") for (int i = 0; i < 4; ++i) { \
;     *(u32x4*)&As[(buf) * GBUF + (srow + 32 * i) * LDT + sc8] = A_[i]; \
;     *(u32x4*)&Bs[(buf) * GBUF + (srow + 32 * i) * LDT + sc8] = B_[i]; } } while (0)
; template <int NK>
; DI void gemm_run(PF& pf, const u16* __restrict__ Ap, int lda, const u16* __restrict__ Wt, f32x16 (&acc)[2][2], char* smem) {
;     ...
;   __builtin_amdgcn_s_setprio(0);
;   __syncthreads();
;   BSTORE(pf.a0, pf.b0, 0);
;   BLOAD(pf.a0, pf.b0, 2);
;   __syncthreads();
; #pragma unroll
;   for (int kt = 0; kt < nk; kt += 2) {
;     BCOMP(0);
;     BSTORE(pf.a1, pf.b1, 1);
;     if (kt + 3 < nk) BLOAD(pf.a1, pf.b1, kt + 3);
;     __syncthreads();
;     BCOMP(1);
;     if (kt + 2 < nk) { BSTORE(pf.a0, pf.b0, 0); if (kt + 4 < nk) BLOAD(pf.a0, pf.b0, kt + 4); }
;     __syncthreads();
	s_setprio 1
	ds_read_b128 v[224:227], v126 offset:0
	ds_read_b128 v[232:235], v128 offset:0
	ds_read_b128 v[236:239], v128 offset:2048
	ds_read_b128 v[228:231], v126 offset:2048
	ds_read_b128 v[240:243], v128 offset:8192
	ds_read_b128 v[244:247], v128 offset:10240
	ds_read_b128 v[248:251], v127 offset:0
	ds_read_b128 v[160:163], v129 offset:0
	ds_read_b128 v[164:167], v129 offset:2048
	ds_read_b128 v[156:159], v127 offset:2048
	ds_read_b128 v[168:171], v129 offset:8192
	ds_read_b128 v[122:125], v129 offset:10240
	s_add_u32 m0, s16, 0xc000
	s_add_u32 s42, s42, 0x100000
	s_addc_u32 s43, s43, 0
	global_load_lds_dwordx4 v137, s[42:43]
	global_load_lds_dwordx4 v150, s[42:43] offset:1024
	s_add_u32 m0, s0, 0xc000
	s_add_u32 s30, s30, 0x10000
	s_addc_u32 s31, s31, 0
	global_load_lds_dwordx4 v151, s[30:31]
	global_load_lds_dwordx4 v152, s[30:31] offset:1024
	global_load_lds_dwordx4 v153, s[30:31] offset:2048
	global_load_lds_dwordx4 v154, s[30:31] offset:3072
	s_waitcnt lgkmcnt(10)
	v_mfma_f32_32x32x16_bf16 v[34:49], v[224:227], v[232:235], v[34:49]
	s_waitcnt lgkmcnt(9)
	v_mfma_f32_32x32x16_bf16 v[50:65], v[224:227], v[236:239], v[50:65]
	s_waitcnt lgkmcnt(8)
	v_mfma_f32_32x32x16_bf16 v[2:17], v[228:231], v[232:235], v[2:17]
	v_mfma_f32_32x32x16_bf16 v[18:33], v[228:231], v[236:239], v[18:33]
	s_waitcnt lgkmcnt(7)
	v_mfma_f32_32x32x16_bf16 v[74:89], v[224:227], v[240:243], v[74:89]
	s_waitcnt lgkmcnt(6)
	v_mfma_f32_32x32x16_bf16 v[90:105], v[224:227], v[244:247], v[90:105]
	v_mfma_f32_32x32x16_bf16 v[106:121], v[228:231], v[240:243], v[106:121]
	v_mfma_f32_32x32x16_bf16 v[208:223], v[228:231], v[244:247], v[208:223]
	s_waitcnt lgkmcnt(4)
	v_mfma_f32_32x32x16_bf16 v[34:49], v[248:251], v[160:163], v[34:49]
	s_waitcnt lgkmcnt(3)
	v_mfma_f32_32x32x16_bf16 v[50:65], v[248:251], v[164:167], v[50:65]
	s_waitcnt lgkmcnt(2)
	v_mfma_f32_32x32x16_bf16 v[2:17], v[156:159], v[160:163], v[2:17]
	v_mfma_f32_32x32x16_bf16 v[18:33], v[156:159], v[164:167], v[18:33]
	s_waitcnt lgkmcnt(1)
	v_mfma_f32_32x32x16_bf16 v[74:89], v[248:251], v[168:171], v[74:89]
	s_waitcnt lgkmcnt(0)
	v_mfma_f32_32x32x16_bf16 v[90:105], v[248:251], v[122:125], v[90:105]
	v_mfma_f32_32x32x16_bf16 v[106:121], v[156:159], v[168:171], v[106:121]
	v_mfma_f32_32x32x16_bf16 v[208:223], v[156:159], v[122:125], v[208:223]
	s_setprio 0
	s_waitcnt vmcnt(6)
	s_barrier
	s_setprio 1
	ds_read_b128 v[224:227], v126 offset:24576
	ds_read_b128 v[232:235], v128 offset:24576
	ds_read_b128 v[236:239], v128 offset:26624
	ds_read_b128 v[228:231], v126 offset:26624
	ds_read_b128 v[240:243], v128 offset:32768
	ds_read_b128 v[244:247], v128 offset:34816
	ds_read_b128 v[248:251], v127 offset:24576
	ds_read_b128 v[160:163], v129 offset:24576
	ds_read_b128 v[164:167], v129 offset:26624
	ds_read_b128 v[156:159], v127 offset:26624
	ds_read_b128 v[168:171], v129 offset:32768
	ds_read_b128 v[122:125], v129 offset:34816
	s_add_u32 m0, s16, 0x0
	s_add_u32 s42, s42, 0x100000
	s_addc_u32 s43, s43, 0
	global_load_lds_dwordx4 v137, s[42:43]
	global_load_lds_dwordx4 v150, s[42:43] offset:1024
	s_add_u32 m0, s0, 0x0
	s_add_u32 s30, s30, 0x10000
	s_addc_u32 s31, s31, 0
	global_load_lds_dwordx4 v151, s[30:31]
	global_load_lds_dwordx4 v152, s[30:31] offset:1024
	global_load_lds_dwordx4 v153, s[30:31] offset:2048
	global_load_lds_dwordx4 v154, s[30:31] offset:3072
	s_waitcnt lgkmcnt(10)
	v_mfma_f32_32x32x16_bf16 v[34:49], v[224:227], v[232:235], v[34:49]
	s_waitcnt lgkmcnt(9)
	v_mfma_f32_32x32x16_bf16 v[50:65], v[224:227], v[236:239], v[50:65]
	s_waitcnt lgkmcnt(8)
	v_mfma_f32_32x32x16_bf16 v[2:17], v[228:231], v[232:235], v[2:17]
	v_mfma_f32_32x32x16_bf16 v[18:33], v[228:231], v[236:239], v[18:33]
	s_waitcnt lgkmcnt(7)
	v_mfma_f32_32x32x16_bf16 v[74:89], v[224:227], v[240:243], v[74:89]
	s_waitcnt lgkmcnt(6)
	v_mfma_f32_32x32x16_bf16 v[90:105], v[224:227], v[244:247], v[90:105]
	v_mfma_f32_32x32x16_bf16 v[106:121], v[228:231], v[240:243], v[106:121]
	v_mfma_f32_32x32x16_bf16 v[208:223], v[228:231], v[244:247], v[208:223]
	s_waitcnt lgkmcnt(4)
	v_mfma_f32_32x32x16_bf16 v[34:49], v[248:251], v[160:163], v[34:49]
	s_waitcnt lgkmcnt(3)
	v_mfma_f32_32x32x16_bf16 v[50:65], v[248:251], v[164:167], v[50:65]
	s_waitcnt lgkmcnt(2)
	v_mfma_f32_32x32x16_bf16 v[2:17], v[156:159], v[160:163], v[2:17]
	v_mfma_f32_32x32x16_bf16 v[18:33], v[156:159], v[164:167], v[18:33]
	s_waitcnt lgkmcnt(1)
	v_mfma_f32_32x32x16_bf16 v[74:89], v[248:251], v[168:171], v[74:89]
	s_waitcnt lgkmcnt(0)
	v_mfma_f32_32x32x16_bf16 v[90:105], v[248:251], v[122:125], v[90:105]
	v_mfma_f32_32x32x16_bf16 v[106:121], v[156:159], v[168:171], v[106:121]
	v_mfma_f32_32x32x16_bf16 v[208:223], v[156:159], v[122:125], v[208:223]
	s_setprio 0
	s_waitcnt vmcnt(6)
	s_barrier
; #define BLOAD(A_, B_, kt) do { _Pragma("unroll") for (int i = 0; i < 4; ++i) { \
;     A_[i] = *(const u32x4*)((const char*)Ap + (aoff + (unsigned)(32 * i * lda + (kt) * 64) * 2u)); B_[i] = *(const u32x4*)((const char*)Wt + (woff + (unsigned)(32 * i * K + (kt) * 64) * 2u)); } } while (0)
; #define BLOAD(A_, B_, kt) do { _Pragma("unroll") for (int i = 0; i < 4; ++i) { \
;     A_[i] = *(const u32x4*)((const char*)Ap + (aoff + (unsigned)(32 * i * lda + (kt) * 64) * 2u)); B_[i] = *(const u32x4*)((const char*)Wt + (woff + (unsigned)(32 * i * K + (kt) * 64) * 2u)); } } while (0)
; #define BSTORE(A_, B_, buf) do { _Pragma("unroll") for (int i = 0; i < 4; ++i) { \
;     *(u32x4*)&As[(buf) * GBUF + (srow + 32 * i) * LDT + sc8] = A_[i]; \
;     *(u32x4*)&Bs[(buf) * GBUF + (srow + 32 * i) * LDT + sc8] = B_[i]; } } while (0)
; template <int NK>
; DI void gemm_run(PF& pf, const u16* __restrict__ Ap, int lda, const u16* __restrict__ Wt, f32x16 (&acc)[2][2], char* smem) {
;     ...
;   __builtin_amdgcn_s_setprio(0);
;   __syncthreads();
;   BSTORE(pf.a0, pf.b0, 0);
;   BLOAD(pf.a0, pf.b0, 2);
;   __syncthreads();
; #pragma unroll
;   for (int kt = 0; kt < nk; kt += 2) {
;     BCOMP(0);
;     BSTORE(pf.a1, pf.b1, 1);
;     if (kt + 3 < nk) BLOAD(pf.a1, pf.b1, kt + 3);
;     __syncthreads();
;     BCOMP(1);
;     if (kt + 2 < nk) { BSTORE(pf.a0, pf.b0, 0); if (kt + 4 < nk) BLOAD(pf.a0, pf.b0, kt + 4); }
;     __syncthreads();
	s_setprio 1
	ds_read_b128 v[224:227], v126 offset:49152
	ds_read_b128 v[232:235], v128 offset:49152
	ds_read_b128 v[236:239], v128 offset:51200
	ds_read_b128 v[228:231], v126 offset:51200
	ds_read_b128 v[240:243], v128 offset:57344
	ds_read_b128 v[244:247], v128 offset:59392
	ds_read_b128 v[248:251], v127 offset:49152
	ds_read_b128 v[160:163], v129 offset:49152
	ds_read_b128 v[164:167], v129 offset:51200
	ds_read_b128 v[156:159], v127 offset:51200
	ds_read_b128 v[168:171], v129 offset:57344
	ds_read_b128 v[122:125], v129 offset:59392
	s_add_u32 m0, s16, 0x6000
	s_add_u32 s42, s42, 0x100000
	s_addc_u32 s43, s43, 0
	global_load_lds_dwordx4 v137, s[42:43]
	global_load_lds_dwordx4 v150, s[42:43] offset:1024
	s_add_u32 m0, s0, 0x6000
	s_add_u32 s30, s30, 0x10000
	s_addc_u32 s31, s31, 0
	global_load_lds_dwordx4 v151, s[30:31]
	global_load_lds_dwordx4 v152, s[30:31] offset:1024
	global_load_lds_dwordx4 v153, s[30:31] offset:2048
	global_load_lds_dwordx4 v154, s[30:31] offset:3072
	s_waitcnt lgkmcnt(10)
	v_mfma_f32_32x32x16_bf16 v[34:49], v[224:227], v[232:235], v[34:49]
	s_waitcnt lgkmcnt(9)
	v_mfma_f32_32x32x16_bf16 v[50:65], v[224:227], v[236:239], v[50:65]
	s_waitcnt lgkmcnt(8)
	v_mfma_f32_32x32x16_bf16 v[2:17], v[228:231], v[232:235], v[2:17]
	v_mfma_f32_32x32x16_bf16 v[18:33], v[228:231], v[236:239], v[18:33]
	s_waitcnt lgkmcnt(7)
	v_mfma_f32_32x32x16_bf16 v[74:89], v[224:227], v[240:243], v[74:89]
	s_waitcnt lgkmcnt(6)
	v_mfma_f32_32x32x16_bf16 v[90:105], v[224:227], v[244:247], v[90:105]
	v_mfma_f32_32x32x16_bf16 v[106:121], v[228:231], v[240:243], v[106:121]
	v_mfma_f32_32x32x16_bf16 v[208:223], v[228:231], v[244:247], v[208:223]
	s_waitcnt lgkmcnt(4)
	v_mfma_f32_32x32x16_bf16 v[34:49], v[248:251], v[160:163], v[34:49]
	s_waitcnt lgkmcnt(3)
	v_mfma_f32_32x32x16_bf16 v[50:65], v[248:251], v[164:167], v[50:65]
	s_waitcnt lgkmcnt(2)
	v_mfma_f32_32x32x16_bf16 v[2:17], v[156:159], v[160:163], v[2:17]
	v_mfma_f32_32x32x16_bf16 v[18:33], v[156:159], v[164:167], v[18:33]
	s_waitcnt lgkmcnt(1)
	v_mfma_f32_32x32x16_bf16 v[74:89], v[248:251], v[168:171], v[74:89]
	s_waitcnt lgkmcnt(0)
	v_mfma_f32_32x32x16_bf16 v[90:105], v[248:251], v[122:125], v[90:105]
	v_mfma_f32_32x32x16_bf16 v[106:121], v[156:159], v[168:171], v[106:121]
	v_mfma_f32_32x32x16_bf16 v[208:223], v[156:159], v[122:125], v[208:223]
	s_setprio 0
	s_waitcnt vmcnt(6)
	s_barrier
	s_setprio 1
	ds_read_b128 v[224:227], v126 offset:0
	ds_read_b128 v[232:235], v128 offset:0
	ds_read_b128 v[236:239], v128 offset:2048
	ds_read_b128 v[228:231], v126 offset:2048
	ds_read_b128 v[240:243], v128 offset:8192
	ds_read_b128 v[244:247], v128 offset:10240
	ds_read_b128 v[248:251], v127 offset:0
	ds_read_b128 v[160:163], v129 offset:0
	ds_read_b128 v[164:167], v129 offset:2048
	ds_read_b128 v[156:159], v127 offset:2048
	ds_read_b128 v[168:171], v129 offset:8192
	ds_read_b128 v[122:125], v129 offset:10240
	s_add_u32 m0, s16, 0xc000
	s_add_u32 s42, s42, 0x100000
	s_addc_u32 s43, s43, 0
	global_load_lds_dwordx4 v137, s[42:43]
	global_load_lds_dwordx4 v150, s[42:43] offset:1024
	s_add_u32 m0, s0, 0xc000
	s_add_u32 s30, s30, 0x10000
	s_addc_u32 s31, s31, 0
	global_load_lds_dwordx4 v151, s[30:31]
	global_load_lds_dwordx4 v152, s[30:31] offset:1024
	global_load_lds_dwordx4 v153, s[30:31] offset:2048
	global_load_lds_dwordx4 v154, s[30:31] offset:3072
	s_waitcnt lgkmcnt(10)
	v_mfma_f32_32x32x16_bf16 v[34:49], v[224:227], v[232:235], v[34:49]
	s_waitcnt lgkmcnt(9)
	v_mfma_f32_32x32x16_bf16 v[50:65], v[224:227], v[236:239], v[50:65]
	s_waitcnt lgkmcnt(8)
	v_mfma_f32_32x32x16_bf16 v[2:17], v[228:231], v[232:235], v[2:17]
	v_mfma_f32_32x32x16_bf16 v[18:33], v[228:231], v[236:239], v[18:33]
	s_waitcnt lgkmcnt(7)
	v_mfma_f32_32x32x16_bf16 v[74:89], v[224:227], v[240:243], v[74:89]
	s_waitcnt lgkmcnt(6)
	v_mfma_f32_32x32x16_bf16 v[90:105], v[224:227], v[244:247], v[90:105]
	v_mfma_f32_32x32x16_bf16 v[106:121], v[228:231], v[240:243], v[106:121]
	v_mfma_f32_32x32x16_bf16 v[208:223], v[228:231], v[244:247], v[208:223]
	s_waitcnt lgkmcnt(4)
	v_mfma_f32_32x32x16_bf16 v[34:49], v[248:251], v[160:163], v[34:49]
	s_waitcnt lgkmcnt(3)
	v_mfma_f32_32x32x16_bf16 v[50:65], v[248:251], v[164:167], v[50:65]
	s_waitcnt lgkmcnt(2)
	v_mfma_f32_32x32x16_bf16 v[2:17], v[156:159], v[160:163], v[2:17]
	v_mfma_f32_32x32x16_bf16 v[18:33], v[156:159], v[164:167], v[18:33]
	s_waitcnt lgkmcnt(1)
	v_mfma_f32_32x32x16_bf16 v[74:89], v[248:251], v[168:171], v[74:89]
	s_waitcnt lgkmcnt(0)
	v_mfma_f32_32x32x16_bf16 v[90:105], v[248:251], v[122:125], v[90:105]
	v_mfma_f32_32x32x16_bf16 v[106:121], v[156:159], v[168:171], v[106:121]
	v_mfma_f32_32x32x16_bf16 v[208:223], v[156:159], v[122:125], v[208:223]
	s_setprio 0
	s_waitcnt vmcnt(6)
	s_barrier
; #define BLOAD(A_, B_, kt) do { _Pragma("unroll") for (int i = 0; i < 4; ++i) { \
;     A_[i] = *(const u32x4*)((const char*)Ap + (aoff + (unsigned)(32 * i * lda + (kt) * 64) * 2u)); B_[i] = *(const u32x4*)((const char*)Wt + (woff + (unsigned)(32 * i * K + (kt) * 64) * 2u)); } } while (0)
; #define BLOAD(A_, B_, kt) do { _Pragma("unroll") for (int i = 0; i < 4; ++i) { \
;     A_[i] = *(const u32x4*)((const char*)Ap + (aoff + (unsigned)(32 * i * lda + (kt) * 64) * 2u)); B_[i] = *(const u32x4*)((const char*)Wt + (woff + (unsigned)(32 * i * K + (kt) * 64) * 2u)); } } while (0)
; #define BSTORE(A_, B_, buf) do { _Pragma("unroll") for (int i = 0; i < 4; ++i) { \
;     *(u32x4*)&As[(buf) * GBUF + (srow + 32 * i) * LDT + sc8] = A_[i]; \
;     *(u32x4*)&Bs[(buf) * GBUF + (srow + 32 * i) * LDT + sc8] = B_[i]; } } while (0)
; template <int NK>
; DI void gemm_run(PF& pf, const u16* __restrict__ Ap, int lda, const u16* __restrict__ Wt, f32x16 (&acc)[2][2], char* smem) {
;     ...
;   __builtin_amdgcn_s_setprio(0);
;   __syncthreads();
;   BSTORE(pf.a0, pf.b0, 0);
;   BLOAD(pf.a0, pf.b0, 2);
;   __syncthreads();
; #pragma unroll
;   for (int kt = 0; kt < nk; kt += 2) {
;     BCOMP(0);
;     BSTORE(pf.a1, pf.b1, 1);
;     if (kt + 3 < nk) BLOAD(pf.a1, pf.b1, kt + 3);
;     __syncthreads();
;     BCOMP(1);
;     if (kt + 2 < nk) { BSTORE(pf.a0, pf.b0, 0); if (kt + 4 < nk) BLOAD(pf.a0, pf.b0, kt + 4); }
;     __syncthreads();
	s_setprio 1
	ds_read_b128 v[224:227], v126 offset:24576
	ds_read_b128 v[232:235], v128 offset:24576
	ds_read_b128 v[236:239], v128 offset:26624
	ds_read_b128 v[228:231], v126 offset:26624
	ds_read_b128 v[240:243], v128 offset:32768
	ds_read_b128 v[244:247], v128 offset:34816
	ds_read_b128 v[248:251], v127 offset:24576
	ds_read_b128 v[160:163], v129 offset:24576
	ds_read_b128 v[164:167], v129 offset:26624
	ds_read_b128 v[156:159], v127 offset:26624
	ds_read_b128 v[168:171], v129 offset:32768
	ds_read_b128 v[122:125], v129 offset:34816
	s_add_u32 m0, s16, 0x0
	s_add_u32 s42, s42, 0x100000
	s_addc_u32 s43, s43, 0
	global_load_lds_dwordx4 v137, s[42:43]
	global_load_lds_dwordx4 v150, s[42:43] offset:1024
	s_add_u32 m0, s0, 0x0
	s_add_u32 s30, s30, 0x10000
	s_addc_u32 s31, s31, 0
	global_load_lds_dwordx4 v151, s[30:31]
	global_load_lds_dwordx4 v152, s[30:31] offset:1024
	global_load_lds_dwordx4 v153, s[30:31] offset:2048
	global_load_lds_dwordx4 v154, s[30:31] offset:3072
	s_waitcnt lgkmcnt(10)
	v_mfma_f32_32x32x16_bf16 v[34:49], v[224:227], v[232:235], v[34:49]
	s_waitcnt lgkmcnt(9)
	v_mfma_f32_32x32x16_bf16 v[50:65], v[224:227], v[236:239], v[50:65]
	s_waitcnt lgkmcnt(8)
	v_mfma_f32_32x32x16_bf16 v[2:17], v[228:231], v[232:235], v[2:17]
	v_mfma_f32_32x32x16_bf16 v[18:33], v[228:231], v[236:239], v[18:33]
	s_waitcnt lgkmcnt(7)
	v_mfma_f32_32x32x16_bf16 v[74:89], v[224:227], v[240:243], v[74:89]
	s_waitcnt lgkmcnt(6)
	v_mfma_f32_32x32x16_bf16 v[90:105], v[224:227], v[244:247], v[90:105]
	v_mfma_f32_32x32x16_bf16 v[106:121], v[228:231], v[240:243], v[106:121]
	v_mfma_f32_32x32x16_bf16 v[208:223], v[228:231], v[244:247], v[208:223]
	s_waitcnt lgkmcnt(4)
	v_mfma_f32_32x32x16_bf16 v[34:49], v[248:251], v[160:163], v[34:49]
	s_waitcnt lgkmcnt(3)
	v_mfma_f32_32x32x16_bf16 v[50:65], v[248:251], v[164:167], v[50:65]
	s_waitcnt lgkmcnt(2)
	v_mfma_f32_32x32x16_bf16 v[2:17], v[156:159], v[160:163], v[2:17]
	v_mfma_f32_32x32x16_bf16 v[18:33], v[156:159], v[164:167], v[18:33]
	s_waitcnt lgkmcnt(1)
	v_mfma_f32_32x32x16_bf16 v[74:89], v[248:251], v[168:171], v[74:89]
	s_waitcnt lgkmcnt(0)
	v_mfma_f32_32x32x16_bf16 v[90:105], v[248:251], v[122:125], v[90:105]
	v_mfma_f32_32x32x16_bf16 v[106:121], v[156:159], v[168:171], v[106:121]
	v_mfma_f32_32x32x16_bf16 v[208:223], v[156:159], v[122:125], v[208:223]
	s_setprio 0
	s_waitcnt vmcnt(6)
	s_barrier
	s_setprio 1
	ds_read_b128 v[224:227], v126 offset:49152
	ds_read_b128 v[232:235], v128 offset:49152
	ds_read_b128 v[236:239], v128 offset:51200
	ds_read_b128 v[228:231], v126 offset:51200
	ds_read_b128 v[240:243], v128 offset:57344
	ds_read_b128 v[244:247], v128 offset:59392
	ds_read_b128 v[248:251], v127 offset:49152
	ds_read_b128 v[160:163], v129 offset:49152
	ds_read_b128 v[164:167], v129 offset:51200
	ds_read_b128 v[156:159], v127 offset:51200
	ds_read_b128 v[168:171], v129 offset:57344
	ds_read_b128 v[122:125], v129 offset:59392
	s_add_u32 m0, s16, 0x6000
	s_add_u32 s42, s42, 0x100000
	s_addc_u32 s43, s43, 0
	global_load_lds_dwordx4 v137, s[42:43]
	global_load_lds_dwordx4 v150, s[42:43] offset:1024
	s_add_u32 m0, s0, 0x6000
	s_add_u32 s30, s30, 0x10000
	s_addc_u32 s31, s31, 0
	global_load_lds_dwordx4 v151, s[30:31]
	global_load_lds_dwordx4 v152, s[30:31] offset:1024
	global_load_lds_dwordx4 v153, s[30:31] offset:2048
	global_load_lds_dwordx4 v154, s[30:31] offset:3072
	s_waitcnt lgkmcnt(10)
	v_mfma_f32_32x32x16_bf16 v[34:49], v[224:227], v[232:235], v[34:49]
	s_waitcnt lgkmcnt(9)
	v_mfma_f32_32x32x16_bf16 v[50:65], v[224:227], v[236:239], v[50:65]
	s_waitcnt lgkmcnt(8)
	v_mfma_f32_32x32x16_bf16 v[2:17], v[228:231], v[232:235], v[2:17]
	v_mfma_f32_32x32x16_bf16 v[18:33], v[228:231], v[236:239], v[18:33]
	s_waitcnt lgkmcnt(7)
	v_mfma_f32_32x32x16_bf16 v[74:89], v[224:227], v[240:243], v[74:89]
	s_waitcnt lgkmcnt(6)
	v_mfma_f32_32x32x16_bf16 v[90:105], v[224:227], v[244:247], v[90:105]
	v_mfma_f32_32x32x16_bf16 v[106:121], v[228:231], v[240:243], v[106:121]
	v_mfma_f32_32x32x16_bf16 v[208:223], v[228:231], v[244:247], v[208:223]
	s_waitcnt lgkmcnt(4)
	v_mfma_f32_32x32x16_bf16 v[34:49], v[248:251], v[160:163], v[34:49]
	s_waitcnt lgkmcnt(3)
	v_mfma_f32_32x32x16_bf16 v[50:65], v[248:251], v[164:167], v[50:65]
	s_waitcnt lgkmcnt(2)
	v_mfma_f32_32x32x16_bf16 v[2:17], v[156:159], v[160:163], v[2:17]
	v_mfma_f32_32x32x16_bf16 v[18:33], v[156:159], v[164:167], v[18:33]
	s_waitcnt lgkmcnt(1)
	v_mfma_f32_32x32x16_bf16 v[74:89], v[248:251], v[168:171], v[74:89]
	s_waitcnt lgkmcnt(0)
	v_mfma_f32_32x32x16_bf16 v[90:105], v[248:251], v[122:125], v[90:105]
	v_mfma_f32_32x32x16_bf16 v[106:121], v[156:159], v[168:171], v[106:121]
	v_mfma_f32_32x32x16_bf16 v[208:223], v[156:159], v[122:125], v[208:223]
	s_setprio 0
	s_waitcnt vmcnt(6)
	s_barrier
; #define BLOAD(A_, B_, kt) do { _Pragma("unroll") for (int i = 0; i < 4; ++i) { \
;     A_[i] = *(const u32x4*)((const char*)Ap + (aoff + (unsigned)(32 * i * lda + (kt) * 64) * 2u)); B_[i] = *(const u32x4*)((const char*)Wt + (woff + (unsigned)(32 * i * K + (kt) * 64) * 2u)); } } while (0)
; #define BLOAD(A_, B_, kt) do { _Pragma("unroll") for (int i = 0; i < 4; ++i) { \
;     A_[i] = *(const u32x4*)((const char*)Ap + (aoff + (unsigned)(32 * i * lda + (kt) * 64) * 2u)); B_[i] = *(const u32x4*)((const char*)Wt + (woff + (unsigned)(32 * i * K + (kt) * 64) * 2u)); } } while (0)
; #define BSTORE(A_, B_, buf) do { _Pragma("unroll") for (int i = 0; i < 4; ++i) { \
;     *(u32x4*)&As[(buf) * GBUF + (srow + 32 * i) * LDT + sc8] = A_[i]; \
;     *(u32x4*)&Bs[(buf) * GBUF + (srow + 32 * i) * LDT + sc8] = B_[i]; } } while (0)
; template <int NK>
; DI void gemm_run(PF& pf, const u16* __restrict__ Ap, int lda, const u16* __restrict__ Wt, f32x16 (&acc)[2][2], char* smem) {
;     ...
;   __builtin_amdgcn_s_setprio(0);
;   __syncthreads();
;   BSTORE(pf.a0, pf.b0, 0);
;   BLOAD(pf.a0, pf.b0, 2);
;   __syncthreads();
; #pragma unroll
;   for (int kt = 0; kt < nk; kt += 2) {
;     BCOMP(0);
;     BSTORE(pf.a1, pf.b1, 1);
;     if (kt + 3 < nk) BLOAD(pf.a1, pf.b1, kt + 3);
;     __syncthreads();
;     BCOMP(1);
;     if (kt + 2 < nk) { BSTORE(pf.a0, pf.b0, 0); if (kt + 4 < nk) BLOAD(pf.a0, pf.b0, kt + 4); }
;     __syncthreads();
	s_setprio 1
	ds_read_b128 v[224:227], v126 offset:0
	ds_read_b128 v[232:235], v128 offset:0
	ds_read_b128 v[236:239], v128 offset:2048
	ds_read_b128 v[228:231], v126 offset:2048
	ds_read_b128 v[240:243], v128 offset:8192
	ds_read_b128 v[244:247], v128 offset:10240
	ds_read_b128 v[248:251], v127 offset:0
	ds_read_b128 v[160:163], v129 offset:0
	ds_read_b128 v[164:167], v129 offset:2048
	ds_read_b128 v[156:159], v127 offset:2048
	ds_read_b128 v[168:171], v129 offset:8192
	ds_read_b128 v[122:125], v129 offset:10240
	s_add_u32 m0, s16, 0xc000
	s_add_u32 s42, s42, 0x100000
	s_addc_u32 s43, s43, 0
	global_load_lds_dwordx4 v137, s[42:43]
	global_load_lds_dwordx4 v150, s[42:43] offset:1024
	s_add_u32 m0, s0, 0xc000
	s_add_u32 s30, s30, 0x10000
	s_addc_u32 s31, s31, 0
	global_load_lds_dwordx4 v151, s[30:31]
	global_load_lds_dwordx4 v152, s[30:31] offset:1024
	global_load_lds_dwordx4 v153, s[30:31] offset:2048
	global_load_lds_dwordx4 v154, s[30:31] offset:3072
	s_waitcnt lgkmcnt(10)
	v_mfma_f32_32x32x16_bf16 v[34:49], v[224:227], v[232:235], v[34:49]
	s_waitcnt lgkmcnt(9)
	v_mfma_f32_32x32x16_bf16 v[50:65], v[224:227], v[236:239], v[50:65]
	s_waitcnt lgkmcnt(8)
	v_mfma_f32_32x32x16_bf16 v[2:17], v[228:231], v[232:235], v[2:17]
	v_mfma_f32_32x32x16_bf16 v[18:33], v[228:231], v[236:239], v[18:33]
	s_waitcnt lgkmcnt(7)
	v_mfma_f32_32x32x16_bf16 v[74:89], v[224:227], v[240:243], v[74:89]
	s_waitcnt lgkmcnt(6)
	v_mfma_f32_32x32x16_bf16 v[90:105], v[224:227], v[244:247], v[90:105]
	v_mfma_f32_32x32x16_bf16 v[106:121], v[228:231], v[240:243], v[106:121]
	v_mfma_f32_32x32x16_bf16 v[208:223], v[228:231], v[244:247], v[208:223]
	s_waitcnt lgkmcnt(4)
	v_mfma_f32_32x32x16_bf16 v[34:49], v[248:251], v[160:163], v[34:49]
	s_waitcnt lgkmcnt(3)
	v_mfma_f32_32x32x16_bf16 v[50:65], v[248:251], v[164:167], v[50:65]
	s_waitcnt lgkmcnt(2)
	v_mfma_f32_32x32x16_bf16 v[2:17], v[156:159], v[160:163], v[2:17]
	v_mfma_f32_32x32x16_bf16 v[18:33], v[156:159], v[164:167], v[18:33]
	s_waitcnt lgkmcnt(1)
	v_mfma_f32_32x32x16_bf16 v[74:89], v[248:251], v[168:171], v[74:89]
	s_waitcnt lgkmcnt(0)
	v_mfma_f32_32x32x16_bf16 v[90:105], v[248:251], v[122:125], v[90:105]
	v_mfma_f32_32x32x16_bf16 v[106:121], v[156:159], v[168:171], v[106:121]
	v_mfma_f32_32x32x16_bf16 v[208:223], v[156:159], v[122:125], v[208:223]
	s_setprio 0
	s_waitcnt vmcnt(6)
	s_barrier
	s_setprio 1
	ds_read_b128 v[224:227], v126 offset:24576
	ds_read_b128 v[232:235], v128 offset:24576
	ds_read_b128 v[236:239], v128 offset:26624
	ds_read_b128 v[228:231], v126 offset:26624
	ds_read_b128 v[240:243], v128 offset:32768
	ds_read_b128 v[244:247], v128 offset:34816
	ds_read_b128 v[248:251], v127 offset:24576
	ds_read_b128 v[160:163], v129 offset:24576
	ds_read_b128 v[164:167], v129 offset:26624
	ds_read_b128 v[156:159], v127 offset:26624
	ds_read_b128 v[168:171], v129 offset:32768
	ds_read_b128 v[122:125], v129 offset:34816
	s_add_u32 m0, s16, 0x0
	s_add_u32 s42, s42, 0x100000
	s_addc_u32 s43, s43, 0
	global_load_lds_dwordx4 v137, s[42:43]
	global_load_lds_dwordx4 v150, s[42:43] offset:1024
	s_add_u32 m0, s0, 0x0
	s_add_u32 s30, s30, 0x10000
	s_addc_u32 s31, s31, 0
	global_load_lds_dwordx4 v151, s[30:31]
	global_load_lds_dwordx4 v152, s[30:31] offset:1024
	global_load_lds_dwordx4 v153, s[30:31] offset:2048
	global_load_lds_dwordx4 v154, s[30:31] offset:3072
	s_waitcnt lgkmcnt(10)
	v_mfma_f32_32x32x16_bf16 v[34:49], v[224:227], v[232:235], v[34:49]
	s_waitcnt lgkmcnt(9)
	v_mfma_f32_32x32x16_bf16 v[50:65], v[224:227], v[236:239], v[50:65]
	s_waitcnt lgkmcnt(8)
	v_mfma_f32_32x32x16_bf16 v[2:17], v[228:231], v[232:235], v[2:17]
	v_mfma_f32_32x32x16_bf16 v[18:33], v[228:231], v[236:239], v[18:33]
	s_waitcnt lgkmcnt(7)
	v_mfma_f32_32x32x16_bf16 v[74:89], v[224:227], v[240:243], v[74:89]
	s_waitcnt lgkmcnt(6)
	v_mfma_f32_32x32x16_bf16 v[90:105], v[224:227], v[244:247], v[90:105]
	v_mfma_f32_32x32x16_bf16 v[106:121], v[228:231], v[240:243], v[106:121]
	v_mfma_f32_32x32x16_bf16 v[208:223], v[228:231], v[244:247], v[208:223]
	s_waitcnt lgkmcnt(4)
	v_mfma_f32_32x32x16_bf16 v[34:49], v[248:251], v[160:163], v[34:49]
	s_waitcnt lgkmcnt(3)
	v_mfma_f32_32x32x16_bf16 v[50:65], v[248:251], v[164:167], v[50:65]
	s_waitcnt lgkmcnt(2)
	v_mfma_f32_32x32x16_bf16 v[2:17], v[156:159], v[160:163], v[2:17]
	v_mfma_f32_32x32x16_bf16 v[18:33], v[156:159], v[164:167], v[18:33]
	s_waitcnt lgkmcnt(1)
	v_mfma_f32_32x32x16_bf16 v[74:89], v[248:251], v[168:171], v[74:89]
	s_waitcnt lgkmcnt(0)
	v_mfma_f32_32x32x16_bf16 v[90:105], v[248:251], v[122:125], v[90:105]
	v_mfma_f32_32x32x16_bf16 v[106:121], v[156:159], v[168:171], v[106:121]
	v_mfma_f32_32x32x16_bf16 v[208:223], v[156:159], v[122:125], v[208:223]
	s_setprio 0
	s_waitcnt vmcnt(6)
	s_barrier
; #define BLOAD(A_, B_, kt) do { _Pragma("unroll") for (int i = 0; i < 4; ++i) { \
;     A_[i] = *(const u32x4*)((const char*)Ap + (aoff + (unsigned)(32 * i * lda + (kt) * 64) * 2u)); B_[i] = *(const u32x4*)((const char*)Wt + (woff + (unsigned)(32 * i * K + (kt) * 64) * 2u)); } } while (0)
; #define BLOAD(A_, B_, kt) do { _Pragma("unroll") for (int i = 0; i < 4; ++i) { \
;     A_[i] = *(const u32x4*)((const char*)Ap + (aoff + (unsigned)(32 * i * lda + (kt) * 64) * 2u)); B_[i] = *(const u32x4*)((const char*)Wt + (woff + (unsigned)(32 * i * K + (kt) * 64) * 2u)); } } while (0)
; #define BSTORE(A_, B_, buf) do { _Pragma("unroll") for (int i = 0; i < 4; ++i) { \
;     *(u32x4*)&As[(buf) * GBUF + (srow + 32 * i) * LDT + sc8] = A_[i]; \
;     *(u32x4*)&Bs[(buf) * GBUF + (srow + 32 * i) * LDT + sc8] = B_[i]; } } while (0)
; template <int NK>
; DI void gemm_run(PF& pf, const u16* __restrict__ Ap, int lda, const u16* __restrict__ Wt, f32x16 (&acc)[2][2], char* smem) {
;     ...
;   __builtin_amdgcn_s_setprio(0);
;   __syncthreads();
;   BSTORE(pf.a0, pf.b0, 0);
;   BLOAD(pf.a0, pf.b0, 2);
;   __syncthreads();
; #pragma unroll
;   for (int kt = 0; kt < nk; kt += 2) {
;     BCOMP(0);
;     BSTORE(pf.a1, pf.b1, 1);
;     if (kt + 3 < nk) BLOAD(pf.a1, pf.b1, kt + 3);
;     __syncthreads();
;     BCOMP(1);
;     if (kt + 2 < nk) { BSTORE(pf.a0, pf.b0, 0); if (kt + 4 < nk) BLOAD(pf.a0, pf.b0, kt + 4); }
;     __syncthreads();
	s_setprio 1
	ds_read_b128 v[224:227], v126 offset:49152
	ds_read_b128 v[232:235], v128 offset:49152
	ds_read_b128 v[236:239], v128 offset:51200
	ds_read_b128 v[228:231], v126 offset:51200
	ds_read_b128 v[240:243], v128 offset:57344
	ds_read_b128 v[244:247], v128 offset:59392
	ds_read_b128 v[248:251], v127 offset:49152
	ds_read_b128 v[160:163], v129 offset:49152
	ds_read_b128 v[164:167], v129 offset:51200
	ds_read_b128 v[156:159], v127 offset:51200
	ds_read_b128 v[168:171], v129 offset:57344
	ds_read_b128 v[122:125], v129 offset:59392
	s_add_u32 m0, s16, 0x6000
	s_add_u32 s42, s42, 0x100000
	s_addc_u32 s43, s43, 0
	global_load_lds_dwordx4 v137, s[42:43]
	global_load_lds_dwordx4 v150, s[42:43] offset:1024
	s_add_u32 m0, s0, 0x6000
	s_add_u32 s30, s30, 0x10000
	s_addc_u32 s31, s31, 0
	global_load_lds_dwordx4 v151, s[30:31]
	global_load_lds_dwordx4 v152, s[30:31] offset:1024
	global_load_lds_dwordx4 v153, s[30:31] offset:2048
	global_load_lds_dwordx4 v154, s[30:31] offset:3072
	s_waitcnt lgkmcnt(10)
	v_mfma_f32_32x32x16_bf16 v[34:49], v[224:227], v[232:235], v[34:49]
	s_waitcnt lgkmcnt(9)
	v_mfma_f32_32x32x16_bf16 v[50:65], v[224:227], v[236:239], v[50:65]
	s_waitcnt lgkmcnt(8)
	v_mfma_f32_32x32x16_bf16 v[2:17], v[228:231], v[232:235], v[2:17]
	v_mfma_f32_32x32x16_bf16 v[18:33], v[228:231], v[236:239], v[18:33]
	s_waitcnt lgkmcnt(7)
	v_mfma_f32_32x32x16_bf16 v[74:89], v[224:227], v[240:243], v[74:89]
	s_waitcnt lgkmcnt(6)
	v_mfma_f32_32x32x16_bf16 v[90:105], v[224:227], v[244:247], v[90:105]
	v_mfma_f32_32x32x16_bf16 v[106:121], v[228:231], v[240:243], v[106:121]
	v_mfma_f32_32x32x16_bf16 v[208:223], v[228:231], v[244:247], v[208:223]
	s_waitcnt lgkmcnt(4)
	v_mfma_f32_32x32x16_bf16 v[34:49], v[248:251], v[160:163], v[34:49]
	s_waitcnt lgkmcnt(3)
	v_mfma_f32_32x32x16_bf16 v[50:65], v[248:251], v[164:167], v[50:65]
	s_waitcnt lgkmcnt(2)
	v_mfma_f32_32x32x16_bf16 v[2:17], v[156:159], v[160:163], v[2:17]
	v_mfma_f32_32x32x16_bf16 v[18:33], v[156:159], v[164:167], v[18:33]
	s_waitcnt lgkmcnt(1)
	v_mfma_f32_32x32x16_bf16 v[74:89], v[248:251], v[168:171], v[74:89]
	s_waitcnt lgkmcnt(0)
	v_mfma_f32_32x32x16_bf16 v[90:105], v[248:251], v[122:125], v[90:105]
	v_mfma_f32_32x32x16_bf16 v[106:121], v[156:159], v[168:171], v[106:121]
	v_mfma_f32_32x32x16_bf16 v[208:223], v[156:159], v[122:125], v[208:223]
	s_setprio 0
	s_waitcnt vmcnt(6)
	s_barrier
	s_setprio 1
	ds_read_b128 v[224:227], v126 offset:0
	ds_read_b128 v[232:235], v128 offset:0
	ds_read_b128 v[236:239], v128 offset:2048
	ds_read_b128 v[228:231], v126 offset:2048
	ds_read_b128 v[240:243], v128 offset:8192
	ds_read_b128 v[244:247], v128 offset:10240
	ds_read_b128 v[248:251], v127 offset:0
	ds_read_b128 v[160:163], v129 offset:0
	ds_read_b128 v[164:167], v129 offset:2048
	ds_read_b128 v[156:159], v127 offset:2048
	ds_read_b128 v[168:171], v129 offset:8192
	ds_read_b128 v[122:125], v129 offset:10240
	s_add_u32 m0, s16, 0xc000
	s_add_u32 s42, s42, 0x100000
	s_addc_u32 s43, s43, 0
	global_load_lds_dwordx4 v137, s[42:43]
	global_load_lds_dwordx4 v150, s[42:43] offset:1024
	s_add_u32 m0, s0, 0xc000
	s_add_u32 s30, s30, 0x10000
	s_addc_u32 s31, s31, 0
	global_load_lds_dwordx4 v151, s[30:31]
	global_load_lds_dwordx4 v152, s[30:31] offset:1024
	global_load_lds_dwordx4 v153, s[30:31] offset:2048
	global_load_lds_dwordx4 v154, s[30:31] offset:3072
	s_waitcnt lgkmcnt(10)
	v_mfma_f32_32x32x16_bf16 v[34:49], v[224:227], v[232:235], v[34:49]
	s_waitcnt lgkmcnt(9)
	v_mfma_f32_32x32x16_bf16 v[50:65], v[224:227], v[236:239], v[50:65]
	s_waitcnt lgkmcnt(8)
	v_mfma_f32_32x32x16_bf16 v[2:17], v[228:231], v[232:235], v[2:17]
	v_mfma_f32_32x32x16_bf16 v[18:33], v[228:231], v[236:239], v[18:33]
	s_waitcnt lgkmcnt(7)
	v_mfma_f32_32x32x16_bf16 v[74:89], v[224:227], v[240:243], v[74:89]
	s_waitcnt lgkmcnt(6)
	v_mfma_f32_32x32x16_bf16 v[90:105], v[224:227], v[244:247], v[90:105]
	v_mfma_f32_32x32x16_bf16 v[106:121], v[228:231], v[240:243], v[106:121]
	v_mfma_f32_32x32x16_bf16 v[208:223], v[228:231], v[244:247], v[208:223]
	s_waitcnt lgkmcnt(4)
	v_mfma_f32_32x32x16_bf16 v[34:49], v[248:251], v[160:163], v[34:49]
	s_waitcnt lgkmcnt(3)
	v_mfma_f32_32x32x16_bf16 v[50:65], v[248:251], v[164:167], v[50:65]
	s_waitcnt lgkmcnt(2)
	v_mfma_f32_32x32x16_bf16 v[2:17], v[156:159], v[160:163], v[2:17]
	v_mfma_f32_32x32x16_bf16 v[18:33], v[156:159], v[164:167], v[18:33]
	s_waitcnt lgkmcnt(1)
	v_mfma_f32_32x32x16_bf16 v[74:89], v[248:251], v[168:171], v[74:89]
	s_waitcnt lgkmcnt(0)
	v_mfma_f32_32x32x16_bf16 v[90:105], v[248:251], v[122:125], v[90:105]
	v_mfma_f32_32x32x16_bf16 v[106:121], v[156:159], v[168:171], v[106:121]
	v_mfma_f32_32x32x16_bf16 v[208:223], v[156:159], v[122:125], v[208:223]
	s_setprio 0
	s_waitcnt vmcnt(6)
	s_barrier
; #define BLOAD(A_, B_, kt) do { _Pragma("unroll") for (int i = 0; i < 4; ++i) { \
;     A_[i] = *(const u32x4*)((const char*)Ap + (aoff + (unsigned)(32 * i * lda + (kt) * 64) * 2u)); B_[i] = *(const u32x4*)((const char*)Wt + (woff + (unsigned)(32 * i * K + (kt) * 64) * 2u)); } } while (0)
; #define BLOAD(A_, B_, kt) do { _Pragma("unroll") for (int i = 0; i < 4; ++i) { \
;     A_[i] = *(const u32x4*)((const char*)Ap + (aoff + (unsigned)(32 * i * lda + (kt) * 64) * 2u)); B_[i] = *(const u32x4*)((const char*)Wt + (woff + (unsigned)(32 * i * K + (kt) * 64) * 2u)); } } while (0)
; #define BSTORE(A_, B_, buf) do { _Pragma("unroll") for (int i = 0; i < 4; ++i) { \
;     *(u32x4*)&As[(buf) * GBUF + (srow + 32 * i) * LDT + sc8] = A_[i]; \
;     *(u32x4*)&Bs[(buf) * GBUF + (srow + 32 * i) * LDT + sc8] = B_[i]; } } while (0)
; template <int NK>
; DI void gemm_run(PF& pf, const u16* __restrict__ Ap, int lda, const u16* __restrict__ Wt, f32x16 (&acc)[2][2], char* smem) {
;     ...
;   __builtin_amdgcn_s_setprio(0);
;   __syncthreads();
;   BSTORE(pf.a0, pf.b0, 0);
;   BLOAD(pf.a0, pf.b0, 2);
;   __syncthreads();
; #pragma unroll
;   for (int kt = 0; kt < nk; kt += 2) {
;     BCOMP(0);
;     BSTORE(pf.a1, pf.b1, 1);
;     if (kt + 3 < nk) BLOAD(pf.a1, pf.b1, kt + 3);
;     __syncthreads();
;     BCOMP(1);
;     if (kt + 2 < nk) { BSTORE(pf.a0, pf.b0, 0); if (kt + 4 < nk) BLOAD(pf.a0, pf.b0, kt + 4); }
;     __syncthreads();
	s_setprio 1
	ds_read_b128 v[224:227], v126 offset:24576
	ds_read_b128 v[232:235], v128 offset:24576
	ds_read_b128 v[236:239], v128 offset:26624
	ds_read_b128 v[228:231], v126 offset:26624
	ds_read_b128 v[240:243], v128 offset:32768
	ds_read_b128 v[244:247], v128 offset:34816
	ds_read_b128 v[248:251], v127 offset:24576
	ds_read_b128 v[160:163], v129 offset:24576
	ds_read_b128 v[164:167], v129 offset:26624
	ds_read_b128 v[156:159], v127 offset:26624
	ds_read_b128 v[168:171], v129 offset:32768
	ds_read_b128 v[122:125], v129 offset:34816
	s_add_u32 m0, s16, 0x0
	s_add_u32 s42, s42, 0x100000
	s_addc_u32 s43, s43, 0
	global_load_lds_dwordx4 v137, s[42:43]
	global_load_lds_dwordx4 v150, s[42:43] offset:1024
	s_add_u32 m0, s0, 0x0
	s_add_u32 s30, s30, 0x10000
	s_addc_u32 s31, s31, 0
	global_load_lds_dwordx4 v151, s[30:31]
	global_load_lds_dwordx4 v152, s[30:31] offset:1024
	global_load_lds_dwordx4 v153, s[30:31] offset:2048
	global_load_lds_dwordx4 v154, s[30:31] offset:3072
	s_waitcnt lgkmcnt(10)
	v_mfma_f32_32x32x16_bf16 v[34:49], v[224:227], v[232:235], v[34:49]
	s_waitcnt lgkmcnt(9)
	v_mfma_f32_32x32x16_bf16 v[50:65], v[224:227], v[236:239], v[50:65]
	s_waitcnt lgkmcnt(8)
	v_mfma_f32_32x32x16_bf16 v[2:17], v[228:231], v[232:235], v[2:17]
	v_mfma_f32_32x32x16_bf16 v[18:33], v[228:231], v[236:239], v[18:33]
	s_waitcnt lgkmcnt(7)
	v_mfma_f32_32x32x16_bf16 v[74:89], v[224:227], v[240:243], v[74:89]
	s_waitcnt lgkmcnt(6)
	v_mfma_f32_32x32x16_bf16 v[90:105], v[224:227], v[244:247], v[90:105]
	v_mfma_f32_32x32x16_bf16 v[106:121], v[228:231], v[240:243], v[106:121]
	v_mfma_f32_32x32x16_bf16 v[208:223], v[228:231], v[244:247], v[208:223]
	s_waitcnt lgkmcnt(4)
	v_mfma_f32_32x32x16_bf16 v[34:49], v[248:251], v[160:163], v[34:49]
	s_waitcnt lgkmcnt(3)
	v_mfma_f32_32x32x16_bf16 v[50:65], v[248:251], v[164:167], v[50:65]
	s_waitcnt lgkmcnt(2)
	v_mfma_f32_32x32x16_bf16 v[2:17], v[156:159], v[160:163], v[2:17]
	v_mfma_f32_32x32x16_bf16 v[18:33], v[156:159], v[164:167], v[18:33]
	s_waitcnt lgkmcnt(1)
	v_mfma_f32_32x32x16_bf16 v[74:89], v[248:251], v[168:171], v[74:89]
	s_waitcnt lgkmcnt(0)
	v_mfma_f32_32x32x16_bf16 v[90:105], v[248:251], v[122:125], v[90:105]
	v_mfma_f32_32x32x16_bf16 v[106:121], v[156:159], v[168:171], v[106:121]
	v_mfma_f32_32x32x16_bf16 v[208:223], v[156:159], v[122:125], v[208:223]
	s_setprio 0
	s_waitcnt vmcnt(6)
	s_barrier
	s_setprio 1
	ds_read_b128 v[224:227], v126 offset:49152
	ds_read_b128 v[232:235], v128 offset:49152
	ds_read_b128 v[236:239], v128 offset:51200
	ds_read_b128 v[228:231], v126 offset:51200
	ds_read_b128 v[240:243], v128 offset:57344
	ds_read_b128 v[244:247], v128 offset:59392
	ds_read_b128 v[248:251], v127 offset:49152
	ds_read_b128 v[160:163], v129 offset:49152
	ds_read_b128 v[164:167], v129 offset:51200
	ds_read_b128 v[156:159], v127 offset:51200
	ds_read_b128 v[168:171], v129 offset:57344
	ds_read_b128 v[122:125], v129 offset:59392
	s_add_u32 m0, s16, 0x6000
	s_add_u32 s42, s42, 0x100000
	s_addc_u32 s43, s43, 0
	global_load_lds_dwordx4 v137, s[42:43]
	global_load_lds_dwordx4 v150, s[42:43] offset:1024
	s_add_u32 m0, s0, 0x6000
	s_add_u32 s30, s30, 0x10000
	s_addc_u32 s31, s31, 0
	global_load_lds_dwordx4 v151, s[30:31]
	global_load_lds_dwordx4 v152, s[30:31] offset:1024
	global_load_lds_dwordx4 v153, s[30:31] offset:2048
	global_load_lds_dwordx4 v154, s[30:31] offset:3072
	s_waitcnt lgkmcnt(10)
	v_mfma_f32_32x32x16_bf16 v[34:49], v[224:227], v[232:235], v[34:49]
	s_waitcnt lgkmcnt(9)
	v_mfma_f32_32x32x16_bf16 v[50:65], v[224:227], v[236:239], v[50:65]
	s_waitcnt lgkmcnt(8)
	v_mfma_f32_32x32x16_bf16 v[2:17], v[228:231], v[232:235], v[2:17]
	v_mfma_f32_32x32x16_bf16 v[18:33], v[228:231], v[236:239], v[18:33]
	s_waitcnt lgkmcnt(7)
	v_mfma_f32_32x32x16_bf16 v[74:89], v[224:227], v[240:243], v[74:89]
	s_waitcnt lgkmcnt(6)
	v_mfma_f32_32x32x16_bf16 v[90:105], v[224:227], v[244:247], v[90:105]
	v_mfma_f32_32x32x16_bf16 v[106:121], v[228:231], v[240:243], v[106:121]
	v_mfma_f32_32x32x16_bf16 v[208:223], v[228:231], v[244:247], v[208:223]
	s_waitcnt lgkmcnt(4)
	v_mfma_f32_32x32x16_bf16 v[34:49], v[248:251], v[160:163], v[34:49]
	s_waitcnt lgkmcnt(3)
	v_mfma_f32_32x32x16_bf16 v[50:65], v[248:251], v[164:167], v[50:65]
	s_waitcnt lgkmcnt(2)
	v_mfma_f32_32x32x16_bf16 v[2:17], v[156:159], v[160:163], v[2:17]
	v_mfma_f32_32x32x16_bf16 v[18:33], v[156:159], v[164:167], v[18:33]
	s_waitcnt lgkmcnt(1)
	v_mfma_f32_32x32x16_bf16 v[74:89], v[248:251], v[168:171], v[74:89]
	s_waitcnt lgkmcnt(0)
	v_mfma_f32_32x32x16_bf16 v[90:105], v[248:251], v[122:125], v[90:105]
	v_mfma_f32_32x32x16_bf16 v[106:121], v[156:159], v[168:171], v[106:121]
	v_mfma_f32_32x32x16_bf16 v[208:223], v[156:159], v[122:125], v[208:223]
	s_setprio 0
	s_waitcnt vmcnt(6)
	s_barrier
; #define BLOAD(A_, B_, kt) do { _Pragma("unroll") for (int i = 0; i < 4; ++i) { \
;     A_[i] = *(const u32x4*)((const char*)Ap + (aoff + (unsigned)(32 * i * lda + (kt) * 64) * 2u)); B_[i] = *(const u32x4*)((const char*)Wt + (woff + (unsigned)(32 * i * K + (kt) * 64) * 2u)); } } while (0)
; #define BLOAD(A_, B_, kt) do { _Pragma("unroll") for (int i = 0; i < 4; ++i) { \
;     A_[i] = *(const u32x4*)((const char*)Ap + (aoff + (unsigned)(32 * i * lda + (kt) * 64) * 2u)); B_[i] = *(const u32x4*)((const char*)Wt + (woff + (unsigned)(32 * i * K + (kt) * 64) * 2u)); } } while (0)
; #define BSTORE(A_, B_, buf) do { _Pragma("unroll") for (int i = 0; i < 4; ++i) { \
;     *(u32x4*)&As[(buf) * GBUF + (srow + 32 * i) * LDT + sc8] = A_[i]; \
;     *(u32x4*)&Bs[(buf) * GBUF + (srow + 32 * i) * LDT + sc8] = B_[i]; } } while (0)
; template <int NK>
; DI void gemm_run(PF& pf, const u16* __restrict__ Ap, int lda, const u16* __restrict__ Wt, f32x16 (&acc)[2][2], char* smem) {
;     ...
;   __builtin_amdgcn_s_setprio(0);
;   __syncthreads();
;   BSTORE(pf.a0, pf.b0, 0);
;   BLOAD(pf.a0, pf.b0, 2);
;   __syncthreads();
; #pragma unroll
;   for (int kt = 0; kt < nk; kt += 2) {
;     BCOMP(0);
;     BSTORE(pf.a1, pf.b1, 1);
;     if (kt + 3 < nk) BLOAD(pf.a1, pf.b1, kt + 3);
;     __syncthreads();
;     BCOMP(1);
;     if (kt + 2 < nk) { BSTORE(pf.a0, pf.b0, 0); if (kt + 4 < nk) BLOAD(pf.a0, pf.b0, kt + 4); }
;     __syncthreads();
	s_setprio 1
	ds_read_b128 v[224:227], v126 offset:0
	ds_read_b128 v[232:235], v128 offset:0
	ds_read_b128 v[236:239], v128 offset:2048
	ds_read_b128 v[228:231], v126 offset:2048
	ds_read_b128 v[240:243], v128 offset:8192
	ds_read_b128 v[244:247], v128 offset:10240
	ds_read_b128 v[248:251], v127 offset:0
	ds_read_b128 v[160:163], v129 offset:0
	ds_read_b128 v[164:167], v129 offset:2048
	ds_read_b128 v[156:159], v127 offset:2048
	ds_read_b128 v[168:171], v129 offset:8192
	ds_read_b128 v[122:125], v129 offset:10240
	s_add_u32 m0, s16, 0xc000
	s_add_u32 s42, s42, 0x100000
	s_addc_u32 s43, s43, 0
	global_load_lds_dwordx4 v137, s[42:43]
	global_load_lds_dwordx4 v150, s[42:43] offset:1024
	s_add_u32 m0, s0, 0xc000
	s_add_u32 s30, s30, 0x10000
	s_addc_u32 s31, s31, 0
	global_load_lds_dwordx4 v151, s[30:31]
	global_load_lds_dwordx4 v152, s[30:31] offset:1024
	global_load_lds_dwordx4 v153, s[30:31] offset:2048
	global_load_lds_dwordx4 v154, s[30:31] offset:3072
	s_waitcnt lgkmcnt(10)
	v_mfma_f32_32x32x16_bf16 v[34:49], v[224:227], v[232:235], v[34:49]
	s_waitcnt lgkmcnt(9)
	v_mfma_f32_32x32x16_bf16 v[50:65], v[224:227], v[236:239], v[50:65]
	s_waitcnt lgkmcnt(8)
	v_mfma_f32_32x32x16_bf16 v[2:17], v[228:231], v[232:235], v[2:17]
	v_mfma_f32_32x32x16_bf16 v[18:33], v[228:231], v[236:239], v[18:33]
	s_waitcnt lgkmcnt(7)
	v_mfma_f32_32x32x16_bf16 v[74:89], v[224:227], v[240:243], v[74:89]
	s_waitcnt lgkmcnt(6)
	v_mfma_f32_32x32x16_bf16 v[90:105], v[224:227], v[244:247], v[90:105]
	v_mfma_f32_32x32x16_bf16 v[106:121], v[228:231], v[240:243], v[106:121]
	v_mfma_f32_32x32x16_bf16 v[208:223], v[228:231], v[244:247], v[208:223]
	s_waitcnt lgkmcnt(4)
	v_mfma_f32_32x32x16_bf16 v[34:49], v[248:251], v[160:163], v[34:49]
	s_waitcnt lgkmcnt(3)
	v_mfma_f32_32x32x16_bf16 v[50:65], v[248:251], v[164:167], v[50:65]
	s_waitcnt lgkmcnt(2)
	v_mfma_f32_32x32x16_bf16 v[2:17], v[156:159], v[160:163], v[2:17]
	v_mfma_f32_32x32x16_bf16 v[18:33], v[156:159], v[164:167], v[18:33]
	s_waitcnt lgkmcnt(1)
	v_mfma_f32_32x32x16_bf16 v[74:89], v[248:251], v[168:171], v[74:89]
	s_waitcnt lgkmcnt(0)
	v_mfma_f32_32x32x16_bf16 v[90:105], v[248:251], v[122:125], v[90:105]
	v_mfma_f32_32x32x16_bf16 v[106:121], v[156:159], v[168:171], v[106:121]
	v_mfma_f32_32x32x16_bf16 v[208:223], v[156:159], v[122:125], v[208:223]
	s_setprio 0
	s_waitcnt vmcnt(6)
	s_barrier
	s_setprio 1
	ds_read_b128 v[224:227], v126 offset:24576
	ds_read_b128 v[232:235], v128 offset:24576
	ds_read_b128 v[236:239], v128 offset:26624
	ds_read_b128 v[228:231], v126 offset:26624
	ds_read_b128 v[240:243], v128 offset:32768
	ds_read_b128 v[244:247], v128 offset:34816
	ds_read_b128 v[248:251], v127 offset:24576
	ds_read_b128 v[160:163], v129 offset:24576
	ds_read_b128 v[164:167], v129 offset:26624
	ds_read_b128 v[156:159], v127 offset:26624
	ds_read_b128 v[168:171], v129 offset:32768
	ds_read_b128 v[122:125], v129 offset:34816
	s_add_u32 m0, s16, 0x0
	s_add_u32 s42, s42, 0x100000
	s_addc_u32 s43, s43, 0
	global_load_lds_dwordx4 v137, s[42:43]
	global_load_lds_dwordx4 v150, s[42:43] offset:1024
	s_add_u32 m0, s0, 0x0
	s_add_u32 s30, s30, 0x10000
	s_addc_u32 s31, s31, 0
	global_load_lds_dwordx4 v151, s[30:31]
	global_load_lds_dwordx4 v152, s[30:31] offset:1024
	global_load_lds_dwordx4 v153, s[30:31] offset:2048
	global_load_lds_dwordx4 v154, s[30:31] offset:3072
	s_waitcnt lgkmcnt(10)
	v_mfma_f32_32x32x16_bf16 v[34:49], v[224:227], v[232:235], v[34:49]
	s_waitcnt lgkmcnt(9)
	v_mfma_f32_32x32x16_bf16 v[50:65], v[224:227], v[236:239], v[50:65]
	s_waitcnt lgkmcnt(8)
	v_mfma_f32_32x32x16_bf16 v[2:17], v[228:231], v[232:235], v[2:17]
	v_mfma_f32_32x32x16_bf16 v[18:33], v[228:231], v[236:239], v[18:33]
	s_waitcnt lgkmcnt(7)
	v_mfma_f32_32x32x16_bf16 v[74:89], v[224:227], v[240:243], v[74:89]
	s_waitcnt lgkmcnt(6)
	v_mfma_f32_32x32x16_bf16 v[90:105], v[224:227], v[244:247], v[90:105]
	v_mfma_f32_32x32x16_bf16 v[106:121], v[228:231], v[240:243], v[106:121]
	v_mfma_f32_32x32x16_bf16 v[208:223], v[228:231], v[244:247], v[208:223]
	s_waitcnt lgkmcnt(4)
	v_mfma_f32_32x32x16_bf16 v[34:49], v[248:251], v[160:163], v[34:49]
	s_waitcnt lgkmcnt(3)
	v_mfma_f32_32x32x16_bf16 v[50:65], v[248:251], v[164:167], v[50:65]
	s_waitcnt lgkmcnt(2)
	v_mfma_f32_32x32x16_bf16 v[2:17], v[156:159], v[160:163], v[2:17]
	v_mfma_f32_32x32x16_bf16 v[18:33], v[156:159], v[164:167], v[18:33]
	s_waitcnt lgkmcnt(1)
	v_mfma_f32_32x32x16_bf16 v[74:89], v[248:251], v[168:171], v[74:89]
	s_waitcnt lgkmcnt(0)
	v_mfma_f32_32x32x16_bf16 v[90:105], v[248:251], v[122:125], v[90:105]
	v_mfma_f32_32x32x16_bf16 v[106:121], v[156:159], v[168:171], v[106:121]
	v_mfma_f32_32x32x16_bf16 v[208:223], v[156:159], v[122:125], v[208:223]
	s_setprio 0
	s_waitcnt vmcnt(6)
	s_barrier
; #define BLOAD(A_, B_, kt) do { _Pragma("unroll") for (int i = 0; i < 4; ++i) { \
;     A_[i] = *(const u32x4*)((const char*)Ap + (aoff + (unsigned)(32 * i * lda + (kt) * 64) * 2u)); B_[i] = *(const u32x4*)((const char*)Wt + (woff + (unsigned)(32 * i * K + (kt) * 64) * 2u)); } } while (0)
; #define BLOAD(A_, B_, kt) do { _Pragma("unroll") for (int i = 0; i < 4; ++i) { \
;     A_[i] = *(const u32x4*)((const char*)Ap + (aoff + (unsigned)(32 * i * lda + (kt) * 64) * 2u)); B_[i] = *(const u32x4*)((const char*)Wt + (woff + (unsigned)(32 * i * K + (kt) * 64) * 2u)); } } while (0)
; #define BSTORE(A_, B_, buf) do { _Pragma("unroll") for (int i = 0; i < 4; ++i) { \
;     *(u32x4*)&As[(buf) * GBUF + (srow + 32 * i) * LDT + sc8] = A_[i]; \
;     *(u32x4*)&Bs[(buf) * GBUF + (srow + 32 * i) * LDT + sc8] = B_[i]; } } while (0)
; template <int NK>
; DI void gemm_run(PF& pf, const u16* __restrict__ Ap, int lda, const u16* __restrict__ Wt, f32x16 (&acc)[2][2], char* smem) {
;     ...
;   __builtin_amdgcn_s_setprio(0);
;   __syncthreads();
;   BSTORE(pf.a0, pf.b0, 0);
;   BLOAD(pf.a0, pf.b0, 2);
;   __syncthreads();
; #pragma unroll
;   for (int kt = 0; kt < nk; kt += 2) {
;     BCOMP(0);
;     BSTORE(pf.a1, pf.b1, 1);
;     if (kt + 3 < nk) BLOAD(pf.a1, pf.b1, kt + 3);
;     __syncthreads();
;     BCOMP(1);
;     if (kt + 2 < nk) { BSTORE(pf.a0, pf.b0, 0); if (kt + 4 < nk) BLOAD(pf.a0, pf.b0, kt + 4); }
;     __syncthreads();
	s_setprio 1
	ds_read_b128 v[224:227], v126 offset:49152
	ds_read_b128 v[232:235], v128 offset:49152
	ds_read_b128 v[236:239], v128 offset:51200
	ds_read_b128 v[228:231], v126 offset:51200
	ds_read_b128 v[240:243], v128 offset:57344
	ds_read_b128 v[244:247], v128 offset:59392
	ds_read_b128 v[248:251], v127 offset:49152
	ds_read_b128 v[160:163], v129 offset:49152
	ds_read_b128 v[164:167], v129 offset:51200
	ds_read_b128 v[156:159], v127 offset:51200
	ds_read_b128 v[168:171], v129 offset:57344
	ds_read_b128 v[122:125], v129 offset:59392
	s_add_u32 m0, s16, 0x6000
	s_add_u32 s42, s42, 0x100000
	s_addc_u32 s43, s43, 0
	global_load_lds_dwordx4 v137, s[42:43]
	global_load_lds_dwordx4 v150, s[42:43] offset:1024
	s_add_u32 m0, s0, 0x6000
	s_add_u32 s30, s30, 0x10000
	s_addc_u32 s31, s31, 0
	global_load_lds_dwordx4 v151, s[30:31]
	global_load_lds_dwordx4 v152, s[30:31] offset:1024
	global_load_lds_dwordx4 v153, s[30:31] offset:2048
	global_load_lds_dwordx4 v154, s[30:31] offset:3072
	s_waitcnt lgkmcnt(10)
	v_mfma_f32_32x32x16_bf16 v[34:49], v[224:227], v[232:235], v[34:49]
	s_waitcnt lgkmcnt(9)
	v_mfma_f32_32x32x16_bf16 v[50:65], v[224:227], v[236:239], v[50:65]
	s_waitcnt lgkmcnt(8)
	v_mfma_f32_32x32x16_bf16 v[2:17], v[228:231], v[232:235], v[2:17]
	v_mfma_f32_32x32x16_bf16 v[18:33], v[228:231], v[236:239], v[18:33]
	s_waitcnt lgkmcnt(7)
	v_mfma_f32_32x32x16_bf16 v[74:89], v[224:227], v[240:243], v[74:89]
	s_waitcnt lgkmcnt(6)
	v_mfma_f32_32x32x16_bf16 v[90:105], v[224:227], v[244:247], v[90:105]
	v_mfma_f32_32x32x16_bf16 v[106:121], v[228:231], v[240:243], v[106:121]
	v_mfma_f32_32x32x16_bf16 v[208:223], v[228:231], v[244:247], v[208:223]
	s_waitcnt lgkmcnt(4)
	v_mfma_f32_32x32x16_bf16 v[34:49], v[248:251], v[160:163], v[34:49]
	s_waitcnt lgkmcnt(3)
	v_mfma_f32_32x32x16_bf16 v[50:65], v[248:251], v[164:167], v[50:65]
	s_waitcnt lgkmcnt(2)
	v_mfma_f32_32x32x16_bf16 v[2:17], v[156:159], v[160:163], v[2:17]
	v_mfma_f32_32x32x16_bf16 v[18:33], v[156:159], v[164:167], v[18:33]
	s_waitcnt lgkmcnt(1)
	v_mfma_f32_32x32x16_bf16 v[74:89], v[248:251], v[168:171], v[74:89]
	s_waitcnt lgkmcnt(0)
	v_mfma_f32_32x32x16_bf16 v[90:105], v[248:251], v[122:125], v[90:105]
	v_mfma_f32_32x32x16_bf16 v[106:121], v[156:159], v[168:171], v[106:121]
	v_mfma_f32_32x32x16_bf16 v[208:223], v[156:159], v[122:125], v[208:223]
	s_setprio 0
	s_waitcnt vmcnt(6)
	s_barrier
	s_setprio 1
	ds_read_b128 v[224:227], v126 offset:0
	ds_read_b128 v[232:235], v128 offset:0
	ds_read_b128 v[236:239], v128 offset:2048
	ds_read_b128 v[228:231], v126 offset:2048
	ds_read_b128 v[240:243], v128 offset:8192
	ds_read_b128 v[244:247], v128 offset:10240
	ds_read_b128 v[248:251], v127 offset:0
	ds_read_b128 v[160:163], v129 offset:0
	ds_read_b128 v[164:167], v129 offset:2048
	ds_read_b128 v[156:159], v127 offset:2048
	ds_read_b128 v[168:171], v129 offset:8192
	ds_read_b128 v[122:125], v129 offset:10240
	s_add_u32 m0, s16, 0xc000
	s_add_u32 s42, s42, 0x100000
	s_addc_u32 s43, s43, 0
	global_load_lds_dwordx4 v137, s[42:43]
	global_load_lds_dwordx4 v150, s[42:43] offset:1024
	s_add_u32 m0, s0, 0xc000
	s_add_u32 s30, s30, 0x10000
	s_addc_u32 s31, s31, 0
	global_load_lds_dwordx4 v151, s[30:31]
	global_load_lds_dwordx4 v152, s[30:31] offset:1024
	global_load_lds_dwordx4 v153, s[30:31] offset:2048
	global_load_lds_dwordx4 v154, s[30:31] offset:3072
	s_waitcnt lgkmcnt(10)
	v_mfma_f32_32x32x16_bf16 v[34:49], v[224:227], v[232:235], v[34:49]
	s_waitcnt lgkmcnt(9)
	v_mfma_f32_32x32x16_bf16 v[50:65], v[224:227], v[236:239], v[50:65]
	s_waitcnt lgkmcnt(8)
	v_mfma_f32_32x32x16_bf16 v[2:17], v[228:231], v[232:235], v[2:17]
	v_mfma_f32_32x32x16_bf16 v[18:33], v[228:231], v[236:239], v[18:33]
	s_waitcnt lgkmcnt(7)
	v_mfma_f32_32x32x16_bf16 v[74:89], v[224:227], v[240:243], v[74:89]
	s_waitcnt lgkmcnt(6)
	v_mfma_f32_32x32x16_bf16 v[90:105], v[224:227], v[244:247], v[90:105]
	v_mfma_f32_32x32x16_bf16 v[106:121], v[228:231], v[240:243], v[106:121]
	v_mfma_f32_32x32x16_bf16 v[208:223], v[228:231], v[244:247], v[208:223]
	s_waitcnt lgkmcnt(4)
	v_mfma_f32_32x32x16_bf16 v[34:49], v[248:251], v[160:163], v[34:49]
	s_waitcnt lgkmcnt(3)
	v_mfma_f32_32x32x16_bf16 v[50:65], v[248:251], v[164:167], v[50:65]
	s_waitcnt lgkmcnt(2)
	v_mfma_f32_32x32x16_bf16 v[2:17], v[156:159], v[160:163], v[2:17]
	v_mfma_f32_32x32x16_bf16 v[18:33], v[156:159], v[164:167], v[18:33]
	s_waitcnt lgkmcnt(1)
	v_mfma_f32_32x32x16_bf16 v[74:89], v[248:251], v[168:171], v[74:89]
	s_waitcnt lgkmcnt(0)
	v_mfma_f32_32x32x16_bf16 v[90:105], v[248:251], v[122:125], v[90:105]
	v_mfma_f32_32x32x16_bf16 v[106:121], v[156:159], v[168:171], v[106:121]
	v_mfma_f32_32x32x16_bf16 v[208:223], v[156:159], v[122:125], v[208:223]
	s_setprio 0
	s_waitcnt vmcnt(6)
	s_barrier
; #define BLOAD(A_, B_, kt) do { _Pragma("unroll") for (int i = 0; i < 4; ++i) { \
;     A_[i] = *(const u32x4*)((const char*)Ap + (aoff + (unsigned)(32 * i * lda + (kt) * 64) * 2u)); B_[i] = *(const u32x4*)((const char*)Wt + (woff + (unsigned)(32 * i * K + (kt) * 64) * 2u)); } } while (0)
; #define BLOAD(A_, B_, kt) do { _Pragma("unroll") for (int i = 0; i < 4; ++i) { \
;     A_[i] = *(const u32x4*)((const char*)Ap + (aoff + (unsigned)(32 * i * lda + (kt) * 64) * 2u)); B_[i] = *(const u32x4*)((const char*)Wt + (woff + (unsigned)(32 * i * K + (kt) * 64) * 2u)); } } while (0)
; #define BSTORE(A_, B_, buf) do { _Pragma("unroll") for (int i = 0; i < 4; ++i) { \
;     *(u32x4*)&As[(buf) * GBUF + (srow + 32 * i) * LDT + sc8] = A_[i]; \
;     *(u32x4*)&Bs[(buf) * GBUF + (srow + 32 * i) * LDT + sc8] = B_[i]; } } while (0)
; template <int NK>
; DI void gemm_run(PF& pf, const u16* __restrict__ Ap, int lda, const u16* __restrict__ Wt, f32x16 (&acc)[2][2], char* smem) {
;     ...
;   __builtin_amdgcn_s_setprio(0);
;   __syncthreads();
;   BSTORE(pf.a0, pf.b0, 0);
;   BLOAD(pf.a0, pf.b0, 2);
;   __syncthreads();
; #pragma unroll
;   for (int kt = 0; kt < nk; kt += 2) {
;     BCOMP(0);
;     BSTORE(pf.a1, pf.b1, 1);
;     if (kt + 3 < nk) BLOAD(pf.a1, pf.b1, kt + 3);
;     __syncthreads();
;     BCOMP(1);
;     if (kt + 2 < nk) { BSTORE(pf.a0, pf.b0, 0); if (kt + 4 < nk) BLOAD(pf.a0, pf.b0, kt + 4); }
;     __syncthreads();
	s_setprio 1
	ds_read_b128 v[224:227], v126 offset:24576
	ds_read_b128 v[232:235], v128 offset:24576
	ds_read_b128 v[236:239], v128 offset:26624
	ds_read_b128 v[228:231], v126 offset:26624
	ds_read_b128 v[240:243], v128 offset:32768
	ds_read_b128 v[244:247], v128 offset:34816
	ds_read_b128 v[248:251], v127 offset:24576
	ds_read_b128 v[160:163], v129 offset:24576
	ds_read_b128 v[164:167], v129 offset:26624
	ds_read_b128 v[156:159], v127 offset:26624
	ds_read_b128 v[168:171], v129 offset:32768
	ds_read_b128 v[122:125], v129 offset:34816
	s_add_u32 m0, s16, 0x0
	s_add_u32 s42, s42, 0x100000
	s_addc_u32 s43, s43, 0
	global_load_lds_dwordx4 v137, s[42:43]
	global_load_lds_dwordx4 v150, s[42:43] offset:1024
	s_add_u32 m0, s0, 0x0
	s_add_u32 s30, s30, 0x10000
	s_addc_u32 s31, s31, 0
	global_load_lds_dwordx4 v151, s[30:31]
	global_load_lds_dwordx4 v152, s[30:31] offset:1024
	global_load_lds_dwordx4 v153, s[30:31] offset:2048
	global_load_lds_dwordx4 v154, s[30:31] offset:3072
	s_waitcnt lgkmcnt(10)
	v_mfma_f32_32x32x16_bf16 v[34:49], v[224:227], v[232:235], v[34:49]
	s_waitcnt lgkmcnt(9)
	v_mfma_f32_32x32x16_bf16 v[50:65], v[224:227], v[236:239], v[50:65]
	s_waitcnt lgkmcnt(8)
	v_mfma_f32_32x32x16_bf16 v[2:17], v[228:231], v[232:235], v[2:17]
	v_mfma_f32_32x32x16_bf16 v[18:33], v[228:231], v[236:239], v[18:33]
	s_waitcnt lgkmcnt(7)
	v_mfma_f32_32x32x16_bf16 v[74:89], v[224:227], v[240:243], v[74:89]
	s_waitcnt lgkmcnt(6)
	v_mfma_f32_32x32x16_bf16 v[90:105], v[224:227], v[244:247], v[90:105]
	v_mfma_f32_32x32x16_bf16 v[106:121], v[228:231], v[240:243], v[106:121]
	v_mfma_f32_32x32x16_bf16 v[208:223], v[228:231], v[244:247], v[208:223]
	s_waitcnt lgkmcnt(4)
	v_mfma_f32_32x32x16_bf16 v[34:49], v[248:251], v[160:163], v[34:49]
	s_waitcnt lgkmcnt(3)
	v_mfma_f32_32x32x16_bf16 v[50:65], v[248:251], v[164:167], v[50:65]
	s_waitcnt lgkmcnt(2)
	v_mfma_f32_32x32x16_bf16 v[2:17], v[156:159], v[160:163], v[2:17]
	v_mfma_f32_32x32x16_bf16 v[18:33], v[156:159], v[164:167], v[18:33]
	s_waitcnt lgkmcnt(1)
	v_mfma_f32_32x32x16_bf16 v[74:89], v[248:251], v[168:171], v[74:89]
	s_waitcnt lgkmcnt(0)
	v_mfma_f32_32x32x16_bf16 v[90:105], v[248:251], v[122:125], v[90:105]
	v_mfma_f32_32x32x16_bf16 v[106:121], v[156:159], v[168:171], v[106:121]
	v_mfma_f32_32x32x16_bf16 v[208:223], v[156:159], v[122:125], v[208:223]
	s_setprio 0
	s_waitcnt vmcnt(6)
	s_barrier
	s_setprio 1
	ds_read_b128 v[224:227], v126 offset:49152
	ds_read_b128 v[232:235], v128 offset:49152
	ds_read_b128 v[236:239], v128 offset:51200
	ds_read_b128 v[228:231], v126 offset:51200
	ds_read_b128 v[240:243], v128 offset:57344
	ds_read_b128 v[244:247], v128 offset:59392
	ds_read_b128 v[248:251], v127 offset:49152
	ds_read_b128 v[160:163], v129 offset:49152
	ds_read_b128 v[164:167], v129 offset:51200
	ds_read_b128 v[156:159], v127 offset:51200
	ds_read_b128 v[168:171], v129 offset:57344
	ds_read_b128 v[122:125], v129 offset:59392
	s_add_u32 m0, s16, 0x6000
	s_add_u32 s42, s42, 0x100000
	s_addc_u32 s43, s43, 0
	global_load_lds_dwordx4 v137, s[42:43]
	global_load_lds_dwordx4 v150, s[42:43] offset:1024
	s_add_u32 m0, s0, 0x6000
	s_add_u32 s30, s30, 0x10000
	s_addc_u32 s31, s31, 0
	global_load_lds_dwordx4 v151, s[30:31]
	global_load_lds_dwordx4 v152, s[30:31] offset:1024
	global_load_lds_dwordx4 v153, s[30:31] offset:2048
	global_load_lds_dwordx4 v154, s[30:31] offset:3072
	s_waitcnt lgkmcnt(10)
	v_mfma_f32_32x32x16_bf16 v[34:49], v[224:227], v[232:235], v[34:49]
	s_waitcnt lgkmcnt(9)
	v_mfma_f32_32x32x16_bf16 v[50:65], v[224:227], v[236:239], v[50:65]
	s_waitcnt lgkmcnt(8)
	v_mfma_f32_32x32x16_bf16 v[2:17], v[228:231], v[232:235], v[2:17]
	v_mfma_f32_32x32x16_bf16 v[18:33], v[228:231], v[236:239], v[18:33]
	s_waitcnt lgkmcnt(7)
	v_mfma_f32_32x32x16_bf16 v[74:89], v[224:227], v[240:243], v[74:89]
	s_waitcnt lgkmcnt(6)
	v_mfma_f32_32x32x16_bf16 v[90:105], v[224:227], v[244:247], v[90:105]
	v_mfma_f32_32x32x16_bf16 v[106:121], v[228:231], v[240:243], v[106:121]
	v_mfma_f32_32x32x16_bf16 v[208:223], v[228:231], v[244:247], v[208:223]
	s_waitcnt lgkmcnt(4)
	v_mfma_f32_32x32x16_bf16 v[34:49], v[248:251], v[160:163], v[34:49]
	s_waitcnt lgkmcnt(3)
	v_mfma_f32_32x32x16_bf16 v[50:65], v[248:251], v[164:167], v[50:65]
	s_waitcnt lgkmcnt(2)
	v_mfma_f32_32x32x16_bf16 v[2:17], v[156:159], v[160:163], v[2:17]
	v_mfma_f32_32x32x16_bf16 v[18:33], v[156:159], v[164:167], v[18:33]
	s_waitcnt lgkmcnt(1)
	v_mfma_f32_32x32x16_bf16 v[74:89], v[248:251], v[168:171], v[74:89]
	s_waitcnt lgkmcnt(0)
	v_mfma_f32_32x32x16_bf16 v[90:105], v[248:251], v[122:125], v[90:105]
	v_mfma_f32_32x32x16_bf16 v[106:121], v[156:159], v[168:171], v[106:121]
	v_mfma_f32_32x32x16_bf16 v[208:223], v[156:159], v[122:125], v[208:223]
	s_setprio 0
	s_waitcnt vmcnt(6)
	s_barrier
; #define BLOAD(A_, B_, kt) do { _Pragma("unroll") for (int i = 0; i < 4; ++i) { \
;     A_[i] = *(const u32x4*)((const char*)Ap + (aoff + (unsigned)(32 * i * lda + (kt) * 64) * 2u)); B_[i] = *(const u32x4*)((const char*)Wt + (woff + (unsigned)(32 * i * K + (kt) * 64) * 2u)); } } while (0)
; #define BLOAD(A_, B_, kt) do { _Pragma("unroll") for (int i = 0; i < 4; ++i) { \
;     A_[i] = *(const u32x4*)((const char*)Ap + (aoff + (unsigned)(32 * i * lda + (kt) * 64) * 2u)); B_[i] = *(const u32x4*)((const char*)Wt + (woff + (unsigned)(32 * i * K + (kt) * 64) * 2u)); } } while (0)
; #define BSTORE(A_, B_, buf) do { _Pragma("unroll") for (int i = 0; i < 4; ++i) { \
;     *(u32x4*)&As[(buf) * GBUF + (srow + 32 * i) * LDT + sc8] = A_[i]; \
;     *(u32x4*)&Bs[(buf) * GBUF + (srow + 32 * i) * LDT + sc8] = B_[i]; } } while (0)
; template <int NK>
; DI void gemm_run(PF& pf, const u16* __restrict__ Ap, int lda, const u16* __restrict__ Wt, f32x16 (&acc)[2][2], char* smem) {
;     ...
;   __builtin_amdgcn_s_setprio(0);
;   __syncthreads();
;   BSTORE(pf.a0, pf.b0, 0);
;   BLOAD(pf.a0, pf.b0, 2);
;   __syncthreads();
; #pragma unroll
;   for (int kt = 0; kt < nk; kt += 2) {
;     BCOMP(0);
;     BSTORE(pf.a1, pf.b1, 1);
;     if (kt + 3 < nk) BLOAD(pf.a1, pf.b1, kt + 3);
;     __syncthreads();
;     BCOMP(1);
;     if (kt + 2 < nk) { BSTORE(pf.a0, pf.b0, 0); if (kt + 4 < nk) BLOAD(pf.a0, pf.b0, kt + 4); }
;     __syncthreads();
	s_setprio 1
	ds_read_b128 v[224:227], v126 offset:0
	ds_read_b128 v[232:235], v128 offset:0
	ds_read_b128 v[236:239], v128 offset:2048
	ds_read_b128 v[228:231], v126 offset:2048
	ds_read_b128 v[240:243], v128 offset:8192
	ds_read_b128 v[244:247], v128 offset:10240
	ds_read_b128 v[248:251], v127 offset:0
	ds_read_b128 v[160:163], v129 offset:0
	ds_read_b128 v[164:167], v129 offset:2048
	ds_read_b128 v[156:159], v127 offset:2048
	ds_read_b128 v[168:171], v129 offset:8192
	ds_read_b128 v[122:125], v129 offset:10240
	s_add_u32 m0, s16, 0xc000
	s_add_u32 s42, s42, 0x100000
	s_addc_u32 s43, s43, 0
	global_load_lds_dwordx4 v137, s[42:43]
	global_load_lds_dwordx4 v150, s[42:43] offset:1024
	s_add_u32 m0, s0, 0xc000
	s_add_u32 s30, s30, 0x10000
	s_addc_u32 s31, s31, 0
	global_load_lds_dwordx4 v151, s[30:31]
	global_load_lds_dwordx4 v152, s[30:31] offset:1024
	global_load_lds_dwordx4 v153, s[30:31] offset:2048
	global_load_lds_dwordx4 v154, s[30:31] offset:3072
	s_waitcnt lgkmcnt(10)
	v_mfma_f32_32x32x16_bf16 v[34:49], v[224:227], v[232:235], v[34:49]
	s_waitcnt lgkmcnt(9)
	v_mfma_f32_32x32x16_bf16 v[50:65], v[224:227], v[236:239], v[50:65]
	s_waitcnt lgkmcnt(8)
	v_mfma_f32_32x32x16_bf16 v[2:17], v[228:231], v[232:235], v[2:17]
	v_mfma_f32_32x32x16_bf16 v[18:33], v[228:231], v[236:239], v[18:33]
	s_waitcnt lgkmcnt(7)
	v_mfma_f32_32x32x16_bf16 v[74:89], v[224:227], v[240:243], v[74:89]
	s_waitcnt lgkmcnt(6)
	v_mfma_f32_32x32x16_bf16 v[90:105], v[224:227], v[244:247], v[90:105]
	v_mfma_f32_32x32x16_bf16 v[106:121], v[228:231], v[240:243], v[106:121]
	v_mfma_f32_32x32x16_bf16 v[208:223], v[228:231], v[244:247], v[208:223]
	s_waitcnt lgkmcnt(4)
	v_mfma_f32_32x32x16_bf16 v[34:49], v[248:251], v[160:163], v[34:49]
	s_waitcnt lgkmcnt(3)
	v_mfma_f32_32x32x16_bf16 v[50:65], v[248:251], v[164:167], v[50:65]
	s_waitcnt lgkmcnt(2)
	v_mfma_f32_32x32x16_bf16 v[2:17], v[156:159], v[160:163], v[2:17]
	v_mfma_f32_32x32x16_bf16 v[18:33], v[156:159], v[164:167], v[18:33]
	s_waitcnt lgkmcnt(1)
	v_mfma_f32_32x32x16_bf16 v[74:89], v[248:251], v[168:171], v[74:89]
	s_waitcnt lgkmcnt(0)
	v_mfma_f32_32x32x16_bf16 v[90:105], v[248:251], v[122:125], v[90:105]
	v_mfma_f32_32x32x16_bf16 v[106:121], v[156:159], v[168:171], v[106:121]
	v_mfma_f32_32x32x16_bf16 v[208:223], v[156:159], v[122:125], v[208:223]
	s_setprio 0
	s_waitcnt vmcnt(6)
	s_barrier
	s_setprio 1
	ds_read_b128 v[224:227], v126 offset:24576
	ds_read_b128 v[232:235], v128 offset:24576
	ds_read_b128 v[236:239], v128 offset:26624
	ds_read_b128 v[228:231], v126 offset:26624
	ds_read_b128 v[240:243], v128 offset:32768
	ds_read_b128 v[244:247], v128 offset:34816
	ds_read_b128 v[248:251], v127 offset:24576
	ds_read_b128 v[160:163], v129 offset:24576
	ds_read_b128 v[164:167], v129 offset:26624
	ds_read_b128 v[156:159], v127 offset:26624
	ds_read_b128 v[168:171], v129 offset:32768
	ds_read_b128 v[122:125], v129 offset:34816
	s_add_u32 m0, s16, 0x0
	s_add_u32 s42, s42, 0x100000
	s_addc_u32 s43, s43, 0
	global_load_lds_dwordx4 v137, s[42:43]
	global_load_lds_dwordx4 v150, s[42:43] offset:1024
	s_add_u32 m0, s0, 0x0
	s_add_u32 s30, s30, 0x10000
	s_addc_u32 s31, s31, 0
	global_load_lds_dwordx4 v151, s[30:31]
	global_load_lds_dwordx4 v152, s[30:31] offset:1024
	global_load_lds_dwordx4 v153, s[30:31] offset:2048
	global_load_lds_dwordx4 v154, s[30:31] offset:3072
	s_waitcnt lgkmcnt(10)
	v_mfma_f32_32x32x16_bf16 v[34:49], v[224:227], v[232:235], v[34:49]
	s_waitcnt lgkmcnt(9)
	v_mfma_f32_32x32x16_bf16 v[50:65], v[224:227], v[236:239], v[50:65]
	s_waitcnt lgkmcnt(8)
	v_mfma_f32_32x32x16_bf16 v[2:17], v[228:231], v[232:235], v[2:17]
	v_mfma_f32_32x32x16_bf16 v[18:33], v[228:231], v[236:239], v[18:33]
	s_waitcnt lgkmcnt(7)
	v_mfma_f32_32x32x16_bf16 v[74:89], v[224:227], v[240:243], v[74:89]
	s_waitcnt lgkmcnt(6)
	v_mfma_f32_32x32x16_bf16 v[90:105], v[224:227], v[244:247], v[90:105]
	v_mfma_f32_32x32x16_bf16 v[106:121], v[228:231], v[240:243], v[106:121]
	v_mfma_f32_32x32x16_bf16 v[208:223], v[228:231], v[244:247], v[208:223]
	s_waitcnt lgkmcnt(4)
	v_mfma_f32_32x32x16_bf16 v[34:49], v[248:251], v[160:163], v[34:49]
	s_waitcnt lgkmcnt(3)
	v_mfma_f32_32x32x16_bf16 v[50:65], v[248:251], v[164:167], v[50:65]
	s_waitcnt lgkmcnt(2)
	v_mfma_f32_32x32x16_bf16 v[2:17], v[156:159], v[160:163], v[2:17]
	v_mfma_f32_32x32x16_bf16 v[18:33], v[156:159], v[164:167], v[18:33]
	s_waitcnt lgkmcnt(1)
	v_mfma_f32_32x32x16_bf16 v[74:89], v[248:251], v[168:171], v[74:89]
	s_waitcnt lgkmcnt(0)
	v_mfma_f32_32x32x16_bf16 v[90:105], v[248:251], v[122:125], v[90:105]
	v_mfma_f32_32x32x16_bf16 v[106:121], v[156:159], v[168:171], v[106:121]
	v_mfma_f32_32x32x16_bf16 v[208:223], v[156:159], v[122:125], v[208:223]
	s_setprio 0
	s_waitcnt vmcnt(6)
	s_barrier
; #define BLOAD(A_, B_, kt) do { _Pragma("unroll") for (int i = 0; i < 4; ++i) { \
;     A_[i] = *(const u32x4*)((const char*)Ap + (aoff + (unsigned)(32 * i * lda + (kt) * 64) * 2u)); B_[i] = *(const u32x4*)((const char*)Wt + (woff + (unsigned)(32 * i * K + (kt) * 64) * 2u)); } } while (0)
; #define BLOAD(A_, B_, kt) do { _Pragma("unroll") for (int i = 0; i < 4; ++i) { \
;     A_[i] = *(const u32x4*)((const char*)Ap + (aoff + (unsigned)(32 * i * lda + (kt) * 64) * 2u)); B_[i] = *(const u32x4*)((const char*)Wt + (woff + (unsigned)(32 * i * K + (kt) * 64) * 2u)); } } while (0)
; #define BSTORE(A_, B_, buf) do { _Pragma("unroll") for (int i = 0; i < 4; ++i) { \
;     *(u32x4*)&As[(buf) * GBUF + (srow + 32 * i) * LDT + sc8] = A_[i]; \
;     *(u32x4*)&Bs[(buf) * GBUF + (srow + 32 * i) * LDT + sc8] = B_[i]; } } while (0)
; template <int NK>
; DI void gemm_run(PF& pf, const u16* __restrict__ Ap, int lda, const u16* __restrict__ Wt, f32x16 (&acc)[2][2], char* smem) {
;     ...
;   __builtin_amdgcn_s_setprio(0);
;   __syncthreads();
;   BSTORE(pf.a0, pf.b0, 0);
;   BLOAD(pf.a0, pf.b0, 2);
;   __syncthreads();
; #pragma unroll
;   for (int kt = 0; kt < nk; kt += 2) {
;     BCOMP(0);
;     BSTORE(pf.a1, pf.b1, 1);
;     if (kt + 3 < nk) BLOAD(pf.a1, pf.b1, kt + 3);
;     __syncthreads();
;     BCOMP(1);
;     if (kt + 2 < nk) { BSTORE(pf.a0, pf.b0, 0); if (kt + 4 < nk) BLOAD(pf.a0, pf.b0, kt + 4); }
;     __syncthreads();
	s_setprio 1
	ds_read_b128 v[224:227], v126 offset:49152
	ds_read_b128 v[232:235], v128 offset:49152
	ds_read_b128 v[236:239], v128 offset:51200
	ds_read_b128 v[228:231], v126 offset:51200
	ds_read_b128 v[240:243], v128 offset:57344
	ds_read_b128 v[244:247], v128 offset:59392
	ds_read_b128 v[248:251], v127 offset:49152
	ds_read_b128 v[160:163], v129 offset:49152
	ds_read_b128 v[164:167], v129 offset:51200
	ds_read_b128 v[156:159], v127 offset:51200
	ds_read_b128 v[168:171], v129 offset:57344
	ds_read_b128 v[122:125], v129 offset:59392
	s_add_u32 m0, s16, 0x6000
	s_add_u32 s42, s42, 0x100000
	s_addc_u32 s43, s43, 0
	global_load_lds_dwordx4 v137, s[42:43]
	global_load_lds_dwordx4 v150, s[42:43] offset:1024
	s_add_u32 m0, s0, 0x6000
	s_add_u32 s30, s30, 0x10000
	s_addc_u32 s31, s31, 0
	global_load_lds_dwordx4 v151, s[30:31]
	global_load_lds_dwordx4 v152, s[30:31] offset:1024
	global_load_lds_dwordx4 v153, s[30:31] offset:2048
	global_load_lds_dwordx4 v154, s[30:31] offset:3072
	s_waitcnt lgkmcnt(10)
	v_mfma_f32_32x32x16_bf16 v[34:49], v[224:227], v[232:235], v[34:49]
	s_waitcnt lgkmcnt(9)
	v_mfma_f32_32x32x16_bf16 v[50:65], v[224:227], v[236:239], v[50:65]
	s_waitcnt lgkmcnt(8)
	v_mfma_f32_32x32x16_bf16 v[2:17], v[228:231], v[232:235], v[2:17]
	v_mfma_f32_32x32x16_bf16 v[18:33], v[228:231], v[236:239], v[18:33]
	s_waitcnt lgkmcnt(7)
	v_mfma_f32_32x32x16_bf16 v[74:89], v[224:227], v[240:243], v[74:89]
	s_waitcnt lgkmcnt(6)
	v_mfma_f32_32x32x16_bf16 v[90:105], v[224:227], v[244:247], v[90:105]
	v_mfma_f32_32x32x16_bf16 v[106:121], v[228:231], v[240:243], v[106:121]
	v_mfma_f32_32x32x16_bf16 v[208:223], v[228:231], v[244:247], v[208:223]
	s_waitcnt lgkmcnt(4)
	v_mfma_f32_32x32x16_bf16 v[34:49], v[248:251], v[160:163], v[34:49]
	s_waitcnt lgkmcnt(3)
	v_mfma_f32_32x32x16_bf16 v[50:65], v[248:251], v[164:167], v[50:65]
	s_waitcnt lgkmcnt(2)
	v_mfma_f32_32x32x16_bf16 v[2:17], v[156:159], v[160:163], v[2:17]
	v_mfma_f32_32x32x16_bf16 v[18:33], v[156:159], v[164:167], v[18:33]
	s_waitcnt lgkmcnt(1)
	v_mfma_f32_32x32x16_bf16 v[74:89], v[248:251], v[168:171], v[74:89]
	s_waitcnt lgkmcnt(0)
	v_mfma_f32_32x32x16_bf16 v[90:105], v[248:251], v[122:125], v[90:105]
	v_mfma_f32_32x32x16_bf16 v[106:121], v[156:159], v[168:171], v[106:121]
	v_mfma_f32_32x32x16_bf16 v[208:223], v[156:159], v[122:125], v[208:223]
	s_setprio 0
	s_waitcnt vmcnt(6)
	s_barrier
	s_setprio 1
	ds_read_b128 v[224:227], v126 offset:0
	ds_read_b128 v[232:235], v128 offset:0
	ds_read_b128 v[236:239], v128 offset:2048
	ds_read_b128 v[228:231], v126 offset:2048
	ds_read_b128 v[240:243], v128 offset:8192
	ds_read_b128 v[244:247], v128 offset:10240
	ds_read_b128 v[248:251], v127 offset:0
	ds_read_b128 v[160:163], v129 offset:0
	ds_read_b128 v[164:167], v129 offset:2048
	ds_read_b128 v[156:159], v127 offset:2048
	ds_read_b128 v[168:171], v129 offset:8192
	ds_read_b128 v[122:125], v129 offset:10240
	s_add_u32 m0, s16, 0xc000
	s_add_u32 s42, s42, 0x100000
	s_addc_u32 s43, s43, 0
	global_load_lds_dwordx4 v137, s[42:43]
	global_load_lds_dwordx4 v150, s[42:43] offset:1024
	s_add_u32 m0, s0, 0xc000
	s_add_u32 s30, s30, 0x10000
	s_addc_u32 s31, s31, 0
	global_load_lds_dwordx4 v151, s[30:31]
	global_load_lds_dwordx4 v152, s[30:31] offset:1024
	global_load_lds_dwordx4 v153, s[30:31] offset:2048
	global_load_lds_dwordx4 v154, s[30:31] offset:3072
	s_waitcnt lgkmcnt(10)
	v_mfma_f32_32x32x16_bf16 v[34:49], v[224:227], v[232:235], v[34:49]
	s_waitcnt lgkmcnt(9)
	v_mfma_f32_32x32x16_bf16 v[50:65], v[224:227], v[236:239], v[50:65]
	s_waitcnt lgkmcnt(8)
	v_mfma_f32_32x32x16_bf16 v[2:17], v[228:231], v[232:235], v[2:17]
	v_mfma_f32_32x32x16_bf16 v[18:33], v[228:231], v[236:239], v[18:33]
	s_waitcnt lgkmcnt(7)
	v_mfma_f32_32x32x16_bf16 v[74:89], v[224:227], v[240:243], v[74:89]
	s_waitcnt lgkmcnt(6)
	v_mfma_f32_32x32x16_bf16 v[90:105], v[224:227], v[244:247], v[90:105]
	v_mfma_f32_32x32x16_bf16 v[106:121], v[228:231], v[240:243], v[106:121]
	v_mfma_f32_32x32x16_bf16 v[208:223], v[228:231], v[244:247], v[208:223]
	s_waitcnt lgkmcnt(4)
	v_mfma_f32_32x32x16_bf16 v[34:49], v[248:251], v[160:163], v[34:49]
	s_waitcnt lgkmcnt(3)
	v_mfma_f32_32x32x16_bf16 v[50:65], v[248:251], v[164:167], v[50:65]
	s_waitcnt lgkmcnt(2)
	v_mfma_f32_32x32x16_bf16 v[2:17], v[156:159], v[160:163], v[2:17]
	v_mfma_f32_32x32x16_bf16 v[18:33], v[156:159], v[164:167], v[18:33]
	s_waitcnt lgkmcnt(1)
	v_mfma_f32_32x32x16_bf16 v[74:89], v[248:251], v[168:171], v[74:89]
	s_waitcnt lgkmcnt(0)
	v_mfma_f32_32x32x16_bf16 v[90:105], v[248:251], v[122:125], v[90:105]
	v_mfma_f32_32x32x16_bf16 v[106:121], v[156:159], v[168:171], v[106:121]
	v_mfma_f32_32x32x16_bf16 v[208:223], v[156:159], v[122:125], v[208:223]
	s_setprio 0
	s_waitcnt vmcnt(6)
	s_barrier
; #define BLOAD(A_, B_, kt) do { _Pragma("unroll") for (int i = 0; i < 4; ++i) { \
;     A_[i] = *(const u32x4*)((const char*)Ap + (aoff + (unsigned)(32 * i * lda + (kt) * 64) * 2u)); B_[i] = *(const u32x4*)((const char*)Wt + (woff + (unsigned)(32 * i * K + (kt) * 64) * 2u)); } } while (0)
; #define BLOAD(A_, B_, kt) do { _Pragma("unroll") for (int i = 0; i < 4; ++i) { \
;     A_[i] = *(const u32x4*)((const char*)Ap + (aoff + (unsigned)(32 * i * lda + (kt) * 64) * 2u)); B_[i] = *(const u32x4*)((const char*)Wt + (woff + (unsigned)(32 * i * K + (kt) * 64) * 2u)); } } while (0)
; #define BSTORE(A_, B_, buf) do { _Pragma("unroll") for (int i = 0; i < 4; ++i) { \
;     *(u32x4*)&As[(buf) * GBUF + (srow + 32 * i) * LDT + sc8] = A_[i]; \
;     *(u32x4*)&Bs[(buf) * GBUF + (srow + 32 * i) * LDT + sc8] = B_[i]; } } while (0)
; template <int NK>
; DI void gemm_run(PF& pf, const u16* __restrict__ Ap, int lda, const u16* __restrict__ Wt, f32x16 (&acc)[2][2], char* smem) {
;     ...
;   __builtin_amdgcn_s_setprio(0);
;   __syncthreads();
;   BSTORE(pf.a0, pf.b0, 0);
;   BLOAD(pf.a0, pf.b0, 2);
;   __syncthreads();
; #pragma unroll
;   for (int kt = 0; kt < nk; kt += 2) {
;     BCOMP(0);
;     BSTORE(pf.a1, pf.b1, 1);
;     if (kt + 3 < nk) BLOAD(pf.a1, pf.b1, kt + 3);
;     __syncthreads();
;     BCOMP(1);
;     if (kt + 2 < nk) { BSTORE(pf.a0, pf.b0, 0); if (kt + 4 < nk) BLOAD(pf.a0, pf.b0, kt + 4); }
;     __syncthreads();
	s_setprio 1
	ds_read_b128 v[224:227], v126 offset:24576
	ds_read_b128 v[232:235], v128 offset:24576
	ds_read_b128 v[236:239], v128 offset:26624
	ds_read_b128 v[228:231], v126 offset:26624
	ds_read_b128 v[240:243], v128 offset:32768
	ds_read_b128 v[244:247], v128 offset:34816
	ds_read_b128 v[248:251], v127 offset:24576
	ds_read_b128 v[160:163], v129 offset:24576
	ds_read_b128 v[164:167], v129 offset:26624
	ds_read_b128 v[156:159], v127 offset:26624
	ds_read_b128 v[168:171], v129 offset:32768
	ds_read_b128 v[122:125], v129 offset:34816
	s_add_u32 m0, s16, 0x0
	s_add_u32 s42, s42, 0x100000
	s_addc_u32 s43, s43, 0
	global_load_lds_dwordx4 v137, s[42:43]
	global_load_lds_dwordx4 v150, s[42:43] offset:1024
	s_add_u32 m0, s0, 0x0
	s_add_u32 s30, s30, 0x10000
	s_addc_u32 s31, s31, 0
	global_load_lds_dwordx4 v151, s[30:31]
	global_load_lds_dwordx4 v152, s[30:31] offset:1024
	global_load_lds_dwordx4 v153, s[30:31] offset:2048
	global_load_lds_dwordx4 v154, s[30:31] offset:3072
	s_waitcnt lgkmcnt(10)
	v_mfma_f32_32x32x16_bf16 v[34:49], v[224:227], v[232:235], v[34:49]
	s_waitcnt lgkmcnt(9)
	v_mfma_f32_32x32x16_bf16 v[50:65], v[224:227], v[236:239], v[50:65]
	s_waitcnt lgkmcnt(8)
	v_mfma_f32_32x32x16_bf16 v[2:17], v[228:231], v[232:235], v[2:17]
	v_mfma_f32_32x32x16_bf16 v[18:33], v[228:231], v[236:239], v[18:33]
	s_waitcnt lgkmcnt(7)
	v_mfma_f32_32x32x16_bf16 v[74:89], v[224:227], v[240:243], v[74:89]
	s_waitcnt lgkmcnt(6)
	v_mfma_f32_32x32x16_bf16 v[90:105], v[224:227], v[244:247], v[90:105]
	v_mfma_f32_32x32x16_bf16 v[106:121], v[228:231], v[240:243], v[106:121]
	v_mfma_f32_32x32x16_bf16 v[208:223], v[228:231], v[244:247], v[208:223]
	s_waitcnt lgkmcnt(4)
	v_mfma_f32_32x32x16_bf16 v[34:49], v[248:251], v[160:163], v[34:49]
	s_waitcnt lgkmcnt(3)
	v_mfma_f32_32x32x16_bf16 v[50:65], v[248:251], v[164:167], v[50:65]
	s_waitcnt lgkmcnt(2)
	v_mfma_f32_32x32x16_bf16 v[2:17], v[156:159], v[160:163], v[2:17]
	v_mfma_f32_32x32x16_bf16 v[18:33], v[156:159], v[164:167], v[18:33]
	s_waitcnt lgkmcnt(1)
	v_mfma_f32_32x32x16_bf16 v[74:89], v[248:251], v[168:171], v[74:89]
	s_waitcnt lgkmcnt(0)
	v_mfma_f32_32x32x16_bf16 v[90:105], v[248:251], v[122:125], v[90:105]
	v_mfma_f32_32x32x16_bf16 v[106:121], v[156:159], v[168:171], v[106:121]
	v_mfma_f32_32x32x16_bf16 v[208:223], v[156:159], v[122:125], v[208:223]
	s_setprio 0
	s_waitcnt vmcnt(6)
	s_barrier
	s_setprio 1
	ds_read_b128 v[224:227], v126 offset:49152
	ds_read_b128 v[232:235], v128 offset:49152
	ds_read_b128 v[236:239], v128 offset:51200
	ds_read_b128 v[228:231], v126 offset:51200
	ds_read_b128 v[240:243], v128 offset:57344
	ds_read_b128 v[244:247], v128 offset:59392
	ds_read_b128 v[248:251], v127 offset:49152
	ds_read_b128 v[160:163], v129 offset:49152
	ds_read_b128 v[164:167], v129 offset:51200
	ds_read_b128 v[156:159], v127 offset:51200
	ds_read_b128 v[168:171], v129 offset:57344
	ds_read_b128 v[122:125], v129 offset:59392
	s_add_u32 m0, s16, 0x6000
	s_add_u32 s42, s42, 0x100000
	s_addc_u32 s43, s43, 0
	global_load_lds_dwordx4 v137, s[42:43]
	global_load_lds_dwordx4 v150, s[42:43] offset:1024
	s_add_u32 m0, s0, 0x6000
	s_add_u32 s30, s30, 0x10000
	s_addc_u32 s31, s31, 0
	global_load_lds_dwordx4 v151, s[30:31]
	global_load_lds_dwordx4 v152, s[30:31] offset:1024
	global_load_lds_dwordx4 v153, s[30:31] offset:2048
	global_load_lds_dwordx4 v154, s[30:31] offset:3072
	s_waitcnt lgkmcnt(10)
	v_mfma_f32_32x32x16_bf16 v[34:49], v[224:227], v[232:235], v[34:49]
	s_waitcnt lgkmcnt(9)
	v_mfma_f32_32x32x16_bf16 v[50:65], v[224:227], v[236:239], v[50:65]
	s_waitcnt lgkmcnt(8)
	v_mfma_f32_32x32x16_bf16 v[2:17], v[228:231], v[232:235], v[2:17]
	v_mfma_f32_32x32x16_bf16 v[18:33], v[228:231], v[236:239], v[18:33]
	s_waitcnt lgkmcnt(7)
	v_mfma_f32_32x32x16_bf16 v[74:89], v[224:227], v[240:243], v[74:89]
	s_waitcnt lgkmcnt(6)
	v_mfma_f32_32x32x16_bf16 v[90:105], v[224:227], v[244:247], v[90:105]
	v_mfma_f32_32x32x16_bf16 v[106:121], v[228:231], v[240:243], v[106:121]
	v_mfma_f32_32x32x16_bf16 v[208:223], v[228:231], v[244:247], v[208:223]
	s_waitcnt lgkmcnt(4)
	v_mfma_f32_32x32x16_bf16 v[34:49], v[248:251], v[160:163], v[34:49]
	s_waitcnt lgkmcnt(3)
	v_mfma_f32_32x32x16_bf16 v[50:65], v[248:251], v[164:167], v[50:65]
	s_waitcnt lgkmcnt(2)
	v_mfma_f32_32x32x16_bf16 v[2:17], v[156:159], v[160:163], v[2:17]
	v_mfma_f32_32x32x16_bf16 v[18:33], v[156:159], v[164:167], v[18:33]
	s_waitcnt lgkmcnt(1)
	v_mfma_f32_32x32x16_bf16 v[74:89], v[248:251], v[168:171], v[74:89]
	s_waitcnt lgkmcnt(0)
	v_mfma_f32_32x32x16_bf16 v[90:105], v[248:251], v[122:125], v[90:105]
	v_mfma_f32_32x32x16_bf16 v[106:121], v[156:159], v[168:171], v[106:121]
	v_mfma_f32_32x32x16_bf16 v[208:223], v[156:159], v[122:125], v[208:223]
	s_setprio 0
	s_waitcnt vmcnt(6)
	s_barrier
; #define BLOAD(A_, B_, kt) do { _Pragma("unroll") for (int i = 0; i < 4; ++i) { \
;     A_[i] = *(const u32x4*)((const char*)Ap + (aoff + (unsigned)(32 * i * lda + (kt) * 64) * 2u)); B_[i] = *(const u32x4*)((const char*)Wt + (woff + (unsigned)(32 * i * K + (kt) * 64) * 2u)); } } while (0)
; #define BLOAD(A_, B_, kt) do { _Pragma("unroll") for (int i = 0; i < 4; ++i) { \
;     A_[i] = *(const u32x4*)((const char*)Ap + (aoff + (unsigned)(32 * i * lda + (kt) * 64) * 2u)); B_[i] = *(const u32x4*)((const char*)Wt + (woff + (unsigned)(32 * i * K + (kt) * 64) * 2u)); } } while (0)
; #define BSTORE(A_, B_, buf) do { _Pragma("unroll") for (int i = 0; i < 4; ++i) { \
;     *(u32x4*)&As[(buf) * GBUF + (srow + 32 * i) * LDT + sc8] = A_[i]; \
;     *(u32x4*)&Bs[(buf) * GBUF + (srow + 32 * i) * LDT + sc8] = B_[i]; } } while (0)
; template <int NK>
; DI void gemm_run(PF& pf, const u16* __restrict__ Ap, int lda, const u16* __restrict__ Wt, f32x16 (&acc)[2][2], char* smem) {
;     ...
;   __builtin_amdgcn_s_setprio(0);
;   __syncthreads();
;   BSTORE(pf.a0, pf.b0, 0);
;   BLOAD(pf.a0, pf.b0, 2);
;   __syncthreads();
; #pragma unroll
;   for (int kt = 0; kt < nk; kt += 2) {
;     BCOMP(0);
;     BSTORE(pf.a1, pf.b1, 1);
;     if (kt + 3 < nk) BLOAD(pf.a1, pf.b1, kt + 3);
;     __syncthreads();
;     BCOMP(1);
;     if (kt + 2 < nk) { BSTORE(pf.a0, pf.b0, 0); if (kt + 4 < nk) BLOAD(pf.a0, pf.b0, kt + 4); }
;     __syncthreads();
	s_setprio 1
	ds_read_b128 v[224:227], v126 offset:0
	ds_read_b128 v[232:235], v128 offset:0
	ds_read_b128 v[236:239], v128 offset:2048
	ds_read_b128 v[228:231], v126 offset:2048
	ds_read_b128 v[240:243], v128 offset:8192
	ds_read_b128 v[244:247], v128 offset:10240
	ds_read_b128 v[248:251], v127 offset:0
	ds_read_b128 v[160:163], v129 offset:0
	ds_read_b128 v[164:167], v129 offset:2048
	ds_read_b128 v[156:159], v127 offset:2048
	ds_read_b128 v[168:171], v129 offset:8192
	ds_read_b128 v[122:125], v129 offset:10240
	s_add_u32 m0, s16, 0xc000
	s_add_u32 s42, s42, 0x100000
	s_addc_u32 s43, s43, 0
	global_load_lds_dwordx4 v137, s[42:43]
	global_load_lds_dwordx4 v150, s[42:43] offset:1024
	s_add_u32 m0, s0, 0xc000
	s_add_u32 s30, s30, 0x10000
	s_addc_u32 s31, s31, 0
	global_load_lds_dwordx4 v151, s[30:31]
	global_load_lds_dwordx4 v152, s[30:31] offset:1024
	global_load_lds_dwordx4 v153, s[30:31] offset:2048
	global_load_lds_dwordx4 v154, s[30:31] offset:3072
	s_waitcnt lgkmcnt(10)
	v_mfma_f32_32x32x16_bf16 v[34:49], v[224:227], v[232:235], v[34:49]
	s_waitcnt lgkmcnt(9)
	v_mfma_f32_32x32x16_bf16 v[50:65], v[224:227], v[236:239], v[50:65]
	s_waitcnt lgkmcnt(8)
	v_mfma_f32_32x32x16_bf16 v[2:17], v[228:231], v[232:235], v[2:17]
	v_mfma_f32_32x32x16_bf16 v[18:33], v[228:231], v[236:239], v[18:33]
	s_waitcnt lgkmcnt(7)
	v_mfma_f32_32x32x16_bf16 v[74:89], v[224:227], v[240:243], v[74:89]
	s_waitcnt lgkmcnt(6)
	v_mfma_f32_32x32x16_bf16 v[90:105], v[224:227], v[244:247], v[90:105]
	v_mfma_f32_32x32x16_bf16 v[106:121], v[228:231], v[240:243], v[106:121]
	v_mfma_f32_32x32x16_bf16 v[208:223], v[228:231], v[244:247], v[208:223]
	s_waitcnt lgkmcnt(4)
	v_mfma_f32_32x32x16_bf16 v[34:49], v[248:251], v[160:163], v[34:49]
	s_waitcnt lgkmcnt(3)
	v_mfma_f32_32x32x16_bf16 v[50:65], v[248:251], v[164:167], v[50:65]
	s_waitcnt lgkmcnt(2)
	v_mfma_f32_32x32x16_bf16 v[2:17], v[156:159], v[160:163], v[2:17]
	v_mfma_f32_32x32x16_bf16 v[18:33], v[156:159], v[164:167], v[18:33]
	s_waitcnt lgkmcnt(1)
	v_mfma_f32_32x32x16_bf16 v[74:89], v[248:251], v[168:171], v[74:89]
	s_waitcnt lgkmcnt(0)
	v_mfma_f32_32x32x16_bf16 v[90:105], v[248:251], v[122:125], v[90:105]
	v_mfma_f32_32x32x16_bf16 v[106:121], v[156:159], v[168:171], v[106:121]
	v_mfma_f32_32x32x16_bf16 v[208:223], v[156:159], v[122:125], v[208:223]
	s_setprio 0
	s_waitcnt vmcnt(6)
	s_barrier
	s_setprio 1
	ds_read_b128 v[224:227], v126 offset:24576
	ds_read_b128 v[232:235], v128 offset:24576
	ds_read_b128 v[236:239], v128 offset:26624
	ds_read_b128 v[228:231], v126 offset:26624
	ds_read_b128 v[240:243], v128 offset:32768
	ds_read_b128 v[244:247], v128 offset:34816
	ds_read_b128 v[248:251], v127 offset:24576
	ds_read_b128 v[160:163], v129 offset:24576
	ds_read_b128 v[164:167], v129 offset:26624
	ds_read_b128 v[156:159], v127 offset:26624
	ds_read_b128 v[168:171], v129 offset:32768
	ds_read_b128 v[122:125], v129 offset:34816
	s_add_u32 m0, s16, 0x0
	s_add_u32 s42, s42, 0x100000
	s_addc_u32 s43, s43, 0
	global_load_lds_dwordx4 v137, s[42:43]
	global_load_lds_dwordx4 v150, s[42:43] offset:1024
	s_add_u32 m0, s0, 0x0
	s_add_u32 s30, s30, 0x10000
	s_addc_u32 s31, s31, 0
	global_load_lds_dwordx4 v151, s[30:31]
	global_load_lds_dwordx4 v152, s[30:31] offset:1024
	global_load_lds_dwordx4 v153, s[30:31] offset:2048
	global_load_lds_dwordx4 v154, s[30:31] offset:3072
	s_waitcnt lgkmcnt(10)
	v_mfma_f32_32x32x16_bf16 v[34:49], v[224:227], v[232:235], v[34:49]
	s_waitcnt lgkmcnt(9)
	v_mfma_f32_32x32x16_bf16 v[50:65], v[224:227], v[236:239], v[50:65]
	s_waitcnt lgkmcnt(8)
	v_mfma_f32_32x32x16_bf16 v[2:17], v[228:231], v[232:235], v[2:17]
	v_mfma_f32_32x32x16_bf16 v[18:33], v[228:231], v[236:239], v[18:33]
	s_waitcnt lgkmcnt(7)
	v_mfma_f32_32x32x16_bf16 v[74:89], v[224:227], v[240:243], v[74:89]
	s_waitcnt lgkmcnt(6)
	v_mfma_f32_32x32x16_bf16 v[90:105], v[224:227], v[244:247], v[90:105]
	v_mfma_f32_32x32x16_bf16 v[106:121], v[228:231], v[240:243], v[106:121]
	v_mfma_f32_32x32x16_bf16 v[208:223], v[228:231], v[244:247], v[208:223]
	s_waitcnt lgkmcnt(4)
	v_mfma_f32_32x32x16_bf16 v[34:49], v[248:251], v[160:163], v[34:49]
	s_waitcnt lgkmcnt(3)
	v_mfma_f32_32x32x16_bf16 v[50:65], v[248:251], v[164:167], v[50:65]
	s_waitcnt lgkmcnt(2)
	v_mfma_f32_32x32x16_bf16 v[2:17], v[156:159], v[160:163], v[2:17]
	v_mfma_f32_32x32x16_bf16 v[18:33], v[156:159], v[164:167], v[18:33]
	s_waitcnt lgkmcnt(1)
	v_mfma_f32_32x32x16_bf16 v[74:89], v[248:251], v[168:171], v[74:89]
	s_waitcnt lgkmcnt(0)
	v_mfma_f32_32x32x16_bf16 v[90:105], v[248:251], v[122:125], v[90:105]
	v_mfma_f32_32x32x16_bf16 v[106:121], v[156:159], v[168:171], v[106:121]
	v_mfma_f32_32x32x16_bf16 v[208:223], v[156:159], v[122:125], v[208:223]
	s_setprio 0
	s_waitcnt vmcnt(6)
	s_barrier
; #define BLOAD(A_, B_, kt) do { _Pragma("unroll") for (int i = 0; i < 4; ++i) { \
;     A_[i] = *(const u32x4*)((const char*)Ap + (aoff + (unsigned)(32 * i * lda + (kt) * 64) * 2u)); B_[i] = *(const u32x4*)((const char*)Wt + (woff + (unsigned)(32 * i * K + (kt) * 64) * 2u)); } } while (0)
; #define BLOAD(A_, B_, kt) do { _Pragma("unroll") for (int i = 0; i < 4; ++i) { \
;     A_[i] = *(const u32x4*)((const char*)Ap + (aoff + (unsigned)(32 * i * lda + (kt) * 64) * 2u)); B_[i] = *(const u32x4*)((const char*)Wt + (woff + (unsigned)(32 * i * K + (kt) * 64) * 2u)); } } while (0)
; #define BSTORE(A_, B_, buf) do { _Pragma("unroll") for (int i = 0; i < 4; ++i) { \
;     *(u32x4*)&As[(buf) * GBUF + (srow + 32 * i) * LDT + sc8] = A_[i]; \
;     *(u32x4*)&Bs[(buf) * GBUF + (srow + 32 * i) * LDT + sc8] = B_[i]; } } while (0)
; template <int NK>
; DI void gemm_run(PF& pf, const u16* __restrict__ Ap, int lda, const u16* __restrict__ Wt, f32x16 (&acc)[2][2], char* smem) {
;     ...
;   __builtin_amdgcn_s_setprio(0);
;   __syncthreads();
;   BSTORE(pf.a0, pf.b0, 0);
;   BLOAD(pf.a0, pf.b0, 2);
;   __syncthreads();
; #pragma unroll
;   for (int kt = 0; kt < nk; kt += 2) {
;     BCOMP(0);
;     BSTORE(pf.a1, pf.b1, 1);
;     if (kt + 3 < nk) BLOAD(pf.a1, pf.b1, kt + 3);
;     __syncthreads();
;     BCOMP(1);
;     if (kt + 2 < nk) { BSTORE(pf.a0, pf.b0, 0); if (kt + 4 < nk) BLOAD(pf.a0, pf.b0, kt + 4); }
;     __syncthreads();
	s_setprio 1
	ds_read_b128 v[224:227], v126 offset:49152
	ds_read_b128 v[232:235], v128 offset:49152
	ds_read_b128 v[236:239], v128 offset:51200
	ds_read_b128 v[228:231], v126 offset:51200
	ds_read_b128 v[240:243], v128 offset:57344
	ds_read_b128 v[244:247], v128 offset:59392
	ds_read_b128 v[248:251], v127 offset:49152
	ds_read_b128 v[160:163], v129 offset:49152
	ds_read_b128 v[164:167], v129 offset:51200
	ds_read_b128 v[156:159], v127 offset:51200
	ds_read_b128 v[168:171], v129 offset:57344
	ds_read_b128 v[122:125], v129 offset:59392
	s_add_u32 m0, s16, 0x6000
	s_add_u32 s42, s42, 0x100000
	s_addc_u32 s43, s43, 0
	global_load_lds_dwordx4 v137, s[42:43]
	global_load_lds_dwordx4 v150, s[42:43] offset:1024
	s_add_u32 m0, s0, 0x6000
	s_add_u32 s30, s30, 0x10000
	s_addc_u32 s31, s31, 0
	global_load_lds_dwordx4 v151, s[30:31]
	global_load_lds_dwordx4 v152, s[30:31] offset:1024
	global_load_lds_dwordx4 v153, s[30:31] offset:2048
	global_load_lds_dwordx4 v154, s[30:31] offset:3072
	s_waitcnt lgkmcnt(10)
	v_mfma_f32_32x32x16_bf16 v[34:49], v[224:227], v[232:235], v[34:49]
	s_waitcnt lgkmcnt(9)
	v_mfma_f32_32x32x16_bf16 v[50:65], v[224:227], v[236:239], v[50:65]
	s_waitcnt lgkmcnt(8)
	v_mfma_f32_32x32x16_bf16 v[2:17], v[228:231], v[232:235], v[2:17]
	v_mfma_f32_32x32x16_bf16 v[18:33], v[228:231], v[236:239], v[18:33]
	s_waitcnt lgkmcnt(7)
	v_mfma_f32_32x32x16_bf16 v[74:89], v[224:227], v[240:243], v[74:89]
	s_waitcnt lgkmcnt(6)
	v_mfma_f32_32x32x16_bf16 v[90:105], v[224:227], v[244:247], v[90:105]
	v_mfma_f32_32x32x16_bf16 v[106:121], v[228:231], v[240:243], v[106:121]
	v_mfma_f32_32x32x16_bf16 v[208:223], v[228:231], v[244:247], v[208:223]
	s_waitcnt lgkmcnt(4)
	v_mfma_f32_32x32x16_bf16 v[34:49], v[248:251], v[160:163], v[34:49]
	s_waitcnt lgkmcnt(3)
	v_mfma_f32_32x32x16_bf16 v[50:65], v[248:251], v[164:167], v[50:65]
	s_waitcnt lgkmcnt(2)
	v_mfma_f32_32x32x16_bf16 v[2:17], v[156:159], v[160:163], v[2:17]
	v_mfma_f32_32x32x16_bf16 v[18:33], v[156:159], v[164:167], v[18:33]
	s_waitcnt lgkmcnt(1)
	v_mfma_f32_32x32x16_bf16 v[74:89], v[248:251], v[168:171], v[74:89]
	s_waitcnt lgkmcnt(0)
	v_mfma_f32_32x32x16_bf16 v[90:105], v[248:251], v[122:125], v[90:105]
	v_mfma_f32_32x32x16_bf16 v[106:121], v[156:159], v[168:171], v[106:121]
	v_mfma_f32_32x32x16_bf16 v[208:223], v[156:159], v[122:125], v[208:223]
	s_setprio 0
	s_waitcnt vmcnt(6)
	s_barrier
	s_setprio 1
	ds_read_b128 v[224:227], v126 offset:0
	ds_read_b128 v[232:235], v128 offset:0
	ds_read_b128 v[236:239], v128 offset:2048
	ds_read_b128 v[228:231], v126 offset:2048
	ds_read_b128 v[240:243], v128 offset:8192
	ds_read_b128 v[244:247], v128 offset:10240
	ds_read_b128 v[248:251], v127 offset:0
	ds_read_b128 v[160:163], v129 offset:0
	ds_read_b128 v[164:167], v129 offset:2048
	ds_read_b128 v[156:159], v127 offset:2048
	ds_read_b128 v[168:171], v129 offset:8192
	ds_read_b128 v[122:125], v129 offset:10240
	s_add_u32 m0, s16, 0xc000
	s_add_u32 s42, s42, 0x100000
	s_addc_u32 s43, s43, 0
	global_load_lds_dwordx4 v137, s[42:43]
	global_load_lds_dwordx4 v150, s[42:43] offset:1024
	s_add_u32 m0, s0, 0xc000
	s_add_u32 s30, s30, 0x10000
	s_addc_u32 s31, s31, 0
	global_load_lds_dwordx4 v151, s[30:31]
	global_load_lds_dwordx4 v152, s[30:31] offset:1024
	global_load_lds_dwordx4 v153, s[30:31] offset:2048
	global_load_lds_dwordx4 v154, s[30:31] offset:3072
	s_waitcnt lgkmcnt(10)
	v_mfma_f32_32x32x16_bf16 v[34:49], v[224:227], v[232:235], v[34:49]
	s_waitcnt lgkmcnt(9)
	v_mfma_f32_32x32x16_bf16 v[50:65], v[224:227], v[236:239], v[50:65]
	s_waitcnt lgkmcnt(8)
	v_mfma_f32_32x32x16_bf16 v[2:17], v[228:231], v[232:235], v[2:17]
	v_mfma_f32_32x32x16_bf16 v[18:33], v[228:231], v[236:239], v[18:33]
	s_waitcnt lgkmcnt(7)
	v_mfma_f32_32x32x16_bf16 v[74:89], v[224:227], v[240:243], v[74:89]
	s_waitcnt lgkmcnt(6)
	v_mfma_f32_32x32x16_bf16 v[90:105], v[224:227], v[244:247], v[90:105]
	v_mfma_f32_32x32x16_bf16 v[106:121], v[228:231], v[240:243], v[106:121]
	v_mfma_f32_32x32x16_bf16 v[208:223], v[228:231], v[244:247], v[208:223]
	s_waitcnt lgkmcnt(4)
	v_mfma_f32_32x32x16_bf16 v[34:49], v[248:251], v[160:163], v[34:49]
	s_waitcnt lgkmcnt(3)
	v_mfma_f32_32x32x16_bf16 v[50:65], v[248:251], v[164:167], v[50:65]
	s_waitcnt lgkmcnt(2)
	v_mfma_f32_32x32x16_bf16 v[2:17], v[156:159], v[160:163], v[2:17]
	v_mfma_f32_32x32x16_bf16 v[18:33], v[156:159], v[164:167], v[18:33]
	s_waitcnt lgkmcnt(1)
	v_mfma_f32_32x32x16_bf16 v[74:89], v[248:251], v[168:171], v[74:89]
	s_waitcnt lgkmcnt(0)
	v_mfma_f32_32x32x16_bf16 v[90:105], v[248:251], v[122:125], v[90:105]
	v_mfma_f32_32x32x16_bf16 v[106:121], v[156:159], v[168:171], v[106:121]
	v_mfma_f32_32x32x16_bf16 v[208:223], v[156:159], v[122:125], v[208:223]
	s_setprio 0
	s_waitcnt vmcnt(6)
	s_barrier
; #define BLOAD(A_, B_, kt) do { _Pragma("unroll") for (int i = 0; i < 4; ++i) { \
;     A_[i] = *(const u32x4*)((const char*)Ap + (aoff + (unsigned)(32 * i * lda + (kt) * 64) * 2u)); B_[i] = *(const u32x4*)((const char*)Wt + (woff + (unsigned)(32 * i * K + (kt) * 64) * 2u)); } } while (0)
; #define BLOAD(A_, B_, kt) do { _Pragma("unroll") for (int i = 0; i < 4; ++i) { \
;     A_[i] = *(const u32x4*)((const char*)Ap + (aoff + (unsigned)(32 * i * lda + (kt) * 64) * 2u)); B_[i] = *(const u32x4*)((const char*)Wt + (woff + (unsigned)(32 * i * K + (kt) * 64) * 2u)); } } while (0)
; #define BSTORE(A_, B_, buf) do { _Pragma("unroll") for (int i = 0; i < 4; ++i) { \
;     *(u32x4*)&As[(buf) * GBUF + (srow + 32 * i) * LDT + sc8] = A_[i]; \
;     *(u32x4*)&Bs[(buf) * GBUF + (srow + 32 * i) * LDT + sc8] = B_[i]; } } while (0)
; template <int NK>
; DI void gemm_run(PF& pf, const u16* __restrict__ Ap, int lda, const u16* __restrict__ Wt, f32x16 (&acc)[2][2], char* smem) {
;     ...
;   __builtin_amdgcn_s_setprio(0);
;   __syncthreads();
;   BSTORE(pf.a0, pf.b0, 0);
;   BLOAD(pf.a0, pf.b0, 2);
;   __syncthreads();
; #pragma unroll
;   for (int kt = 0; kt < nk; kt += 2) {
;     BCOMP(0);
;     BSTORE(pf.a1, pf.b1, 1);
;     if (kt + 3 < nk) BLOAD(pf.a1, pf.b1, kt + 3);
;     __syncthreads();
;     BCOMP(1);
;     if (kt + 2 < nk) { BSTORE(pf.a0, pf.b0, 0); if (kt + 4 < nk) BLOAD(pf.a0, pf.b0, kt + 4); }
;     __syncthreads();
	s_setprio 1
	ds_read_b128 v[224:227], v126 offset:24576
	ds_read_b128 v[232:235], v128 offset:24576
	ds_read_b128 v[236:239], v128 offset:26624
	ds_read_b128 v[228:231], v126 offset:26624
	ds_read_b128 v[240:243], v128 offset:32768
	ds_read_b128 v[244:247], v128 offset:34816
	ds_read_b128 v[248:251], v127 offset:24576
	ds_read_b128 v[160:163], v129 offset:24576
	ds_read_b128 v[164:167], v129 offset:26624
	ds_read_b128 v[156:159], v127 offset:26624
	ds_read_b128 v[168:171], v129 offset:32768
	ds_read_b128 v[122:125], v129 offset:34816
	s_add_u32 m0, s16, 0x0
	s_add_u32 s42, s42, 0x100000
	s_addc_u32 s43, s43, 0
	global_load_lds_dwordx4 v137, s[42:43]
	global_load_lds_dwordx4 v150, s[42:43] offset:1024
	s_add_u32 m0, s0, 0x0
	s_add_u32 s30, s30, 0x10000
	s_addc_u32 s31, s31, 0
	global_load_lds_dwordx4 v151, s[30:31]
	global_load_lds_dwordx4 v152, s[30:31] offset:1024
	global_load_lds_dwordx4 v153, s[30:31] offset:2048
	global_load_lds_dwordx4 v154, s[30:31] offset:3072
	s_waitcnt lgkmcnt(10)
	v_mfma_f32_32x32x16_bf16 v[34:49], v[224:227], v[232:235], v[34:49]
	s_waitcnt lgkmcnt(9)
	v_mfma_f32_32x32x16_bf16 v[50:65], v[224:227], v[236:239], v[50:65]
	s_waitcnt lgkmcnt(8)
	v_mfma_f32_32x32x16_bf16 v[2:17], v[228:231], v[232:235], v[2:17]
	v_mfma_f32_32x32x16_bf16 v[18:33], v[228:231], v[236:239], v[18:33]
	s_waitcnt lgkmcnt(7)
	v_mfma_f32_32x32x16_bf16 v[74:89], v[224:227], v[240:243], v[74:89]
	s_waitcnt lgkmcnt(6)
	v_mfma_f32_32x32x16_bf16 v[90:105], v[224:227], v[244:247], v[90:105]
	v_mfma_f32_32x32x16_bf16 v[106:121], v[228:231], v[240:243], v[106:121]
	v_mfma_f32_32x32x16_bf16 v[208:223], v[228:231], v[244:247], v[208:223]
	s_waitcnt lgkmcnt(4)
	v_mfma_f32_32x32x16_bf16 v[34:49], v[248:251], v[160:163], v[34:49]
	s_waitcnt lgkmcnt(3)
	v_mfma_f32_32x32x16_bf16 v[50:65], v[248:251], v[164:167], v[50:65]
	s_waitcnt lgkmcnt(2)
	v_mfma_f32_32x32x16_bf16 v[2:17], v[156:159], v[160:163], v[2:17]
	v_mfma_f32_32x32x16_bf16 v[18:33], v[156:159], v[164:167], v[18:33]
	s_waitcnt lgkmcnt(1)
	v_mfma_f32_32x32x16_bf16 v[74:89], v[248:251], v[168:171], v[74:89]
	s_waitcnt lgkmcnt(0)
	v_mfma_f32_32x32x16_bf16 v[90:105], v[248:251], v[122:125], v[90:105]
	v_mfma_f32_32x32x16_bf16 v[106:121], v[156:159], v[168:171], v[106:121]
	v_mfma_f32_32x32x16_bf16 v[208:223], v[156:159], v[122:125], v[208:223]
	s_setprio 0
	s_waitcnt vmcnt(6)
	s_barrier
	s_setprio 1
	ds_read_b128 v[224:227], v126 offset:49152
	ds_read_b128 v[232:235], v128 offset:49152
	ds_read_b128 v[236:239], v128 offset:51200
	ds_read_b128 v[228:231], v126 offset:51200
	ds_read_b128 v[240:243], v128 offset:57344
	ds_read_b128 v[244:247], v128 offset:59392
	ds_read_b128 v[248:251], v127 offset:49152
	ds_read_b128 v[160:163], v129 offset:49152
	ds_read_b128 v[164:167], v129 offset:51200
	ds_read_b128 v[156:159], v127 offset:51200
	ds_read_b128 v[168:171], v129 offset:57344
	ds_read_b128 v[122:125], v129 offset:59392
	s_add_u32 m0, s16, 0x6000
	s_add_u32 s42, s42, 0x100000
	s_addc_u32 s43, s43, 0
	global_load_lds_dwordx4 v137, s[42:43]
	global_load_lds_dwordx4 v150, s[42:43] offset:1024
	s_add_u32 m0, s0, 0x6000
	s_add_u32 s30, s30, 0x10000
	s_addc_u32 s31, s31, 0
	global_load_lds_dwordx4 v151, s[30:31]
	global_load_lds_dwordx4 v152, s[30:31] offset:1024
	global_load_lds_dwordx4 v153, s[30:31] offset:2048
	global_load_lds_dwordx4 v154, s[30:31] offset:3072
	s_waitcnt lgkmcnt(10)
	v_mfma_f32_32x32x16_bf16 v[34:49], v[224:227], v[232:235], v[34:49]
	s_waitcnt lgkmcnt(9)
	v_mfma_f32_32x32x16_bf16 v[50:65], v[224:227], v[236:239], v[50:65]
	s_waitcnt lgkmcnt(8)
	v_mfma_f32_32x32x16_bf16 v[2:17], v[228:231], v[232:235], v[2:17]
	v_mfma_f32_32x32x16_bf16 v[18:33], v[228:231], v[236:239], v[18:33]
	s_waitcnt lgkmcnt(7)
	v_mfma_f32_32x32x16_bf16 v[74:89], v[224:227], v[240:243], v[74:89]
	s_waitcnt lgkmcnt(6)
	v_mfma_f32_32x32x16_bf16 v[90:105], v[224:227], v[244:247], v[90:105]
	v_mfma_f32_32x32x16_bf16 v[106:121], v[228:231], v[240:243], v[106:121]
	v_mfma_f32_32x32x16_bf16 v[208:223], v[228:231], v[244:247], v[208:223]
	s_waitcnt lgkmcnt(4)
	v_mfma_f32_32x32x16_bf16 v[34:49], v[248:251], v[160:163], v[34:49]
	s_waitcnt lgkmcnt(3)
	v_mfma_f32_32x32x16_bf16 v[50:65], v[248:251], v[164:167], v[50:65]
	s_waitcnt lgkmcnt(2)
	v_mfma_f32_32x32x16_bf16 v[2:17], v[156:159], v[160:163], v[2:17]
	v_mfma_f32_32x32x16_bf16 v[18:33], v[156:159], v[164:167], v[18:33]
	s_waitcnt lgkmcnt(1)
	v_mfma_f32_32x32x16_bf16 v[74:89], v[248:251], v[168:171], v[74:89]
	s_waitcnt lgkmcnt(0)
	v_mfma_f32_32x32x16_bf16 v[90:105], v[248:251], v[122:125], v[90:105]
	v_mfma_f32_32x32x16_bf16 v[106:121], v[156:159], v[168:171], v[106:121]
	v_mfma_f32_32x32x16_bf16 v[208:223], v[156:159], v[122:125], v[208:223]
	s_setprio 0
	s_waitcnt vmcnt(6)
	s_barrier
; #define BLOAD(A_, B_, kt) do { _Pragma("unroll") for (int i = 0; i < 4; ++i) { \
;     A_[i] = *(const u32x4*)((const char*)Ap + (aoff + (unsigned)(32 * i * lda + (kt) * 64) * 2u)); B_[i] = *(const u32x4*)((const char*)Wt + (woff + (unsigned)(32 * i * K + (kt) * 64) * 2u)); } } while (0)
; #define BLOAD(A_, B_, kt) do { _Pragma("unroll") for (int i = 0; i < 4; ++i) { \
;     A_[i] = *(const u32x4*)((const char*)Ap + (aoff + (unsigned)(32 * i * lda + (kt) * 64) * 2u)); B_[i] = *(const u32x4*)((const char*)Wt + (woff + (unsigned)(32 * i * K + (kt) * 64) * 2u)); } } while (0)
; #define BSTORE(A_, B_, buf) do { _Pragma("unroll") for (int i = 0; i < 4; ++i) { \
;     *(u32x4*)&As[(buf) * GBUF + (srow + 32 * i) * LDT + sc8] = A_[i]; \
;     *(u32x4*)&Bs[(buf) * GBUF + (srow + 32 * i) * LDT + sc8] = B_[i]; } } while (0)
; template <int NK>
; DI void gemm_run(PF& pf, const u16* __restrict__ Ap, int lda, const u16* __restrict__ Wt, f32x16 (&acc)[2][2], char* smem) {
;     ...
;   __builtin_amdgcn_s_setprio(0);
;   __syncthreads();
;   BSTORE(pf.a0, pf.b0, 0);
;   BLOAD(pf.a0, pf.b0, 2);
;   __syncthreads();
; #pragma unroll
;   for (int kt = 0; kt < nk; kt += 2) {
;     BCOMP(0);
;     BSTORE(pf.a1, pf.b1, 1);
;     if (kt + 3 < nk) BLOAD(pf.a1, pf.b1, kt + 3);
;     __syncthreads();
;     BCOMP(1);
;     if (kt + 2 < nk) { BSTORE(pf.a0, pf.b0, 0); if (kt + 4 < nk) BLOAD(pf.a0, pf.b0, kt + 4); }
;     __syncthreads();
	s_setprio 1
	ds_read_b128 v[224:227], v126 offset:0
	ds_read_b128 v[232:235], v128 offset:0
	ds_read_b128 v[236:239], v128 offset:2048
	ds_read_b128 v[228:231], v126 offset:2048
	ds_read_b128 v[240:243], v128 offset:8192
	ds_read_b128 v[244:247], v128 offset:10240
	ds_read_b128 v[248:251], v127 offset:0
	ds_read_b128 v[160:163], v129 offset:0
	ds_read_b128 v[164:167], v129 offset:2048
	ds_read_b128 v[156:159], v127 offset:2048
	ds_read_b128 v[168:171], v129 offset:8192
	ds_read_b128 v[122:125], v129 offset:10240
	s_add_u32 m0, s16, 0xc000
	s_add_u32 s42, s42, 0x100000
	s_addc_u32 s43, s43, 0
	global_load_lds_dwordx4 v137, s[42:43]
	global_load_lds_dwordx4 v150, s[42:43] offset:1024
	s_add_u32 m0, s0, 0xc000
	s_add_u32 s30, s30, 0x10000
	s_addc_u32 s31, s31, 0
	global_load_lds_dwordx4 v151, s[30:31]
	global_load_lds_dwordx4 v152, s[30:31] offset:1024
	global_load_lds_dwordx4 v153, s[30:31] offset:2048
	global_load_lds_dwordx4 v154, s[30:31] offset:3072
	s_waitcnt lgkmcnt(10)
	v_mfma_f32_32x32x16_bf16 v[34:49], v[224:227], v[232:235], v[34:49]
	s_waitcnt lgkmcnt(9)
	v_mfma_f32_32x32x16_bf16 v[50:65], v[224:227], v[236:239], v[50:65]
	s_waitcnt lgkmcnt(8)
	v_mfma_f32_32x32x16_bf16 v[2:17], v[228:231], v[232:235], v[2:17]
	v_mfma_f32_32x32x16_bf16 v[18:33], v[228:231], v[236:239], v[18:33]
	s_waitcnt lgkmcnt(7)
	v_mfma_f32_32x32x16_bf16 v[74:89], v[224:227], v[240:243], v[74:89]
	s_waitcnt lgkmcnt(6)
	v_mfma_f32_32x32x16_bf16 v[90:105], v[224:227], v[244:247], v[90:105]
	v_mfma_f32_32x32x16_bf16 v[106:121], v[228:231], v[240:243], v[106:121]
	v_mfma_f32_32x32x16_bf16 v[208:223], v[228:231], v[244:247], v[208:223]
	s_waitcnt lgkmcnt(4)
	v_mfma_f32_32x32x16_bf16 v[34:49], v[248:251], v[160:163], v[34:49]
	s_waitcnt lgkmcnt(3)
	v_mfma_f32_32x32x16_bf16 v[50:65], v[248:251], v[164:167], v[50:65]
	s_waitcnt lgkmcnt(2)
	v_mfma_f32_32x32x16_bf16 v[2:17], v[156:159], v[160:163], v[2:17]
	v_mfma_f32_32x32x16_bf16 v[18:33], v[156:159], v[164:167], v[18:33]
	s_waitcnt lgkmcnt(1)
	v_mfma_f32_32x32x16_bf16 v[74:89], v[248:251], v[168:171], v[74:89]
	s_waitcnt lgkmcnt(0)
	v_mfma_f32_32x32x16_bf16 v[90:105], v[248:251], v[122:125], v[90:105]
	v_mfma_f32_32x32x16_bf16 v[106:121], v[156:159], v[168:171], v[106:121]
	v_mfma_f32_32x32x16_bf16 v[208:223], v[156:159], v[122:125], v[208:223]
	s_setprio 0
	s_waitcnt vmcnt(6)
	s_barrier
	s_setprio 1
	ds_read_b128 v[224:227], v126 offset:24576
	ds_read_b128 v[232:235], v128 offset:24576
	ds_read_b128 v[236:239], v128 offset:26624
	ds_read_b128 v[228:231], v126 offset:26624
	ds_read_b128 v[240:243], v128 offset:32768
	ds_read_b128 v[244:247], v128 offset:34816
	ds_read_b128 v[248:251], v127 offset:24576
	ds_read_b128 v[160:163], v129 offset:24576
	ds_read_b128 v[164:167], v129 offset:26624
	ds_read_b128 v[156:159], v127 offset:26624
	ds_read_b128 v[168:171], v129 offset:32768
	ds_read_b128 v[122:125], v129 offset:34816
	s_add_u32 m0, s16, 0x0
	s_add_u32 s42, s42, 0x100000
	s_addc_u32 s43, s43, 0
	global_load_lds_dwordx4 v137, s[42:43]
	global_load_lds_dwordx4 v150, s[42:43] offset:1024
	s_add_u32 m0, s0, 0x0
	s_add_u32 s30, s30, 0x10000
	s_addc_u32 s31, s31, 0
	global_load_lds_dwordx4 v151, s[30:31]
	global_load_lds_dwordx4 v152, s[30:31] offset:1024
	global_load_lds_dwordx4 v153, s[30:31] offset:2048
	global_load_lds_dwordx4 v154, s[30:31] offset:3072
	s_waitcnt lgkmcnt(10)
	v_mfma_f32_32x32x16_bf16 v[34:49], v[224:227], v[232:235], v[34:49]
	s_waitcnt lgkmcnt(9)
	v_mfma_f32_32x32x16_bf16 v[50:65], v[224:227], v[236:239], v[50:65]
	s_waitcnt lgkmcnt(8)
	v_mfma_f32_32x32x16_bf16 v[2:17], v[228:231], v[232:235], v[2:17]
	v_mfma_f32_32x32x16_bf16 v[18:33], v[228:231], v[236:239], v[18:33]
	s_waitcnt lgkmcnt(7)
	v_mfma_f32_32x32x16_bf16 v[74:89], v[224:227], v[240:243], v[74:89]
	s_waitcnt lgkmcnt(6)
	v_mfma_f32_32x32x16_bf16 v[90:105], v[224:227], v[244:247], v[90:105]
	v_mfma_f32_32x32x16_bf16 v[106:121], v[228:231], v[240:243], v[106:121]
	v_mfma_f32_32x32x16_bf16 v[208:223], v[228:231], v[244:247], v[208:223]
	s_waitcnt lgkmcnt(4)
	v_mfma_f32_32x32x16_bf16 v[34:49], v[248:251], v[160:163], v[34:49]
	s_waitcnt lgkmcnt(3)
	v_mfma_f32_32x32x16_bf16 v[50:65], v[248:251], v[164:167], v[50:65]
	s_waitcnt lgkmcnt(2)
	v_mfma_f32_32x32x16_bf16 v[2:17], v[156:159], v[160:163], v[2:17]
	v_mfma_f32_32x32x16_bf16 v[18:33], v[156:159], v[164:167], v[18:33]
	s_waitcnt lgkmcnt(1)
	v_mfma_f32_32x32x16_bf16 v[74:89], v[248:251], v[168:171], v[74:89]
	s_waitcnt lgkmcnt(0)
	v_mfma_f32_32x32x16_bf16 v[90:105], v[248:251], v[122:125], v[90:105]
	v_mfma_f32_32x32x16_bf16 v[106:121], v[156:159], v[168:171], v[106:121]
	v_mfma_f32_32x32x16_bf16 v[208:223], v[156:159], v[122:125], v[208:223]
	s_setprio 0
	s_waitcnt vmcnt(6)
	s_barrier
; #define BLOAD(A_, B_, kt) do { _Pragma("unroll") for (int i = 0; i < 4; ++i) { \
;     A_[i] = *(const u32x4*)((const char*)Ap + (aoff + (unsigned)(32 * i * lda + (kt) * 64) * 2u)); B_[i] = *(const u32x4*)((const char*)Wt + (woff + (unsigned)(32 * i * K + (kt) * 64) * 2u)); } } while (0)
; #define BLOAD(A_, B_, kt) do { _Pragma("unroll") for (int i = 0; i < 4; ++i) { \
;     A_[i] = *(const u32x4*)((const char*)Ap + (aoff + (unsigned)(32 * i * lda + (kt) * 64) * 2u)); B_[i] = *(const u32x4*)((const char*)Wt + (woff + (unsigned)(32 * i * K + (kt) * 64) * 2u)); } } while (0)
; #define BSTORE(A_, B_, buf) do { _Pragma("unroll") for (int i = 0; i < 4; ++i) { \
;     *(u32x4*)&As[(buf) * GBUF + (srow + 32 * i) * LDT + sc8] = A_[i]; \
;     *(u32x4*)&Bs[(buf) * GBUF + (srow + 32 * i) * LDT + sc8] = B_[i]; } } while (0)
; template <int NK>
; DI void gemm_run(PF& pf, const u16* __restrict__ Ap, int lda, const u16* __restrict__ Wt, f32x16 (&acc)[2][2], char* smem) {
;     ...
;   __builtin_amdgcn_s_setprio(0);
;   __syncthreads();
;   BSTORE(pf.a0, pf.b0, 0);
;   BLOAD(pf.a0, pf.b0, 2);
;   __syncthreads();
; #pragma unroll
;   for (int kt = 0; kt < nk; kt += 2) {
;     BCOMP(0);
;     BSTORE(pf.a1, pf.b1, 1);
;     if (kt + 3 < nk) BLOAD(pf.a1, pf.b1, kt + 3);
;     __syncthreads();
;     BCOMP(1);
;     if (kt + 2 < nk) { BSTORE(pf.a0, pf.b0, 0); if (kt + 4 < nk) BLOAD(pf.a0, pf.b0, kt + 4); }
;     __syncthreads();
;   }
	s_setprio 1
	ds_read_b128 v[224:227], v126 offset:49152
	ds_read_b128 v[232:235], v128 offset:49152
	ds_read_b128 v[236:239], v128 offset:51200
	ds_read_b128 v[228:231], v126 offset:51200
	ds_read_b128 v[240:243], v128 offset:57344
	ds_read_b128 v[244:247], v128 offset:59392
	ds_read_b128 v[248:251], v127 offset:49152
	ds_read_b128 v[160:163], v129 offset:49152
	ds_read_b128 v[164:167], v129 offset:51200
	ds_read_b128 v[156:159], v127 offset:51200
	ds_read_b128 v[168:171], v129 offset:57344
	ds_read_b128 v[122:125], v129 offset:59392
	s_add_u32 m0, s16, 0x6000
	s_add_u32 s42, s42, 0x100000
	s_addc_u32 s43, s43, 0
	global_load_lds_dwordx4 v137, s[42:43]
	global_load_lds_dwordx4 v150, s[42:43] offset:1024
	s_add_u32 m0, s0, 0x6000
	s_add_u32 s30, s30, 0x10000
	s_addc_u32 s31, s31, 0
	global_load_lds_dwordx4 v151, s[30:31]
	global_load_lds_dwordx4 v152, s[30:31] offset:1024
	global_load_lds_dwordx4 v153, s[30:31] offset:2048
	global_load_lds_dwordx4 v154, s[30:31] offset:3072
	s_waitcnt lgkmcnt(10)
	v_mfma_f32_32x32x16_bf16 v[34:49], v[224:227], v[232:235], v[34:49]
	s_waitcnt lgkmcnt(9)
	v_mfma_f32_32x32x16_bf16 v[50:65], v[224:227], v[236:239], v[50:65]
	s_waitcnt lgkmcnt(8)
	v_mfma_f32_32x32x16_bf16 v[2:17], v[228:231], v[232:235], v[2:17]
	v_mfma_f32_32x32x16_bf16 v[18:33], v[228:231], v[236:239], v[18:33]
	s_waitcnt lgkmcnt(7)
	v_mfma_f32_32x32x16_bf16 v[74:89], v[224:227], v[240:243], v[74:89]
	s_waitcnt lgkmcnt(6)
	v_mfma_f32_32x32x16_bf16 v[90:105], v[224:227], v[244:247], v[90:105]
	v_mfma_f32_32x32x16_bf16 v[106:121], v[228:231], v[240:243], v[106:121]
	v_mfma_f32_32x32x16_bf16 v[208:223], v[228:231], v[244:247], v[208:223]
	s_waitcnt lgkmcnt(4)
	v_mfma_f32_32x32x16_bf16 v[34:49], v[248:251], v[160:163], v[34:49]
	s_waitcnt lgkmcnt(3)
	v_mfma_f32_32x32x16_bf16 v[50:65], v[248:251], v[164:167], v[50:65]
	s_waitcnt lgkmcnt(2)
	v_mfma_f32_32x32x16_bf16 v[2:17], v[156:159], v[160:163], v[2:17]
	v_mfma_f32_32x32x16_bf16 v[18:33], v[156:159], v[164:167], v[18:33]
	s_waitcnt lgkmcnt(1)
	v_mfma_f32_32x32x16_bf16 v[74:89], v[248:251], v[168:171], v[74:89]
	s_waitcnt lgkmcnt(0)
	v_mfma_f32_32x32x16_bf16 v[90:105], v[248:251], v[122:125], v[90:105]
	v_mfma_f32_32x32x16_bf16 v[106:121], v[156:159], v[168:171], v[106:121]
	v_mfma_f32_32x32x16_bf16 v[208:223], v[156:159], v[122:125], v[208:223]
	s_setprio 0
	s_waitcnt vmcnt(6)
	s_barrier
	s_setprio 1
	ds_read_b128 v[224:227], v126 offset:0
	ds_read_b128 v[232:235], v128 offset:0
	ds_read_b128 v[236:239], v128 offset:2048
	ds_read_b128 v[228:231], v126 offset:2048
	ds_read_b128 v[240:243], v128 offset:8192
	ds_read_b128 v[244:247], v128 offset:10240
	ds_read_b128 v[248:251], v127 offset:0
	ds_read_b128 v[160:163], v129 offset:0
	ds_read_b128 v[164:167], v129 offset:2048
	ds_read_b128 v[156:159], v127 offset:2048
	ds_read_b128 v[168:171], v129 offset:8192
	ds_read_b128 v[122:125], v129 offset:10240
	s_waitcnt lgkmcnt(10)
	v_mfma_f32_32x32x16_bf16 v[34:49], v[224:227], v[232:235], v[34:49]
	s_waitcnt lgkmcnt(9)
	v_mfma_f32_32x32x16_bf16 v[50:65], v[224:227], v[236:239], v[50:65]
	s_waitcnt lgkmcnt(8)
	v_mfma_f32_32x32x16_bf16 v[2:17], v[228:231], v[232:235], v[2:17]
	v_mfma_f32_32x32x16_bf16 v[18:33], v[228:231], v[236:239], v[18:33]
	s_waitcnt lgkmcnt(7)
	v_mfma_f32_32x32x16_bf16 v[74:89], v[224:227], v[240:243], v[74:89]
	s_waitcnt lgkmcnt(6)
	v_mfma_f32_32x32x16_bf16 v[90:105], v[224:227], v[244:247], v[90:105]
	v_mfma_f32_32x32x16_bf16 v[106:121], v[228:231], v[240:243], v[106:121]
	v_mfma_f32_32x32x16_bf16 v[208:223], v[228:231], v[244:247], v[208:223]
	s_waitcnt lgkmcnt(4)
	v_mfma_f32_32x32x16_bf16 v[34:49], v[248:251], v[160:163], v[34:49]
	s_waitcnt lgkmcnt(3)
	v_mfma_f32_32x32x16_bf16 v[50:65], v[248:251], v[164:167], v[50:65]
	s_waitcnt lgkmcnt(2)
	v_mfma_f32_32x32x16_bf16 v[2:17], v[156:159], v[160:163], v[2:17]
	v_mfma_f32_32x32x16_bf16 v[18:33], v[156:159], v[164:167], v[18:33]
	s_waitcnt lgkmcnt(1)
	v_mfma_f32_32x32x16_bf16 v[74:89], v[248:251], v[168:171], v[74:89]
	s_waitcnt lgkmcnt(0)
	v_mfma_f32_32x32x16_bf16 v[90:105], v[248:251], v[122:125], v[90:105]
	v_mfma_f32_32x32x16_bf16 v[106:121], v[156:159], v[168:171], v[106:121]
	v_mfma_f32_32x32x16_bf16 v[208:223], v[156:159], v[122:125], v[208:223]
	s_setprio 0
	s_waitcnt vmcnt(0)
	s_barrier
	s_setprio 1
	ds_read_b128 v[224:227], v126 offset:24576
	ds_read_b128 v[232:235], v128 offset:24576
	ds_read_b128 v[236:239], v128 offset:26624
	ds_read_b128 v[228:231], v126 offset:26624
	ds_read_b128 v[240:243], v128 offset:32768
	ds_read_b128 v[244:247], v128 offset:34816
	ds_read_b128 v[248:251], v127 offset:24576
	ds_read_b128 v[160:163], v129 offset:24576
	ds_read_b128 v[164:167], v129 offset:26624
	ds_read_b128 v[156:159], v127 offset:26624
	ds_read_b128 v[168:171], v129 offset:32768
	ds_read_b128 v[122:125], v129 offset:34816
	s_waitcnt lgkmcnt(10)
	v_mfma_f32_32x32x16_bf16 v[34:49], v[224:227], v[232:235], v[34:49]
	s_waitcnt lgkmcnt(9)
	v_mfma_f32_32x32x16_bf16 v[50:65], v[224:227], v[236:239], v[50:65]
	s_waitcnt lgkmcnt(8)
	v_mfma_f32_32x32x16_bf16 v[2:17], v[228:231], v[232:235], v[2:17]
	v_mfma_f32_32x32x16_bf16 v[18:33], v[228:231], v[236:239], v[18:33]
	s_waitcnt lgkmcnt(7)
	v_mfma_f32_32x32x16_bf16 v[74:89], v[224:227], v[240:243], v[74:89]
	s_waitcnt lgkmcnt(6)
	v_mfma_f32_32x32x16_bf16 v[90:105], v[224:227], v[244:247], v[90:105]
	v_mfma_f32_32x32x16_bf16 v[106:121], v[228:231], v[240:243], v[106:121]
	v_mfma_f32_32x32x16_bf16 v[208:223], v[228:231], v[244:247], v[208:223]
	s_waitcnt lgkmcnt(4)
	v_mfma_f32_32x32x16_bf16 v[34:49], v[248:251], v[160:163], v[34:49]
	s_waitcnt lgkmcnt(3)
	v_mfma_f32_32x32x16_bf16 v[50:65], v[248:251], v[164:167], v[50:65]
	s_waitcnt lgkmcnt(2)
	v_mfma_f32_32x32x16_bf16 v[2:17], v[156:159], v[160:163], v[2:17]
	v_mfma_f32_32x32x16_bf16 v[18:33], v[156:159], v[164:167], v[18:33]
	s_waitcnt lgkmcnt(1)
	v_mfma_f32_32x32x16_bf16 v[74:89], v[248:251], v[168:171], v[74:89]
	s_waitcnt lgkmcnt(0)
	v_mfma_f32_32x32x16_bf16 v[90:105], v[248:251], v[122:125], v[90:105]
	v_mfma_f32_32x32x16_bf16 v[106:121], v[156:159], v[168:171], v[106:121]
	v_mfma_f32_32x32x16_bf16 v[208:223], v[156:159], v[122:125], v[208:223]
	s_setprio 0
	s_barrier
	s_mov_b32 s16, 0
; DI int TID() { int t = (int)__builtin_amdgcn_workitem_id_x(); asm volatile("" : "+v"(t)); return t; }
; DI u32x4 pack8(const float (&v)[8]) { u32x4 r = {pk2(v[0], v[1]), pk2(v[2], v[3]), pk2(v[4], v[5]), pk2(v[6], v[7])}; return r; }
; DI int crow(int r, int hi) { return (r & 3) + 8 * (r >> 2) + 4 * hi; }
; DI void acc_to_cs(const f32x16 (&acc)[2][2], float* Cs) {
;   __builtin_amdgcn_s_setprio(2);
;   const int tid = TID(), lane = tid & 63, w = tid >> 6, wm = w >> 1, wn = w & 1, r32 = lane & 31, hi = lane >> 5;
; #pragma unroll
;   for (int mt = 0; mt < 2; ++mt)
; #pragma unroll
;     for (int nt = 0; nt < 2; ++nt)
; #pragma unroll
;       for (int r = 0; r < 16; ++r) Cs[(wm * 64 + mt * 32 + crow(r, hi)) * CSL + wn * 64 + nt * 32 + r32] = acc[mt][nt][r];
;   __syncthreads();
; DI void tile_ffn2(const Params& p, int l, const Chunk& ck, int tile, int next, PF& pf, char* smem) {
;     ...
;   acc_to_cs(acc, Cs);
;   const int row = tid >> 1, half = tid & 1; float ssq = 0.f;
;   float* xd = p.out + (size_t)(ck.tok0 + m0 + row) * 1024 + n0 + half * 64;
;   u16* xb = (u16*)(p.ws + OFF_XB) + (size_t)(m0 + row) * 1024 + n0 + half * 64;
; #pragma unroll
;   for (int c8 = 0; c8 < 8; ++c8) {
;     float v[8], x[8]; cs_ld8(Cs, row, half * 64 + c8 * 8, v); unpack8(*(const u32x4*)(xb + c8 * 8), x);
; #pragma unroll
;     for (int j = 0; j < 8; ++j) { v[j] += x[j]; ssq += v[j] * v[j]; }
;     if (l == 0) *(u32x4*)(xb + c8 * 8) = pack8(v);
;     else { *(f32x4*)(xd + c8 * 8) = f32x4{v[0], v[1], v[2], v[3]}; *(f32x4*)(xd + c8 * 8 + 4) = f32x4{v[4], v[5], v[6], v[7]}; }
.LBB1_208:
.Lffn2_epi2:
	s_and_b32 s0, s24, 0x3f80
	s_setprio 2
	v_mov_b32_e32 v130, v172
	v_and_b32_e32 v136, 1, v0
	v_lshrrev_b32_e32 v131, 1, v130
	v_and_b32_e32 v131, 0xfffffc0, v131
	v_lshrrev_b32_e32 v132, 3, v130
	v_and_or_b32 v131, v132, 4, v131
	v_and_b32_e32 v130, 0x5f, v130
	v_mul_lo_u32 v131, v131, s5
	v_lshl_add_u32 v130, v130, 2, v131
	ds_write2_b32 v130, v34, v50 offset1:32
	ds_write2_b32 v130, v35, v51 offset0:132 offset1:164
	v_add_u32_e32 v34, 0x400, v130
	ds_write2_b32 v34, v36, v52 offset0:8 offset1:40
	ds_write2_b32 v34, v37, v53 offset0:140 offset1:172
	v_add_u32_e32 v34, 0x1000, v130
	ds_write2_b32 v34, v38, v54 offset0:32 offset1:64
	ds_write2_b32 v34, v39, v55 offset0:164 offset1:196
	v_add_u32_e32 v34, 0x1400, v130
	ds_write2_b32 v34, v40, v56 offset0:40 offset1:72
	ds_write2_b32 v34, v41, v57 offset0:172 offset1:204
	v_add_u32_e32 v34, 0x2000, v130
	ds_write2_b32 v34, v42, v58 offset0:64 offset1:96
	ds_write2_b32 v34, v43, v59 offset0:196 offset1:228
	v_add_u32_e32 v34, 0x2400, v130
	ds_write2_b32 v34, v44, v60 offset0:72 offset1:104
	ds_write2_b32 v34, v45, v61 offset0:204 offset1:236
	v_add_u32_e32 v34, 0x3000, v130
	ds_write2_b32 v34, v46, v62 offset0:96 offset1:128
	v_add_u32_e32 v34, 0x3200, v130
	ds_write2_b32 v34, v47, v63 offset0:100 offset1:132
	v_add_u32_e32 v34, 0x3400, v130
	ds_write2_b32 v34, v48, v64 offset0:104 offset1:136
	v_add_u32_e32 v34, 0x3600, v130
	ds_write2_b32 v34, v49, v65 offset0:108 offset1:140
	v_add_u32_e32 v34, 0x4000, v130
	ds_write2_b32 v34, v2, v18 offset0:128 offset1:160
	v_add_u32_e32 v2, 0x4400, v130
	ds_write2_b32 v2, v3, v19 offset0:4 offset1:36
	ds_write2_b32 v2, v4, v20 offset0:136 offset1:168
	v_add_u32_e32 v2, 0x4800, v130
	ds_write2_b32 v2, v5, v21 offset0:12 offset1:44
	v_add_u32_e32 v2, 0x5000, v130
	ds_write2_b32 v2, v6, v22 offset0:160 offset1:192
	v_add_u32_e32 v2, 0x5400, v130
	ds_write2_b32 v2, v7, v23 offset0:36 offset1:68
	ds_write2_b32 v2, v8, v24 offset0:168 offset1:200
	v_add_u32_e32 v2, 0x5800, v130
	ds_write2_b32 v2, v9, v25 offset0:44 offset1:76
	v_add_u32_e32 v2, 0x6000, v130
	ds_write2_b32 v2, v10, v26 offset0:192 offset1:224
	v_add_u32_e32 v2, 0x6400, v130
	ds_write2_b32 v2, v11, v27 offset0:68 offset1:100
	ds_write2_b32 v2, v12, v28 offset0:200 offset1:232
	v_add_u32_e32 v2, 0x6800, v130
	ds_write2_b32 v2, v13, v29 offset0:76 offset1:108
	v_add_u32_e32 v2, 0x7200, v130
	ds_write2_b32 v2, v14, v30 offset0:96 offset1:128
	v_add_u32_e32 v2, 0x7400, v130
	ds_write2_b32 v2, v15, v31 offset0:100 offset1:132
	v_add_u32_e32 v2, 0x7600, v130
	v_ashrrev_i32_e32 v12, 1, v0
	ds_write2_b32 v2, v16, v32 offset0:104 offset1:136
	v_add_u32_e32 v2, 0x7800, v130
	v_add_u32_e32 v130, s0, v12
	v_ashrrev_i32_e32 v131, 31, v130
	ds_write2_b32 v2, v17, v33 offset0:108 offset1:140
	v_lshlrev_b64 v[2:3], 11, v[130:131]
	v_lshl_add_u64 v[2:3], s[50:51], 0, v[2:3]
	v_lshl_add_u64 v[2:3], s[36:37], 1, v[2:3]
	v_lshlrev_b32_e32 v4, 7, v136
	v_mov_b32_e32 v5, v1
	v_lshl_add_u64 v[132:133], v[2:3], 0, v[4:5]
	s_waitcnt lgkmcnt(0)
	s_barrier
	global_load_dwordx4 v[6:9], v[132:133], off
	s_add_i32 s0, s0, s35
	v_add_u32_e32 v2, s0, v12
	v_ashrrev_i32_e32 v3, 31, v2
	v_lshlrev_b64 v[2:3], 12, v[2:3]
	v_lshlrev_b32_e32 v0, 8, v136
	v_lshl_add_u64 v[2:3], s[20:21], 0, v[2:3]
	v_mad_u64_u32 v[58:59], s[30:31], v12, s5, v[0:1]
	v_lshl_add_u64 v[10:11], s[36:37], 2, v[2:3]
	ds_read_b128 v[2:5], v58
	v_lshl_add_u64 v[134:135], v[10:11], 0, v[0:1]
	ds_read_b128 v[10:13], v58 offset:16
	s_mov_b64 s[30:31], -1
	s_and_b64 vcc, exec, s[22:23]
	s_waitcnt vmcnt(0)
	v_lshlrev_b32_e32 v14, 16, v6
	v_and_b32_e32 v15, 0xffff0000, v6
	v_lshlrev_b32_e32 v6, 16, v7
	v_and_b32_e32 v7, 0xffff0000, v7
	s_waitcnt lgkmcnt(1)
	v_pk_add_f32 v[4:5], v[4:5], v[6:7]
	v_lshlrev_b32_e32 v6, 16, v8
	v_and_b32_e32 v7, 0xffff0000, v8
	v_lshlrev_b32_e32 v8, 16, v9
	v_and_b32_e32 v9, 0xffff0000, v9
	v_pk_add_f32 v[2:3], v[2:3], v[14:15]
	s_waitcnt lgkmcnt(0)
	v_pk_add_f32 v[6:7], v[10:11], v[6:7]
	v_pk_add_f32 v[8:9], v[12:13], v[8:9]
	s_cbranch_vccz .LBB1_210
	global_store_dwordx4 v[134:135], v[2:5], off
	global_store_dwordx4 v[134:135], v[6:9], off offset:16
	s_mov_b64 s[30:31], 0

; DI int BID() { int b = (int)__builtin_amdgcn_workgroup_id_x(); asm volatile("" : "+s"(b)); return b; }
; DI void run_phase(const Params& p, int ph, int l, int c, char* smem) {
;     ...
;     case PH_FFN1: {
;       PF pf; int t = BID();
;       if (t < MTN * 32) { const u16* A0; const u16* W0; ffn1_ptrs(p, l, t, A0, W0); gemm_issue(pf, A0, 1024, W0, 1024); }
;       for (; t < MTN * 32; t += gridDim.x) { const int tn = t + (int)gridDim.x; tile_ffn1(p, l, ck, t, tn < MTN * 32 ? tn : -1, pf, smem); }
.LBB1_242:
	s_and_b64 vcc, exec, s[22:23]
	s_cbranch_vccz .LBB1_250
	s_mov_b32 s16, s92
	s_bfe_u32 s0, s16, 0x10008
	s_bfe_u32 s20, s16, 0x20006
	s_andn2_b32 s16, s16, 0x1c0
	s_lshl_b32 s0, s0, 6
	s_lshl_b32 s20, s20, 7
	s_or_b32 s16, s16, s0
	s_or_b32 s16, s16, s20
	s_cmpk_gt_i32 s16, 0x7ff
	s_cbranch_scc1 .LBB1_250
	s_add_u32 s17, s18, 0x1c14c000
	s_addc_u32 s34, s19, 0
	s_lshl_b32 s0, s16, 18
	s_lshl_b32 s35, s16, 17
	s_and_b32 s0, s0, 0x1fc0000
	v_readlane_b32 s22, v255, 28
	s_add_u32 s20, s17, s0
	v_readlane_b32 s23, v255, 29
	s_addc_u32 s21, s34, 0
	s_ashr_i32 s23, s22, 31
	s_mov_b32 s0, s22
	v_writelane_b32 v255, s0, 28
	s_lshl_b64 s[22:23], s[22:23], 23
	v_writelane_b32 v255, s1, 29
	s_add_u32 s0, s18, s22
	s_addc_u32 s22, s19, s23
	s_add_u32 s36, s0, 0x3380000
	s_addc_u32 s37, s22, 0
	s_and_b32 s22, s16, 0xffffff80
	s_ashr_i32 s23, s22, 31
	s_lshl_b64 s[22:23], s[22:23], 11
	s_add_u32 s22, s36, s22
	s_addc_u32 s23, s37, s23
	s_add_u32 s20, s18, 0x1e24c000
	s_addc_u32 s21, s19, 0
	s_add_u32 s22, s18, 0x6b80000
	s_addc_u32 s23, s19, 0
	s_lshl_b32 s40, s16, 7
	s_branch .LBB1_246

; DI int TID() { int t = (int)__builtin_amdgcn_workitem_id_x(); asm volatile("" : "+v"(t)); return t; }
; DI int crow(int r, int hi) { return (r & 3) + 8 * (r >> 2) + 4 * hi; }
; DI void st8(u16* dst, const float (&v)[8]) { *(u32x4*)dst = pack8(v); }
; DI void acc_to_cs(const f32x16 (&acc)[2][2], float* Cs) {
;   __builtin_amdgcn_s_setprio(2);
;   const int tid = TID(), lane = tid & 63, w = tid >> 6, wm = w >> 1, wn = w & 1, r32 = lane & 31, hi = lane >> 5;
; #pragma unroll
;   for (int mt = 0; mt < 2; ++mt)
; #pragma unroll
;     for (int nt = 0; nt < 2; ++nt)
; #pragma unroll
;       for (int r = 0; r < 16; ++r) Cs[(wm * 64 + mt * 32 + crow(r, hi)) * CSL + wn * 64 + nt * 32 + r32] = acc[mt][nt][r];
;   __syncthreads();
; DI void tile_ffn1(const Params& p, int l, const Chunk& ck, int tile, int next, PF& pf, char* smem) {
;     ...
;   acc_to_cs(acc, Cs);
;   const int row = tid >> 1, half = tid & 1; const float rinv = rinv_s[row]; float v[8];
;   u16* dst = (u16*)(p.ws + OFF_H) + (size_t)(m0 + row) * 4096 + n0 + half * 64;
; #pragma unroll
;   for (int c8 = 0; c8 < 8; ++c8) { cs_ld8(Cs, row, half * 64 + c8 * 8, v);
; #pragma unroll
;     for (int j = 0; j < 8; ++j) { const float r = fmaxf(v[j] * rinv, 0.f); v[j] = r * r; }
;     st8(dst + c8 * 8, v); }
.Lffn1_epi2:
	s_setprio 2
	v_mov_b32_e32 v0, v172
	s_add_i32 s35, s35, s59
	v_lshrrev_b32_e32 v66, 1, v0
	v_and_b32_e32 v66, 0xfffffc0, v66
	s_waitcnt lgkmcnt(0)
	v_lshrrev_b32_e32 v67, 3, v0
	v_and_or_b32 v66, v67, 4, v66
	v_and_b32_e32 v0, 0x5f, v0
	v_mul_lo_u32 v66, v66, s5
	v_lshl_add_u32 v0, v0, 2, v66
	ds_write2_b32 v0, v34, v50 offset1:32
	ds_write2_b32 v0, v35, v51 offset0:132 offset1:164
	v_add_u32_e32 v34, 0x400, v0
	ds_write2_b32 v34, v36, v52 offset0:8 offset1:40
	ds_write2_b32 v34, v37, v53 offset0:140 offset1:172
	v_add_u32_e32 v34, 0x1000, v0
	ds_write2_b32 v34, v38, v54 offset0:32 offset1:64
	ds_write2_b32 v34, v39, v55 offset0:164 offset1:196
	v_add_u32_e32 v34, 0x1400, v0
	ds_write2_b32 v34, v40, v56 offset0:40 offset1:72
	ds_write2_b32 v34, v41, v57 offset0:172 offset1:204
	v_add_u32_e32 v34, 0x2000, v0
	ds_write2_b32 v34, v42, v58 offset0:64 offset1:96
	ds_write2_b32 v34, v43, v59 offset0:196 offset1:228
	v_add_u32_e32 v34, 0x2400, v0
	ds_write2_b32 v34, v44, v60 offset0:72 offset1:104
	ds_write2_b32 v34, v45, v61 offset0:204 offset1:236
	v_add_u32_e32 v34, 0x3000, v0
	ds_write2_b32 v34, v46, v62 offset0:96 offset1:128
	v_add_u32_e32 v34, 0x3200, v0
	ds_write2_b32 v34, v47, v63 offset0:100 offset1:132
	v_add_u32_e32 v34, 0x3400, v0
	ds_write2_b32 v34, v48, v64 offset0:104 offset1:136
	v_add_u32_e32 v34, 0x3600, v0
	ds_write2_b32 v34, v49, v65 offset0:108 offset1:140
	v_add_u32_e32 v34, 0x4000, v0
	ds_write2_b32 v34, v2, v18 offset0:128 offset1:160
	v_add_u32_e32 v2, 0x4400, v0
	ds_write2_b32 v2, v3, v19 offset0:4 offset1:36
	ds_write2_b32 v2, v4, v20 offset0:136 offset1:168
	v_add_u32_e32 v2, 0x4800, v0
	ds_write2_b32 v2, v5, v21 offset0:12 offset1:44
	v_add_u32_e32 v2, 0x5000, v0
	ds_write2_b32 v2, v6, v22 offset0:160 offset1:192
	v_add_u32_e32 v2, 0x5400, v0
	ds_write2_b32 v2, v7, v23 offset0:36 offset1:68
	ds_write2_b32 v2, v8, v24 offset0:168 offset1:200
	v_add_u32_e32 v2, 0x5800, v0
	ds_write2_b32 v2, v9, v25 offset0:44 offset1:76
	v_add_u32_e32 v2, 0x6000, v0
	ds_write2_b32 v2, v10, v26 offset0:192 offset1:224
	v_add_u32_e32 v2, 0x6400, v0
	ds_write2_b32 v2, v11, v27 offset0:68 offset1:100
	ds_write2_b32 v2, v12, v28 offset0:200 offset1:232
	v_add_u32_e32 v2, 0x6800, v0
	ds_write2_b32 v2, v13, v29 offset0:76 offset1:108
	v_add_u32_e32 v2, 0x7200, v0
	ds_write2_b32 v2, v14, v30 offset0:96 offset1:128
	v_add_u32_e32 v2, 0x7400, v0
	ds_write2_b32 v2, v15, v31 offset0:100 offset1:132
	v_add_u32_e32 v2, 0x7600, v0
	v_add_u32_e32 v0, 0x7800, v0
	ds_write2_b32 v0, v17, v33 offset0:108 offset1:140
	v_ashrrev_i32_e32 v4, 1, v148
	v_lshlrev_b32_e32 v0, 6, v148
	ds_write2_b32 v2, v16, v32 offset0:104 offset1:136
	v_lshl_add_u32 v5, v4, 2, v201
	v_add_u32_e32 v2, s41, v4
	v_and_b32_e32 v6, 64, v0
	v_mul_lo_u32 v4, v4, s5
	s_waitcnt lgkmcnt(0)
	s_barrier
	v_lshlrev_b32_e32 v0, 15, v6
	v_lshl_add_u32 v20, v6, 2, v4
	ds_read_b32 v21, v5
	ds_read_b128 v[4:7], v20
	v_ashrrev_i32_e32 v3, 31, v2
	v_lshlrev_b64 v[2:3], 6, v[2:3]
	v_lshl_add_u64 v[2:3], s[22:23], 0, v[2:3]
	s_lshl_b64 s[42:43], s[26:27], 15
	v_lshl_add_u64 v[2:3], s[42:43], 0, v[2:3]
	v_lshl_add_u64 v[2:3], v[2:3], 0, v[0:1]
	v_mov_b32_e32 v24, 0x100000
	v_mov_b32_e32 v25, 0
	v_lshl_add_u64 v[22:23], v[2:3], 0, v[24:25]
	s_waitcnt lgkmcnt(0)
	v_mul_f32_e32 v0, v21, v4
	ds_read_b128 v[8:11], v20 offset:16
	ds_read_b128 v[12:15], v20 offset:32
	ds_read_b128 v[16:19], v20 offset:48
	v_max_f32_e32 v4, 0, v0
	v_mul_f32_e32 v0, v21, v5
	v_max_f32_e32 v5, 0, v0
	v_mul_f32_e32 v0, v21, v6
	v_max_f32_e32 v6, 0, v0
	v_mul_f32_e32 v0, v21, v7
	v_max_f32_e32 v7, 0, v0
	s_waitcnt lgkmcnt(2)
	v_mul_f32_e32 v0, v21, v8
	v_max_f32_e32 v8, 0, v0
	v_mul_f32_e32 v0, v21, v9
	v_max_f32_e32 v9, 0, v0
	v_mul_f32_e32 v0, v21, v10
	v_max_f32_e32 v10, 0, v0
	v_mul_f32_e32 v0, v21, v11
	v_max_f32_e32 v11, 0, v0
	v_pk_mul_f32 v[4:5], v[4:5], v[4:5]
	v_pk_mul_f32 v[6:7], v[6:7], v[6:7]
	v_pk_mul_f32 v[8:9], v[8:9], v[8:9]
	v_pk_mul_f32 v[10:11], v[10:11], v[10:11]
	v_cvt_pk_bf16_f32 v4, v4, v5
	v_cvt_pk_bf16_f32 v5, v6, v7
	v_cvt_pk_bf16_f32 v6, v8, v9
	v_cvt_pk_bf16_f32 v7, v10, v11
	s_waitcnt lgkmcnt(1)
	v_mul_f32_e32 v0, v21, v12
	global_store_dwordx4 v[2:3], v[4:7], off
	s_add_i32 s40, s40, s95
	s_and_b64 vcc, exec, s[24:25]
	v_max_f32_e32 v4, 0, v0
	v_mul_f32_e32 v0, v21, v13
	v_max_f32_e32 v5, 0, v0
	v_mul_f32_e32 v0, v21, v14
	v_pk_mul_f32 v[8:9], v[4:5], v[4:5]
	v_max_f32_e32 v4, 0, v0
	v_mul_f32_e32 v0, v21, v15
	v_max_f32_e32 v5, 0, v0
	s_waitcnt lgkmcnt(0)
	v_mul_f32_e32 v0, v21, v16
	v_max_f32_e32 v12, 0, v0
	v_mul_f32_e32 v0, v21, v17
	v_max_f32_e32 v13, 0, v0
	v_mul_f32_e32 v0, v21, v18
	v_pk_mul_f32 v[10:11], v[4:5], v[4:5]
	ds_read_b128 v[4:7], v20 offset:64
	v_max_f32_e32 v14, 0, v0
	v_mul_f32_e32 v0, v21, v19
	v_max_f32_e32 v15, 0, v0
	v_pk_mul_f32 v[12:13], v[12:13], v[12:13]
	v_pk_mul_f32 v[14:15], v[14:15], v[14:15]
	v_cvt_pk_bf16_f32 v8, v8, v9
	v_cvt_pk_bf16_f32 v9, v10, v11
	v_cvt_pk_bf16_f32 v10, v12, v13
	v_cvt_pk_bf16_f32 v11, v14, v15
	global_store_dwordx4 v[2:3], v[8:11], off offset:16
	ds_read_b128 v[8:11], v20 offset:80
	s_waitcnt lgkmcnt(1)
	v_mul_f32_e32 v0, v21, v4
	v_max_f32_e32 v4, 0, v0
	v_mul_f32_e32 v0, v21, v5
	v_max_f32_e32 v5, 0, v0
	v_mul_f32_e32 v0, v21, v6
	v_pk_mul_f32 v[12:13], v[4:5], v[4:5]
	v_max_f32_e32 v4, 0, v0
	v_mul_f32_e32 v0, v21, v7
	v_max_f32_e32 v5, 0, v0
	s_waitcnt lgkmcnt(0)
; DI void st8(u16* dst, const float (&v)[8]) { *(u32x4*)dst = pack8(v); }
; DI void tile_ffn1(const Params& p, int l, const Chunk& ck, int tile, int next, PF& pf, char* smem) {
;     ...
;   const int row = tid >> 1, half = tid & 1; const float rinv = rinv_s[row]; float v[8];
;   u16* dst = (u16*)(p.ws + OFF_H) + (size_t)(m0 + row) * 4096 + n0 + half * 64;
; #pragma unroll
;   for (int c8 = 0; c8 < 8; ++c8) { cs_ld8(Cs, row, half * 64 + c8 * 8, v);
; #pragma unroll
;     for (int j = 0; j < 8; ++j) { const float r = fmaxf(v[j] * rinv, 0.f); v[j] = r * r; }
;     st8(dst + c8 * 8, v); }
	v_mul_f32_e32 v0, v21, v8
	v_max_f32_e32 v8, 0, v0
	v_mul_f32_e32 v0, v21, v9
	v_max_f32_e32 v9, 0, v0
	v_mul_f32_e32 v0, v21, v10
	v_pk_mul_f32 v[14:15], v[4:5], v[4:5]
	ds_read_b128 v[4:7], v20 offset:96
	v_pk_mul_f32 v[16:17], v[8:9], v[8:9]
	v_max_f32_e32 v8, 0, v0
	v_mul_f32_e32 v0, v21, v11
	v_max_f32_e32 v9, 0, v0
	v_pk_mul_f32 v[18:19], v[8:9], v[8:9]
	v_cvt_pk_bf16_f32 v8, v12, v13
	v_cvt_pk_bf16_f32 v9, v14, v15
	v_cvt_pk_bf16_f32 v10, v16, v17
	v_cvt_pk_bf16_f32 v11, v18, v19
	global_store_dwordx4 v[2:3], v[8:11], off offset:32
	ds_read_b128 v[8:11], v20 offset:112
	s_waitcnt lgkmcnt(1)
	v_mul_f32_e32 v0, v21, v4
	v_max_f32_e32 v4, 0, v0
	v_mul_f32_e32 v0, v21, v5
	v_max_f32_e32 v5, 0, v0
	v_mul_f32_e32 v0, v21, v6
	v_pk_mul_f32 v[12:13], v[4:5], v[4:5]
	v_max_f32_e32 v4, 0, v0
	v_mul_f32_e32 v0, v21, v7
	v_max_f32_e32 v5, 0, v0
	s_waitcnt lgkmcnt(0)
	v_mul_f32_e32 v0, v21, v8
	v_max_f32_e32 v8, 0, v0
	v_mul_f32_e32 v0, v21, v9
	v_max_f32_e32 v9, 0, v0
	v_mul_f32_e32 v0, v21, v10
	v_pk_mul_f32 v[14:15], v[4:5], v[4:5]
	ds_read_b128 v[4:7], v20 offset:128
	v_pk_mul_f32 v[16:17], v[8:9], v[8:9]
	v_max_f32_e32 v8, 0, v0
	v_mul_f32_e32 v0, v21, v11
	v_max_f32_e32 v9, 0, v0
	v_pk_mul_f32 v[18:19], v[8:9], v[8:9]
	v_cvt_pk_bf16_f32 v8, v12, v13
	v_cvt_pk_bf16_f32 v9, v14, v15
	v_cvt_pk_bf16_f32 v10, v16, v17
	v_cvt_pk_bf16_f32 v11, v18, v19
	global_store_dwordx4 v[2:3], v[8:11], off offset:48
	ds_read_b128 v[8:11], v20 offset:144
	s_waitcnt lgkmcnt(1)
	v_mul_f32_e32 v0, v21, v4
	v_max_f32_e32 v4, 0, v0
	v_mul_f32_e32 v0, v21, v5
	v_max_f32_e32 v5, 0, v0
	v_mul_f32_e32 v0, v21, v6
	v_pk_mul_f32 v[12:13], v[4:5], v[4:5]
	v_max_f32_e32 v4, 0, v0
	v_mul_f32_e32 v0, v21, v7
	v_max_f32_e32 v5, 0, v0
	s_waitcnt lgkmcnt(0)
	v_mul_f32_e32 v0, v21, v8
	v_max_f32_e32 v8, 0, v0
	v_mul_f32_e32 v0, v21, v9
	v_max_f32_e32 v9, 0, v0
	v_mul_f32_e32 v0, v21, v10
	v_pk_mul_f32 v[14:15], v[4:5], v[4:5]
	ds_read_b128 v[4:7], v20 offset:160
	v_pk_mul_f32 v[16:17], v[8:9], v[8:9]
	v_max_f32_e32 v8, 0, v0
	v_mul_f32_e32 v0, v21, v11
	v_max_f32_e32 v9, 0, v0
	v_pk_mul_f32 v[18:19], v[8:9], v[8:9]
	v_cvt_pk_bf16_f32 v8, v12, v13
	v_cvt_pk_bf16_f32 v9, v14, v15
	v_cvt_pk_bf16_f32 v10, v16, v17
	v_cvt_pk_bf16_f32 v11, v18, v19
	global_store_dwordx4 v[22:23], v[8:11], off
	ds_read_b128 v[8:11], v20 offset:176
	s_waitcnt lgkmcnt(1)
	v_mul_f32_e32 v0, v21, v4
	v_max_f32_e32 v4, 0, v0
	v_mul_f32_e32 v0, v21, v5
	v_max_f32_e32 v5, 0, v0
	v_mul_f32_e32 v0, v21, v6
	v_pk_mul_f32 v[12:13], v[4:5], v[4:5]
	v_max_f32_e32 v4, 0, v0
	v_mul_f32_e32 v0, v21, v7
	v_max_f32_e32 v5, 0, v0
	s_waitcnt lgkmcnt(0)
	v_mul_f32_e32 v0, v21, v8
	v_max_f32_e32 v8, 0, v0
	v_mul_f32_e32 v0, v21, v9
	v_pk_mul_f32 v[14:15], v[4:5], v[4:5]
	ds_read_b128 v[4:7], v20 offset:192
	v_max_f32_e32 v9, 0, v0
	v_mul_f32_e32 v0, v21, v10
	v_pk_mul_f32 v[16:17], v[8:9], v[8:9]
	v_max_f32_e32 v8, 0, v0
	v_mul_f32_e32 v0, v21, v11
	v_max_f32_e32 v9, 0, v0
	v_pk_mul_f32 v[18:19], v[8:9], v[8:9]
	v_cvt_pk_bf16_f32 v8, v12, v13
	v_cvt_pk_bf16_f32 v9, v14, v15
	v_cvt_pk_bf16_f32 v10, v16, v17
	v_cvt_pk_bf16_f32 v11, v18, v19
	global_store_dwordx4 v[22:23], v[8:11], off offset:16
	s_waitcnt lgkmcnt(0)
	v_mul_f32_e32 v0, v21, v4
	ds_read_b128 v[8:11], v20 offset:208
	ds_read_b128 v[12:15], v20 offset:224
	ds_read_b128 v[16:19], v20 offset:240
	v_max_f32_e32 v4, 0, v0
	v_mul_f32_e32 v0, v21, v5
	v_max_f32_e32 v5, 0, v0
	v_mul_f32_e32 v0, v21, v6
	v_max_f32_e32 v6, 0, v0
	v_mul_f32_e32 v0, v21, v7
	v_max_f32_e32 v7, 0, v0
	s_waitcnt lgkmcnt(2)
	v_mul_f32_e32 v0, v21, v8
	v_max_f32_e32 v8, 0, v0
	v_mul_f32_e32 v0, v21, v9
	v_max_f32_e32 v9, 0, v0
	v_mul_f32_e32 v0, v21, v10
	v_max_f32_e32 v10, 0, v0
	v_mul_f32_e32 v0, v21, v11
	v_max_f32_e32 v11, 0, v0
	v_pk_mul_f32 v[4:5], v[4:5], v[4:5]
	v_pk_mul_f32 v[6:7], v[6:7], v[6:7]
	v_pk_mul_f32 v[8:9], v[8:9], v[8:9]
	v_pk_mul_f32 v[10:11], v[10:11], v[10:11]
	v_cvt_pk_bf16_f32 v4, v4, v5
	v_cvt_pk_bf16_f32 v5, v6, v7
	v_cvt_pk_bf16_f32 v6, v8, v9
	v_cvt_pk_bf16_f32 v7, v10, v11
	s_waitcnt lgkmcnt(1)
	v_mul_f32_e32 v0, v21, v12
	global_store_dwordx4 v[22:23], v[4:7], off offset:32
	s_nop 1
	v_max_f32_e32 v4, 0, v0
	v_mul_f32_e32 v0, v21, v13
	v_max_f32_e32 v5, 0, v0
	v_mul_f32_e32 v0, v21, v14
	v_max_f32_e32 v6, 0, v0
	v_mul_f32_e32 v0, v21, v15
	v_max_f32_e32 v7, 0, v0
	s_waitcnt lgkmcnt(0)
	v_mul_f32_e32 v0, v21, v16
	v_max_f32_e32 v8, 0, v0
	v_mul_f32_e32 v0, v21, v17
	v_max_f32_e32 v9, 0, v0
	v_mul_f32_e32 v0, v21, v18
	v_max_f32_e32 v10, 0, v0
	v_mul_f32_e32 v0, v21, v19
	v_max_f32_e32 v11, 0, v0
	v_pk_mul_f32 v[4:5], v[4:5], v[4:5]
	v_pk_mul_f32 v[6:7], v[6:7], v[6:7]
	v_pk_mul_f32 v[8:9], v[8:9], v[8:9]
	v_pk_mul_f32 v[10:11], v[10:11], v[10:11]
	v_cvt_pk_bf16_f32 v4, v4, v5
	v_cvt_pk_bf16_f32 v5, v6, v7
	v_cvt_pk_bf16_f32 v6, v8, v9
	v_cvt_pk_bf16_f32 v7, v10, v11
	global_store_dwordx4 v[22:23], v[4:7], off offset:48
	s_cmp_lg_u32 s0, 0
	s_cbranch_scc1 .Lffn1_p2done
	s_mov_b32 s0, 1
	s_sub_i32 s35, s35, s59
	s_sub_i32 s40, s40, s95
	s_add_u32 s26, s26, 0x80
	v_mov_b32_e32 v34, v74
	v_mov_b32_e32 v35, v75
	v_mov_b32_e32 v36, v76
	v_mov_b32_e32 v37, v77
	v_mov_b32_e32 v38, v78
	v_mov_b32_e32 v39, v79
	v_mov_b32_e32 v40, v80
	v_mov_b32_e32 v41, v81
	v_mov_b32_e32 v42, v82
	v_mov_b32_e32 v43, v83
	v_mov_b32_e32 v44, v84
	v_mov_b32_e32 v45, v85
	v_mov_b32_e32 v46, v86
	v_mov_b32_e32 v47, v87
	v_mov_b32_e32 v48, v88
	v_mov_b32_e32 v49, v89
	v_mov_b32_e32 v50, v90
	v_mov_b32_e32 v51, v91
	v_mov_b32_e32 v52, v92
	v_mov_b32_e32 v53, v93
	v_mov_b32_e32 v54, v94
	v_mov_b32_e32 v55, v95
	v_mov_b32_e32 v56, v96
	v_mov_b32_e32 v57, v97
	v_mov_b32_e32 v58, v98
	v_mov_b32_e32 v59, v99
	v_mov_b32_e32 v60, v100
	v_mov_b32_e32 v61, v101
	v_mov_b32_e32 v62, v102
	v_mov_b32_e32 v63, v103
	v_mov_b32_e32 v64, v104
	v_mov_b32_e32 v65, v105
	v_mov_b32_e32 v2, v106
	v_mov_b32_e32 v3, v107
	v_mov_b32_e32 v4, v108
	v_mov_b32_e32 v5, v109
	v_mov_b32_e32 v6, v110
	v_mov_b32_e32 v7, v111
	v_mov_b32_e32 v8, v112
	v_mov_b32_e32 v9, v113
	v_mov_b32_e32 v10, v114
	v_mov_b32_e32 v11, v115
	v_mov_b32_e32 v12, v116
	v_mov_b32_e32 v13, v117
	v_mov_b32_e32 v14, v118
	v_mov_b32_e32 v15, v119
	v_mov_b32_e32 v16, v120
	v_mov_b32_e32 v17, v121
	v_mov_b32_e32 v18, v122
	v_mov_b32_e32 v19, v123
	v_mov_b32_e32 v20, v124
	v_mov_b32_e32 v21, v125
	v_mov_b32_e32 v22, v126
	v_mov_b32_e32 v23, v127
	v_mov_b32_e32 v24, v128
	v_mov_b32_e32 v25, v129
	v_mov_b32_e32 v26, v130
	v_mov_b32_e32 v27, v131
	v_mov_b32_e32 v28, v132
	v_mov_b32_e32 v29, v133
	v_mov_b32_e32 v30, v134
	v_mov_b32_e32 v31, v135
	v_mov_b32_e32 v32, v136
	v_mov_b32_e32 v33, v137
	s_waitcnt lgkmcnt(0)
	s_barrier
	s_branch .Lffn1_epi2

; DI int TID() { int t = (int)__builtin_amdgcn_workitem_id_x(); asm volatile("" : "+v"(t)); return t; }
; #define BLOAD(A_, B_, kt) do { _Pragma("unroll") for (int i = 0; i < 4; ++i) { \
;     A_[i] = *(const u32x4*)((const char*)Ap + (aoff + (unsigned)(32 * i * lda + (kt) * 64) * 2u)); B_[i] = *(const u32x4*)((const char*)Wt + (woff + (unsigned)(32 * i * K + (kt) * 64) * 2u)); } } while (0)
; DI RowSS rowss_load(const float* ps, int m0) { const int tid = TID(); const float* q = ps + (size_t)(m0 + (tid >> 1)) * 16 + (tid & 1) * 8; RowSS r; r.a = *(const f32x4*)q; r.b = *(const f32x4*)(q + 4); return r; }
; #define BLOAD(A_, B_, kt) do { _Pragma("unroll") for (int i = 0; i < 4; ++i) { \
;     A_[i] = *(const u32x4*)((const char*)Ap + (aoff + (unsigned)(32 * i * lda + (kt) * 64) * 2u)); B_[i] = *(const u32x4*)((const char*)Wt + (woff + (unsigned)(32 * i * K + (kt) * 64) * 2u)); } } while (0)
; #define BSTORE(A_, B_, buf) do { _Pragma("unroll") for (int i = 0; i < 4; ++i) { \
;     *(u32x4*)&As[(buf) * GBUF + (srow + 32 * i) * LDT + sc8] = A_[i]; \
;     *(u32x4*)&Bs[(buf) * GBUF + (srow + 32 * i) * LDT + sc8] = B_[i]; } } while (0)
; template <int NK>
; DI void gemm_run(PF& pf, const u16* __restrict__ Ap, int lda, const u16* __restrict__ Wt, f32x16 (&acc)[2][2], char* smem) {
;     ...
;   __builtin_amdgcn_s_setprio(0);
;   __syncthreads();
;   BSTORE(pf.a0, pf.b0, 0);
;   BLOAD(pf.a0, pf.b0, 2);
;   __syncthreads();
; #pragma unroll
;   for (int kt = 0; kt < nk; kt += 2) {
;     BCOMP(0);
;     BSTORE(pf.a1, pf.b1, 1);
;     if (kt + 3 < nk) BLOAD(pf.a1, pf.b1, kt + 3);
;     __syncthreads();
; DI void tile_ffn1(const Params& p, int l, const Chunk& ck, int tile, int next, PF& pf, char* smem) {
;   float* Cs = (float*)smem; float* rinv_s = (float*)(smem + SMEM_CS);
;   const int tid = TID(); const int mi = tile & (MTN - 1), ni = tile >> MTS; const int m0 = mi * 128, n0 = ni * 128;
;   f32x16 acc[2][2]; zero_acc(acc);
;   const RowSS rss = rowss_load((const float*)(p.ws + OFF_PSMID), m0);
;   { const u16* Ap; const u16* Wt; ffn1_ptrs(p, l, tile, Ap, Wt); gemm_run<16>(pf, Ap, 1024, Wt, acc, smem); }
;   if (next >= 0) { const u16* An; const u16* Wn; ffn1_ptrs(p, l, next, An, Wn); gemm_issue(pf, An, 1024, Wn, 1024); }
.LBB1_246:
	s_mov_b32 s26, s16
	s_add_i32 s16, s16, s78
	s_cmpk_gt_i32 s16, 0x7ff
	s_cselect_b64 s[24:25], -1, 0
	s_cmpk_lt_i32 s16, 0x800
	v_mov_b32_e32 v148, v172
	v_mov_b32_e32 v0, v172
	s_cselect_b32 s0, s16, -1
	s_and_b32 s41, s40, 0x3f80
	s_and_b32 s27, s35, 0xfe0000
	v_ashrrev_i32_e32 v2, 1, v0
	v_add_u32_e32 v2, s41, v2
	v_ashrrev_i32_e32 v3, 31, v2
	v_lshlrev_b64 v[2:3], 6, v[2:3]
	v_lshlrev_b32_e32 v0, 5, v0
	v_lshl_add_u64 v[2:3], s[20:21], 0, v[2:3]
	v_and_b32_e32 v0, 32, v0
	v_lshl_add_u64 v[2:3], v[2:3], 0, v[0:1]
	global_load_dwordx4 v[66:69], v[2:3], off offset:16
	global_load_dwordx4 v[70:73], v[2:3], off
	s_and_b32 s26, s26, 0xffffff80
	s_lshl_b32 s26, s26, 1
	s_lshl_b32 s27, s27, 1
	s_add_u32 s28, s17, s27
	s_addc_u32 s29, s34, 0
	s_ashr_i32 s27, s26, 31
	s_lshl_b64 s[30:31], s[26:27], 6
	s_add_u32 s30, s36, s30
	s_addc_u32 s31, s37, s31
	s_setprio 0
	s_waitcnt lgkmcnt(0)
	s_mov_b32 s0, 0
	v_and_b32_e32 v149, 63, v172
	v_lshrrev_b32_e32 v151, 6, v172
	v_lshrrev_b32_e32 v152, 4, v149
	v_xor_b32_e32 v152, v152, v149
	v_and_b32_e32 v152, 3, v152
	v_lshlrev_b32_e32 v152, 4, v152
	v_lshrrev_b32_e32 v153, 2, v149
	v_lshl_add_u32 v142, v151, 5, v153
	v_lshl_add_u32 v142, v142, 11, v152
	v_add_u32_e32 v143, 0x7c00, v142
	v_lshl_add_u32 v144, v151, 6, v153
	v_lshl_add_u32 v144, v144, 6, v152
	v_mov_b32_e32 v145, v144
	v_mov_b32_e32 v146, v144
	v_mov_b32_e32 v147, v144
	v_readfirstlane_b32 s42, v151
	s_lshl_b32 s43, s42, 12
	s_lshl_b32 s42, s42, 11
	s_add_u32 s43, s43, 0x2000
	v_and_b32_e32 v152, 31, v149
	v_lshrrev_b32_e32 v153, 5, v149
	v_lshrrev_b32_e32 v149, 2, v152
	v_and_b32_e32 v149, 3, v149
	v_xor_b32_e32 v149, v149, v153
	v_lshlrev_b32_e32 v149, 4, v149
	v_lshl_add_u32 v149, v152, 6, v149
	v_lshrrev_b32_e32 v152, 1, v151
	v_and_b32_e32 v153, 1, v151
	v_lshl_add_u32 v138, v152, 12, v149
	v_lshl_add_u32 v140, v153, 12, v149
	v_add_u32_e32 v140, 0x2000, v140
	v_xor_b32_e32 v139, 32, v138
	v_xor_b32_e32 v141, 32, v140
	s_barrier
	s_add_u32 m0, s42, 0x0
	s_nop 0
	global_load_lds_dwordx4 v142, s[28:29]
	global_load_lds_dwordx4 v143, s[28:29] offset:1024
	s_add_u32 m0, s43, 0x0
	s_nop 0
	global_load_lds_dwordx4 v144, s[30:31]
	global_load_lds_dwordx4 v145, s[30:31] offset:1024
	global_load_lds_dwordx4 v146, s[30:31] offset:2048
	global_load_lds_dwordx4 v147, s[30:31] offset:3072
	s_add_u32 m0, s42, 0x6000
	s_add_u32 s28, s28, 0x40
	s_addc_u32 s29, s29, 0
	global_load_lds_dwordx4 v142, s[28:29]
	global_load_lds_dwordx4 v143, s[28:29] offset:1024
	s_add_u32 m0, s43, 0x6000
	s_add_u32 s30, s30, 0x40000
	s_addc_u32 s31, s31, 0
	global_load_lds_dwordx4 v144, s[30:31]
	global_load_lds_dwordx4 v145, s[30:31] offset:1024
	global_load_lds_dwordx4 v146, s[30:31] offset:2048
	global_load_lds_dwordx4 v147, s[30:31] offset:3072
	s_waitcnt vmcnt(6)
	s_barrier
	s_setprio 1
	ds_read_b128 v[208:211], v138 offset:0
	ds_read_b128 v[216:219], v140 offset:0
	ds_read_b128 v[220:223], v140 offset:2048
	ds_read_b128 v[212:215], v138 offset:2048
	ds_read_b128 v[224:227], v140 offset:8192
	ds_read_b128 v[228:231], v140 offset:10240
	ds_read_b128 v[232:235], v139 offset:0
	ds_read_b128 v[240:243], v141 offset:0
	ds_read_b128 v[244:247], v141 offset:2048
	ds_read_b128 v[236:239], v139 offset:2048
	ds_read_b128 v[248:251], v141 offset:8192
	ds_read_b128 v[156:159], v141 offset:10240
	s_add_u32 m0, s42, 0xc000
	s_add_u32 s28, s28, 0x40
	s_addc_u32 s29, s29, 0
	global_load_lds_dwordx4 v142, s[28:29]
	global_load_lds_dwordx4 v143, s[28:29] offset:1024
	s_add_u32 m0, s43, 0xc000
	s_add_u32 s30, s30, 0x40000
	s_addc_u32 s31, s31, 0
	global_load_lds_dwordx4 v144, s[30:31]
	global_load_lds_dwordx4 v145, s[30:31] offset:1024
	global_load_lds_dwordx4 v146, s[30:31] offset:2048
	global_load_lds_dwordx4 v147, s[30:31] offset:3072
	s_waitcnt lgkmcnt(10)
	v_mfma_f32_32x32x16_bf16 v[34:49], v[208:211], v[216:219], 0
	s_waitcnt lgkmcnt(9)
	v_mfma_f32_32x32x16_bf16 v[50:65], v[208:211], v[220:223], 0
	s_waitcnt lgkmcnt(8)
	v_mfma_f32_32x32x16_bf16 v[2:17], v[212:215], v[216:219], 0
	v_mfma_f32_32x32x16_bf16 v[18:33], v[212:215], v[220:223], 0
	s_waitcnt lgkmcnt(7)
	v_mfma_f32_32x32x16_bf16 v[74:89], v[208:211], v[224:227], 0
	s_waitcnt lgkmcnt(6)
	v_mfma_f32_32x32x16_bf16 v[90:105], v[208:211], v[228:231], 0
	v_mfma_f32_32x32x16_bf16 v[106:121], v[212:215], v[224:227], 0
	v_mfma_f32_32x32x16_bf16 v[122:137], v[212:215], v[228:231], 0
	s_waitcnt lgkmcnt(4)
	v_mfma_f32_32x32x16_bf16 v[34:49], v[232:235], v[240:243], v[34:49]
	s_waitcnt lgkmcnt(3)
	v_mfma_f32_32x32x16_bf16 v[50:65], v[232:235], v[244:247], v[50:65]
	s_waitcnt lgkmcnt(2)
	v_mfma_f32_32x32x16_bf16 v[2:17], v[236:239], v[240:243], v[2:17]
	v_mfma_f32_32x32x16_bf16 v[18:33], v[236:239], v[244:247], v[18:33]
	s_waitcnt lgkmcnt(1)
	v_mfma_f32_32x32x16_bf16 v[74:89], v[232:235], v[248:251], v[74:89]
	s_waitcnt lgkmcnt(0)
	v_mfma_f32_32x32x16_bf16 v[90:105], v[232:235], v[156:159], v[90:105]
	v_mfma_f32_32x32x16_bf16 v[106:121], v[236:239], v[248:251], v[106:121]
	v_mfma_f32_32x32x16_bf16 v[122:137], v[236:239], v[156:159], v[122:137]
	s_setprio 0
	s_waitcnt vmcnt(6)
	s_barrier
; #define BLOAD(A_, B_, kt) do { _Pragma("unroll") for (int i = 0; i < 4; ++i) { \
;     A_[i] = *(const u32x4*)((const char*)Ap + (aoff + (unsigned)(32 * i * lda + (kt) * 64) * 2u)); B_[i] = *(const u32x4*)((const char*)Wt + (woff + (unsigned)(32 * i * K + (kt) * 64) * 2u)); } } while (0)
; #define BLOAD(A_, B_, kt) do { _Pragma("unroll") for (int i = 0; i < 4; ++i) { \
;     A_[i] = *(const u32x4*)((const char*)Ap + (aoff + (unsigned)(32 * i * lda + (kt) * 64) * 2u)); B_[i] = *(const u32x4*)((const char*)Wt + (woff + (unsigned)(32 * i * K + (kt) * 64) * 2u)); } } while (0)
; #define BSTORE(A_, B_, buf) do { _Pragma("unroll") for (int i = 0; i < 4; ++i) { \
;     *(u32x4*)&As[(buf) * GBUF + (srow + 32 * i) * LDT + sc8] = A_[i]; \
;     *(u32x4*)&Bs[(buf) * GBUF + (srow + 32 * i) * LDT + sc8] = B_[i]; } } while (0)
; template <int NK>
; DI void gemm_run(PF& pf, const u16* __restrict__ Ap, int lda, const u16* __restrict__ Wt, f32x16 (&acc)[2][2], char* smem) {
;     ...
; #pragma unroll
;   for (int kt = 0; kt < nk; kt += 2) {
;     BCOMP(0);
;     BSTORE(pf.a1, pf.b1, 1);
;     if (kt + 3 < nk) BLOAD(pf.a1, pf.b1, kt + 3);
;     __syncthreads();
;     BCOMP(1);
;     if (kt + 2 < nk) { BSTORE(pf.a0, pf.b0, 0); if (kt + 4 < nk) BLOAD(pf.a0, pf.b0, kt + 4); }
;     __syncthreads();
;   }
	s_setprio 1
	ds_read_b128 v[208:211], v138 offset:24576
	ds_read_b128 v[216:219], v140 offset:24576
	ds_read_b128 v[220:223], v140 offset:26624
	ds_read_b128 v[212:215], v138 offset:26624
	ds_read_b128 v[224:227], v140 offset:32768
	ds_read_b128 v[228:231], v140 offset:34816
	ds_read_b128 v[232:235], v139 offset:24576
	ds_read_b128 v[240:243], v141 offset:24576
	ds_read_b128 v[244:247], v141 offset:26624
	ds_read_b128 v[236:239], v139 offset:26624
	ds_read_b128 v[248:251], v141 offset:32768
	ds_read_b128 v[156:159], v141 offset:34816
	s_add_u32 m0, s42, 0x0
	s_add_u32 s28, s28, 0x40
	s_addc_u32 s29, s29, 0
	global_load_lds_dwordx4 v142, s[28:29]
	global_load_lds_dwordx4 v143, s[28:29] offset:1024
	s_add_u32 m0, s43, 0x0
	s_add_u32 s30, s30, 0x40000
	s_addc_u32 s31, s31, 0
	global_load_lds_dwordx4 v144, s[30:31]
	global_load_lds_dwordx4 v145, s[30:31] offset:1024
	global_load_lds_dwordx4 v146, s[30:31] offset:2048
	global_load_lds_dwordx4 v147, s[30:31] offset:3072
	s_waitcnt lgkmcnt(10)
	v_mfma_f32_32x32x16_bf16 v[34:49], v[208:211], v[216:219], v[34:49]
	s_waitcnt lgkmcnt(9)
	v_mfma_f32_32x32x16_bf16 v[50:65], v[208:211], v[220:223], v[50:65]
	s_waitcnt lgkmcnt(8)
	v_mfma_f32_32x32x16_bf16 v[2:17], v[212:215], v[216:219], v[2:17]
	v_mfma_f32_32x32x16_bf16 v[18:33], v[212:215], v[220:223], v[18:33]
	s_waitcnt lgkmcnt(7)
	v_mfma_f32_32x32x16_bf16 v[74:89], v[208:211], v[224:227], v[74:89]
	s_waitcnt lgkmcnt(6)
	v_mfma_f32_32x32x16_bf16 v[90:105], v[208:211], v[228:231], v[90:105]
	v_mfma_f32_32x32x16_bf16 v[106:121], v[212:215], v[224:227], v[106:121]
	v_mfma_f32_32x32x16_bf16 v[122:137], v[212:215], v[228:231], v[122:137]
	s_waitcnt lgkmcnt(4)
	v_mfma_f32_32x32x16_bf16 v[34:49], v[232:235], v[240:243], v[34:49]
	s_waitcnt lgkmcnt(3)
	v_mfma_f32_32x32x16_bf16 v[50:65], v[232:235], v[244:247], v[50:65]
	s_waitcnt lgkmcnt(2)
	v_mfma_f32_32x32x16_bf16 v[2:17], v[236:239], v[240:243], v[2:17]
	v_mfma_f32_32x32x16_bf16 v[18:33], v[236:239], v[244:247], v[18:33]
	s_waitcnt lgkmcnt(1)
	v_mfma_f32_32x32x16_bf16 v[74:89], v[232:235], v[248:251], v[74:89]
	s_waitcnt lgkmcnt(0)
	v_mfma_f32_32x32x16_bf16 v[90:105], v[232:235], v[156:159], v[90:105]
	v_mfma_f32_32x32x16_bf16 v[106:121], v[236:239], v[248:251], v[106:121]
	v_mfma_f32_32x32x16_bf16 v[122:137], v[236:239], v[156:159], v[122:137]
	s_setprio 0
	s_waitcnt vmcnt(6)
	s_barrier
	s_setprio 1
	ds_read_b128 v[208:211], v138 offset:49152
	ds_read_b128 v[216:219], v140 offset:49152
	ds_read_b128 v[220:223], v140 offset:51200
	ds_read_b128 v[212:215], v138 offset:51200
	ds_read_b128 v[224:227], v140 offset:57344
	ds_read_b128 v[228:231], v140 offset:59392
	ds_read_b128 v[232:235], v139 offset:49152
	ds_read_b128 v[240:243], v141 offset:49152
	ds_read_b128 v[244:247], v141 offset:51200
	ds_read_b128 v[236:239], v139 offset:51200
	ds_read_b128 v[248:251], v141 offset:57344
	ds_read_b128 v[156:159], v141 offset:59392
	s_add_u32 m0, s42, 0x6000
	s_add_u32 s28, s28, 0x40
	s_addc_u32 s29, s29, 0
	global_load_lds_dwordx4 v142, s[28:29]
	global_load_lds_dwordx4 v143, s[28:29] offset:1024
	s_add_u32 m0, s43, 0x6000
	s_add_u32 s30, s30, 0x40000
	s_addc_u32 s31, s31, 0
	global_load_lds_dwordx4 v144, s[30:31]
	global_load_lds_dwordx4 v145, s[30:31] offset:1024
	global_load_lds_dwordx4 v146, s[30:31] offset:2048
	global_load_lds_dwordx4 v147, s[30:31] offset:3072
	s_waitcnt lgkmcnt(10)
	v_mfma_f32_32x32x16_bf16 v[34:49], v[208:211], v[216:219], v[34:49]
	s_waitcnt lgkmcnt(9)
	v_mfma_f32_32x32x16_bf16 v[50:65], v[208:211], v[220:223], v[50:65]
	s_waitcnt lgkmcnt(8)
	v_mfma_f32_32x32x16_bf16 v[2:17], v[212:215], v[216:219], v[2:17]
	v_mfma_f32_32x32x16_bf16 v[18:33], v[212:215], v[220:223], v[18:33]
	s_waitcnt lgkmcnt(7)
	v_mfma_f32_32x32x16_bf16 v[74:89], v[208:211], v[224:227], v[74:89]
	s_waitcnt lgkmcnt(6)
	v_mfma_f32_32x32x16_bf16 v[90:105], v[208:211], v[228:231], v[90:105]
	v_mfma_f32_32x32x16_bf16 v[106:121], v[212:215], v[224:227], v[106:121]
	v_mfma_f32_32x32x16_bf16 v[122:137], v[212:215], v[228:231], v[122:137]
	s_waitcnt lgkmcnt(4)
	v_mfma_f32_32x32x16_bf16 v[34:49], v[232:235], v[240:243], v[34:49]
	s_waitcnt lgkmcnt(3)
	v_mfma_f32_32x32x16_bf16 v[50:65], v[232:235], v[244:247], v[50:65]
	s_waitcnt lgkmcnt(2)
	v_mfma_f32_32x32x16_bf16 v[2:17], v[236:239], v[240:243], v[2:17]
	v_mfma_f32_32x32x16_bf16 v[18:33], v[236:239], v[244:247], v[18:33]
	s_waitcnt lgkmcnt(1)
	v_mfma_f32_32x32x16_bf16 v[74:89], v[232:235], v[248:251], v[74:89]
	s_waitcnt lgkmcnt(0)
	v_mfma_f32_32x32x16_bf16 v[90:105], v[232:235], v[156:159], v[90:105]
	v_mfma_f32_32x32x16_bf16 v[106:121], v[236:239], v[248:251], v[106:121]
	v_mfma_f32_32x32x16_bf16 v[122:137], v[236:239], v[156:159], v[122:137]
	s_setprio 0
	s_waitcnt vmcnt(6)
	s_barrier
; #define BLOAD(A_, B_, kt) do { _Pragma("unroll") for (int i = 0; i < 4; ++i) { \
;     A_[i] = *(const u32x4*)((const char*)Ap + (aoff + (unsigned)(32 * i * lda + (kt) * 64) * 2u)); B_[i] = *(const u32x4*)((const char*)Wt + (woff + (unsigned)(32 * i * K + (kt) * 64) * 2u)); } } while (0)
; #define BLOAD(A_, B_, kt) do { _Pragma("unroll") for (int i = 0; i < 4; ++i) { \
;     A_[i] = *(const u32x4*)((const char*)Ap + (aoff + (unsigned)(32 * i * lda + (kt) * 64) * 2u)); B_[i] = *(const u32x4*)((const char*)Wt + (woff + (unsigned)(32 * i * K + (kt) * 64) * 2u)); } } while (0)
; #define BSTORE(A_, B_, buf) do { _Pragma("unroll") for (int i = 0; i < 4; ++i) { \
;     *(u32x4*)&As[(buf) * GBUF + (srow + 32 * i) * LDT + sc8] = A_[i]; \
;     *(u32x4*)&Bs[(buf) * GBUF + (srow + 32 * i) * LDT + sc8] = B_[i]; } } while (0)
; template <int NK>
; DI void gemm_run(PF& pf, const u16* __restrict__ Ap, int lda, const u16* __restrict__ Wt, f32x16 (&acc)[2][2], char* smem) {
;     ...
; #pragma unroll
;   for (int kt = 0; kt < nk; kt += 2) {
;     BCOMP(0);
;     BSTORE(pf.a1, pf.b1, 1);
;     if (kt + 3 < nk) BLOAD(pf.a1, pf.b1, kt + 3);
;     __syncthreads();
;     BCOMP(1);
;     if (kt + 2 < nk) { BSTORE(pf.a0, pf.b0, 0); if (kt + 4 < nk) BLOAD(pf.a0, pf.b0, kt + 4); }
;     __syncthreads();
;   }
	s_setprio 1
	ds_read_b128 v[208:211], v138 offset:0
	ds_read_b128 v[216:219], v140 offset:0
	ds_read_b128 v[220:223], v140 offset:2048
	ds_read_b128 v[212:215], v138 offset:2048
	ds_read_b128 v[224:227], v140 offset:8192
	ds_read_b128 v[228:231], v140 offset:10240
	ds_read_b128 v[232:235], v139 offset:0
	ds_read_b128 v[240:243], v141 offset:0
	ds_read_b128 v[244:247], v141 offset:2048
	ds_read_b128 v[236:239], v139 offset:2048
	ds_read_b128 v[248:251], v141 offset:8192
	ds_read_b128 v[156:159], v141 offset:10240
	s_add_u32 m0, s42, 0xc000
	s_add_u32 s28, s28, 0x40
	s_addc_u32 s29, s29, 0
	global_load_lds_dwordx4 v142, s[28:29]
	global_load_lds_dwordx4 v143, s[28:29] offset:1024
	s_add_u32 m0, s43, 0xc000
	s_add_u32 s30, s30, 0x40000
	s_addc_u32 s31, s31, 0
	global_load_lds_dwordx4 v144, s[30:31]
	global_load_lds_dwordx4 v145, s[30:31] offset:1024
	global_load_lds_dwordx4 v146, s[30:31] offset:2048
	global_load_lds_dwordx4 v147, s[30:31] offset:3072
	s_waitcnt lgkmcnt(10)
	v_mfma_f32_32x32x16_bf16 v[34:49], v[208:211], v[216:219], v[34:49]
	s_waitcnt lgkmcnt(9)
	v_mfma_f32_32x32x16_bf16 v[50:65], v[208:211], v[220:223], v[50:65]
	s_waitcnt lgkmcnt(8)
	v_mfma_f32_32x32x16_bf16 v[2:17], v[212:215], v[216:219], v[2:17]
	v_mfma_f32_32x32x16_bf16 v[18:33], v[212:215], v[220:223], v[18:33]
	s_waitcnt lgkmcnt(7)
	v_mfma_f32_32x32x16_bf16 v[74:89], v[208:211], v[224:227], v[74:89]
	s_waitcnt lgkmcnt(6)
	v_mfma_f32_32x32x16_bf16 v[90:105], v[208:211], v[228:231], v[90:105]
	v_mfma_f32_32x32x16_bf16 v[106:121], v[212:215], v[224:227], v[106:121]
	v_mfma_f32_32x32x16_bf16 v[122:137], v[212:215], v[228:231], v[122:137]
	s_waitcnt lgkmcnt(4)
	v_mfma_f32_32x32x16_bf16 v[34:49], v[232:235], v[240:243], v[34:49]
	s_waitcnt lgkmcnt(3)
	v_mfma_f32_32x32x16_bf16 v[50:65], v[232:235], v[244:247], v[50:65]
	s_waitcnt lgkmcnt(2)
	v_mfma_f32_32x32x16_bf16 v[2:17], v[236:239], v[240:243], v[2:17]
	v_mfma_f32_32x32x16_bf16 v[18:33], v[236:239], v[244:247], v[18:33]
	s_waitcnt lgkmcnt(1)
	v_mfma_f32_32x32x16_bf16 v[74:89], v[232:235], v[248:251], v[74:89]
	s_waitcnt lgkmcnt(0)
	v_mfma_f32_32x32x16_bf16 v[90:105], v[232:235], v[156:159], v[90:105]
	v_mfma_f32_32x32x16_bf16 v[106:121], v[236:239], v[248:251], v[106:121]
	v_mfma_f32_32x32x16_bf16 v[122:137], v[236:239], v[156:159], v[122:137]
	s_setprio 0
	s_waitcnt vmcnt(6)
	s_barrier
	s_setprio 1
	ds_read_b128 v[208:211], v138 offset:24576
	ds_read_b128 v[216:219], v140 offset:24576
	ds_read_b128 v[220:223], v140 offset:26624
	ds_read_b128 v[212:215], v138 offset:26624
	ds_read_b128 v[224:227], v140 offset:32768
	ds_read_b128 v[228:231], v140 offset:34816
	ds_read_b128 v[232:235], v139 offset:24576
	ds_read_b128 v[240:243], v141 offset:24576
	ds_read_b128 v[244:247], v141 offset:26624
	ds_read_b128 v[236:239], v139 offset:26624
	ds_read_b128 v[248:251], v141 offset:32768
	ds_read_b128 v[156:159], v141 offset:34816
	s_add_u32 m0, s42, 0x0
	s_add_u32 s28, s28, 0x40
	s_addc_u32 s29, s29, 0
	global_load_lds_dwordx4 v142, s[28:29]
	global_load_lds_dwordx4 v143, s[28:29] offset:1024
	s_add_u32 m0, s43, 0x0
	s_add_u32 s30, s30, 0x40000
	s_addc_u32 s31, s31, 0
	global_load_lds_dwordx4 v144, s[30:31]
	global_load_lds_dwordx4 v145, s[30:31] offset:1024
	global_load_lds_dwordx4 v146, s[30:31] offset:2048
	global_load_lds_dwordx4 v147, s[30:31] offset:3072
	s_waitcnt lgkmcnt(10)
	v_mfma_f32_32x32x16_bf16 v[34:49], v[208:211], v[216:219], v[34:49]
	s_waitcnt lgkmcnt(9)
	v_mfma_f32_32x32x16_bf16 v[50:65], v[208:211], v[220:223], v[50:65]
	s_waitcnt lgkmcnt(8)
	v_mfma_f32_32x32x16_bf16 v[2:17], v[212:215], v[216:219], v[2:17]
	v_mfma_f32_32x32x16_bf16 v[18:33], v[212:215], v[220:223], v[18:33]
	s_waitcnt lgkmcnt(7)
	v_mfma_f32_32x32x16_bf16 v[74:89], v[208:211], v[224:227], v[74:89]
	s_waitcnt lgkmcnt(6)
	v_mfma_f32_32x32x16_bf16 v[90:105], v[208:211], v[228:231], v[90:105]
	v_mfma_f32_32x32x16_bf16 v[106:121], v[212:215], v[224:227], v[106:121]
	v_mfma_f32_32x32x16_bf16 v[122:137], v[212:215], v[228:231], v[122:137]
	s_waitcnt lgkmcnt(4)
	v_mfma_f32_32x32x16_bf16 v[34:49], v[232:235], v[240:243], v[34:49]
	s_waitcnt lgkmcnt(3)
	v_mfma_f32_32x32x16_bf16 v[50:65], v[232:235], v[244:247], v[50:65]
	s_waitcnt lgkmcnt(2)
	v_mfma_f32_32x32x16_bf16 v[2:17], v[236:239], v[240:243], v[2:17]
	v_mfma_f32_32x32x16_bf16 v[18:33], v[236:239], v[244:247], v[18:33]
	s_waitcnt lgkmcnt(1)
	v_mfma_f32_32x32x16_bf16 v[74:89], v[232:235], v[248:251], v[74:89]
	s_waitcnt lgkmcnt(0)
	v_mfma_f32_32x32x16_bf16 v[90:105], v[232:235], v[156:159], v[90:105]
	v_mfma_f32_32x32x16_bf16 v[106:121], v[236:239], v[248:251], v[106:121]
	v_mfma_f32_32x32x16_bf16 v[122:137], v[236:239], v[156:159], v[122:137]
	s_setprio 0
	s_waitcnt vmcnt(6)
	s_barrier
; #define BLOAD(A_, B_, kt) do { _Pragma("unroll") for (int i = 0; i < 4; ++i) { \
;     A_[i] = *(const u32x4*)((const char*)Ap + (aoff + (unsigned)(32 * i * lda + (kt) * 64) * 2u)); B_[i] = *(const u32x4*)((const char*)Wt + (woff + (unsigned)(32 * i * K + (kt) * 64) * 2u)); } } while (0)
; #define BLOAD(A_, B_, kt) do { _Pragma("unroll") for (int i = 0; i < 4; ++i) { \
;     A_[i] = *(const u32x4*)((const char*)Ap + (aoff + (unsigned)(32 * i * lda + (kt) * 64) * 2u)); B_[i] = *(const u32x4*)((const char*)Wt + (woff + (unsigned)(32 * i * K + (kt) * 64) * 2u)); } } while (0)
; #define BSTORE(A_, B_, buf) do { _Pragma("unroll") for (int i = 0; i < 4; ++i) { \
;     *(u32x4*)&As[(buf) * GBUF + (srow + 32 * i) * LDT + sc8] = A_[i]; \
;     *(u32x4*)&Bs[(buf) * GBUF + (srow + 32 * i) * LDT + sc8] = B_[i]; } } while (0)
; template <int NK>
; DI void gemm_run(PF& pf, const u16* __restrict__ Ap, int lda, const u16* __restrict__ Wt, f32x16 (&acc)[2][2], char* smem) {
;     ...
; #pragma unroll
;   for (int kt = 0; kt < nk; kt += 2) {
;     BCOMP(0);
;     BSTORE(pf.a1, pf.b1, 1);
;     if (kt + 3 < nk) BLOAD(pf.a1, pf.b1, kt + 3);
;     __syncthreads();
;     BCOMP(1);
;     if (kt + 2 < nk) { BSTORE(pf.a0, pf.b0, 0); if (kt + 4 < nk) BLOAD(pf.a0, pf.b0, kt + 4); }
;     __syncthreads();
;   }
	s_setprio 1
	ds_read_b128 v[208:211], v138 offset:49152
	ds_read_b128 v[216:219], v140 offset:49152
	ds_read_b128 v[220:223], v140 offset:51200
	ds_read_b128 v[212:215], v138 offset:51200
	ds_read_b128 v[224:227], v140 offset:57344
	ds_read_b128 v[228:231], v140 offset:59392
	ds_read_b128 v[232:235], v139 offset:49152
	ds_read_b128 v[240:243], v141 offset:49152
	ds_read_b128 v[244:247], v141 offset:51200
	ds_read_b128 v[236:239], v139 offset:51200
	ds_read_b128 v[248:251], v141 offset:57344
	ds_read_b128 v[156:159], v141 offset:59392
	s_add_u32 m0, s42, 0x6000
	s_add_u32 s28, s28, 0x40
	s_addc_u32 s29, s29, 0
	global_load_lds_dwordx4 v142, s[28:29]
	global_load_lds_dwordx4 v143, s[28:29] offset:1024
	s_add_u32 m0, s43, 0x6000
	s_add_u32 s30, s30, 0x40000
	s_addc_u32 s31, s31, 0
	global_load_lds_dwordx4 v144, s[30:31]
	global_load_lds_dwordx4 v145, s[30:31] offset:1024
	global_load_lds_dwordx4 v146, s[30:31] offset:2048
	global_load_lds_dwordx4 v147, s[30:31] offset:3072
	s_waitcnt lgkmcnt(10)
	v_mfma_f32_32x32x16_bf16 v[34:49], v[208:211], v[216:219], v[34:49]
	s_waitcnt lgkmcnt(9)
	v_mfma_f32_32x32x16_bf16 v[50:65], v[208:211], v[220:223], v[50:65]
	s_waitcnt lgkmcnt(8)
	v_mfma_f32_32x32x16_bf16 v[2:17], v[212:215], v[216:219], v[2:17]
	v_mfma_f32_32x32x16_bf16 v[18:33], v[212:215], v[220:223], v[18:33]
	s_waitcnt lgkmcnt(7)
	v_mfma_f32_32x32x16_bf16 v[74:89], v[208:211], v[224:227], v[74:89]
	s_waitcnt lgkmcnt(6)
	v_mfma_f32_32x32x16_bf16 v[90:105], v[208:211], v[228:231], v[90:105]
	v_mfma_f32_32x32x16_bf16 v[106:121], v[212:215], v[224:227], v[106:121]
	v_mfma_f32_32x32x16_bf16 v[122:137], v[212:215], v[228:231], v[122:137]
	s_waitcnt lgkmcnt(4)
	v_mfma_f32_32x32x16_bf16 v[34:49], v[232:235], v[240:243], v[34:49]
	s_waitcnt lgkmcnt(3)
	v_mfma_f32_32x32x16_bf16 v[50:65], v[232:235], v[244:247], v[50:65]
	s_waitcnt lgkmcnt(2)
	v_mfma_f32_32x32x16_bf16 v[2:17], v[236:239], v[240:243], v[2:17]
	v_mfma_f32_32x32x16_bf16 v[18:33], v[236:239], v[244:247], v[18:33]
	s_waitcnt lgkmcnt(1)
	v_mfma_f32_32x32x16_bf16 v[74:89], v[232:235], v[248:251], v[74:89]
	s_waitcnt lgkmcnt(0)
	v_mfma_f32_32x32x16_bf16 v[90:105], v[232:235], v[156:159], v[90:105]
	v_mfma_f32_32x32x16_bf16 v[106:121], v[236:239], v[248:251], v[106:121]
	v_mfma_f32_32x32x16_bf16 v[122:137], v[236:239], v[156:159], v[122:137]
	s_setprio 0
	s_waitcnt vmcnt(6)
	s_barrier
	s_setprio 1
	ds_read_b128 v[208:211], v138 offset:0
	ds_read_b128 v[216:219], v140 offset:0
	ds_read_b128 v[220:223], v140 offset:2048
	ds_read_b128 v[212:215], v138 offset:2048
	ds_read_b128 v[224:227], v140 offset:8192
	ds_read_b128 v[228:231], v140 offset:10240
	ds_read_b128 v[232:235], v139 offset:0
	ds_read_b128 v[240:243], v141 offset:0
	ds_read_b128 v[244:247], v141 offset:2048
	ds_read_b128 v[236:239], v139 offset:2048
	ds_read_b128 v[248:251], v141 offset:8192
	ds_read_b128 v[156:159], v141 offset:10240
	s_add_u32 m0, s42, 0xc000
	s_add_u32 s28, s28, 0x40
	s_addc_u32 s29, s29, 0
	global_load_lds_dwordx4 v142, s[28:29]
	global_load_lds_dwordx4 v143, s[28:29] offset:1024
	s_add_u32 m0, s43, 0xc000
	s_add_u32 s30, s30, 0x40000
	s_addc_u32 s31, s31, 0
	global_load_lds_dwordx4 v144, s[30:31]
	global_load_lds_dwordx4 v145, s[30:31] offset:1024
	global_load_lds_dwordx4 v146, s[30:31] offset:2048
	global_load_lds_dwordx4 v147, s[30:31] offset:3072
	s_waitcnt lgkmcnt(10)
	v_mfma_f32_32x32x16_bf16 v[34:49], v[208:211], v[216:219], v[34:49]
	s_waitcnt lgkmcnt(9)
	v_mfma_f32_32x32x16_bf16 v[50:65], v[208:211], v[220:223], v[50:65]
	s_waitcnt lgkmcnt(8)
	v_mfma_f32_32x32x16_bf16 v[2:17], v[212:215], v[216:219], v[2:17]
	v_mfma_f32_32x32x16_bf16 v[18:33], v[212:215], v[220:223], v[18:33]
	s_waitcnt lgkmcnt(7)
	v_mfma_f32_32x32x16_bf16 v[74:89], v[208:211], v[224:227], v[74:89]
	s_waitcnt lgkmcnt(6)
	v_mfma_f32_32x32x16_bf16 v[90:105], v[208:211], v[228:231], v[90:105]
	v_mfma_f32_32x32x16_bf16 v[106:121], v[212:215], v[224:227], v[106:121]
	v_mfma_f32_32x32x16_bf16 v[122:137], v[212:215], v[228:231], v[122:137]
	s_waitcnt lgkmcnt(4)
	v_mfma_f32_32x32x16_bf16 v[34:49], v[232:235], v[240:243], v[34:49]
	s_waitcnt lgkmcnt(3)
	v_mfma_f32_32x32x16_bf16 v[50:65], v[232:235], v[244:247], v[50:65]
	s_waitcnt lgkmcnt(2)
	v_mfma_f32_32x32x16_bf16 v[2:17], v[236:239], v[240:243], v[2:17]
	v_mfma_f32_32x32x16_bf16 v[18:33], v[236:239], v[244:247], v[18:33]
	s_waitcnt lgkmcnt(1)
	v_mfma_f32_32x32x16_bf16 v[74:89], v[232:235], v[248:251], v[74:89]
	s_waitcnt lgkmcnt(0)
	v_mfma_f32_32x32x16_bf16 v[90:105], v[232:235], v[156:159], v[90:105]
	v_mfma_f32_32x32x16_bf16 v[106:121], v[236:239], v[248:251], v[106:121]
	v_mfma_f32_32x32x16_bf16 v[122:137], v[236:239], v[156:159], v[122:137]
	s_setprio 0
	s_waitcnt vmcnt(6)
	s_barrier
; #define BLOAD(A_, B_, kt) do { _Pragma("unroll") for (int i = 0; i < 4; ++i) { \
;     A_[i] = *(const u32x4*)((const char*)Ap + (aoff + (unsigned)(32 * i * lda + (kt) * 64) * 2u)); B_[i] = *(const u32x4*)((const char*)Wt + (woff + (unsigned)(32 * i * K + (kt) * 64) * 2u)); } } while (0)
; #define BLOAD(A_, B_, kt) do { _Pragma("unroll") for (int i = 0; i < 4; ++i) { \
;     A_[i] = *(const u32x4*)((const char*)Ap + (aoff + (unsigned)(32 * i * lda + (kt) * 64) * 2u)); B_[i] = *(const u32x4*)((const char*)Wt + (woff + (unsigned)(32 * i * K + (kt) * 64) * 2u)); } } while (0)
; #define BSTORE(A_, B_, buf) do { _Pragma("unroll") for (int i = 0; i < 4; ++i) { \
;     *(u32x4*)&As[(buf) * GBUF + (srow + 32 * i) * LDT + sc8] = A_[i]; \
;     *(u32x4*)&Bs[(buf) * GBUF + (srow + 32 * i) * LDT + sc8] = B_[i]; } } while (0)
; template <int NK>
; DI void gemm_run(PF& pf, const u16* __restrict__ Ap, int lda, const u16* __restrict__ Wt, f32x16 (&acc)[2][2], char* smem) {
;     ...
; #pragma unroll
;   for (int kt = 0; kt < nk; kt += 2) {
;     BCOMP(0);
;     BSTORE(pf.a1, pf.b1, 1);
;     if (kt + 3 < nk) BLOAD(pf.a1, pf.b1, kt + 3);
;     __syncthreads();
;     BCOMP(1);
;     if (kt + 2 < nk) { BSTORE(pf.a0, pf.b0, 0); if (kt + 4 < nk) BLOAD(pf.a0, pf.b0, kt + 4); }
;     __syncthreads();
;   }
	s_setprio 1
	ds_read_b128 v[208:211], v138 offset:24576
	ds_read_b128 v[216:219], v140 offset:24576
	ds_read_b128 v[220:223], v140 offset:26624
	ds_read_b128 v[212:215], v138 offset:26624
	ds_read_b128 v[224:227], v140 offset:32768
	ds_read_b128 v[228:231], v140 offset:34816
	ds_read_b128 v[232:235], v139 offset:24576
	ds_read_b128 v[240:243], v141 offset:24576
	ds_read_b128 v[244:247], v141 offset:26624
	ds_read_b128 v[236:239], v139 offset:26624
	ds_read_b128 v[248:251], v141 offset:32768
	ds_read_b128 v[156:159], v141 offset:34816
	s_add_u32 m0, s42, 0x0
	s_add_u32 s28, s28, 0x40
	s_addc_u32 s29, s29, 0
	global_load_lds_dwordx4 v142, s[28:29]
	global_load_lds_dwordx4 v143, s[28:29] offset:1024
	s_add_u32 m0, s43, 0x0
	s_add_u32 s30, s30, 0x40000
	s_addc_u32 s31, s31, 0
	global_load_lds_dwordx4 v144, s[30:31]
	global_load_lds_dwordx4 v145, s[30:31] offset:1024
	global_load_lds_dwordx4 v146, s[30:31] offset:2048
	global_load_lds_dwordx4 v147, s[30:31] offset:3072
	s_waitcnt lgkmcnt(10)
	v_mfma_f32_32x32x16_bf16 v[34:49], v[208:211], v[216:219], v[34:49]
	s_waitcnt lgkmcnt(9)
	v_mfma_f32_32x32x16_bf16 v[50:65], v[208:211], v[220:223], v[50:65]
	s_waitcnt lgkmcnt(8)
	v_mfma_f32_32x32x16_bf16 v[2:17], v[212:215], v[216:219], v[2:17]
	v_mfma_f32_32x32x16_bf16 v[18:33], v[212:215], v[220:223], v[18:33]
	s_waitcnt lgkmcnt(7)
	v_mfma_f32_32x32x16_bf16 v[74:89], v[208:211], v[224:227], v[74:89]
	s_waitcnt lgkmcnt(6)
	v_mfma_f32_32x32x16_bf16 v[90:105], v[208:211], v[228:231], v[90:105]
	v_mfma_f32_32x32x16_bf16 v[106:121], v[212:215], v[224:227], v[106:121]
	v_mfma_f32_32x32x16_bf16 v[122:137], v[212:215], v[228:231], v[122:137]
	s_waitcnt lgkmcnt(4)
	v_mfma_f32_32x32x16_bf16 v[34:49], v[232:235], v[240:243], v[34:49]
	s_waitcnt lgkmcnt(3)
	v_mfma_f32_32x32x16_bf16 v[50:65], v[232:235], v[244:247], v[50:65]
	s_waitcnt lgkmcnt(2)
	v_mfma_f32_32x32x16_bf16 v[2:17], v[236:239], v[240:243], v[2:17]
	v_mfma_f32_32x32x16_bf16 v[18:33], v[236:239], v[244:247], v[18:33]
	s_waitcnt lgkmcnt(1)
	v_mfma_f32_32x32x16_bf16 v[74:89], v[232:235], v[248:251], v[74:89]
	s_waitcnt lgkmcnt(0)
	v_mfma_f32_32x32x16_bf16 v[90:105], v[232:235], v[156:159], v[90:105]
	v_mfma_f32_32x32x16_bf16 v[106:121], v[236:239], v[248:251], v[106:121]
	v_mfma_f32_32x32x16_bf16 v[122:137], v[236:239], v[156:159], v[122:137]
	s_setprio 0
	s_waitcnt vmcnt(6)
	s_barrier
	s_setprio 1
	ds_read_b128 v[208:211], v138 offset:49152
	ds_read_b128 v[216:219], v140 offset:49152
	ds_read_b128 v[220:223], v140 offset:51200
	ds_read_b128 v[212:215], v138 offset:51200
	ds_read_b128 v[224:227], v140 offset:57344
	ds_read_b128 v[228:231], v140 offset:59392
	ds_read_b128 v[232:235], v139 offset:49152
	ds_read_b128 v[240:243], v141 offset:49152
	ds_read_b128 v[244:247], v141 offset:51200
	ds_read_b128 v[236:239], v139 offset:51200
	ds_read_b128 v[248:251], v141 offset:57344
	ds_read_b128 v[156:159], v141 offset:59392
	s_add_u32 m0, s42, 0x6000
	s_add_u32 s28, s28, 0x40
	s_addc_u32 s29, s29, 0
	global_load_lds_dwordx4 v142, s[28:29]
	global_load_lds_dwordx4 v143, s[28:29] offset:1024
	s_add_u32 m0, s43, 0x6000
	s_add_u32 s30, s30, 0x40000
	s_addc_u32 s31, s31, 0
	global_load_lds_dwordx4 v144, s[30:31]
	global_load_lds_dwordx4 v145, s[30:31] offset:1024
	global_load_lds_dwordx4 v146, s[30:31] offset:2048
	global_load_lds_dwordx4 v147, s[30:31] offset:3072
	s_waitcnt lgkmcnt(10)
	v_mfma_f32_32x32x16_bf16 v[34:49], v[208:211], v[216:219], v[34:49]
	s_waitcnt lgkmcnt(9)
	v_mfma_f32_32x32x16_bf16 v[50:65], v[208:211], v[220:223], v[50:65]
	s_waitcnt lgkmcnt(8)
	v_mfma_f32_32x32x16_bf16 v[2:17], v[212:215], v[216:219], v[2:17]
	v_mfma_f32_32x32x16_bf16 v[18:33], v[212:215], v[220:223], v[18:33]
	s_waitcnt lgkmcnt(7)
	v_mfma_f32_32x32x16_bf16 v[74:89], v[208:211], v[224:227], v[74:89]
	s_waitcnt lgkmcnt(6)
	v_mfma_f32_32x32x16_bf16 v[90:105], v[208:211], v[228:231], v[90:105]
	v_mfma_f32_32x32x16_bf16 v[106:121], v[212:215], v[224:227], v[106:121]
	v_mfma_f32_32x32x16_bf16 v[122:137], v[212:215], v[228:231], v[122:137]
	s_waitcnt lgkmcnt(4)
	v_mfma_f32_32x32x16_bf16 v[34:49], v[232:235], v[240:243], v[34:49]
	s_waitcnt lgkmcnt(3)
	v_mfma_f32_32x32x16_bf16 v[50:65], v[232:235], v[244:247], v[50:65]
	s_waitcnt lgkmcnt(2)
	v_mfma_f32_32x32x16_bf16 v[2:17], v[236:239], v[240:243], v[2:17]
	v_mfma_f32_32x32x16_bf16 v[18:33], v[236:239], v[244:247], v[18:33]
	s_waitcnt lgkmcnt(1)
	v_mfma_f32_32x32x16_bf16 v[74:89], v[232:235], v[248:251], v[74:89]
	s_waitcnt lgkmcnt(0)
	v_mfma_f32_32x32x16_bf16 v[90:105], v[232:235], v[156:159], v[90:105]
	v_mfma_f32_32x32x16_bf16 v[106:121], v[236:239], v[248:251], v[106:121]
	v_mfma_f32_32x32x16_bf16 v[122:137], v[236:239], v[156:159], v[122:137]
	s_setprio 0
	s_waitcnt vmcnt(6)
	s_barrier
; #define BLOAD(A_, B_, kt) do { _Pragma("unroll") for (int i = 0; i < 4; ++i) { \
;     A_[i] = *(const u32x4*)((const char*)Ap + (aoff + (unsigned)(32 * i * lda + (kt) * 64) * 2u)); B_[i] = *(const u32x4*)((const char*)Wt + (woff + (unsigned)(32 * i * K + (kt) * 64) * 2u)); } } while (0)
; #define BLOAD(A_, B_, kt) do { _Pragma("unroll") for (int i = 0; i < 4; ++i) { \
;     A_[i] = *(const u32x4*)((const char*)Ap + (aoff + (unsigned)(32 * i * lda + (kt) * 64) * 2u)); B_[i] = *(const u32x4*)((const char*)Wt + (woff + (unsigned)(32 * i * K + (kt) * 64) * 2u)); } } while (0)
; #define BSTORE(A_, B_, buf) do { _Pragma("unroll") for (int i = 0; i < 4; ++i) { \
;     *(u32x4*)&As[(buf) * GBUF + (srow + 32 * i) * LDT + sc8] = A_[i]; \
;     *(u32x4*)&Bs[(buf) * GBUF + (srow + 32 * i) * LDT + sc8] = B_[i]; } } while (0)
; template <int NK>
; DI void gemm_run(PF& pf, const u16* __restrict__ Ap, int lda, const u16* __restrict__ Wt, f32x16 (&acc)[2][2], char* smem) {
;     ...
; #pragma unroll
;   for (int kt = 0; kt < nk; kt += 2) {
;     BCOMP(0);
;     BSTORE(pf.a1, pf.b1, 1);
;     if (kt + 3 < nk) BLOAD(pf.a1, pf.b1, kt + 3);
;     __syncthreads();
;     BCOMP(1);
;     if (kt + 2 < nk) { BSTORE(pf.a0, pf.b0, 0); if (kt + 4 < nk) BLOAD(pf.a0, pf.b0, kt + 4); }
;     __syncthreads();
;   }
	s_setprio 1
	ds_read_b128 v[208:211], v138 offset:0
	ds_read_b128 v[216:219], v140 offset:0
	ds_read_b128 v[220:223], v140 offset:2048
	ds_read_b128 v[212:215], v138 offset:2048
	ds_read_b128 v[224:227], v140 offset:8192
	ds_read_b128 v[228:231], v140 offset:10240
	ds_read_b128 v[232:235], v139 offset:0
	ds_read_b128 v[240:243], v141 offset:0
	ds_read_b128 v[244:247], v141 offset:2048
	ds_read_b128 v[236:239], v139 offset:2048
	ds_read_b128 v[248:251], v141 offset:8192
	ds_read_b128 v[156:159], v141 offset:10240
	s_add_u32 m0, s42, 0xc000
	s_add_u32 s28, s28, 0x40
	s_addc_u32 s29, s29, 0
	global_load_lds_dwordx4 v142, s[28:29]
	global_load_lds_dwordx4 v143, s[28:29] offset:1024
	s_add_u32 m0, s43, 0xc000
	s_add_u32 s30, s30, 0x40000
	s_addc_u32 s31, s31, 0
	global_load_lds_dwordx4 v144, s[30:31]
	global_load_lds_dwordx4 v145, s[30:31] offset:1024
	global_load_lds_dwordx4 v146, s[30:31] offset:2048
	global_load_lds_dwordx4 v147, s[30:31] offset:3072
	s_waitcnt lgkmcnt(10)
	v_mfma_f32_32x32x16_bf16 v[34:49], v[208:211], v[216:219], v[34:49]
	s_waitcnt lgkmcnt(9)
	v_mfma_f32_32x32x16_bf16 v[50:65], v[208:211], v[220:223], v[50:65]
	s_waitcnt lgkmcnt(8)
	v_mfma_f32_32x32x16_bf16 v[2:17], v[212:215], v[216:219], v[2:17]
	v_mfma_f32_32x32x16_bf16 v[18:33], v[212:215], v[220:223], v[18:33]
	s_waitcnt lgkmcnt(7)
	v_mfma_f32_32x32x16_bf16 v[74:89], v[208:211], v[224:227], v[74:89]
	s_waitcnt lgkmcnt(6)
	v_mfma_f32_32x32x16_bf16 v[90:105], v[208:211], v[228:231], v[90:105]
	v_mfma_f32_32x32x16_bf16 v[106:121], v[212:215], v[224:227], v[106:121]
	v_mfma_f32_32x32x16_bf16 v[122:137], v[212:215], v[228:231], v[122:137]
	s_waitcnt lgkmcnt(4)
	v_mfma_f32_32x32x16_bf16 v[34:49], v[232:235], v[240:243], v[34:49]
	s_waitcnt lgkmcnt(3)
	v_mfma_f32_32x32x16_bf16 v[50:65], v[232:235], v[244:247], v[50:65]
	s_waitcnt lgkmcnt(2)
	v_mfma_f32_32x32x16_bf16 v[2:17], v[236:239], v[240:243], v[2:17]
	v_mfma_f32_32x32x16_bf16 v[18:33], v[236:239], v[244:247], v[18:33]
	s_waitcnt lgkmcnt(1)
	v_mfma_f32_32x32x16_bf16 v[74:89], v[232:235], v[248:251], v[74:89]
	s_waitcnt lgkmcnt(0)
	v_mfma_f32_32x32x16_bf16 v[90:105], v[232:235], v[156:159], v[90:105]
	v_mfma_f32_32x32x16_bf16 v[106:121], v[236:239], v[248:251], v[106:121]
	v_mfma_f32_32x32x16_bf16 v[122:137], v[236:239], v[156:159], v[122:137]
	s_setprio 0
	s_waitcnt vmcnt(6)
	s_barrier
	s_setprio 1
	ds_read_b128 v[208:211], v138 offset:24576
	ds_read_b128 v[216:219], v140 offset:24576
	ds_read_b128 v[220:223], v140 offset:26624
	ds_read_b128 v[212:215], v138 offset:26624
	ds_read_b128 v[224:227], v140 offset:32768
	ds_read_b128 v[228:231], v140 offset:34816
	ds_read_b128 v[232:235], v139 offset:24576
	ds_read_b128 v[240:243], v141 offset:24576
	ds_read_b128 v[244:247], v141 offset:26624
	ds_read_b128 v[236:239], v139 offset:26624
	ds_read_b128 v[248:251], v141 offset:32768
	ds_read_b128 v[156:159], v141 offset:34816
	s_add_u32 m0, s42, 0x0
	s_add_u32 s28, s28, 0x40
	s_addc_u32 s29, s29, 0
	global_load_lds_dwordx4 v142, s[28:29]
	global_load_lds_dwordx4 v143, s[28:29] offset:1024
	s_add_u32 m0, s43, 0x0
	s_add_u32 s30, s30, 0x40000
	s_addc_u32 s31, s31, 0
	global_load_lds_dwordx4 v144, s[30:31]
	global_load_lds_dwordx4 v145, s[30:31] offset:1024
	global_load_lds_dwordx4 v146, s[30:31] offset:2048
	global_load_lds_dwordx4 v147, s[30:31] offset:3072
	s_waitcnt lgkmcnt(10)
	v_mfma_f32_32x32x16_bf16 v[34:49], v[208:211], v[216:219], v[34:49]
	s_waitcnt lgkmcnt(9)
	v_mfma_f32_32x32x16_bf16 v[50:65], v[208:211], v[220:223], v[50:65]
	s_waitcnt lgkmcnt(8)
	v_mfma_f32_32x32x16_bf16 v[2:17], v[212:215], v[216:219], v[2:17]
	v_mfma_f32_32x32x16_bf16 v[18:33], v[212:215], v[220:223], v[18:33]
	s_waitcnt lgkmcnt(7)
	v_mfma_f32_32x32x16_bf16 v[74:89], v[208:211], v[224:227], v[74:89]
	s_waitcnt lgkmcnt(6)
	v_mfma_f32_32x32x16_bf16 v[90:105], v[208:211], v[228:231], v[90:105]
	v_mfma_f32_32x32x16_bf16 v[106:121], v[212:215], v[224:227], v[106:121]
	v_mfma_f32_32x32x16_bf16 v[122:137], v[212:215], v[228:231], v[122:137]
	s_waitcnt lgkmcnt(4)
	v_mfma_f32_32x32x16_bf16 v[34:49], v[232:235], v[240:243], v[34:49]
	s_waitcnt lgkmcnt(3)
	v_mfma_f32_32x32x16_bf16 v[50:65], v[232:235], v[244:247], v[50:65]
	s_waitcnt lgkmcnt(2)
	v_mfma_f32_32x32x16_bf16 v[2:17], v[236:239], v[240:243], v[2:17]
	v_mfma_f32_32x32x16_bf16 v[18:33], v[236:239], v[244:247], v[18:33]
	s_waitcnt lgkmcnt(1)
	v_mfma_f32_32x32x16_bf16 v[74:89], v[232:235], v[248:251], v[74:89]
	s_waitcnt lgkmcnt(0)
	v_mfma_f32_32x32x16_bf16 v[90:105], v[232:235], v[156:159], v[90:105]
	v_mfma_f32_32x32x16_bf16 v[106:121], v[236:239], v[248:251], v[106:121]
	v_mfma_f32_32x32x16_bf16 v[122:137], v[236:239], v[156:159], v[122:137]
	s_setprio 0
	s_waitcnt vmcnt(6)
	s_barrier
; #define BLOAD(A_, B_, kt) do { _Pragma("unroll") for (int i = 0; i < 4; ++i) { \
;     A_[i] = *(const u32x4*)((const char*)Ap + (aoff + (unsigned)(32 * i * lda + (kt) * 64) * 2u)); B_[i] = *(const u32x4*)((const char*)Wt + (woff + (unsigned)(32 * i * K + (kt) * 64) * 2u)); } } while (0)
; #define BLOAD(A_, B_, kt) do { _Pragma("unroll") for (int i = 0; i < 4; ++i) { \
;     A_[i] = *(const u32x4*)((const char*)Ap + (aoff + (unsigned)(32 * i * lda + (kt) * 64) * 2u)); B_[i] = *(const u32x4*)((const char*)Wt + (woff + (unsigned)(32 * i * K + (kt) * 64) * 2u)); } } while (0)
; #define BSTORE(A_, B_, buf) do { _Pragma("unroll") for (int i = 0; i < 4; ++i) { \
;     *(u32x4*)&As[(buf) * GBUF + (srow + 32 * i) * LDT + sc8] = A_[i]; \
;     *(u32x4*)&Bs[(buf) * GBUF + (srow + 32 * i) * LDT + sc8] = B_[i]; } } while (0)
; template <int NK>
; DI void gemm_run(PF& pf, const u16* __restrict__ Ap, int lda, const u16* __restrict__ Wt, f32x16 (&acc)[2][2], char* smem) {
;     ...
; #pragma unroll
;   for (int kt = 0; kt < nk; kt += 2) {
;     BCOMP(0);
;     BSTORE(pf.a1, pf.b1, 1);
;     if (kt + 3 < nk) BLOAD(pf.a1, pf.b1, kt + 3);
;     __syncthreads();
;     BCOMP(1);
;     if (kt + 2 < nk) { BSTORE(pf.a0, pf.b0, 0); if (kt + 4 < nk) BLOAD(pf.a0, pf.b0, kt + 4); }
;     __syncthreads();
;   }
	s_setprio 1
	ds_read_b128 v[208:211], v138 offset:49152
	ds_read_b128 v[216:219], v140 offset:49152
	ds_read_b128 v[220:223], v140 offset:51200
	ds_read_b128 v[212:215], v138 offset:51200
	ds_read_b128 v[224:227], v140 offset:57344
	ds_read_b128 v[228:231], v140 offset:59392
	ds_read_b128 v[232:235], v139 offset:49152
	ds_read_b128 v[240:243], v141 offset:49152
	ds_read_b128 v[244:247], v141 offset:51200
	ds_read_b128 v[236:239], v139 offset:51200
	ds_read_b128 v[248:251], v141 offset:57344
	ds_read_b128 v[156:159], v141 offset:59392
	s_add_u32 m0, s42, 0x6000
	s_add_u32 s28, s28, 0x40
	s_addc_u32 s29, s29, 0
	global_load_lds_dwordx4 v142, s[28:29]
	global_load_lds_dwordx4 v143, s[28:29] offset:1024
	s_add_u32 m0, s43, 0x6000
	s_add_u32 s30, s30, 0x40000
	s_addc_u32 s31, s31, 0
	global_load_lds_dwordx4 v144, s[30:31]
	global_load_lds_dwordx4 v145, s[30:31] offset:1024
	global_load_lds_dwordx4 v146, s[30:31] offset:2048
	global_load_lds_dwordx4 v147, s[30:31] offset:3072
	s_waitcnt lgkmcnt(10)
	v_mfma_f32_32x32x16_bf16 v[34:49], v[208:211], v[216:219], v[34:49]
	s_waitcnt lgkmcnt(9)
	v_mfma_f32_32x32x16_bf16 v[50:65], v[208:211], v[220:223], v[50:65]
	s_waitcnt lgkmcnt(8)
	v_mfma_f32_32x32x16_bf16 v[2:17], v[212:215], v[216:219], v[2:17]
	v_mfma_f32_32x32x16_bf16 v[18:33], v[212:215], v[220:223], v[18:33]
	s_waitcnt lgkmcnt(7)
	v_mfma_f32_32x32x16_bf16 v[74:89], v[208:211], v[224:227], v[74:89]
	s_waitcnt lgkmcnt(6)
	v_mfma_f32_32x32x16_bf16 v[90:105], v[208:211], v[228:231], v[90:105]
	v_mfma_f32_32x32x16_bf16 v[106:121], v[212:215], v[224:227], v[106:121]
	v_mfma_f32_32x32x16_bf16 v[122:137], v[212:215], v[228:231], v[122:137]
	s_waitcnt lgkmcnt(4)
	v_mfma_f32_32x32x16_bf16 v[34:49], v[232:235], v[240:243], v[34:49]
	s_waitcnt lgkmcnt(3)
	v_mfma_f32_32x32x16_bf16 v[50:65], v[232:235], v[244:247], v[50:65]
	s_waitcnt lgkmcnt(2)
	v_mfma_f32_32x32x16_bf16 v[2:17], v[236:239], v[240:243], v[2:17]
	v_mfma_f32_32x32x16_bf16 v[18:33], v[236:239], v[244:247], v[18:33]
	s_waitcnt lgkmcnt(1)
	v_mfma_f32_32x32x16_bf16 v[74:89], v[232:235], v[248:251], v[74:89]
	s_waitcnt lgkmcnt(0)
	v_mfma_f32_32x32x16_bf16 v[90:105], v[232:235], v[156:159], v[90:105]
	v_mfma_f32_32x32x16_bf16 v[106:121], v[236:239], v[248:251], v[106:121]
	v_mfma_f32_32x32x16_bf16 v[122:137], v[236:239], v[156:159], v[122:137]
	s_setprio 0
	s_waitcnt vmcnt(6)
	s_barrier
	s_setprio 1
	ds_read_b128 v[208:211], v138 offset:0
	ds_read_b128 v[216:219], v140 offset:0
	ds_read_b128 v[220:223], v140 offset:2048
	ds_read_b128 v[212:215], v138 offset:2048
	ds_read_b128 v[224:227], v140 offset:8192
	ds_read_b128 v[228:231], v140 offset:10240
	ds_read_b128 v[232:235], v139 offset:0
	ds_read_b128 v[240:243], v141 offset:0
	ds_read_b128 v[244:247], v141 offset:2048
	ds_read_b128 v[236:239], v139 offset:2048
	ds_read_b128 v[248:251], v141 offset:8192
	ds_read_b128 v[156:159], v141 offset:10240
	s_add_u32 m0, s42, 0xc000
	s_add_u32 s28, s28, 0x40
	s_addc_u32 s29, s29, 0
	global_load_lds_dwordx4 v142, s[28:29]
	global_load_lds_dwordx4 v143, s[28:29] offset:1024
	s_add_u32 m0, s43, 0xc000
	s_add_u32 s30, s30, 0x40000
	s_addc_u32 s31, s31, 0
	global_load_lds_dwordx4 v144, s[30:31]
	global_load_lds_dwordx4 v145, s[30:31] offset:1024
	global_load_lds_dwordx4 v146, s[30:31] offset:2048
	global_load_lds_dwordx4 v147, s[30:31] offset:3072
	s_waitcnt lgkmcnt(10)
	v_mfma_f32_32x32x16_bf16 v[34:49], v[208:211], v[216:219], v[34:49]
	s_waitcnt lgkmcnt(9)
	v_mfma_f32_32x32x16_bf16 v[50:65], v[208:211], v[220:223], v[50:65]
	s_waitcnt lgkmcnt(8)
	v_mfma_f32_32x32x16_bf16 v[2:17], v[212:215], v[216:219], v[2:17]
	v_mfma_f32_32x32x16_bf16 v[18:33], v[212:215], v[220:223], v[18:33]
	s_waitcnt lgkmcnt(7)
	v_mfma_f32_32x32x16_bf16 v[74:89], v[208:211], v[224:227], v[74:89]
	s_waitcnt lgkmcnt(6)
	v_mfma_f32_32x32x16_bf16 v[90:105], v[208:211], v[228:231], v[90:105]
	v_mfma_f32_32x32x16_bf16 v[106:121], v[212:215], v[224:227], v[106:121]
	v_mfma_f32_32x32x16_bf16 v[122:137], v[212:215], v[228:231], v[122:137]
	s_waitcnt lgkmcnt(4)
	v_mfma_f32_32x32x16_bf16 v[34:49], v[232:235], v[240:243], v[34:49]
	s_waitcnt lgkmcnt(3)
	v_mfma_f32_32x32x16_bf16 v[50:65], v[232:235], v[244:247], v[50:65]
	s_waitcnt lgkmcnt(2)
	v_mfma_f32_32x32x16_bf16 v[2:17], v[236:239], v[240:243], v[2:17]
	v_mfma_f32_32x32x16_bf16 v[18:33], v[236:239], v[244:247], v[18:33]
	s_waitcnt lgkmcnt(1)
	v_mfma_f32_32x32x16_bf16 v[74:89], v[232:235], v[248:251], v[74:89]
	s_waitcnt lgkmcnt(0)
	v_mfma_f32_32x32x16_bf16 v[90:105], v[232:235], v[156:159], v[90:105]
	v_mfma_f32_32x32x16_bf16 v[106:121], v[236:239], v[248:251], v[106:121]
	v_mfma_f32_32x32x16_bf16 v[122:137], v[236:239], v[156:159], v[122:137]
	s_setprio 0
	s_waitcnt vmcnt(6)
	s_barrier
; #define BLOAD(A_, B_, kt) do { _Pragma("unroll") for (int i = 0; i < 4; ++i) { \
;     A_[i] = *(const u32x4*)((const char*)Ap + (aoff + (unsigned)(32 * i * lda + (kt) * 64) * 2u)); B_[i] = *(const u32x4*)((const char*)Wt + (woff + (unsigned)(32 * i * K + (kt) * 64) * 2u)); } } while (0)
; #define BLOAD(A_, B_, kt) do { _Pragma("unroll") for (int i = 0; i < 4; ++i) { \
;     A_[i] = *(const u32x4*)((const char*)Ap + (aoff + (unsigned)(32 * i * lda + (kt) * 64) * 2u)); B_[i] = *(const u32x4*)((const char*)Wt + (woff + (unsigned)(32 * i * K + (kt) * 64) * 2u)); } } while (0)
; #define BSTORE(A_, B_, buf) do { _Pragma("unroll") for (int i = 0; i < 4; ++i) { \
;     *(u32x4*)&As[(buf) * GBUF + (srow + 32 * i) * LDT + sc8] = A_[i]; \
;     *(u32x4*)&Bs[(buf) * GBUF + (srow + 32 * i) * LDT + sc8] = B_[i]; } } while (0)
; template <int NK>
; DI void gemm_run(PF& pf, const u16* __restrict__ Ap, int lda, const u16* __restrict__ Wt, f32x16 (&acc)[2][2], char* smem) {
;     ...
; #pragma unroll
;   for (int kt = 0; kt < nk; kt += 2) {
;     BCOMP(0);
;     BSTORE(pf.a1, pf.b1, 1);
;     if (kt + 3 < nk) BLOAD(pf.a1, pf.b1, kt + 3);
;     __syncthreads();
;     BCOMP(1);
;     if (kt + 2 < nk) { BSTORE(pf.a0, pf.b0, 0); if (kt + 4 < nk) BLOAD(pf.a0, pf.b0, kt + 4); }
;     __syncthreads();
;   }
	s_setprio 1
	ds_read_b128 v[208:211], v138 offset:24576
	ds_read_b128 v[216:219], v140 offset:24576
	ds_read_b128 v[220:223], v140 offset:26624
	ds_read_b128 v[212:215], v138 offset:26624
	ds_read_b128 v[224:227], v140 offset:32768
	ds_read_b128 v[228:231], v140 offset:34816
	ds_read_b128 v[232:235], v139 offset:24576
	ds_read_b128 v[240:243], v141 offset:24576
	ds_read_b128 v[244:247], v141 offset:26624
	ds_read_b128 v[236:239], v139 offset:26624
	ds_read_b128 v[248:251], v141 offset:32768
	ds_read_b128 v[156:159], v141 offset:34816
	s_add_u32 m0, s42, 0x0
	s_add_u32 s28, s28, 0x40
	s_addc_u32 s29, s29, 0
	global_load_lds_dwordx4 v142, s[28:29]
	global_load_lds_dwordx4 v143, s[28:29] offset:1024
	s_add_u32 m0, s43, 0x0
	s_add_u32 s30, s30, 0x40000
	s_addc_u32 s31, s31, 0
	global_load_lds_dwordx4 v144, s[30:31]
	global_load_lds_dwordx4 v145, s[30:31] offset:1024
	global_load_lds_dwordx4 v146, s[30:31] offset:2048
	global_load_lds_dwordx4 v147, s[30:31] offset:3072
	s_waitcnt lgkmcnt(10)
	v_mfma_f32_32x32x16_bf16 v[34:49], v[208:211], v[216:219], v[34:49]
	s_waitcnt lgkmcnt(9)
	v_mfma_f32_32x32x16_bf16 v[50:65], v[208:211], v[220:223], v[50:65]
	s_waitcnt lgkmcnt(8)
	v_mfma_f32_32x32x16_bf16 v[2:17], v[212:215], v[216:219], v[2:17]
	v_mfma_f32_32x32x16_bf16 v[18:33], v[212:215], v[220:223], v[18:33]
	s_waitcnt lgkmcnt(7)
	v_mfma_f32_32x32x16_bf16 v[74:89], v[208:211], v[224:227], v[74:89]
	s_waitcnt lgkmcnt(6)
	v_mfma_f32_32x32x16_bf16 v[90:105], v[208:211], v[228:231], v[90:105]
	v_mfma_f32_32x32x16_bf16 v[106:121], v[212:215], v[224:227], v[106:121]
	v_mfma_f32_32x32x16_bf16 v[122:137], v[212:215], v[228:231], v[122:137]
	s_waitcnt lgkmcnt(4)
	v_mfma_f32_32x32x16_bf16 v[34:49], v[232:235], v[240:243], v[34:49]
	s_waitcnt lgkmcnt(3)
	v_mfma_f32_32x32x16_bf16 v[50:65], v[232:235], v[244:247], v[50:65]
	s_waitcnt lgkmcnt(2)
	v_mfma_f32_32x32x16_bf16 v[2:17], v[236:239], v[240:243], v[2:17]
	v_mfma_f32_32x32x16_bf16 v[18:33], v[236:239], v[244:247], v[18:33]
	s_waitcnt lgkmcnt(1)
	v_mfma_f32_32x32x16_bf16 v[74:89], v[232:235], v[248:251], v[74:89]
	s_waitcnt lgkmcnt(0)
	v_mfma_f32_32x32x16_bf16 v[90:105], v[232:235], v[156:159], v[90:105]
	v_mfma_f32_32x32x16_bf16 v[106:121], v[236:239], v[248:251], v[106:121]
	v_mfma_f32_32x32x16_bf16 v[122:137], v[236:239], v[156:159], v[122:137]
	s_setprio 0
	s_waitcnt vmcnt(6)
	s_barrier
	s_setprio 1
	ds_read_b128 v[208:211], v138 offset:49152
	ds_read_b128 v[216:219], v140 offset:49152
	ds_read_b128 v[220:223], v140 offset:51200
	ds_read_b128 v[212:215], v138 offset:51200
	ds_read_b128 v[224:227], v140 offset:57344
	ds_read_b128 v[228:231], v140 offset:59392
	ds_read_b128 v[232:235], v139 offset:49152
	ds_read_b128 v[240:243], v141 offset:49152
	ds_read_b128 v[244:247], v141 offset:51200
	ds_read_b128 v[236:239], v139 offset:51200
	ds_read_b128 v[248:251], v141 offset:57344
	ds_read_b128 v[156:159], v141 offset:59392
	s_add_u32 m0, s42, 0x6000
	s_add_u32 s28, s28, 0x40
	s_addc_u32 s29, s29, 0
	global_load_lds_dwordx4 v142, s[28:29]
	global_load_lds_dwordx4 v143, s[28:29] offset:1024
	s_add_u32 m0, s43, 0x6000
	s_add_u32 s30, s30, 0x40000
	s_addc_u32 s31, s31, 0
	global_load_lds_dwordx4 v144, s[30:31]
	global_load_lds_dwordx4 v145, s[30:31] offset:1024
	global_load_lds_dwordx4 v146, s[30:31] offset:2048
	global_load_lds_dwordx4 v147, s[30:31] offset:3072
	s_waitcnt lgkmcnt(10)
	v_mfma_f32_32x32x16_bf16 v[34:49], v[208:211], v[216:219], v[34:49]
	s_waitcnt lgkmcnt(9)
	v_mfma_f32_32x32x16_bf16 v[50:65], v[208:211], v[220:223], v[50:65]
	s_waitcnt lgkmcnt(8)
	v_mfma_f32_32x32x16_bf16 v[2:17], v[212:215], v[216:219], v[2:17]
	v_mfma_f32_32x32x16_bf16 v[18:33], v[212:215], v[220:223], v[18:33]
	s_waitcnt lgkmcnt(7)
	v_mfma_f32_32x32x16_bf16 v[74:89], v[208:211], v[224:227], v[74:89]
	s_waitcnt lgkmcnt(6)
	v_mfma_f32_32x32x16_bf16 v[90:105], v[208:211], v[228:231], v[90:105]
	v_mfma_f32_32x32x16_bf16 v[106:121], v[212:215], v[224:227], v[106:121]
	v_mfma_f32_32x32x16_bf16 v[122:137], v[212:215], v[228:231], v[122:137]
	s_waitcnt lgkmcnt(4)
	v_mfma_f32_32x32x16_bf16 v[34:49], v[232:235], v[240:243], v[34:49]
	s_waitcnt lgkmcnt(3)
	v_mfma_f32_32x32x16_bf16 v[50:65], v[232:235], v[244:247], v[50:65]
	s_waitcnt lgkmcnt(2)
	v_mfma_f32_32x32x16_bf16 v[2:17], v[236:239], v[240:243], v[2:17]
	v_mfma_f32_32x32x16_bf16 v[18:33], v[236:239], v[244:247], v[18:33]
	s_waitcnt lgkmcnt(1)
	v_mfma_f32_32x32x16_bf16 v[74:89], v[232:235], v[248:251], v[74:89]
	s_waitcnt lgkmcnt(0)
	v_mfma_f32_32x32x16_bf16 v[90:105], v[232:235], v[156:159], v[90:105]
	v_mfma_f32_32x32x16_bf16 v[106:121], v[236:239], v[248:251], v[106:121]
	v_mfma_f32_32x32x16_bf16 v[122:137], v[236:239], v[156:159], v[122:137]
	s_setprio 0
	s_waitcnt vmcnt(6)
	s_barrier
; #define BLOAD(A_, B_, kt) do { _Pragma("unroll") for (int i = 0; i < 4; ++i) { \
;     A_[i] = *(const u32x4*)((const char*)Ap + (aoff + (unsigned)(32 * i * lda + (kt) * 64) * 2u)); B_[i] = *(const u32x4*)((const char*)Wt + (woff + (unsigned)(32 * i * K + (kt) * 64) * 2u)); } } while (0)
; #define BLOAD(A_, B_, kt) do { _Pragma("unroll") for (int i = 0; i < 4; ++i) { \
;     A_[i] = *(const u32x4*)((const char*)Ap + (aoff + (unsigned)(32 * i * lda + (kt) * 64) * 2u)); B_[i] = *(const u32x4*)((const char*)Wt + (woff + (unsigned)(32 * i * K + (kt) * 64) * 2u)); } } while (0)
; #define BSTORE(A_, B_, buf) do { _Pragma("unroll") for (int i = 0; i < 4; ++i) { \
;     *(u32x4*)&As[(buf) * GBUF + (srow + 32 * i) * LDT + sc8] = A_[i]; \
;     *(u32x4*)&Bs[(buf) * GBUF + (srow + 32 * i) * LDT + sc8] = B_[i]; } } while (0)
; template <int NK>
; DI void gemm_run(PF& pf, const u16* __restrict__ Ap, int lda, const u16* __restrict__ Wt, f32x16 (&acc)[2][2], char* smem) {
;     ...
; #pragma unroll
;   for (int kt = 0; kt < nk; kt += 2) {
;     BCOMP(0);
;     BSTORE(pf.a1, pf.b1, 1);
;     if (kt + 3 < nk) BLOAD(pf.a1, pf.b1, kt + 3);
;     __syncthreads();
;     BCOMP(1);
;     if (kt + 2 < nk) { BSTORE(pf.a0, pf.b0, 0); if (kt + 4 < nk) BLOAD(pf.a0, pf.b0, kt + 4); }
;     __syncthreads();
;   }
	s_setprio 1
	ds_read_b128 v[208:211], v138 offset:0
	ds_read_b128 v[216:219], v140 offset:0
	ds_read_b128 v[220:223], v140 offset:2048
	ds_read_b128 v[212:215], v138 offset:2048
	ds_read_b128 v[224:227], v140 offset:8192
	ds_read_b128 v[228:231], v140 offset:10240
	ds_read_b128 v[232:235], v139 offset:0
	ds_read_b128 v[240:243], v141 offset:0
	ds_read_b128 v[244:247], v141 offset:2048
	ds_read_b128 v[236:239], v139 offset:2048
	ds_read_b128 v[248:251], v141 offset:8192
	ds_read_b128 v[156:159], v141 offset:10240
	s_add_u32 m0, s42, 0xc000
	s_add_u32 s28, s28, 0x40
	s_addc_u32 s29, s29, 0
	global_load_lds_dwordx4 v142, s[28:29]
	global_load_lds_dwordx4 v143, s[28:29] offset:1024
	s_add_u32 m0, s43, 0xc000
	s_add_u32 s30, s30, 0x40000
	s_addc_u32 s31, s31, 0
	global_load_lds_dwordx4 v144, s[30:31]
	global_load_lds_dwordx4 v145, s[30:31] offset:1024
	global_load_lds_dwordx4 v146, s[30:31] offset:2048
	global_load_lds_dwordx4 v147, s[30:31] offset:3072
	s_waitcnt lgkmcnt(10)
	v_mfma_f32_32x32x16_bf16 v[34:49], v[208:211], v[216:219], v[34:49]
	s_waitcnt lgkmcnt(9)
	v_mfma_f32_32x32x16_bf16 v[50:65], v[208:211], v[220:223], v[50:65]
	s_waitcnt lgkmcnt(8)
	v_mfma_f32_32x32x16_bf16 v[2:17], v[212:215], v[216:219], v[2:17]
	v_mfma_f32_32x32x16_bf16 v[18:33], v[212:215], v[220:223], v[18:33]
	s_waitcnt lgkmcnt(7)
	v_mfma_f32_32x32x16_bf16 v[74:89], v[208:211], v[224:227], v[74:89]
	s_waitcnt lgkmcnt(6)
	v_mfma_f32_32x32x16_bf16 v[90:105], v[208:211], v[228:231], v[90:105]
	v_mfma_f32_32x32x16_bf16 v[106:121], v[212:215], v[224:227], v[106:121]
	v_mfma_f32_32x32x16_bf16 v[122:137], v[212:215], v[228:231], v[122:137]
	s_waitcnt lgkmcnt(4)
	v_mfma_f32_32x32x16_bf16 v[34:49], v[232:235], v[240:243], v[34:49]
	s_waitcnt lgkmcnt(3)
	v_mfma_f32_32x32x16_bf16 v[50:65], v[232:235], v[244:247], v[50:65]
	s_waitcnt lgkmcnt(2)
	v_mfma_f32_32x32x16_bf16 v[2:17], v[236:239], v[240:243], v[2:17]
	v_mfma_f32_32x32x16_bf16 v[18:33], v[236:239], v[244:247], v[18:33]
	s_waitcnt lgkmcnt(1)
	v_mfma_f32_32x32x16_bf16 v[74:89], v[232:235], v[248:251], v[74:89]
	s_waitcnt lgkmcnt(0)
	v_mfma_f32_32x32x16_bf16 v[90:105], v[232:235], v[156:159], v[90:105]
	v_mfma_f32_32x32x16_bf16 v[106:121], v[236:239], v[248:251], v[106:121]
	v_mfma_f32_32x32x16_bf16 v[122:137], v[236:239], v[156:159], v[122:137]
	s_setprio 0
	s_waitcnt vmcnt(6)
	s_barrier
	s_setprio 1
	ds_read_b128 v[208:211], v138 offset:24576
	ds_read_b128 v[216:219], v140 offset:24576
	ds_read_b128 v[220:223], v140 offset:26624
	ds_read_b128 v[212:215], v138 offset:26624
	ds_read_b128 v[224:227], v140 offset:32768
	ds_read_b128 v[228:231], v140 offset:34816
	ds_read_b128 v[232:235], v139 offset:24576
	ds_read_b128 v[240:243], v141 offset:24576
	ds_read_b128 v[244:247], v141 offset:26624
	ds_read_b128 v[236:239], v139 offset:26624
	ds_read_b128 v[248:251], v141 offset:32768
	ds_read_b128 v[156:159], v141 offset:34816
	s_add_u32 m0, s42, 0x0
	s_add_u32 s28, s28, 0x40
	s_addc_u32 s29, s29, 0
	global_load_lds_dwordx4 v142, s[28:29]
	global_load_lds_dwordx4 v143, s[28:29] offset:1024
	s_add_u32 m0, s43, 0x0
	s_add_u32 s30, s30, 0x40000
	s_addc_u32 s31, s31, 0
	global_load_lds_dwordx4 v144, s[30:31]
	global_load_lds_dwordx4 v145, s[30:31] offset:1024
	global_load_lds_dwordx4 v146, s[30:31] offset:2048
	global_load_lds_dwordx4 v147, s[30:31] offset:3072
	s_waitcnt lgkmcnt(10)
	v_mfma_f32_32x32x16_bf16 v[34:49], v[208:211], v[216:219], v[34:49]
	s_waitcnt lgkmcnt(9)
	v_mfma_f32_32x32x16_bf16 v[50:65], v[208:211], v[220:223], v[50:65]
	s_waitcnt lgkmcnt(8)
	v_mfma_f32_32x32x16_bf16 v[2:17], v[212:215], v[216:219], v[2:17]
	v_mfma_f32_32x32x16_bf16 v[18:33], v[212:215], v[220:223], v[18:33]
	s_waitcnt lgkmcnt(7)
	v_mfma_f32_32x32x16_bf16 v[74:89], v[208:211], v[224:227], v[74:89]
	s_waitcnt lgkmcnt(6)
	v_mfma_f32_32x32x16_bf16 v[90:105], v[208:211], v[228:231], v[90:105]
	v_mfma_f32_32x32x16_bf16 v[106:121], v[212:215], v[224:227], v[106:121]
	v_mfma_f32_32x32x16_bf16 v[122:137], v[212:215], v[228:231], v[122:137]
	s_waitcnt lgkmcnt(4)
	v_mfma_f32_32x32x16_bf16 v[34:49], v[232:235], v[240:243], v[34:49]
	s_waitcnt lgkmcnt(3)
	v_mfma_f32_32x32x16_bf16 v[50:65], v[232:235], v[244:247], v[50:65]
	s_waitcnt lgkmcnt(2)
	v_mfma_f32_32x32x16_bf16 v[2:17], v[236:239], v[240:243], v[2:17]
	v_mfma_f32_32x32x16_bf16 v[18:33], v[236:239], v[244:247], v[18:33]
	s_waitcnt lgkmcnt(1)
	v_mfma_f32_32x32x16_bf16 v[74:89], v[232:235], v[248:251], v[74:89]
	s_waitcnt lgkmcnt(0)
	v_mfma_f32_32x32x16_bf16 v[90:105], v[232:235], v[156:159], v[90:105]
	v_mfma_f32_32x32x16_bf16 v[106:121], v[236:239], v[248:251], v[106:121]
	v_mfma_f32_32x32x16_bf16 v[122:137], v[236:239], v[156:159], v[122:137]
	s_setprio 0
	s_waitcnt vmcnt(6)
	s_barrier
; #define BLOAD(A_, B_, kt) do { _Pragma("unroll") for (int i = 0; i < 4; ++i) { \
;     A_[i] = *(const u32x4*)((const char*)Ap + (aoff + (unsigned)(32 * i * lda + (kt) * 64) * 2u)); B_[i] = *(const u32x4*)((const char*)Wt + (woff + (unsigned)(32 * i * K + (kt) * 64) * 2u)); } } while (0)
; #define BLOAD(A_, B_, kt) do { _Pragma("unroll") for (int i = 0; i < 4; ++i) { \
;     A_[i] = *(const u32x4*)((const char*)Ap + (aoff + (unsigned)(32 * i * lda + (kt) * 64) * 2u)); B_[i] = *(const u32x4*)((const char*)Wt + (woff + (unsigned)(32 * i * K + (kt) * 64) * 2u)); } } while (0)
; #define BSTORE(A_, B_, buf) do { _Pragma("unroll") for (int i = 0; i < 4; ++i) { \
;     *(u32x4*)&As[(buf) * GBUF + (srow + 32 * i) * LDT + sc8] = A_[i]; \
;     *(u32x4*)&Bs[(buf) * GBUF + (srow + 32 * i) * LDT + sc8] = B_[i]; } } while (0)
; template <int NK>
; DI void gemm_run(PF& pf, const u16* __restrict__ Ap, int lda, const u16* __restrict__ Wt, f32x16 (&acc)[2][2], char* smem) {
;     ...
; #pragma unroll
;   for (int kt = 0; kt < nk; kt += 2) {
;     BCOMP(0);
;     BSTORE(pf.a1, pf.b1, 1);
;     if (kt + 3 < nk) BLOAD(pf.a1, pf.b1, kt + 3);
;     __syncthreads();
;     BCOMP(1);
;     if (kt + 2 < nk) { BSTORE(pf.a0, pf.b0, 0); if (kt + 4 < nk) BLOAD(pf.a0, pf.b0, kt + 4); }
;     __syncthreads();
;   }
	s_setprio 1
	ds_read_b128 v[208:211], v138 offset:49152
	ds_read_b128 v[216:219], v140 offset:49152
	ds_read_b128 v[220:223], v140 offset:51200
	ds_read_b128 v[212:215], v138 offset:51200
	ds_read_b128 v[224:227], v140 offset:57344
	ds_read_b128 v[228:231], v140 offset:59392
	ds_read_b128 v[232:235], v139 offset:49152
	ds_read_b128 v[240:243], v141 offset:49152
	ds_read_b128 v[244:247], v141 offset:51200
	ds_read_b128 v[236:239], v139 offset:51200
	ds_read_b128 v[248:251], v141 offset:57344
	ds_read_b128 v[156:159], v141 offset:59392
	s_add_u32 m0, s42, 0x6000
	s_add_u32 s28, s28, 0x40
	s_addc_u32 s29, s29, 0
	global_load_lds_dwordx4 v142, s[28:29]
	global_load_lds_dwordx4 v143, s[28:29] offset:1024
	s_add_u32 m0, s43, 0x6000
	s_add_u32 s30, s30, 0x40000
	s_addc_u32 s31, s31, 0
	global_load_lds_dwordx4 v144, s[30:31]
	global_load_lds_dwordx4 v145, s[30:31] offset:1024
	global_load_lds_dwordx4 v146, s[30:31] offset:2048
	global_load_lds_dwordx4 v147, s[30:31] offset:3072
	s_waitcnt lgkmcnt(10)
	v_mfma_f32_32x32x16_bf16 v[34:49], v[208:211], v[216:219], v[34:49]
	s_waitcnt lgkmcnt(9)
	v_mfma_f32_32x32x16_bf16 v[50:65], v[208:211], v[220:223], v[50:65]
	s_waitcnt lgkmcnt(8)
	v_mfma_f32_32x32x16_bf16 v[2:17], v[212:215], v[216:219], v[2:17]
	v_mfma_f32_32x32x16_bf16 v[18:33], v[212:215], v[220:223], v[18:33]
	s_waitcnt lgkmcnt(7)
	v_mfma_f32_32x32x16_bf16 v[74:89], v[208:211], v[224:227], v[74:89]
	s_waitcnt lgkmcnt(6)
	v_mfma_f32_32x32x16_bf16 v[90:105], v[208:211], v[228:231], v[90:105]
	v_mfma_f32_32x32x16_bf16 v[106:121], v[212:215], v[224:227], v[106:121]
	v_mfma_f32_32x32x16_bf16 v[122:137], v[212:215], v[228:231], v[122:137]
	s_waitcnt lgkmcnt(4)
	v_mfma_f32_32x32x16_bf16 v[34:49], v[232:235], v[240:243], v[34:49]
	s_waitcnt lgkmcnt(3)
	v_mfma_f32_32x32x16_bf16 v[50:65], v[232:235], v[244:247], v[50:65]
	s_waitcnt lgkmcnt(2)
	v_mfma_f32_32x32x16_bf16 v[2:17], v[236:239], v[240:243], v[2:17]
	v_mfma_f32_32x32x16_bf16 v[18:33], v[236:239], v[244:247], v[18:33]
	s_waitcnt lgkmcnt(1)
	v_mfma_f32_32x32x16_bf16 v[74:89], v[232:235], v[248:251], v[74:89]
	s_waitcnt lgkmcnt(0)
	v_mfma_f32_32x32x16_bf16 v[90:105], v[232:235], v[156:159], v[90:105]
	v_mfma_f32_32x32x16_bf16 v[106:121], v[236:239], v[248:251], v[106:121]
	v_mfma_f32_32x32x16_bf16 v[122:137], v[236:239], v[156:159], v[122:137]
	s_setprio 0
	s_waitcnt vmcnt(6)
	s_barrier
	s_setprio 1
	ds_read_b128 v[208:211], v138 offset:0
	ds_read_b128 v[216:219], v140 offset:0
	ds_read_b128 v[220:223], v140 offset:2048
	ds_read_b128 v[212:215], v138 offset:2048
	ds_read_b128 v[224:227], v140 offset:8192
	ds_read_b128 v[228:231], v140 offset:10240
	ds_read_b128 v[232:235], v139 offset:0
	ds_read_b128 v[240:243], v141 offset:0
	ds_read_b128 v[244:247], v141 offset:2048
	ds_read_b128 v[236:239], v139 offset:2048
	ds_read_b128 v[248:251], v141 offset:8192
	ds_read_b128 v[156:159], v141 offset:10240
	s_add_u32 m0, s42, 0xc000
	s_add_u32 s28, s28, 0x40
	s_addc_u32 s29, s29, 0
	global_load_lds_dwordx4 v142, s[28:29]
	global_load_lds_dwordx4 v143, s[28:29] offset:1024
	s_add_u32 m0, s43, 0xc000
	s_add_u32 s30, s30, 0x40000
	s_addc_u32 s31, s31, 0
	global_load_lds_dwordx4 v144, s[30:31]
	global_load_lds_dwordx4 v145, s[30:31] offset:1024
	global_load_lds_dwordx4 v146, s[30:31] offset:2048
	global_load_lds_dwordx4 v147, s[30:31] offset:3072
	s_waitcnt lgkmcnt(10)
	v_mfma_f32_32x32x16_bf16 v[34:49], v[208:211], v[216:219], v[34:49]
	s_waitcnt lgkmcnt(9)
	v_mfma_f32_32x32x16_bf16 v[50:65], v[208:211], v[220:223], v[50:65]
	s_waitcnt lgkmcnt(8)
	v_mfma_f32_32x32x16_bf16 v[2:17], v[212:215], v[216:219], v[2:17]
	v_mfma_f32_32x32x16_bf16 v[18:33], v[212:215], v[220:223], v[18:33]
	s_waitcnt lgkmcnt(7)
	v_mfma_f32_32x32x16_bf16 v[74:89], v[208:211], v[224:227], v[74:89]
	s_waitcnt lgkmcnt(6)
	v_mfma_f32_32x32x16_bf16 v[90:105], v[208:211], v[228:231], v[90:105]
	v_mfma_f32_32x32x16_bf16 v[106:121], v[212:215], v[224:227], v[106:121]
	v_mfma_f32_32x32x16_bf16 v[122:137], v[212:215], v[228:231], v[122:137]
	s_waitcnt lgkmcnt(4)
	v_mfma_f32_32x32x16_bf16 v[34:49], v[232:235], v[240:243], v[34:49]
	s_waitcnt lgkmcnt(3)
	v_mfma_f32_32x32x16_bf16 v[50:65], v[232:235], v[244:247], v[50:65]
	s_waitcnt lgkmcnt(2)
	v_mfma_f32_32x32x16_bf16 v[2:17], v[236:239], v[240:243], v[2:17]
	v_mfma_f32_32x32x16_bf16 v[18:33], v[236:239], v[244:247], v[18:33]
	s_waitcnt lgkmcnt(1)
	v_mfma_f32_32x32x16_bf16 v[74:89], v[232:235], v[248:251], v[74:89]
	s_waitcnt lgkmcnt(0)
	v_mfma_f32_32x32x16_bf16 v[90:105], v[232:235], v[156:159], v[90:105]
	v_mfma_f32_32x32x16_bf16 v[106:121], v[236:239], v[248:251], v[106:121]
	v_mfma_f32_32x32x16_bf16 v[122:137], v[236:239], v[156:159], v[122:137]
	s_setprio 0
	s_waitcnt vmcnt(6)
	s_barrier
; #define BLOAD(A_, B_, kt) do { _Pragma("unroll") for (int i = 0; i < 4; ++i) { \
;     A_[i] = *(const u32x4*)((const char*)Ap + (aoff + (unsigned)(32 * i * lda + (kt) * 64) * 2u)); B_[i] = *(const u32x4*)((const char*)Wt + (woff + (unsigned)(32 * i * K + (kt) * 64) * 2u)); } } while (0)
; #define BLOAD(A_, B_, kt) do { _Pragma("unroll") for (int i = 0; i < 4; ++i) { \
;     A_[i] = *(const u32x4*)((const char*)Ap + (aoff + (unsigned)(32 * i * lda + (kt) * 64) * 2u)); B_[i] = *(const u32x4*)((const char*)Wt + (woff + (unsigned)(32 * i * K + (kt) * 64) * 2u)); } } while (0)
; #define BSTORE(A_, B_, buf) do { _Pragma("unroll") for (int i = 0; i < 4; ++i) { \
;     *(u32x4*)&As[(buf) * GBUF + (srow + 32 * i) * LDT + sc8] = A_[i]; \
;     *(u32x4*)&Bs[(buf) * GBUF + (srow + 32 * i) * LDT + sc8] = B_[i]; } } while (0)
; template <int NK>
; DI void gemm_run(PF& pf, const u16* __restrict__ Ap, int lda, const u16* __restrict__ Wt, f32x16 (&acc)[2][2], char* smem) {
;     ...
; #pragma unroll
;   for (int kt = 0; kt < nk; kt += 2) {
;     BCOMP(0);
;     BSTORE(pf.a1, pf.b1, 1);
;     if (kt + 3 < nk) BLOAD(pf.a1, pf.b1, kt + 3);
;     __syncthreads();
;     BCOMP(1);
;     if (kt + 2 < nk) { BSTORE(pf.a0, pf.b0, 0); if (kt + 4 < nk) BLOAD(pf.a0, pf.b0, kt + 4); }
;     __syncthreads();
;   }
	s_setprio 1
	ds_read_b128 v[208:211], v138 offset:24576
	ds_read_b128 v[216:219], v140 offset:24576
	ds_read_b128 v[220:223], v140 offset:26624
	ds_read_b128 v[212:215], v138 offset:26624
	ds_read_b128 v[224:227], v140 offset:32768
	ds_read_b128 v[228:231], v140 offset:34816
	ds_read_b128 v[232:235], v139 offset:24576
	ds_read_b128 v[240:243], v141 offset:24576
	ds_read_b128 v[244:247], v141 offset:26624
	ds_read_b128 v[236:239], v139 offset:26624
	ds_read_b128 v[248:251], v141 offset:32768
	ds_read_b128 v[156:159], v141 offset:34816
	s_add_u32 m0, s42, 0x0
	s_add_u32 s28, s28, 0x40
	s_addc_u32 s29, s29, 0
	global_load_lds_dwordx4 v142, s[28:29]
	global_load_lds_dwordx4 v143, s[28:29] offset:1024
	s_add_u32 m0, s43, 0x0
	s_add_u32 s30, s30, 0x40000
	s_addc_u32 s31, s31, 0
	global_load_lds_dwordx4 v144, s[30:31]
	global_load_lds_dwordx4 v145, s[30:31] offset:1024
	global_load_lds_dwordx4 v146, s[30:31] offset:2048
	global_load_lds_dwordx4 v147, s[30:31] offset:3072
	s_waitcnt lgkmcnt(10)
	v_mfma_f32_32x32x16_bf16 v[34:49], v[208:211], v[216:219], v[34:49]
	s_waitcnt lgkmcnt(9)
	v_mfma_f32_32x32x16_bf16 v[50:65], v[208:211], v[220:223], v[50:65]
	s_waitcnt lgkmcnt(8)
	v_mfma_f32_32x32x16_bf16 v[2:17], v[212:215], v[216:219], v[2:17]
	v_mfma_f32_32x32x16_bf16 v[18:33], v[212:215], v[220:223], v[18:33]
	s_waitcnt lgkmcnt(7)
	v_mfma_f32_32x32x16_bf16 v[74:89], v[208:211], v[224:227], v[74:89]
	s_waitcnt lgkmcnt(6)
	v_mfma_f32_32x32x16_bf16 v[90:105], v[208:211], v[228:231], v[90:105]
	v_mfma_f32_32x32x16_bf16 v[106:121], v[212:215], v[224:227], v[106:121]
	v_mfma_f32_32x32x16_bf16 v[122:137], v[212:215], v[228:231], v[122:137]
	s_waitcnt lgkmcnt(4)
	v_mfma_f32_32x32x16_bf16 v[34:49], v[232:235], v[240:243], v[34:49]
	s_waitcnt lgkmcnt(3)
	v_mfma_f32_32x32x16_bf16 v[50:65], v[232:235], v[244:247], v[50:65]
	s_waitcnt lgkmcnt(2)
	v_mfma_f32_32x32x16_bf16 v[2:17], v[236:239], v[240:243], v[2:17]
	v_mfma_f32_32x32x16_bf16 v[18:33], v[236:239], v[244:247], v[18:33]
	s_waitcnt lgkmcnt(1)
	v_mfma_f32_32x32x16_bf16 v[74:89], v[232:235], v[248:251], v[74:89]
	s_waitcnt lgkmcnt(0)
	v_mfma_f32_32x32x16_bf16 v[90:105], v[232:235], v[156:159], v[90:105]
	v_mfma_f32_32x32x16_bf16 v[106:121], v[236:239], v[248:251], v[106:121]
	v_mfma_f32_32x32x16_bf16 v[122:137], v[236:239], v[156:159], v[122:137]
	s_setprio 0
	s_waitcnt vmcnt(6)
	s_barrier
	s_setprio 1
	ds_read_b128 v[208:211], v138 offset:49152
	ds_read_b128 v[216:219], v140 offset:49152
	ds_read_b128 v[220:223], v140 offset:51200
	ds_read_b128 v[212:215], v138 offset:51200
	ds_read_b128 v[224:227], v140 offset:57344
	ds_read_b128 v[228:231], v140 offset:59392
	ds_read_b128 v[232:235], v139 offset:49152
	ds_read_b128 v[240:243], v141 offset:49152
	ds_read_b128 v[244:247], v141 offset:51200
	ds_read_b128 v[236:239], v139 offset:51200
	ds_read_b128 v[248:251], v141 offset:57344
	ds_read_b128 v[156:159], v141 offset:59392
	s_add_u32 m0, s42, 0x6000
	s_add_u32 s28, s28, 0x40
	s_addc_u32 s29, s29, 0
	global_load_lds_dwordx4 v142, s[28:29]
	global_load_lds_dwordx4 v143, s[28:29] offset:1024
	s_add_u32 m0, s43, 0x6000
	s_add_u32 s30, s30, 0x40000
	s_addc_u32 s31, s31, 0
	global_load_lds_dwordx4 v144, s[30:31]
	global_load_lds_dwordx4 v145, s[30:31] offset:1024
	global_load_lds_dwordx4 v146, s[30:31] offset:2048
	global_load_lds_dwordx4 v147, s[30:31] offset:3072
	s_waitcnt lgkmcnt(10)
	v_mfma_f32_32x32x16_bf16 v[34:49], v[208:211], v[216:219], v[34:49]
	s_waitcnt lgkmcnt(9)
	v_mfma_f32_32x32x16_bf16 v[50:65], v[208:211], v[220:223], v[50:65]
	s_waitcnt lgkmcnt(8)
	v_mfma_f32_32x32x16_bf16 v[2:17], v[212:215], v[216:219], v[2:17]
	v_mfma_f32_32x32x16_bf16 v[18:33], v[212:215], v[220:223], v[18:33]
	s_waitcnt lgkmcnt(7)
	v_mfma_f32_32x32x16_bf16 v[74:89], v[208:211], v[224:227], v[74:89]
	s_waitcnt lgkmcnt(6)
	v_mfma_f32_32x32x16_bf16 v[90:105], v[208:211], v[228:231], v[90:105]
	v_mfma_f32_32x32x16_bf16 v[106:121], v[212:215], v[224:227], v[106:121]
	v_mfma_f32_32x32x16_bf16 v[122:137], v[212:215], v[228:231], v[122:137]
	s_waitcnt lgkmcnt(4)
	v_mfma_f32_32x32x16_bf16 v[34:49], v[232:235], v[240:243], v[34:49]
	s_waitcnt lgkmcnt(3)
	v_mfma_f32_32x32x16_bf16 v[50:65], v[232:235], v[244:247], v[50:65]
	s_waitcnt lgkmcnt(2)
	v_mfma_f32_32x32x16_bf16 v[2:17], v[236:239], v[240:243], v[2:17]
	v_mfma_f32_32x32x16_bf16 v[18:33], v[236:239], v[244:247], v[18:33]
	s_waitcnt lgkmcnt(1)
	v_mfma_f32_32x32x16_bf16 v[74:89], v[232:235], v[248:251], v[74:89]
	s_waitcnt lgkmcnt(0)
	v_mfma_f32_32x32x16_bf16 v[90:105], v[232:235], v[156:159], v[90:105]
	v_mfma_f32_32x32x16_bf16 v[106:121], v[236:239], v[248:251], v[106:121]
	v_mfma_f32_32x32x16_bf16 v[122:137], v[236:239], v[156:159], v[122:137]
	s_setprio 0
	s_waitcnt vmcnt(6)
	s_barrier
; #define BLOAD(A_, B_, kt) do { _Pragma("unroll") for (int i = 0; i < 4; ++i) { \
;     A_[i] = *(const u32x4*)((const char*)Ap + (aoff + (unsigned)(32 * i * lda + (kt) * 64) * 2u)); B_[i] = *(const u32x4*)((const char*)Wt + (woff + (unsigned)(32 * i * K + (kt) * 64) * 2u)); } } while (0)
; #define BLOAD(A_, B_, kt) do { _Pragma("unroll") for (int i = 0; i < 4; ++i) { \
;     A_[i] = *(const u32x4*)((const char*)Ap + (aoff + (unsigned)(32 * i * lda + (kt) * 64) * 2u)); B_[i] = *(const u32x4*)((const char*)Wt + (woff + (unsigned)(32 * i * K + (kt) * 64) * 2u)); } } while (0)
; #define BSTORE(A_, B_, buf) do { _Pragma("unroll") for (int i = 0; i < 4; ++i) { \
;     *(u32x4*)&As[(buf) * GBUF + (srow + 32 * i) * LDT + sc8] = A_[i]; \
;     *(u32x4*)&Bs[(buf) * GBUF + (srow + 32 * i) * LDT + sc8] = B_[i]; } } while (0)
; template <int NK>
; DI void gemm_run(PF& pf, const u16* __restrict__ Ap, int lda, const u16* __restrict__ Wt, f32x16 (&acc)[2][2], char* smem) {
;     ...
; #pragma unroll
;   for (int kt = 0; kt < nk; kt += 2) {
;     BCOMP(0);
;     BSTORE(pf.a1, pf.b1, 1);
;     if (kt + 3 < nk) BLOAD(pf.a1, pf.b1, kt + 3);
;     __syncthreads();
;     BCOMP(1);
;     if (kt + 2 < nk) { BSTORE(pf.a0, pf.b0, 0); if (kt + 4 < nk) BLOAD(pf.a0, pf.b0, kt + 4); }
;     __syncthreads();
;   }
	s_setprio 1
	ds_read_b128 v[208:211], v138 offset:0
	ds_read_b128 v[216:219], v140 offset:0
	ds_read_b128 v[220:223], v140 offset:2048
	ds_read_b128 v[212:215], v138 offset:2048
	ds_read_b128 v[224:227], v140 offset:8192
	ds_read_b128 v[228:231], v140 offset:10240
	ds_read_b128 v[232:235], v139 offset:0
	ds_read_b128 v[240:243], v141 offset:0
	ds_read_b128 v[244:247], v141 offset:2048
	ds_read_b128 v[236:239], v139 offset:2048
	ds_read_b128 v[248:251], v141 offset:8192
	ds_read_b128 v[156:159], v141 offset:10240
	s_add_u32 m0, s42, 0xc000
	s_add_u32 s28, s28, 0x40
	s_addc_u32 s29, s29, 0
	global_load_lds_dwordx4 v142, s[28:29]
	global_load_lds_dwordx4 v143, s[28:29] offset:1024
	s_add_u32 m0, s43, 0xc000
	s_add_u32 s30, s30, 0x40000
	s_addc_u32 s31, s31, 0
	global_load_lds_dwordx4 v144, s[30:31]
	global_load_lds_dwordx4 v145, s[30:31] offset:1024
	global_load_lds_dwordx4 v146, s[30:31] offset:2048
	global_load_lds_dwordx4 v147, s[30:31] offset:3072
	s_waitcnt lgkmcnt(10)
	v_mfma_f32_32x32x16_bf16 v[34:49], v[208:211], v[216:219], v[34:49]
	s_waitcnt lgkmcnt(9)
	v_mfma_f32_32x32x16_bf16 v[50:65], v[208:211], v[220:223], v[50:65]
	s_waitcnt lgkmcnt(8)
	v_mfma_f32_32x32x16_bf16 v[2:17], v[212:215], v[216:219], v[2:17]
	v_mfma_f32_32x32x16_bf16 v[18:33], v[212:215], v[220:223], v[18:33]
	s_waitcnt lgkmcnt(7)
	v_mfma_f32_32x32x16_bf16 v[74:89], v[208:211], v[224:227], v[74:89]
	s_waitcnt lgkmcnt(6)
	v_mfma_f32_32x32x16_bf16 v[90:105], v[208:211], v[228:231], v[90:105]
	v_mfma_f32_32x32x16_bf16 v[106:121], v[212:215], v[224:227], v[106:121]
	v_mfma_f32_32x32x16_bf16 v[122:137], v[212:215], v[228:231], v[122:137]
	s_waitcnt lgkmcnt(4)
	v_mfma_f32_32x32x16_bf16 v[34:49], v[232:235], v[240:243], v[34:49]
	s_waitcnt lgkmcnt(3)
	v_mfma_f32_32x32x16_bf16 v[50:65], v[232:235], v[244:247], v[50:65]
	s_waitcnt lgkmcnt(2)
	v_mfma_f32_32x32x16_bf16 v[2:17], v[236:239], v[240:243], v[2:17]
	v_mfma_f32_32x32x16_bf16 v[18:33], v[236:239], v[244:247], v[18:33]
	s_waitcnt lgkmcnt(1)
	v_mfma_f32_32x32x16_bf16 v[74:89], v[232:235], v[248:251], v[74:89]
	s_waitcnt lgkmcnt(0)
	v_mfma_f32_32x32x16_bf16 v[90:105], v[232:235], v[156:159], v[90:105]
	v_mfma_f32_32x32x16_bf16 v[106:121], v[236:239], v[248:251], v[106:121]
	v_mfma_f32_32x32x16_bf16 v[122:137], v[236:239], v[156:159], v[122:137]
	s_setprio 0
	s_waitcnt vmcnt(6)
	s_barrier
	s_setprio 1
	ds_read_b128 v[208:211], v138 offset:24576
	ds_read_b128 v[216:219], v140 offset:24576
	ds_read_b128 v[220:223], v140 offset:26624
	ds_read_b128 v[212:215], v138 offset:26624
	ds_read_b128 v[224:227], v140 offset:32768
	ds_read_b128 v[228:231], v140 offset:34816
	ds_read_b128 v[232:235], v139 offset:24576
	ds_read_b128 v[240:243], v141 offset:24576
	ds_read_b128 v[244:247], v141 offset:26624
	ds_read_b128 v[236:239], v139 offset:26624
	ds_read_b128 v[248:251], v141 offset:32768
	ds_read_b128 v[156:159], v141 offset:34816
	s_add_u32 m0, s42, 0x0
	s_add_u32 s28, s28, 0x40
	s_addc_u32 s29, s29, 0
	global_load_lds_dwordx4 v142, s[28:29]
	global_load_lds_dwordx4 v143, s[28:29] offset:1024
	s_add_u32 m0, s43, 0x0
	s_add_u32 s30, s30, 0x40000
	s_addc_u32 s31, s31, 0
	global_load_lds_dwordx4 v144, s[30:31]
	global_load_lds_dwordx4 v145, s[30:31] offset:1024
	global_load_lds_dwordx4 v146, s[30:31] offset:2048
	global_load_lds_dwordx4 v147, s[30:31] offset:3072
	s_waitcnt lgkmcnt(10)
	v_mfma_f32_32x32x16_bf16 v[34:49], v[208:211], v[216:219], v[34:49]
	s_waitcnt lgkmcnt(9)
	v_mfma_f32_32x32x16_bf16 v[50:65], v[208:211], v[220:223], v[50:65]
	s_waitcnt lgkmcnt(8)
	v_mfma_f32_32x32x16_bf16 v[2:17], v[212:215], v[216:219], v[2:17]
	v_mfma_f32_32x32x16_bf16 v[18:33], v[212:215], v[220:223], v[18:33]
	s_waitcnt lgkmcnt(7)
	v_mfma_f32_32x32x16_bf16 v[74:89], v[208:211], v[224:227], v[74:89]
	s_waitcnt lgkmcnt(6)
	v_mfma_f32_32x32x16_bf16 v[90:105], v[208:211], v[228:231], v[90:105]
	v_mfma_f32_32x32x16_bf16 v[106:121], v[212:215], v[224:227], v[106:121]
	v_mfma_f32_32x32x16_bf16 v[122:137], v[212:215], v[228:231], v[122:137]
	s_waitcnt lgkmcnt(4)
	v_mfma_f32_32x32x16_bf16 v[34:49], v[232:235], v[240:243], v[34:49]
	s_waitcnt lgkmcnt(3)
	v_mfma_f32_32x32x16_bf16 v[50:65], v[232:235], v[244:247], v[50:65]
	s_waitcnt lgkmcnt(2)
	v_mfma_f32_32x32x16_bf16 v[2:17], v[236:239], v[240:243], v[2:17]
	v_mfma_f32_32x32x16_bf16 v[18:33], v[236:239], v[244:247], v[18:33]
	s_waitcnt lgkmcnt(1)
	v_mfma_f32_32x32x16_bf16 v[74:89], v[232:235], v[248:251], v[74:89]
	s_waitcnt lgkmcnt(0)
	v_mfma_f32_32x32x16_bf16 v[90:105], v[232:235], v[156:159], v[90:105]
	v_mfma_f32_32x32x16_bf16 v[106:121], v[236:239], v[248:251], v[106:121]
	v_mfma_f32_32x32x16_bf16 v[122:137], v[236:239], v[156:159], v[122:137]
	s_setprio 0
	s_waitcnt vmcnt(6)
	s_barrier
; #define BLOAD(A_, B_, kt) do { _Pragma("unroll") for (int i = 0; i < 4; ++i) { \
;     A_[i] = *(const u32x4*)((const char*)Ap + (aoff + (unsigned)(32 * i * lda + (kt) * 64) * 2u)); B_[i] = *(const u32x4*)((const char*)Wt + (woff + (unsigned)(32 * i * K + (kt) * 64) * 2u)); } } while (0)
; #define BLOAD(A_, B_, kt) do { _Pragma("unroll") for (int i = 0; i < 4; ++i) { \
;     A_[i] = *(const u32x4*)((const char*)Ap + (aoff + (unsigned)(32 * i * lda + (kt) * 64) * 2u)); B_[i] = *(const u32x4*)((const char*)Wt + (woff + (unsigned)(32 * i * K + (kt) * 64) * 2u)); } } while (0)
; #define BSTORE(A_, B_, buf) do { _Pragma("unroll") for (int i = 0; i < 4; ++i) { \
;     *(u32x4*)&As[(buf) * GBUF + (srow + 32 * i) * LDT + sc8] = A_[i]; \
;     *(u32x4*)&Bs[(buf) * GBUF + (srow + 32 * i) * LDT + sc8] = B_[i]; } } while (0)
; template <int NK>
; DI void gemm_run(PF& pf, const u16* __restrict__ Ap, int lda, const u16* __restrict__ Wt, f32x16 (&acc)[2][2], char* smem) {
;     ...
; #pragma unroll
;   for (int kt = 0; kt < nk; kt += 2) {
;     BCOMP(0);
;     BSTORE(pf.a1, pf.b1, 1);
;     if (kt + 3 < nk) BLOAD(pf.a1, pf.b1, kt + 3);
;     __syncthreads();
;     BCOMP(1);
;     if (kt + 2 < nk) { BSTORE(pf.a0, pf.b0, 0); if (kt + 4 < nk) BLOAD(pf.a0, pf.b0, kt + 4); }
;     __syncthreads();
;   }
	s_setprio 1
	ds_read_b128 v[208:211], v138 offset:49152
	ds_read_b128 v[216:219], v140 offset:49152
	ds_read_b128 v[220:223], v140 offset:51200
	ds_read_b128 v[212:215], v138 offset:51200
	ds_read_b128 v[224:227], v140 offset:57344
	ds_read_b128 v[228:231], v140 offset:59392
	ds_read_b128 v[232:235], v139 offset:49152
	ds_read_b128 v[240:243], v141 offset:49152
	ds_read_b128 v[244:247], v141 offset:51200
	ds_read_b128 v[236:239], v139 offset:51200
	ds_read_b128 v[248:251], v141 offset:57344
	ds_read_b128 v[156:159], v141 offset:59392
	s_add_u32 m0, s42, 0x6000
	s_add_u32 s28, s28, 0x40
	s_addc_u32 s29, s29, 0
	global_load_lds_dwordx4 v142, s[28:29]
	global_load_lds_dwordx4 v143, s[28:29] offset:1024
	s_add_u32 m0, s43, 0x6000
	s_add_u32 s30, s30, 0x40000
	s_addc_u32 s31, s31, 0
	global_load_lds_dwordx4 v144, s[30:31]
	global_load_lds_dwordx4 v145, s[30:31] offset:1024
	global_load_lds_dwordx4 v146, s[30:31] offset:2048
	global_load_lds_dwordx4 v147, s[30:31] offset:3072
	s_waitcnt lgkmcnt(10)
	v_mfma_f32_32x32x16_bf16 v[34:49], v[208:211], v[216:219], v[34:49]
	s_waitcnt lgkmcnt(9)
	v_mfma_f32_32x32x16_bf16 v[50:65], v[208:211], v[220:223], v[50:65]
	s_waitcnt lgkmcnt(8)
	v_mfma_f32_32x32x16_bf16 v[2:17], v[212:215], v[216:219], v[2:17]
	v_mfma_f32_32x32x16_bf16 v[18:33], v[212:215], v[220:223], v[18:33]
	s_waitcnt lgkmcnt(7)
	v_mfma_f32_32x32x16_bf16 v[74:89], v[208:211], v[224:227], v[74:89]
	s_waitcnt lgkmcnt(6)
	v_mfma_f32_32x32x16_bf16 v[90:105], v[208:211], v[228:231], v[90:105]
	v_mfma_f32_32x32x16_bf16 v[106:121], v[212:215], v[224:227], v[106:121]
	v_mfma_f32_32x32x16_bf16 v[122:137], v[212:215], v[228:231], v[122:137]
	s_waitcnt lgkmcnt(4)
	v_mfma_f32_32x32x16_bf16 v[34:49], v[232:235], v[240:243], v[34:49]
	s_waitcnt lgkmcnt(3)
	v_mfma_f32_32x32x16_bf16 v[50:65], v[232:235], v[244:247], v[50:65]
	s_waitcnt lgkmcnt(2)
	v_mfma_f32_32x32x16_bf16 v[2:17], v[236:239], v[240:243], v[2:17]
	v_mfma_f32_32x32x16_bf16 v[18:33], v[236:239], v[244:247], v[18:33]
	s_waitcnt lgkmcnt(1)
	v_mfma_f32_32x32x16_bf16 v[74:89], v[232:235], v[248:251], v[74:89]
	s_waitcnt lgkmcnt(0)
	v_mfma_f32_32x32x16_bf16 v[90:105], v[232:235], v[156:159], v[90:105]
	v_mfma_f32_32x32x16_bf16 v[106:121], v[236:239], v[248:251], v[106:121]
	v_mfma_f32_32x32x16_bf16 v[122:137], v[236:239], v[156:159], v[122:137]
	s_setprio 0
	s_waitcnt vmcnt(6)
	s_barrier
	s_setprio 1
	ds_read_b128 v[208:211], v138 offset:0
	ds_read_b128 v[216:219], v140 offset:0
	ds_read_b128 v[220:223], v140 offset:2048
	ds_read_b128 v[212:215], v138 offset:2048
	ds_read_b128 v[224:227], v140 offset:8192
	ds_read_b128 v[228:231], v140 offset:10240
	ds_read_b128 v[232:235], v139 offset:0
	ds_read_b128 v[240:243], v141 offset:0
	ds_read_b128 v[244:247], v141 offset:2048
	ds_read_b128 v[236:239], v139 offset:2048
	ds_read_b128 v[248:251], v141 offset:8192
	ds_read_b128 v[156:159], v141 offset:10240
	s_add_u32 m0, s42, 0xc000
	s_add_u32 s28, s28, 0x40
	s_addc_u32 s29, s29, 0
	global_load_lds_dwordx4 v142, s[28:29]
	global_load_lds_dwordx4 v143, s[28:29] offset:1024
	s_add_u32 m0, s43, 0xc000
	s_add_u32 s30, s30, 0x40000
	s_addc_u32 s31, s31, 0
	global_load_lds_dwordx4 v144, s[30:31]
	global_load_lds_dwordx4 v145, s[30:31] offset:1024
	global_load_lds_dwordx4 v146, s[30:31] offset:2048
	global_load_lds_dwordx4 v147, s[30:31] offset:3072
	s_waitcnt lgkmcnt(10)
	v_mfma_f32_32x32x16_bf16 v[34:49], v[208:211], v[216:219], v[34:49]
	s_waitcnt lgkmcnt(9)
	v_mfma_f32_32x32x16_bf16 v[50:65], v[208:211], v[220:223], v[50:65]
	s_waitcnt lgkmcnt(8)
	v_mfma_f32_32x32x16_bf16 v[2:17], v[212:215], v[216:219], v[2:17]
	v_mfma_f32_32x32x16_bf16 v[18:33], v[212:215], v[220:223], v[18:33]
	s_waitcnt lgkmcnt(7)
	v_mfma_f32_32x32x16_bf16 v[74:89], v[208:211], v[224:227], v[74:89]
	s_waitcnt lgkmcnt(6)
	v_mfma_f32_32x32x16_bf16 v[90:105], v[208:211], v[228:231], v[90:105]
	v_mfma_f32_32x32x16_bf16 v[106:121], v[212:215], v[224:227], v[106:121]
	v_mfma_f32_32x32x16_bf16 v[122:137], v[212:215], v[228:231], v[122:137]
	s_waitcnt lgkmcnt(4)
	v_mfma_f32_32x32x16_bf16 v[34:49], v[232:235], v[240:243], v[34:49]
	s_waitcnt lgkmcnt(3)
	v_mfma_f32_32x32x16_bf16 v[50:65], v[232:235], v[244:247], v[50:65]
	s_waitcnt lgkmcnt(2)
	v_mfma_f32_32x32x16_bf16 v[2:17], v[236:239], v[240:243], v[2:17]
	v_mfma_f32_32x32x16_bf16 v[18:33], v[236:239], v[244:247], v[18:33]
	s_waitcnt lgkmcnt(1)
	v_mfma_f32_32x32x16_bf16 v[74:89], v[232:235], v[248:251], v[74:89]
	s_waitcnt lgkmcnt(0)
	v_mfma_f32_32x32x16_bf16 v[90:105], v[232:235], v[156:159], v[90:105]
	v_mfma_f32_32x32x16_bf16 v[106:121], v[236:239], v[248:251], v[106:121]
	v_mfma_f32_32x32x16_bf16 v[122:137], v[236:239], v[156:159], v[122:137]
	s_setprio 0
	s_waitcnt vmcnt(6)
	s_barrier
; #define BLOAD(A_, B_, kt) do { _Pragma("unroll") for (int i = 0; i < 4; ++i) { \
;     A_[i] = *(const u32x4*)((const char*)Ap + (aoff + (unsigned)(32 * i * lda + (kt) * 64) * 2u)); B_[i] = *(const u32x4*)((const char*)Wt + (woff + (unsigned)(32 * i * K + (kt) * 64) * 2u)); } } while (0)
; #define BLOAD(A_, B_, kt) do { _Pragma("unroll") for (int i = 0; i < 4; ++i) { \
;     A_[i] = *(const u32x4*)((const char*)Ap + (aoff + (unsigned)(32 * i * lda + (kt) * 64) * 2u)); B_[i] = *(const u32x4*)((const char*)Wt + (woff + (unsigned)(32 * i * K + (kt) * 64) * 2u)); } } while (0)
; #define BSTORE(A_, B_, buf) do { _Pragma("unroll") for (int i = 0; i < 4; ++i) { \
;     *(u32x4*)&As[(buf) * GBUF + (srow + 32 * i) * LDT + sc8] = A_[i]; \
;     *(u32x4*)&Bs[(buf) * GBUF + (srow + 32 * i) * LDT + sc8] = B_[i]; } } while (0)
; template <int NK>
; DI void gemm_run(PF& pf, const u16* __restrict__ Ap, int lda, const u16* __restrict__ Wt, f32x16 (&acc)[2][2], char* smem) {
;     ...
; #pragma unroll
;   for (int kt = 0; kt < nk; kt += 2) {
;     BCOMP(0);
;     BSTORE(pf.a1, pf.b1, 1);
;     if (kt + 3 < nk) BLOAD(pf.a1, pf.b1, kt + 3);
;     __syncthreads();
;     BCOMP(1);
;     if (kt + 2 < nk) { BSTORE(pf.a0, pf.b0, 0); if (kt + 4 < nk) BLOAD(pf.a0, pf.b0, kt + 4); }
;     __syncthreads();
;   }
	s_setprio 1
	ds_read_b128 v[208:211], v138 offset:24576
	ds_read_b128 v[216:219], v140 offset:24576
	ds_read_b128 v[220:223], v140 offset:26624
	ds_read_b128 v[212:215], v138 offset:26624
	ds_read_b128 v[224:227], v140 offset:32768
	ds_read_b128 v[228:231], v140 offset:34816
	ds_read_b128 v[232:235], v139 offset:24576
	ds_read_b128 v[240:243], v141 offset:24576
	ds_read_b128 v[244:247], v141 offset:26624
	ds_read_b128 v[236:239], v139 offset:26624
	ds_read_b128 v[248:251], v141 offset:32768
	ds_read_b128 v[156:159], v141 offset:34816
	s_add_u32 m0, s42, 0x0
	s_add_u32 s28, s28, 0x40
	s_addc_u32 s29, s29, 0
	global_load_lds_dwordx4 v142, s[28:29]
	global_load_lds_dwordx4 v143, s[28:29] offset:1024
	s_add_u32 m0, s43, 0x0
	s_add_u32 s30, s30, 0x40000
	s_addc_u32 s31, s31, 0
	global_load_lds_dwordx4 v144, s[30:31]
	global_load_lds_dwordx4 v145, s[30:31] offset:1024
	global_load_lds_dwordx4 v146, s[30:31] offset:2048
	global_load_lds_dwordx4 v147, s[30:31] offset:3072
	s_waitcnt lgkmcnt(10)
	v_mfma_f32_32x32x16_bf16 v[34:49], v[208:211], v[216:219], v[34:49]
	s_waitcnt lgkmcnt(9)
	v_mfma_f32_32x32x16_bf16 v[50:65], v[208:211], v[220:223], v[50:65]
	s_waitcnt lgkmcnt(8)
	v_mfma_f32_32x32x16_bf16 v[2:17], v[212:215], v[216:219], v[2:17]
	v_mfma_f32_32x32x16_bf16 v[18:33], v[212:215], v[220:223], v[18:33]
	s_waitcnt lgkmcnt(7)
	v_mfma_f32_32x32x16_bf16 v[74:89], v[208:211], v[224:227], v[74:89]
	s_waitcnt lgkmcnt(6)
	v_mfma_f32_32x32x16_bf16 v[90:105], v[208:211], v[228:231], v[90:105]
	v_mfma_f32_32x32x16_bf16 v[106:121], v[212:215], v[224:227], v[106:121]
	v_mfma_f32_32x32x16_bf16 v[122:137], v[212:215], v[228:231], v[122:137]
	s_waitcnt lgkmcnt(4)
	v_mfma_f32_32x32x16_bf16 v[34:49], v[232:235], v[240:243], v[34:49]
	s_waitcnt lgkmcnt(3)
	v_mfma_f32_32x32x16_bf16 v[50:65], v[232:235], v[244:247], v[50:65]
	s_waitcnt lgkmcnt(2)
	v_mfma_f32_32x32x16_bf16 v[2:17], v[236:239], v[240:243], v[2:17]
	v_mfma_f32_32x32x16_bf16 v[18:33], v[236:239], v[244:247], v[18:33]
	s_waitcnt lgkmcnt(1)
	v_mfma_f32_32x32x16_bf16 v[74:89], v[232:235], v[248:251], v[74:89]
	s_waitcnt lgkmcnt(0)
	v_mfma_f32_32x32x16_bf16 v[90:105], v[232:235], v[156:159], v[90:105]
	v_mfma_f32_32x32x16_bf16 v[106:121], v[236:239], v[248:251], v[106:121]
	v_mfma_f32_32x32x16_bf16 v[122:137], v[236:239], v[156:159], v[122:137]
	s_setprio 0
	s_waitcnt vmcnt(6)
	s_barrier
	s_setprio 1
	ds_read_b128 v[208:211], v138 offset:49152
	ds_read_b128 v[216:219], v140 offset:49152
	ds_read_b128 v[220:223], v140 offset:51200
	ds_read_b128 v[212:215], v138 offset:51200
	ds_read_b128 v[224:227], v140 offset:57344
	ds_read_b128 v[228:231], v140 offset:59392
	ds_read_b128 v[232:235], v139 offset:49152
	ds_read_b128 v[240:243], v141 offset:49152
	ds_read_b128 v[244:247], v141 offset:51200
	ds_read_b128 v[236:239], v139 offset:51200
	ds_read_b128 v[248:251], v141 offset:57344
	ds_read_b128 v[156:159], v141 offset:59392
	s_add_u32 m0, s42, 0x6000
	s_add_u32 s28, s28, 0x40
	s_addc_u32 s29, s29, 0
	global_load_lds_dwordx4 v142, s[28:29]
	global_load_lds_dwordx4 v143, s[28:29] offset:1024
	s_add_u32 m0, s43, 0x6000
	s_add_u32 s30, s30, 0x40000
	s_addc_u32 s31, s31, 0
	global_load_lds_dwordx4 v144, s[30:31]
	global_load_lds_dwordx4 v145, s[30:31] offset:1024
	global_load_lds_dwordx4 v146, s[30:31] offset:2048
	global_load_lds_dwordx4 v147, s[30:31] offset:3072
	s_waitcnt lgkmcnt(10)
	v_mfma_f32_32x32x16_bf16 v[34:49], v[208:211], v[216:219], v[34:49]
	s_waitcnt lgkmcnt(9)
	v_mfma_f32_32x32x16_bf16 v[50:65], v[208:211], v[220:223], v[50:65]
	s_waitcnt lgkmcnt(8)
	v_mfma_f32_32x32x16_bf16 v[2:17], v[212:215], v[216:219], v[2:17]
	v_mfma_f32_32x32x16_bf16 v[18:33], v[212:215], v[220:223], v[18:33]
	s_waitcnt lgkmcnt(7)
	v_mfma_f32_32x32x16_bf16 v[74:89], v[208:211], v[224:227], v[74:89]
	s_waitcnt lgkmcnt(6)
	v_mfma_f32_32x32x16_bf16 v[90:105], v[208:211], v[228:231], v[90:105]
	v_mfma_f32_32x32x16_bf16 v[106:121], v[212:215], v[224:227], v[106:121]
	v_mfma_f32_32x32x16_bf16 v[122:137], v[212:215], v[228:231], v[122:137]
	s_waitcnt lgkmcnt(4)
	v_mfma_f32_32x32x16_bf16 v[34:49], v[232:235], v[240:243], v[34:49]
	s_waitcnt lgkmcnt(3)
	v_mfma_f32_32x32x16_bf16 v[50:65], v[232:235], v[244:247], v[50:65]
	s_waitcnt lgkmcnt(2)
	v_mfma_f32_32x32x16_bf16 v[2:17], v[236:239], v[240:243], v[2:17]
	v_mfma_f32_32x32x16_bf16 v[18:33], v[236:239], v[244:247], v[18:33]
	s_waitcnt lgkmcnt(1)
	v_mfma_f32_32x32x16_bf16 v[74:89], v[232:235], v[248:251], v[74:89]
	s_waitcnt lgkmcnt(0)
	v_mfma_f32_32x32x16_bf16 v[90:105], v[232:235], v[156:159], v[90:105]
	v_mfma_f32_32x32x16_bf16 v[106:121], v[236:239], v[248:251], v[106:121]
	v_mfma_f32_32x32x16_bf16 v[122:137], v[236:239], v[156:159], v[122:137]
	s_setprio 0
	s_waitcnt vmcnt(6)
	s_barrier
; #define BLOAD(A_, B_, kt) do { _Pragma("unroll") for (int i = 0; i < 4; ++i) { \
;     A_[i] = *(const u32x4*)((const char*)Ap + (aoff + (unsigned)(32 * i * lda + (kt) * 64) * 2u)); B_[i] = *(const u32x4*)((const char*)Wt + (woff + (unsigned)(32 * i * K + (kt) * 64) * 2u)); } } while (0)
; #define BLOAD(A_, B_, kt) do { _Pragma("unroll") for (int i = 0; i < 4; ++i) { \
;     A_[i] = *(const u32x4*)((const char*)Ap + (aoff + (unsigned)(32 * i * lda + (kt) * 64) * 2u)); B_[i] = *(const u32x4*)((const char*)Wt + (woff + (unsigned)(32 * i * K + (kt) * 64) * 2u)); } } while (0)
; #define BSTORE(A_, B_, buf) do { _Pragma("unroll") for (int i = 0; i < 4; ++i) { \
;     *(u32x4*)&As[(buf) * GBUF + (srow + 32 * i) * LDT + sc8] = A_[i]; \
;     *(u32x4*)&Bs[(buf) * GBUF + (srow + 32 * i) * LDT + sc8] = B_[i]; } } while (0)
; template <int NK>
; DI void gemm_run(PF& pf, const u16* __restrict__ Ap, int lda, const u16* __restrict__ Wt, f32x16 (&acc)[2][2], char* smem) {
;     ...
; #pragma unroll
;   for (int kt = 0; kt < nk; kt += 2) {
;     BCOMP(0);
;     BSTORE(pf.a1, pf.b1, 1);
;     if (kt + 3 < nk) BLOAD(pf.a1, pf.b1, kt + 3);
;     __syncthreads();
;     BCOMP(1);
;     if (kt + 2 < nk) { BSTORE(pf.a0, pf.b0, 0); if (kt + 4 < nk) BLOAD(pf.a0, pf.b0, kt + 4); }
;     __syncthreads();
;   }
	s_setprio 1
	ds_read_b128 v[208:211], v138 offset:0
	ds_read_b128 v[216:219], v140 offset:0
	ds_read_b128 v[220:223], v140 offset:2048
	ds_read_b128 v[212:215], v138 offset:2048
	ds_read_b128 v[224:227], v140 offset:8192
	ds_read_b128 v[228:231], v140 offset:10240
	ds_read_b128 v[232:235], v139 offset:0
	ds_read_b128 v[240:243], v141 offset:0
	ds_read_b128 v[244:247], v141 offset:2048
	ds_read_b128 v[236:239], v139 offset:2048
	ds_read_b128 v[248:251], v141 offset:8192
	ds_read_b128 v[156:159], v141 offset:10240
	s_add_u32 m0, s42, 0xc000
	s_add_u32 s28, s28, 0x40
	s_addc_u32 s29, s29, 0
	global_load_lds_dwordx4 v142, s[28:29]
	global_load_lds_dwordx4 v143, s[28:29] offset:1024
	s_add_u32 m0, s43, 0xc000
	s_add_u32 s30, s30, 0x40000
	s_addc_u32 s31, s31, 0
	global_load_lds_dwordx4 v144, s[30:31]
	global_load_lds_dwordx4 v145, s[30:31] offset:1024
	global_load_lds_dwordx4 v146, s[30:31] offset:2048
	global_load_lds_dwordx4 v147, s[30:31] offset:3072
	s_waitcnt lgkmcnt(10)
	v_mfma_f32_32x32x16_bf16 v[34:49], v[208:211], v[216:219], v[34:49]
	s_waitcnt lgkmcnt(9)
	v_mfma_f32_32x32x16_bf16 v[50:65], v[208:211], v[220:223], v[50:65]
	s_waitcnt lgkmcnt(8)
	v_mfma_f32_32x32x16_bf16 v[2:17], v[212:215], v[216:219], v[2:17]
	v_mfma_f32_32x32x16_bf16 v[18:33], v[212:215], v[220:223], v[18:33]
	s_waitcnt lgkmcnt(7)
	v_mfma_f32_32x32x16_bf16 v[74:89], v[208:211], v[224:227], v[74:89]
	s_waitcnt lgkmcnt(6)
	v_mfma_f32_32x32x16_bf16 v[90:105], v[208:211], v[228:231], v[90:105]
	v_mfma_f32_32x32x16_bf16 v[106:121], v[212:215], v[224:227], v[106:121]
	v_mfma_f32_32x32x16_bf16 v[122:137], v[212:215], v[228:231], v[122:137]
	s_waitcnt lgkmcnt(4)
	v_mfma_f32_32x32x16_bf16 v[34:49], v[232:235], v[240:243], v[34:49]
	s_waitcnt lgkmcnt(3)
	v_mfma_f32_32x32x16_bf16 v[50:65], v[232:235], v[244:247], v[50:65]
	s_waitcnt lgkmcnt(2)
	v_mfma_f32_32x32x16_bf16 v[2:17], v[236:239], v[240:243], v[2:17]
	v_mfma_f32_32x32x16_bf16 v[18:33], v[236:239], v[244:247], v[18:33]
	s_waitcnt lgkmcnt(1)
	v_mfma_f32_32x32x16_bf16 v[74:89], v[232:235], v[248:251], v[74:89]
	s_waitcnt lgkmcnt(0)
	v_mfma_f32_32x32x16_bf16 v[90:105], v[232:235], v[156:159], v[90:105]
	v_mfma_f32_32x32x16_bf16 v[106:121], v[236:239], v[248:251], v[106:121]
	v_mfma_f32_32x32x16_bf16 v[122:137], v[236:239], v[156:159], v[122:137]
	s_setprio 0
	s_waitcnt vmcnt(6)
	s_barrier
	s_setprio 1
	ds_read_b128 v[208:211], v138 offset:24576
	ds_read_b128 v[216:219], v140 offset:24576
	ds_read_b128 v[220:223], v140 offset:26624
	ds_read_b128 v[212:215], v138 offset:26624
	ds_read_b128 v[224:227], v140 offset:32768
	ds_read_b128 v[228:231], v140 offset:34816
	ds_read_b128 v[232:235], v139 offset:24576
	ds_read_b128 v[240:243], v141 offset:24576
	ds_read_b128 v[244:247], v141 offset:26624
	ds_read_b128 v[236:239], v139 offset:26624
	ds_read_b128 v[248:251], v141 offset:32768
	ds_read_b128 v[156:159], v141 offset:34816
	s_add_u32 m0, s42, 0x0
	s_add_u32 s28, s28, 0x40
	s_addc_u32 s29, s29, 0
	global_load_lds_dwordx4 v142, s[28:29]
	global_load_lds_dwordx4 v143, s[28:29] offset:1024
	s_add_u32 m0, s43, 0x0
	s_add_u32 s30, s30, 0x40000
	s_addc_u32 s31, s31, 0
	global_load_lds_dwordx4 v144, s[30:31]
	global_load_lds_dwordx4 v145, s[30:31] offset:1024
	global_load_lds_dwordx4 v146, s[30:31] offset:2048
	global_load_lds_dwordx4 v147, s[30:31] offset:3072
	s_waitcnt lgkmcnt(10)
	v_mfma_f32_32x32x16_bf16 v[34:49], v[208:211], v[216:219], v[34:49]
	s_waitcnt lgkmcnt(9)
	v_mfma_f32_32x32x16_bf16 v[50:65], v[208:211], v[220:223], v[50:65]
	s_waitcnt lgkmcnt(8)
	v_mfma_f32_32x32x16_bf16 v[2:17], v[212:215], v[216:219], v[2:17]
	v_mfma_f32_32x32x16_bf16 v[18:33], v[212:215], v[220:223], v[18:33]
	s_waitcnt lgkmcnt(7)
	v_mfma_f32_32x32x16_bf16 v[74:89], v[208:211], v[224:227], v[74:89]
	s_waitcnt lgkmcnt(6)
	v_mfma_f32_32x32x16_bf16 v[90:105], v[208:211], v[228:231], v[90:105]
	v_mfma_f32_32x32x16_bf16 v[106:121], v[212:215], v[224:227], v[106:121]
	v_mfma_f32_32x32x16_bf16 v[122:137], v[212:215], v[228:231], v[122:137]
	s_waitcnt lgkmcnt(4)
	v_mfma_f32_32x32x16_bf16 v[34:49], v[232:235], v[240:243], v[34:49]
	s_waitcnt lgkmcnt(3)
	v_mfma_f32_32x32x16_bf16 v[50:65], v[232:235], v[244:247], v[50:65]
	s_waitcnt lgkmcnt(2)
	v_mfma_f32_32x32x16_bf16 v[2:17], v[236:239], v[240:243], v[2:17]
	v_mfma_f32_32x32x16_bf16 v[18:33], v[236:239], v[244:247], v[18:33]
	s_waitcnt lgkmcnt(1)
	v_mfma_f32_32x32x16_bf16 v[74:89], v[232:235], v[248:251], v[74:89]
	s_waitcnt lgkmcnt(0)
	v_mfma_f32_32x32x16_bf16 v[90:105], v[232:235], v[156:159], v[90:105]
	v_mfma_f32_32x32x16_bf16 v[106:121], v[236:239], v[248:251], v[106:121]
	v_mfma_f32_32x32x16_bf16 v[122:137], v[236:239], v[156:159], v[122:137]
	s_setprio 0
	s_waitcnt vmcnt(6)
	s_barrier
; #define BLOAD(A_, B_, kt) do { _Pragma("unroll") for (int i = 0; i < 4; ++i) { \
;     A_[i] = *(const u32x4*)((const char*)Ap + (aoff + (unsigned)(32 * i * lda + (kt) * 64) * 2u)); B_[i] = *(const u32x4*)((const char*)Wt + (woff + (unsigned)(32 * i * K + (kt) * 64) * 2u)); } } while (0)
; #define BLOAD(A_, B_, kt) do { _Pragma("unroll") for (int i = 0; i < 4; ++i) { \
;     A_[i] = *(const u32x4*)((const char*)Ap + (aoff + (unsigned)(32 * i * lda + (kt) * 64) * 2u)); B_[i] = *(const u32x4*)((const char*)Wt + (woff + (unsigned)(32 * i * K + (kt) * 64) * 2u)); } } while (0)
; #define BSTORE(A_, B_, buf) do { _Pragma("unroll") for (int i = 0; i < 4; ++i) { \
;     *(u32x4*)&As[(buf) * GBUF + (srow + 32 * i) * LDT + sc8] = A_[i]; \
;     *(u32x4*)&Bs[(buf) * GBUF + (srow + 32 * i) * LDT + sc8] = B_[i]; } } while (0)
; template <int NK>
; DI void gemm_run(PF& pf, const u16* __restrict__ Ap, int lda, const u16* __restrict__ Wt, f32x16 (&acc)[2][2], char* smem) {
;     ...
; #pragma unroll
;   for (int kt = 0; kt < nk; kt += 2) {
;     BCOMP(0);
;     BSTORE(pf.a1, pf.b1, 1);
;     if (kt + 3 < nk) BLOAD(pf.a1, pf.b1, kt + 3);
;     __syncthreads();
;     BCOMP(1);
;     if (kt + 2 < nk) { BSTORE(pf.a0, pf.b0, 0); if (kt + 4 < nk) BLOAD(pf.a0, pf.b0, kt + 4); }
;     __syncthreads();
;   }
	s_setprio 1
	ds_read_b128 v[208:211], v138 offset:49152
	ds_read_b128 v[216:219], v140 offset:49152
	ds_read_b128 v[220:223], v140 offset:51200
	ds_read_b128 v[212:215], v138 offset:51200
	ds_read_b128 v[224:227], v140 offset:57344
	ds_read_b128 v[228:231], v140 offset:59392
	ds_read_b128 v[232:235], v139 offset:49152
	ds_read_b128 v[240:243], v141 offset:49152
	ds_read_b128 v[244:247], v141 offset:51200
	ds_read_b128 v[236:239], v139 offset:51200
	ds_read_b128 v[248:251], v141 offset:57344
	ds_read_b128 v[156:159], v141 offset:59392
	s_add_u32 m0, s42, 0x6000
	s_add_u32 s28, s28, 0x40
	s_addc_u32 s29, s29, 0
	global_load_lds_dwordx4 v142, s[28:29]
	global_load_lds_dwordx4 v143, s[28:29] offset:1024
	s_add_u32 m0, s43, 0x6000
	s_add_u32 s30, s30, 0x40000
	s_addc_u32 s31, s31, 0
	global_load_lds_dwordx4 v144, s[30:31]
	global_load_lds_dwordx4 v145, s[30:31] offset:1024
	global_load_lds_dwordx4 v146, s[30:31] offset:2048
	global_load_lds_dwordx4 v147, s[30:31] offset:3072
	s_waitcnt lgkmcnt(10)
	v_mfma_f32_32x32x16_bf16 v[34:49], v[208:211], v[216:219], v[34:49]
	s_waitcnt lgkmcnt(9)
	v_mfma_f32_32x32x16_bf16 v[50:65], v[208:211], v[220:223], v[50:65]
	s_waitcnt lgkmcnt(8)
	v_mfma_f32_32x32x16_bf16 v[2:17], v[212:215], v[216:219], v[2:17]
	v_mfma_f32_32x32x16_bf16 v[18:33], v[212:215], v[220:223], v[18:33]
	s_waitcnt lgkmcnt(7)
	v_mfma_f32_32x32x16_bf16 v[74:89], v[208:211], v[224:227], v[74:89]
	s_waitcnt lgkmcnt(6)
	v_mfma_f32_32x32x16_bf16 v[90:105], v[208:211], v[228:231], v[90:105]
	v_mfma_f32_32x32x16_bf16 v[106:121], v[212:215], v[224:227], v[106:121]
	v_mfma_f32_32x32x16_bf16 v[122:137], v[212:215], v[228:231], v[122:137]
	s_waitcnt lgkmcnt(4)
	v_mfma_f32_32x32x16_bf16 v[34:49], v[232:235], v[240:243], v[34:49]
	s_waitcnt lgkmcnt(3)
	v_mfma_f32_32x32x16_bf16 v[50:65], v[232:235], v[244:247], v[50:65]
	s_waitcnt lgkmcnt(2)
	v_mfma_f32_32x32x16_bf16 v[2:17], v[236:239], v[240:243], v[2:17]
	v_mfma_f32_32x32x16_bf16 v[18:33], v[236:239], v[244:247], v[18:33]
	s_waitcnt lgkmcnt(1)
	v_mfma_f32_32x32x16_bf16 v[74:89], v[232:235], v[248:251], v[74:89]
	s_waitcnt lgkmcnt(0)
	v_mfma_f32_32x32x16_bf16 v[90:105], v[232:235], v[156:159], v[90:105]
	v_mfma_f32_32x32x16_bf16 v[106:121], v[236:239], v[248:251], v[106:121]
	v_mfma_f32_32x32x16_bf16 v[122:137], v[236:239], v[156:159], v[122:137]
	s_setprio 0
	s_waitcnt vmcnt(6)
	s_barrier
	s_setprio 1
	ds_read_b128 v[208:211], v138 offset:0
	ds_read_b128 v[216:219], v140 offset:0
	ds_read_b128 v[220:223], v140 offset:2048
	ds_read_b128 v[212:215], v138 offset:2048
	ds_read_b128 v[224:227], v140 offset:8192
	ds_read_b128 v[228:231], v140 offset:10240
	ds_read_b128 v[232:235], v139 offset:0
	ds_read_b128 v[240:243], v141 offset:0
	ds_read_b128 v[244:247], v141 offset:2048
	ds_read_b128 v[236:239], v139 offset:2048
	ds_read_b128 v[248:251], v141 offset:8192
	ds_read_b128 v[156:159], v141 offset:10240
	s_waitcnt lgkmcnt(10)
	v_mfma_f32_32x32x16_bf16 v[34:49], v[208:211], v[216:219], v[34:49]
	s_waitcnt lgkmcnt(9)
	v_mfma_f32_32x32x16_bf16 v[50:65], v[208:211], v[220:223], v[50:65]
	s_waitcnt lgkmcnt(8)
	v_mfma_f32_32x32x16_bf16 v[2:17], v[212:215], v[216:219], v[2:17]
	v_mfma_f32_32x32x16_bf16 v[18:33], v[212:215], v[220:223], v[18:33]
	s_waitcnt lgkmcnt(7)
	v_mfma_f32_32x32x16_bf16 v[74:89], v[208:211], v[224:227], v[74:89]
	s_waitcnt lgkmcnt(6)
	v_mfma_f32_32x32x16_bf16 v[90:105], v[208:211], v[228:231], v[90:105]
	v_mfma_f32_32x32x16_bf16 v[106:121], v[212:215], v[224:227], v[106:121]
	v_mfma_f32_32x32x16_bf16 v[122:137], v[212:215], v[228:231], v[122:137]
	s_waitcnt lgkmcnt(4)
	v_mfma_f32_32x32x16_bf16 v[34:49], v[232:235], v[240:243], v[34:49]
	s_waitcnt lgkmcnt(3)
	v_mfma_f32_32x32x16_bf16 v[50:65], v[232:235], v[244:247], v[50:65]
	s_waitcnt lgkmcnt(2)
	v_mfma_f32_32x32x16_bf16 v[2:17], v[236:239], v[240:243], v[2:17]
	v_mfma_f32_32x32x16_bf16 v[18:33], v[236:239], v[244:247], v[18:33]
	s_waitcnt lgkmcnt(1)
	v_mfma_f32_32x32x16_bf16 v[74:89], v[232:235], v[248:251], v[74:89]
	s_waitcnt lgkmcnt(0)
	v_mfma_f32_32x32x16_bf16 v[90:105], v[232:235], v[156:159], v[90:105]
	v_mfma_f32_32x32x16_bf16 v[106:121], v[236:239], v[248:251], v[106:121]
	v_mfma_f32_32x32x16_bf16 v[122:137], v[236:239], v[156:159], v[122:137]
	s_setprio 0
	s_waitcnt vmcnt(0)
	s_barrier
	s_setprio 1
	ds_read_b128 v[208:211], v138 offset:24576
	ds_read_b128 v[216:219], v140 offset:24576
	ds_read_b128 v[220:223], v140 offset:26624
	ds_read_b128 v[212:215], v138 offset:26624
	ds_read_b128 v[224:227], v140 offset:32768
	ds_read_b128 v[228:231], v140 offset:34816
	ds_read_b128 v[232:235], v139 offset:24576
	ds_read_b128 v[240:243], v141 offset:24576
	ds_read_b128 v[244:247], v141 offset:26624
	ds_read_b128 v[236:239], v139 offset:26624
	ds_read_b128 v[248:251], v141 offset:32768
	ds_read_b128 v[156:159], v141 offset:34816
	s_waitcnt lgkmcnt(10)
	v_mfma_f32_32x32x16_bf16 v[34:49], v[208:211], v[216:219], v[34:49]
	s_waitcnt lgkmcnt(9)
	v_mfma_f32_32x32x16_bf16 v[50:65], v[208:211], v[220:223], v[50:65]
	s_waitcnt lgkmcnt(8)
	v_mfma_f32_32x32x16_bf16 v[2:17], v[212:215], v[216:219], v[2:17]
	v_mfma_f32_32x32x16_bf16 v[18:33], v[212:215], v[220:223], v[18:33]
	s_waitcnt lgkmcnt(7)
	v_mfma_f32_32x32x16_bf16 v[74:89], v[208:211], v[224:227], v[74:89]
	s_waitcnt lgkmcnt(6)
	v_mfma_f32_32x32x16_bf16 v[90:105], v[208:211], v[228:231], v[90:105]
	v_mfma_f32_32x32x16_bf16 v[106:121], v[212:215], v[224:227], v[106:121]
	v_mfma_f32_32x32x16_bf16 v[122:137], v[212:215], v[228:231], v[122:137]
	s_waitcnt lgkmcnt(4)
	v_mfma_f32_32x32x16_bf16 v[34:49], v[232:235], v[240:243], v[34:49]
	s_waitcnt lgkmcnt(3)
	v_mfma_f32_32x32x16_bf16 v[50:65], v[232:235], v[244:247], v[50:65]
	s_waitcnt lgkmcnt(2)
	v_mfma_f32_32x32x16_bf16 v[2:17], v[236:239], v[240:243], v[2:17]
	v_mfma_f32_32x32x16_bf16 v[18:33], v[236:239], v[244:247], v[18:33]
	s_waitcnt lgkmcnt(1)
	v_mfma_f32_32x32x16_bf16 v[74:89], v[232:235], v[248:251], v[74:89]
	s_waitcnt lgkmcnt(0)
	v_mfma_f32_32x32x16_bf16 v[90:105], v[232:235], v[156:159], v[90:105]
	v_mfma_f32_32x32x16_bf16 v[106:121], v[236:239], v[248:251], v[106:121]
	v_mfma_f32_32x32x16_bf16 v[122:137], v[236:239], v[156:159], v[122:137]
	s_setprio 0
	s_barrier
